# speedup vs baseline: 1.0163x; 1.0082x over previous
; #define STAGE(P, RS, SOFF, OFF, kt) do { const int _so = (SOFF) + (kt) * (BK * 2); \
;     _Pragma("unroll") for (int _i = 0; _i < 2; ++_i) { \
;       __builtin_amdgcn_raw_ptr_buffer_load_lds(RS, (__attribute__((address_space(3))) void*)((P) + wave * 1024 + _i * 8192), 16, OFF[_i], _so, 0, 0); } } while (0)
; #define LDA(dst, b, h) _Pragma("unroll") for (int m = 0; m < 4; ++m) _Pragma("unroll") for (int k = 0; k < 2; ++k) \
;     dst[m][k] = *reinterpret_cast<const bf16x8*>(SA(b, h) + lds_byte(wr * 64 + m * 16 + fr, k * 32 + fq * 8))
; #define LDB(dst, b, h) _Pragma("unroll") for (int n = 0; n < 2; ++n) _Pragma("unroll") for (int k = 0; k < 2; ++k) \
;     dst[n][k] = *reinterpret_cast<const bf16x8*>(SB(b, h) + lds_byte(wc * 32 + n * 16 + fr, k * 32 + fq * 8))
; #define WAIT_V(n) asm volatile("s_waitcnt vmcnt(" #n ")" ::: "memory")
; #define WAIT_L(n) asm volatile("s_waitcnt lgkmcnt(" #n ")" ::: "memory")
; #define BAR __builtin_amdgcn_s_barrier()
; #define SCHED __builtin_amdgcn_sched_barrier(0)
;     ...
;       LDB(B0, 0, 0); SCHED; LDA(At, 0, 0); STAGE(SA(1, 1), rsA, sA1, offA, t + 1);
;       WAIT_L(8); BAR; WAIT_L(0); MMA(0, 0, At, B0); BAR; SCHED;
;       LDB(B1, 0, 1); STAGE(SB(0, 0), rsB, sB0, offB, t + 2);
;       BAR; WAIT_L(0); MMA(0, 1, At, B1); BAR;
;       LDA(At, 0, 1); STAGE(SA(0, 0), rsA, sA0, offA, t + 2);
;       BAR; WAIT_L(0); MMA(1, 0, At, B0); BAR; SCHED;
;       STAGE(SB(0, 1), rsB, sB1, offB, t + 2);
;       WAIT_V(6); BAR; MMA(1, 1, At, B1); BAR;
.LBB0_95:
	ds_read_b128 v[154:157], v149
	ds_read_b128 v[158:161], v150
	ds_read_b128 v[162:165], v151
	ds_read_b128 v[166:169], v152
	s_add_i32 s43, s37, s15
	s_add_i32 s10, s43, 0x80
	s_mov_b32 m0, s30
	ds_read_b128 v[170:173], v131
	ds_read_b128 v[174:177], v131 offset:1024
	ds_read_b128 v[178:181], v134
	ds_read_b128 v[182:185], v134 offset:1024
	ds_read_b128 v[186:189], v133
	ds_read_b128 v[190:193], v133 offset:1024
	ds_read_b128 v[194:197], v132
	ds_read_b128 v[198:201], v132 offset:1024
	buffer_load_dwordx4 v143, s[4:7], s10 offen lds
	s_mov_b32 m0, s31
	s_nop 0
	buffer_load_dwordx4 v144, s[4:7], s10 offen lds
	s_waitcnt lgkmcnt(8)
	s_barrier
	s_waitcnt lgkmcnt(0)
	s_waitcnt lgkmcnt(7)
	v_mfma_f32_16x16x32_bf16 v[124:127], v[154:157], v[170:173], v[124:127]
	v_mfma_f32_16x16x32_bf16 v[120:123], v[162:165], v[170:173], v[120:123]
	s_waitcnt lgkmcnt(5)
	v_mfma_f32_16x16x32_bf16 v[116:119], v[154:157], v[178:181], v[116:119]
	v_mfma_f32_16x16x32_bf16 v[112:115], v[162:165], v[178:181], v[112:115]
	s_waitcnt lgkmcnt(3)
	v_mfma_f32_16x16x32_bf16 v[108:111], v[154:157], v[186:189], v[108:111]
	v_mfma_f32_16x16x32_bf16 v[104:107], v[162:165], v[186:189], v[104:107]
	s_waitcnt lgkmcnt(1)
	v_mfma_f32_16x16x32_bf16 v[100:103], v[154:157], v[194:197], v[100:103]
	v_mfma_f32_16x16x32_bf16 v[96:99], v[162:165], v[194:197], v[96:99]
	v_mfma_f32_16x16x32_bf16 v[124:127], v[158:161], v[174:177], v[124:127]
	v_mfma_f32_16x16x32_bf16 v[120:123], v[166:169], v[174:177], v[120:123]
	v_mfma_f32_16x16x32_bf16 v[116:119], v[158:161], v[182:185], v[116:119]
	v_mfma_f32_16x16x32_bf16 v[112:115], v[166:169], v[182:185], v[112:115]
	v_mfma_f32_16x16x32_bf16 v[108:111], v[158:161], v[190:193], v[108:111]
	v_mfma_f32_16x16x32_bf16 v[104:107], v[166:169], v[190:193], v[104:107]
	s_waitcnt lgkmcnt(0)
	v_mfma_f32_16x16x32_bf16 v[100:103], v[158:161], v[198:201], v[100:103]
	v_mfma_f32_16x16x32_bf16 v[96:99], v[166:169], v[198:201], v[96:99]
	s_barrier
	s_add_i32 s44, s39, s15
	s_add_i32 s45, s44, 0x100
	s_mov_b32 s10, s6
	s_mov_b32 s11, s7
	s_mov_b32 m0, s1
	ds_read_b128 v[202:205], v145
	ds_read_b128 v[206:209], v146
	ds_read_b128 v[210:213], v147
	ds_read_b128 v[214:217], v148
	buffer_load_dwordx4 v143, s[8:11], s45 offen lds
	s_mov_b32 m0, s3
	s_nop 0
	buffer_load_dwordx4 v144, s[8:11], s45 offen lds
	s_barrier
	s_waitcnt lgkmcnt(0)
	s_waitcnt lgkmcnt(3)
	v_mfma_f32_16x16x32_bf16 v[92:95], v[202:205], v[170:173], v[92:95]
	s_waitcnt lgkmcnt(1)
	v_mfma_f32_16x16x32_bf16 v[88:91], v[210:213], v[170:173], v[88:91]
	v_mfma_f32_16x16x32_bf16 v[84:87], v[202:205], v[178:181], v[84:87]
	v_mfma_f32_16x16x32_bf16 v[80:83], v[210:213], v[178:181], v[80:83]
	v_mfma_f32_16x16x32_bf16 v[76:79], v[202:205], v[186:189], v[76:79]
	v_mfma_f32_16x16x32_bf16 v[72:75], v[210:213], v[186:189], v[72:75]
	v_mfma_f32_16x16x32_bf16 v[68:71], v[202:205], v[194:197], v[68:71]
	v_mfma_f32_16x16x32_bf16 v[64:67], v[210:213], v[194:197], v[64:67]
	v_mfma_f32_16x16x32_bf16 v[92:95], v[206:209], v[174:177], v[92:95]
	s_waitcnt lgkmcnt(0)
	v_mfma_f32_16x16x32_bf16 v[88:91], v[214:217], v[174:177], v[88:91]
	v_mfma_f32_16x16x32_bf16 v[84:87], v[206:209], v[182:185], v[84:87]
	v_mfma_f32_16x16x32_bf16 v[80:83], v[214:217], v[182:185], v[80:83]
	v_mfma_f32_16x16x32_bf16 v[76:79], v[206:209], v[190:193], v[76:79]
	v_mfma_f32_16x16x32_bf16 v[72:75], v[214:217], v[190:193], v[72:75]
	v_mfma_f32_16x16x32_bf16 v[68:71], v[206:209], v[198:201], v[68:71]
	v_mfma_f32_16x16x32_bf16 v[64:67], v[214:217], v[198:201], v[64:67]
	s_add_i32 s45, s38, s15
	s_add_i32 s46, s45, 0x100
	s_mov_b32 m0, s0
	s_barrier
	ds_read_b128 v[170:173], v131 offset:16384
	ds_read_b128 v[174:177], v131 offset:17408
	ds_read_b128 v[178:181], v134 offset:16384
	ds_read_b128 v[182:185], v134 offset:17408
	ds_read_b128 v[186:189], v133 offset:16384
	ds_read_b128 v[190:193], v133 offset:17408
	ds_read_b128 v[194:197], v132 offset:16384
	ds_read_b128 v[198:201], v132 offset:17408
	buffer_load_dwordx4 v143, s[4:7], s46 offen lds
	s_mov_b32 m0, s18
	s_nop 0
	buffer_load_dwordx4 v144, s[4:7], s46 offen lds
	s_barrier
	s_waitcnt lgkmcnt(0)
	s_waitcnt lgkmcnt(7)
	v_mfma_f32_16x16x32_bf16 v[60:63], v[154:157], v[170:173], v[60:63]
	v_mfma_f32_16x16x32_bf16 v[56:59], v[162:165], v[170:173], v[56:59]
	s_waitcnt lgkmcnt(5)
	v_mfma_f32_16x16x32_bf16 v[52:55], v[154:157], v[178:181], v[52:55]
	v_mfma_f32_16x16x32_bf16 v[48:51], v[162:165], v[178:181], v[48:51]
	s_waitcnt lgkmcnt(3)
	v_mfma_f32_16x16x32_bf16 v[44:47], v[154:157], v[186:189], v[44:47]
	v_mfma_f32_16x16x32_bf16 v[40:43], v[162:165], v[186:189], v[40:43]
	s_waitcnt lgkmcnt(1)
	v_mfma_f32_16x16x32_bf16 v[36:39], v[154:157], v[194:197], v[36:39]
	v_mfma_f32_16x16x32_bf16 v[32:35], v[162:165], v[194:197], v[32:35]
	v_mfma_f32_16x16x32_bf16 v[60:63], v[158:161], v[174:177], v[60:63]
	v_mfma_f32_16x16x32_bf16 v[56:59], v[166:169], v[174:177], v[56:59]
	v_mfma_f32_16x16x32_bf16 v[52:55], v[158:161], v[182:185], v[52:55]
	v_mfma_f32_16x16x32_bf16 v[48:51], v[166:169], v[182:185], v[48:51]
	v_mfma_f32_16x16x32_bf16 v[44:47], v[158:161], v[190:193], v[44:47]
	v_mfma_f32_16x16x32_bf16 v[40:43], v[166:169], v[190:193], v[40:43]
	s_waitcnt lgkmcnt(0)
	v_mfma_f32_16x16x32_bf16 v[36:39], v[158:161], v[198:201], v[36:39]
	v_mfma_f32_16x16x32_bf16 v[32:35], v[166:169], v[198:201], v[32:35]
	s_barrier
	s_add_i32 s46, s40, s15
	s_add_i32 s47, s46, 0x100
	s_mov_b32 m0, s19
	s_nop 0
	buffer_load_dwordx4 v143, s[8:11], s47 offen lds
	s_mov_b32 m0, s20
	s_nop 0
	buffer_load_dwordx4 v144, s[8:11], s47 offen lds
	s_waitcnt vmcnt(6)
	s_barrier
; #define STAGE(P, RS, SOFF, OFF, kt) do { const int _so = (SOFF) + (kt) * (BK * 2); \
;     _Pragma("unroll") for (int _i = 0; _i < 2; ++_i) { \
;       __builtin_amdgcn_raw_ptr_buffer_load_lds(RS, (__attribute__((address_space(3))) void*)((P) + wave * 1024 + _i * 8192), 16, OFF[_i], _so, 0, 0); } } while (0)
; #define LDA(dst, b, h) _Pragma("unroll") for (int m = 0; m < 4; ++m) _Pragma("unroll") for (int k = 0; k < 2; ++k) \
;     dst[m][k] = *reinterpret_cast<const bf16x8*>(SA(b, h) + lds_byte(wr * 64 + m * 16 + fr, k * 32 + fq * 8))
; #define LDB(dst, b, h) _Pragma("unroll") for (int n = 0; n < 2; ++n) _Pragma("unroll") for (int k = 0; k < 2; ++k) \
;     dst[n][k] = *reinterpret_cast<const bf16x8*>(SB(b, h) + lds_byte(wc * 32 + n * 16 + fr, k * 32 + fq * 8))
; #define WAIT_V(n) asm volatile("s_waitcnt vmcnt(" #n ")" ::: "memory")
; #define WAIT_L(n) asm volatile("s_waitcnt lgkmcnt(" #n ")" ::: "memory")
; #define BAR __builtin_amdgcn_s_barrier()
; #define SCHED __builtin_amdgcn_sched_barrier(0)
;     ...
;       WAIT_V(6); BAR; MMA(1, 1, At, B1); BAR;
;       LDB(B0, 1, 0); SCHED; LDA(At, 1, 0); STAGE(SA(0, 1), rsA, sA1, offA, t + 2);
;       WAIT_L(8); BAR; WAIT_L(0); MMA(0, 0, At, B0); BAR; SCHED;
;       LDB(B1, 1, 1); STAGE(SB(1, 0), rsB, sB0, offB, t + 3);
;       BAR; WAIT_L(0); MMA(0, 1, At, B1); BAR;
;       LDA(At, 1, 1); STAGE(SA(1, 0), rsA, sA0, offA, t + 3);
	v_mfma_f32_16x16x32_bf16 v[28:31], v[202:205], v[170:173], v[28:31]
	v_mfma_f32_16x16x32_bf16 v[24:27], v[210:213], v[170:173], v[24:27]
	v_mfma_f32_16x16x32_bf16 v[20:23], v[202:205], v[178:181], v[20:23]
	v_mfma_f32_16x16x32_bf16 v[16:19], v[210:213], v[178:181], v[16:19]
	v_mfma_f32_16x16x32_bf16 v[12:15], v[202:205], v[186:189], v[12:15]
	v_mfma_f32_16x16x32_bf16 v[8:11], v[210:213], v[186:189], v[8:11]
	v_mfma_f32_16x16x32_bf16 v[4:7], v[202:205], v[194:197], v[4:7]
	v_mfma_f32_16x16x32_bf16 v[0:3], v[210:213], v[194:197], v[0:3]
	v_mfma_f32_16x16x32_bf16 v[28:31], v[206:209], v[174:177], v[28:31]
	v_mfma_f32_16x16x32_bf16 v[24:27], v[214:217], v[174:177], v[24:27]
	v_mfma_f32_16x16x32_bf16 v[20:23], v[206:209], v[182:185], v[20:23]
	v_mfma_f32_16x16x32_bf16 v[16:19], v[214:217], v[182:185], v[16:19]
	v_mfma_f32_16x16x32_bf16 v[12:15], v[206:209], v[190:193], v[12:15]
	v_mfma_f32_16x16x32_bf16 v[8:11], v[214:217], v[190:193], v[8:11]
	v_mfma_f32_16x16x32_bf16 v[4:7], v[206:209], v[198:201], v[4:7]
	v_mfma_f32_16x16x32_bf16 v[0:3], v[214:217], v[198:201], v[0:3]
	s_barrier
	ds_read_b128 v[154:157], v139
	ds_read_b128 v[158:161], v140
	ds_read_b128 v[162:165], v141
	ds_read_b128 v[166:169], v142
	s_addk_i32 s43, 0x100
	s_mov_b32 m0, s21
	ds_read_b128 v[170:173], v131 offset:32768
	ds_read_b128 v[174:177], v131 offset:33792
	ds_read_b128 v[178:181], v134 offset:32768
	ds_read_b128 v[182:185], v134 offset:33792
	ds_read_b128 v[186:189], v133 offset:32768
	ds_read_b128 v[190:193], v133 offset:33792
	ds_read_b128 v[194:197], v132 offset:32768
	ds_read_b128 v[198:201], v132 offset:33792
	buffer_load_dwordx4 v143, s[4:7], s43 offen lds
	s_mov_b32 m0, s22
	s_nop 0
	buffer_load_dwordx4 v144, s[4:7], s43 offen lds
	s_waitcnt lgkmcnt(8)
	s_barrier
	s_waitcnt lgkmcnt(0)
	s_waitcnt lgkmcnt(7)
	v_mfma_f32_16x16x32_bf16 v[124:127], v[154:157], v[170:173], v[124:127]
	v_mfma_f32_16x16x32_bf16 v[120:123], v[162:165], v[170:173], v[120:123]
	s_waitcnt lgkmcnt(5)
	v_mfma_f32_16x16x32_bf16 v[116:119], v[154:157], v[178:181], v[116:119]
	v_mfma_f32_16x16x32_bf16 v[112:115], v[162:165], v[178:181], v[112:115]
	s_waitcnt lgkmcnt(3)
	v_mfma_f32_16x16x32_bf16 v[108:111], v[154:157], v[186:189], v[108:111]
	v_mfma_f32_16x16x32_bf16 v[104:107], v[162:165], v[186:189], v[104:107]
	s_waitcnt lgkmcnt(1)
	v_mfma_f32_16x16x32_bf16 v[100:103], v[154:157], v[194:197], v[100:103]
	v_mfma_f32_16x16x32_bf16 v[96:99], v[162:165], v[194:197], v[96:99]
	v_mfma_f32_16x16x32_bf16 v[124:127], v[158:161], v[174:177], v[124:127]
	v_mfma_f32_16x16x32_bf16 v[120:123], v[166:169], v[174:177], v[120:123]
	v_mfma_f32_16x16x32_bf16 v[116:119], v[158:161], v[182:185], v[116:119]
	v_mfma_f32_16x16x32_bf16 v[112:115], v[166:169], v[182:185], v[112:115]
	v_mfma_f32_16x16x32_bf16 v[108:111], v[158:161], v[190:193], v[108:111]
	v_mfma_f32_16x16x32_bf16 v[104:107], v[166:169], v[190:193], v[104:107]
	s_waitcnt lgkmcnt(0)
	v_mfma_f32_16x16x32_bf16 v[100:103], v[158:161], v[198:201], v[100:103]
	v_mfma_f32_16x16x32_bf16 v[96:99], v[166:169], v[198:201], v[96:99]
	s_barrier
	s_addk_i32 s44, 0x180
	s_mov_b32 m0, s23
	ds_read_b128 v[202:205], v135
	ds_read_b128 v[206:209], v136
	ds_read_b128 v[210:213], v137
	ds_read_b128 v[214:217], v138
	buffer_load_dwordx4 v143, s[8:11], s44 offen lds
	s_mov_b32 m0, s24
	s_nop 0
	buffer_load_dwordx4 v144, s[8:11], s44 offen lds
	s_barrier
	s_waitcnt lgkmcnt(0)
	s_waitcnt lgkmcnt(3)
	v_mfma_f32_16x16x32_bf16 v[92:95], v[202:205], v[170:173], v[92:95]
	s_waitcnt lgkmcnt(1)
	v_mfma_f32_16x16x32_bf16 v[88:91], v[210:213], v[170:173], v[88:91]
	v_mfma_f32_16x16x32_bf16 v[84:87], v[202:205], v[178:181], v[84:87]
	v_mfma_f32_16x16x32_bf16 v[80:83], v[210:213], v[178:181], v[80:83]
	v_mfma_f32_16x16x32_bf16 v[76:79], v[202:205], v[186:189], v[76:79]
	v_mfma_f32_16x16x32_bf16 v[72:75], v[210:213], v[186:189], v[72:75]
	v_mfma_f32_16x16x32_bf16 v[68:71], v[202:205], v[194:197], v[68:71]
	v_mfma_f32_16x16x32_bf16 v[64:67], v[210:213], v[194:197], v[64:67]
	v_mfma_f32_16x16x32_bf16 v[92:95], v[206:209], v[174:177], v[92:95]
	s_waitcnt lgkmcnt(0)
	v_mfma_f32_16x16x32_bf16 v[88:91], v[214:217], v[174:177], v[88:91]
	v_mfma_f32_16x16x32_bf16 v[84:87], v[206:209], v[182:185], v[84:87]
	v_mfma_f32_16x16x32_bf16 v[80:83], v[214:217], v[182:185], v[80:83]
	v_mfma_f32_16x16x32_bf16 v[76:79], v[206:209], v[190:193], v[76:79]
	v_mfma_f32_16x16x32_bf16 v[72:75], v[214:217], v[190:193], v[72:75]
	v_mfma_f32_16x16x32_bf16 v[68:71], v[206:209], v[198:201], v[68:71]
	v_mfma_f32_16x16x32_bf16 v[64:67], v[214:217], v[198:201], v[64:67]
	s_addk_i32 s45, 0x180
	s_mov_b32 m0, s25
	s_barrier
	ds_read_b128 v[170:173], v131 offset:49152
	ds_read_b128 v[174:177], v131 offset:50176
	ds_read_b128 v[178:181], v134 offset:49152
	ds_read_b128 v[182:185], v134 offset:50176
	ds_read_b128 v[186:189], v133 offset:49152
	ds_read_b128 v[190:193], v133 offset:50176
	ds_read_b128 v[194:197], v132 offset:49152
	ds_read_b128 v[198:201], v132 offset:50176
	buffer_load_dwordx4 v143, s[4:7], s45 offen lds
	s_mov_b32 m0, s26
	s_nop 0
	buffer_load_dwordx4 v144, s[4:7], s45 offen lds
	s_barrier
; #define STAGE(P, RS, SOFF, OFF, kt) do { const int _so = (SOFF) + (kt) * (BK * 2); \
;     _Pragma("unroll") for (int _i = 0; _i < 2; ++_i) { \
;       __builtin_amdgcn_raw_ptr_buffer_load_lds(RS, (__attribute__((address_space(3))) void*)((P) + wave * 1024 + _i * 8192), 16, OFF[_i], _so, 0, 0); } } while (0)
; #define LDA(dst, b, h) _Pragma("unroll") for (int m = 0; m < 4; ++m) _Pragma("unroll") for (int k = 0; k < 2; ++k) \
;     dst[m][k] = *reinterpret_cast<const bf16x8*>(SA(b, h) + lds_byte(wr * 64 + m * 16 + fr, k * 32 + fq * 8))
; #define LDB(dst, b, h) _Pragma("unroll") for (int n = 0; n < 2; ++n) _Pragma("unroll") for (int k = 0; k < 2; ++k) \
;     dst[n][k] = *reinterpret_cast<const bf16x8*>(SB(b, h) + lds_byte(wc * 32 + n * 16 + fr, k * 32 + fq * 8))
; #define WAIT_V(n) asm volatile("s_waitcnt vmcnt(" #n ")" ::: "memory")
; #define WAIT_L(n) asm volatile("s_waitcnt lgkmcnt(" #n ")" ::: "memory")
; #define BAR __builtin_amdgcn_s_barrier()
; #define SCHED __builtin_amdgcn_sched_barrier(0)
;     ...
;       BAR; WAIT_L(0); MMA(1, 0, At, B0); BAR; SCHED;
;       STAGE(SB(1, 1), rsB, sB1, offB, t + 3);
;       WAIT_V(6); BAR; MMA(1, 1, At, B1); BAR;
;     }
;     { LDB(B0, 0, 0); LDA(At, 0, 0); STAGE(SA(1, 1), rsA, sA1, offA, nt - 1);
;       BAR; WAIT_L(0); MMA(0, 0, At, B0); BAR;
;       LDB(B1, 0, 1); BAR; WAIT_L(0); MMA(0, 1, At, B1); BAR;
	s_waitcnt lgkmcnt(0)
	s_waitcnt lgkmcnt(7)
	v_mfma_f32_16x16x32_bf16 v[60:63], v[154:157], v[170:173], v[60:63]
	v_mfma_f32_16x16x32_bf16 v[56:59], v[162:165], v[170:173], v[56:59]
	s_waitcnt lgkmcnt(5)
	v_mfma_f32_16x16x32_bf16 v[52:55], v[154:157], v[178:181], v[52:55]
	v_mfma_f32_16x16x32_bf16 v[48:51], v[162:165], v[178:181], v[48:51]
	s_waitcnt lgkmcnt(3)
	v_mfma_f32_16x16x32_bf16 v[44:47], v[154:157], v[186:189], v[44:47]
	v_mfma_f32_16x16x32_bf16 v[40:43], v[162:165], v[186:189], v[40:43]
	s_waitcnt lgkmcnt(1)
	v_mfma_f32_16x16x32_bf16 v[36:39], v[154:157], v[194:197], v[36:39]
	v_mfma_f32_16x16x32_bf16 v[32:35], v[162:165], v[194:197], v[32:35]
	v_mfma_f32_16x16x32_bf16 v[60:63], v[158:161], v[174:177], v[60:63]
	v_mfma_f32_16x16x32_bf16 v[56:59], v[166:169], v[174:177], v[56:59]
	v_mfma_f32_16x16x32_bf16 v[52:55], v[158:161], v[182:185], v[52:55]
	v_mfma_f32_16x16x32_bf16 v[48:51], v[166:169], v[182:185], v[48:51]
	v_mfma_f32_16x16x32_bf16 v[44:47], v[158:161], v[190:193], v[44:47]
	v_mfma_f32_16x16x32_bf16 v[40:43], v[166:169], v[190:193], v[40:43]
	s_waitcnt lgkmcnt(0)
	v_mfma_f32_16x16x32_bf16 v[36:39], v[158:161], v[198:201], v[36:39]
	v_mfma_f32_16x16x32_bf16 v[32:35], v[166:169], v[198:201], v[32:35]
	s_barrier
	s_addk_i32 s46, 0x180
	s_mov_b32 m0, s27
	s_nop 0
	buffer_load_dwordx4 v143, s[8:11], s46 offen lds
	s_mov_b32 m0, s28
	s_nop 0
	buffer_load_dwordx4 v144, s[8:11], s46 offen lds
	s_waitcnt vmcnt(6)
	s_barrier
	v_mfma_f32_16x16x32_bf16 v[28:31], v[202:205], v[170:173], v[28:31]
	v_mfma_f32_16x16x32_bf16 v[24:27], v[210:213], v[170:173], v[24:27]
	v_mfma_f32_16x16x32_bf16 v[20:23], v[202:205], v[178:181], v[20:23]
	v_mfma_f32_16x16x32_bf16 v[16:19], v[210:213], v[178:181], v[16:19]
	v_mfma_f32_16x16x32_bf16 v[12:15], v[202:205], v[186:189], v[12:15]
	v_mfma_f32_16x16x32_bf16 v[8:11], v[210:213], v[186:189], v[8:11]
	v_mfma_f32_16x16x32_bf16 v[4:7], v[202:205], v[194:197], v[4:7]
	v_mfma_f32_16x16x32_bf16 v[0:3], v[210:213], v[194:197], v[0:3]
	v_mfma_f32_16x16x32_bf16 v[28:31], v[206:209], v[174:177], v[28:31]
	v_mfma_f32_16x16x32_bf16 v[24:27], v[214:217], v[174:177], v[24:27]
	v_mfma_f32_16x16x32_bf16 v[20:23], v[206:209], v[182:185], v[20:23]
	v_mfma_f32_16x16x32_bf16 v[16:19], v[214:217], v[182:185], v[16:19]
	v_mfma_f32_16x16x32_bf16 v[12:15], v[206:209], v[190:193], v[12:15]
	v_mfma_f32_16x16x32_bf16 v[8:11], v[214:217], v[190:193], v[8:11]
	v_mfma_f32_16x16x32_bf16 v[4:7], v[206:209], v[198:201], v[4:7]
	v_mfma_f32_16x16x32_bf16 v[0:3], v[214:217], v[198:201], v[0:3]
	s_add_i32 s14, s14, 2
	s_addk_i32 s15, 0x100
	s_cmp_gt_u32 s14, 27
	s_barrier
	s_cbranch_scc0 .LBB0_95
	s_add_i32 s10, s37, 0xf80
	s_mov_b32 m0, s30
	ds_read_b128 v[154:157], v149
	ds_read_b128 v[158:161], v150
	ds_read_b128 v[162:165], v151
	ds_read_b128 v[150:153], v152
	ds_read_b128 v[166:169], v131
	ds_read_b128 v[170:173], v131 offset:1024
	ds_read_b128 v[174:177], v134
	ds_read_b128 v[178:181], v134 offset:1024
	ds_read_b128 v[182:185], v133
	ds_read_b128 v[186:189], v133 offset:1024
	ds_read_b128 v[190:193], v132
	ds_read_b128 v[194:197], v132 offset:1024
	buffer_load_dwordx4 v143, s[4:7], s10 offen lds
	s_mov_b32 m0, s31
	s_nop 0
	buffer_load_dwordx4 v144, s[4:7], s10 offen lds
	s_barrier
	s_waitcnt lgkmcnt(0)
	s_waitcnt lgkmcnt(7)
	v_mfma_f32_16x16x32_bf16 v[124:127], v[154:157], v[166:169], v[124:127]
	v_mfma_f32_16x16x32_bf16 v[120:123], v[162:165], v[166:169], v[120:123]
	s_waitcnt lgkmcnt(5)
	v_mfma_f32_16x16x32_bf16 v[116:119], v[154:157], v[174:177], v[116:119]
	v_mfma_f32_16x16x32_bf16 v[112:115], v[162:165], v[174:177], v[112:115]
	s_waitcnt lgkmcnt(3)
	v_mfma_f32_16x16x32_bf16 v[108:111], v[154:157], v[182:185], v[108:111]
	v_mfma_f32_16x16x32_bf16 v[104:107], v[162:165], v[182:185], v[104:107]
	s_waitcnt lgkmcnt(1)
	v_mfma_f32_16x16x32_bf16 v[100:103], v[154:157], v[190:193], v[100:103]
	v_mfma_f32_16x16x32_bf16 v[96:99], v[162:165], v[190:193], v[96:99]
	v_mfma_f32_16x16x32_bf16 v[124:127], v[158:161], v[170:173], v[124:127]
	v_mfma_f32_16x16x32_bf16 v[120:123], v[150:153], v[170:173], v[120:123]
	v_mfma_f32_16x16x32_bf16 v[116:119], v[158:161], v[178:181], v[116:119]
	v_mfma_f32_16x16x32_bf16 v[112:115], v[150:153], v[178:181], v[112:115]
	v_mfma_f32_16x16x32_bf16 v[108:111], v[158:161], v[186:189], v[108:111]
	v_mfma_f32_16x16x32_bf16 v[104:107], v[150:153], v[186:189], v[104:107]
	s_waitcnt lgkmcnt(0)
	v_mfma_f32_16x16x32_bf16 v[100:103], v[158:161], v[194:197], v[100:103]
	v_mfma_f32_16x16x32_bf16 v[96:99], v[150:153], v[194:197], v[96:99]
	s_barrier
	ds_read_b128 v[198:201], v145
	ds_read_b128 v[202:205], v146
	ds_read_b128 v[144:147], v147
	ds_read_b128 v[206:209], v148
	s_barrier
	s_waitcnt lgkmcnt(0)
	s_waitcnt lgkmcnt(3)
	v_mfma_f32_16x16x32_bf16 v[92:95], v[198:201], v[166:169], v[92:95]
	v_mfma_f32_16x16x32_bf16 v[84:87], v[198:201], v[174:177], v[84:87]
	v_mfma_f32_16x16x32_bf16 v[76:79], v[198:201], v[182:185], v[76:79]
	v_mfma_f32_16x16x32_bf16 v[68:71], v[198:201], v[190:193], v[68:71]
	s_waitcnt lgkmcnt(1)
	v_mfma_f32_16x16x32_bf16 v[88:91], v[144:147], v[166:169], v[88:91]
	v_mfma_f32_16x16x32_bf16 v[80:83], v[144:147], v[174:177], v[80:83]
	v_mfma_f32_16x16x32_bf16 v[72:75], v[144:147], v[182:185], v[72:75]
	v_mfma_f32_16x16x32_bf16 v[64:67], v[144:147], v[190:193], v[64:67]
	v_mfma_f32_16x16x32_bf16 v[92:95], v[202:205], v[170:173], v[92:95]
	v_mfma_f32_16x16x32_bf16 v[84:87], v[202:205], v[178:181], v[84:87]
	v_mfma_f32_16x16x32_bf16 v[76:79], v[202:205], v[186:189], v[76:79]
	v_mfma_f32_16x16x32_bf16 v[68:71], v[202:205], v[194:197], v[68:71]
	s_waitcnt lgkmcnt(0)
	v_mfma_f32_16x16x32_bf16 v[166:169], v[206:209], v[170:173], v[88:91]
	v_mfma_f32_16x16x32_bf16 v[170:173], v[206:209], v[178:181], v[80:83]
	v_mfma_f32_16x16x32_bf16 v[174:177], v[206:209], v[186:189], v[72:75]
	v_mfma_f32_16x16x32_bf16 v[178:181], v[206:209], v[194:197], v[64:67]
	s_barrier
; #define LDA(dst, b, h) _Pragma("unroll") for (int m = 0; m < 4; ++m) _Pragma("unroll") for (int k = 0; k < 2; ++k) \
;     dst[m][k] = *reinterpret_cast<const bf16x8*>(SA(b, h) + lds_byte(wr * 64 + m * 16 + fr, k * 32 + fq * 8))
; #define LDB(dst, b, h) _Pragma("unroll") for (int n = 0; n < 2; ++n) _Pragma("unroll") for (int k = 0; k < 2; ++k) \
;     dst[n][k] = *reinterpret_cast<const bf16x8*>(SB(b, h) + lds_byte(wc * 32 + n * 16 + fr, k * 32 + fq * 8))
; #define WAIT_V(n) asm volatile("s_waitcnt vmcnt(" #n ")" ::: "memory")
; #define WAIT_L(n) asm volatile("s_waitcnt lgkmcnt(" #n ")" ::: "memory")
; #define BAR __builtin_amdgcn_s_barrier()
;     ...
;       LDA(At, 0, 1); WAIT_V(4); BAR; WAIT_L(0); MMA(1, 0, At, B0); MMA(1, 1, At, B1); BAR; }
;     { LDB(B0, 1, 0); LDA(At, 1, 0); WAIT_V(2); BAR; WAIT_L(0); MMA(0, 0, At, B0); BAR;
	s_nop 0
	ds_read_b128 v[64:67], v131 offset:16384
	ds_read_b128 v[72:75], v131 offset:17408
	ds_read_b128 v[80:83], v134 offset:16384
	ds_read_b128 v[88:91], v134 offset:17408
	ds_read_b128 v[182:185], v133 offset:16384
	ds_read_b128 v[186:189], v133 offset:17408
	ds_read_b128 v[190:193], v132 offset:16384
	ds_read_b128 v[194:197], v132 offset:17408
	s_waitcnt vmcnt(4)
	s_barrier
	s_waitcnt lgkmcnt(0)
	s_waitcnt lgkmcnt(7)
	v_mfma_f32_16x16x32_bf16 v[60:63], v[154:157], v[64:67], v[60:63]
	v_mfma_f32_16x16x32_bf16 v[56:59], v[162:165], v[64:67], v[56:59]
	s_waitcnt lgkmcnt(5)
	v_mfma_f32_16x16x32_bf16 v[52:55], v[154:157], v[80:83], v[52:55]
	v_mfma_f32_16x16x32_bf16 v[48:51], v[162:165], v[80:83], v[48:51]
	s_waitcnt lgkmcnt(3)
	v_mfma_f32_16x16x32_bf16 v[44:47], v[154:157], v[182:185], v[44:47]
	v_mfma_f32_16x16x32_bf16 v[40:43], v[162:165], v[182:185], v[40:43]
	s_waitcnt lgkmcnt(1)
	v_mfma_f32_16x16x32_bf16 v[36:39], v[154:157], v[190:193], v[36:39]
	v_mfma_f32_16x16x32_bf16 v[32:35], v[162:165], v[190:193], v[32:35]
	v_mfma_f32_16x16x32_bf16 v[60:63], v[158:161], v[72:75], v[60:63]
	v_mfma_f32_16x16x32_bf16 v[56:59], v[150:153], v[72:75], v[56:59]
	v_mfma_f32_16x16x32_bf16 v[52:55], v[158:161], v[88:91], v[52:55]
	v_mfma_f32_16x16x32_bf16 v[48:51], v[150:153], v[88:91], v[48:51]
	v_mfma_f32_16x16x32_bf16 v[44:47], v[158:161], v[186:189], v[44:47]
	v_mfma_f32_16x16x32_bf16 v[40:43], v[150:153], v[186:189], v[40:43]
	s_waitcnt lgkmcnt(0)
	v_mfma_f32_16x16x32_bf16 v[36:39], v[158:161], v[194:197], v[36:39]
	v_mfma_f32_16x16x32_bf16 v[32:35], v[150:153], v[194:197], v[32:35]
	v_mfma_f32_16x16x32_bf16 v[28:31], v[198:201], v[64:67], v[28:31]
	v_mfma_f32_16x16x32_bf16 v[20:23], v[198:201], v[80:83], v[20:23]
	v_mfma_f32_16x16x32_bf16 v[12:15], v[198:201], v[182:185], v[12:15]
	v_mfma_f32_16x16x32_bf16 v[4:7], v[198:201], v[190:193], v[4:7]
	v_mfma_f32_16x16x32_bf16 v[24:27], v[144:147], v[64:67], v[24:27]
	v_mfma_f32_16x16x32_bf16 v[16:19], v[144:147], v[80:83], v[16:19]
	v_mfma_f32_16x16x32_bf16 v[8:11], v[144:147], v[182:185], v[8:11]
	v_mfma_f32_16x16x32_bf16 v[0:3], v[144:147], v[190:193], v[0:3]
	v_mfma_f32_16x16x32_bf16 v[28:31], v[202:205], v[72:75], v[28:31]
	v_mfma_f32_16x16x32_bf16 v[20:23], v[202:205], v[88:91], v[20:23]
	v_mfma_f32_16x16x32_bf16 v[12:15], v[202:205], v[186:189], v[12:15]
	v_mfma_f32_16x16x32_bf16 v[4:7], v[202:205], v[194:197], v[4:7]
	v_mfma_f32_16x16x32_bf16 v[144:147], v[206:209], v[72:75], v[24:27]
	v_mfma_f32_16x16x32_bf16 v[148:151], v[206:209], v[88:91], v[16:19]
	v_mfma_f32_16x16x32_bf16 v[152:155], v[206:209], v[186:189], v[8:11]
	v_mfma_f32_16x16x32_bf16 v[156:159], v[206:209], v[194:197], v[0:3]
	s_barrier
	s_nop 0
	ds_read_b128 v[0:3], v139
	ds_read_b128 v[8:11], v140
	ds_read_b128 v[16:19], v141
	ds_read_b128 v[140:143], v142
	ds_read_b128 v[24:27], v131 offset:32768
	ds_read_b128 v[160:163], v131 offset:33792
	ds_read_b128 v[182:185], v134 offset:32768
	ds_read_b128 v[186:189], v134 offset:33792
	ds_read_b128 v[190:193], v133 offset:32768
	ds_read_b128 v[194:197], v133 offset:33792
	ds_read_b128 v[198:201], v132 offset:32768
	ds_read_b128 v[202:205], v132 offset:33792
	s_waitcnt vmcnt(2)
	s_barrier
	s_waitcnt lgkmcnt(0)
	s_waitcnt lgkmcnt(7)
	v_mfma_f32_16x16x32_bf16 v[64:67], v[0:3], v[24:27], v[124:127]
	v_mfma_f32_16x16x32_bf16 v[72:75], v[16:19], v[24:27], v[120:123]
	s_waitcnt lgkmcnt(5)
	v_mfma_f32_16x16x32_bf16 v[80:83], v[0:3], v[182:185], v[116:119]
	v_mfma_f32_16x16x32_bf16 v[88:91], v[16:19], v[182:185], v[112:115]
	s_waitcnt lgkmcnt(3)
	v_mfma_f32_16x16x32_bf16 v[108:111], v[0:3], v[190:193], v[108:111]
	v_mfma_f32_16x16x32_bf16 v[116:119], v[16:19], v[190:193], v[104:107]
	s_waitcnt lgkmcnt(1)
	v_mfma_f32_16x16x32_bf16 v[100:103], v[0:3], v[198:201], v[100:103]
	v_mfma_f32_16x16x32_bf16 v[124:127], v[16:19], v[198:201], v[96:99]
	v_mfma_f32_16x16x32_bf16 v[120:123], v[8:11], v[160:163], v[64:67]
	v_mfma_f32_16x16x32_bf16 v[112:115], v[140:143], v[160:163], v[72:75]
	v_mfma_f32_16x16x32_bf16 v[104:107], v[8:11], v[186:189], v[80:83]
	v_mfma_f32_16x16x32_bf16 v[96:99], v[140:143], v[186:189], v[88:91]
	v_mfma_f32_16x16x32_bf16 v[88:91], v[8:11], v[194:197], v[108:111]
	v_mfma_f32_16x16x32_bf16 v[80:83], v[140:143], v[194:197], v[116:119]
	s_waitcnt lgkmcnt(0)
	v_mfma_f32_16x16x32_bf16 v[72:75], v[8:11], v[202:205], v[100:103]
	v_mfma_f32_16x16x32_bf16 v[64:67], v[140:143], v[202:205], v[124:127]
	s_barrier
; #define LDA(dst, b, h) _Pragma("unroll") for (int m = 0; m < 4; ++m) _Pragma("unroll") for (int k = 0; k < 2; ++k) \
;     dst[m][k] = *reinterpret_cast<const bf16x8*>(SA(b, h) + lds_byte(wr * 64 + m * 16 + fr, k * 32 + fq * 8))
; #define LDB(dst, b, h) _Pragma("unroll") for (int n = 0; n < 2; ++n) _Pragma("unroll") for (int k = 0; k < 2; ++k) \
;     dst[n][k] = *reinterpret_cast<const bf16x8*>(SB(b, h) + lds_byte(wc * 32 + n * 16 + fr, k * 32 + fq * 8))
; #define WAIT_V(n) asm volatile("s_waitcnt vmcnt(" #n ")" ::: "memory")
; #define WAIT_L(n) asm volatile("s_waitcnt lgkmcnt(" #n ")" ::: "memory")
; #define BAR __builtin_amdgcn_s_barrier()
;     ...
;       LDB(B1, 1, 1); WAIT_V(0); BAR; WAIT_L(0); MMA(0, 1, At, B1); BAR;
;       LDA(At, 1, 1); BAR; WAIT_L(0); MMA(1, 0, At, B0); MMA(1, 1, At, B1); BAR; }
;     if (wr == 0) BAR;
	ds_read_b128 v[206:209], v135
	ds_read_b128 v[210:213], v136
	ds_read_b128 v[214:217], v137
	ds_read_b128 v[136:139], v138
	s_waitcnt vmcnt(0)
	s_barrier
	s_waitcnt lgkmcnt(0)
	s_waitcnt lgkmcnt(3)
	v_mfma_f32_16x16x32_bf16 v[92:95], v[206:209], v[24:27], v[92:95]
	s_waitcnt lgkmcnt(1)
	v_mfma_f32_16x16x32_bf16 v[24:27], v[214:217], v[24:27], v[166:169]
	v_mfma_f32_16x16x32_bf16 v[84:87], v[206:209], v[182:185], v[84:87]
	v_mfma_f32_16x16x32_bf16 v[100:103], v[214:217], v[182:185], v[170:173]
	v_mfma_f32_16x16x32_bf16 v[76:79], v[206:209], v[190:193], v[76:79]
	v_mfma_f32_16x16x32_bf16 v[164:167], v[214:217], v[190:193], v[174:177]
	v_mfma_f32_16x16x32_bf16 v[68:71], v[206:209], v[198:201], v[68:71]
	v_mfma_f32_16x16x32_bf16 v[168:171], v[214:217], v[198:201], v[178:181]
	v_mfma_f32_16x16x32_bf16 v[124:127], v[210:213], v[160:163], v[92:95]
	s_waitcnt lgkmcnt(0)
	v_mfma_f32_16x16x32_bf16 v[116:119], v[136:139], v[160:163], v[24:27]
	v_mfma_f32_16x16x32_bf16 v[108:111], v[210:213], v[186:189], v[84:87]
	v_mfma_f32_16x16x32_bf16 v[100:103], v[136:139], v[186:189], v[100:103]
	v_mfma_f32_16x16x32_bf16 v[92:95], v[210:213], v[194:197], v[76:79]
	v_mfma_f32_16x16x32_bf16 v[84:87], v[136:139], v[194:197], v[164:167]
	v_mfma_f32_16x16x32_bf16 v[76:79], v[210:213], v[202:205], v[68:71]
	v_mfma_f32_16x16x32_bf16 v[68:71], v[136:139], v[202:205], v[168:171]
	s_barrier
	ds_read_b128 v[160:163], v131 offset:49152
	ds_read_b128 v[164:167], v131 offset:50176
	ds_read_b128 v[168:171], v134 offset:49152
	ds_read_b128 v[172:175], v134 offset:50176
	ds_read_b128 v[176:179], v133 offset:49152
	ds_read_b128 v[180:183], v133 offset:50176
	ds_read_b128 v[184:187], v132 offset:49152
	ds_read_b128 v[132:135], v132 offset:50176
	s_barrier
	s_waitcnt lgkmcnt(0)
	s_waitcnt lgkmcnt(7)
	v_mfma_f32_16x16x32_bf16 v[24:27], v[0:3], v[160:163], v[60:63]
	v_mfma_f32_16x16x32_bf16 v[60:63], v[16:19], v[160:163], v[56:59]
	s_waitcnt lgkmcnt(5)
	v_mfma_f32_16x16x32_bf16 v[52:55], v[0:3], v[168:171], v[52:55]
	v_mfma_f32_16x16x32_bf16 v[188:191], v[16:19], v[168:171], v[48:51]
	s_waitcnt lgkmcnt(3)
	v_mfma_f32_16x16x32_bf16 v[44:47], v[0:3], v[176:179], v[44:47]
	v_mfma_f32_16x16x32_bf16 v[192:195], v[16:19], v[176:179], v[40:43]
	s_waitcnt lgkmcnt(1)
	v_mfma_f32_16x16x32_bf16 v[0:3], v[0:3], v[184:187], v[36:39]
	v_mfma_f32_16x16x32_bf16 v[36:39], v[16:19], v[184:187], v[32:35]
	v_mfma_f32_16x16x32_bf16 v[56:59], v[8:11], v[164:167], v[24:27]
	v_mfma_f32_16x16x32_bf16 v[48:51], v[140:143], v[164:167], v[60:63]
	v_mfma_f32_16x16x32_bf16 v[40:43], v[8:11], v[172:175], v[52:55]
	v_mfma_f32_16x16x32_bf16 v[32:35], v[140:143], v[172:175], v[188:191]
	v_mfma_f32_16x16x32_bf16 v[24:27], v[8:11], v[180:183], v[44:47]
	v_mfma_f32_16x16x32_bf16 v[16:19], v[140:143], v[180:183], v[192:195]
	s_waitcnt lgkmcnt(0)
	v_mfma_f32_16x16x32_bf16 v[8:11], v[8:11], v[132:135], v[0:3]
	v_mfma_f32_16x16x32_bf16 v[0:3], v[140:143], v[132:135], v[36:39]
	v_mfma_f32_16x16x32_bf16 v[28:31], v[206:209], v[160:163], v[28:31]
	v_mfma_f32_16x16x32_bf16 v[36:39], v[214:217], v[160:163], v[144:147]
	v_mfma_f32_16x16x32_bf16 v[20:23], v[206:209], v[168:171], v[20:23]
	v_mfma_f32_16x16x32_bf16 v[140:143], v[214:217], v[168:171], v[148:151]
	v_mfma_f32_16x16x32_bf16 v[12:15], v[206:209], v[176:179], v[12:15]
	v_mfma_f32_16x16x32_bf16 v[144:147], v[214:217], v[176:179], v[152:155]
	v_mfma_f32_16x16x32_bf16 v[4:7], v[206:209], v[184:187], v[4:7]
	v_mfma_f32_16x16x32_bf16 v[148:151], v[214:217], v[184:187], v[156:159]
	v_mfma_f32_16x16x32_bf16 v[60:63], v[210:213], v[164:167], v[28:31]
	v_mfma_f32_16x16x32_bf16 v[52:55], v[136:139], v[164:167], v[36:39]
	v_mfma_f32_16x16x32_bf16 v[44:47], v[210:213], v[172:175], v[20:23]
	v_mfma_f32_16x16x32_bf16 v[36:39], v[136:139], v[172:175], v[140:143]
	v_mfma_f32_16x16x32_bf16 v[28:31], v[210:213], v[180:183], v[12:15]
	v_mfma_f32_16x16x32_bf16 v[20:23], v[136:139], v[180:183], v[144:147]
	v_mfma_f32_16x16x32_bf16 v[12:15], v[210:213], v[132:135], v[4:7]
	v_mfma_f32_16x16x32_bf16 v[4:7], v[136:139], v[132:135], v[148:151]
	v_cmp_gt_u32_e32 vcc, s35, v130
	s_barrier
	s_and_saveexec_b64 s[10:11], vcc
	s_cbranch_execz .LBB0_98
	s_barrier

; #define STAGE(P, RS, SOFF, OFF, kt) do { const int _so = (SOFF) + (kt) * (BK * 2); \
;     _Pragma("unroll") for (int _i = 0; _i < 2; ++_i) { \
;       __builtin_amdgcn_raw_ptr_buffer_load_lds(RS, (__attribute__((address_space(3))) void*)((P) + wave * 1024 + _i * 8192), 16, OFF[_i], _so, 0, 0); } } while (0)
; #define LDA(dst, b, h) _Pragma("unroll") for (int m = 0; m < 4; ++m) _Pragma("unroll") for (int k = 0; k < 2; ++k) \
;     dst[m][k] = *reinterpret_cast<const bf16x8*>(SA(b, h) + lds_byte(wr * 64 + m * 16 + fr, k * 32 + fq * 8))
; #define LDB(dst, b, h) _Pragma("unroll") for (int n = 0; n < 2; ++n) _Pragma("unroll") for (int k = 0; k < 2; ++k) \
;     dst[n][k] = *reinterpret_cast<const bf16x8*>(SB(b, h) + lds_byte(wc * 32 + n * 16 + fr, k * 32 + fq * 8))
; #define WAIT_V(n) asm volatile("s_waitcnt vmcnt(" #n ")" ::: "memory")
; #define WAIT_L(n) asm volatile("s_waitcnt lgkmcnt(" #n ")" ::: "memory")
; #define BAR __builtin_amdgcn_s_barrier()
; #define SCHED __builtin_amdgcn_sched_barrier(0)
;     ...
;       LDB(B0, 0, 0); SCHED; LDA(At, 0, 0); STAGE(SA(1, 1), rsA, sA1, offA, t + 1);
;       WAIT_L(8); BAR; WAIT_L(0); MMA(0, 0, At, B0); BAR; SCHED;
;       LDB(B1, 0, 1); STAGE(SB(0, 0), rsB, sB0, offB, t + 2);
;       BAR; WAIT_L(0); MMA(0, 1, At, B1); BAR;
;       LDA(At, 0, 1); STAGE(SA(0, 0), rsA, sA0, offA, t + 2);
;       BAR; WAIT_L(0); MMA(1, 0, At, B0); BAR; SCHED;
;       STAGE(SB(0, 1), rsB, sB1, offB, t + 2);
;       WAIT_V(6); BAR; MMA(1, 1, At, B1); BAR;
.LBB0_110:
	ds_read_b128 v[156:159], v151
	ds_read_b128 v[160:163], v152
	ds_read_b128 v[164:167], v153
	ds_read_b128 v[168:171], v154
	s_add_i32 s44, s38, s17
	s_add_i32 s10, s44, 0x80
	s_mov_b32 m0, s31
	ds_read_b128 v[172:175], v131
	ds_read_b128 v[176:179], v131 offset:1024
	ds_read_b128 v[180:183], v138
	ds_read_b128 v[184:187], v138 offset:1024
	ds_read_b128 v[188:191], v137
	ds_read_b128 v[192:195], v137 offset:1024
	ds_read_b128 v[196:199], v135
	ds_read_b128 v[200:203], v135 offset:1024
	buffer_load_dwordx4 v128, s[4:7], s10 offen lds
	s_mov_b32 m0, s33
	s_nop 0
	buffer_load_dwordx4 v132, s[4:7], s10 offen lds
	s_waitcnt lgkmcnt(8)
	s_barrier
	s_waitcnt lgkmcnt(0)
	s_waitcnt lgkmcnt(7)
	v_mfma_f32_16x16x32_bf16 v[124:127], v[156:159], v[172:175], v[124:127]
	v_mfma_f32_16x16x32_bf16 v[120:123], v[164:167], v[172:175], v[120:123]
	s_waitcnt lgkmcnt(5)
	v_mfma_f32_16x16x32_bf16 v[116:119], v[156:159], v[180:183], v[116:119]
	v_mfma_f32_16x16x32_bf16 v[112:115], v[164:167], v[180:183], v[112:115]
	s_waitcnt lgkmcnt(3)
	v_mfma_f32_16x16x32_bf16 v[108:111], v[156:159], v[188:191], v[108:111]
	v_mfma_f32_16x16x32_bf16 v[104:107], v[164:167], v[188:191], v[104:107]
	s_waitcnt lgkmcnt(1)
	v_mfma_f32_16x16x32_bf16 v[100:103], v[156:159], v[196:199], v[100:103]
	v_mfma_f32_16x16x32_bf16 v[96:99], v[164:167], v[196:199], v[96:99]
	v_mfma_f32_16x16x32_bf16 v[124:127], v[160:163], v[176:179], v[124:127]
	v_mfma_f32_16x16x32_bf16 v[120:123], v[168:171], v[176:179], v[120:123]
	v_mfma_f32_16x16x32_bf16 v[116:119], v[160:163], v[184:187], v[116:119]
	v_mfma_f32_16x16x32_bf16 v[112:115], v[168:171], v[184:187], v[112:115]
	v_mfma_f32_16x16x32_bf16 v[108:111], v[160:163], v[192:195], v[108:111]
	v_mfma_f32_16x16x32_bf16 v[104:107], v[168:171], v[192:195], v[104:107]
	s_waitcnt lgkmcnt(0)
	v_mfma_f32_16x16x32_bf16 v[100:103], v[160:163], v[200:203], v[100:103]
	v_mfma_f32_16x16x32_bf16 v[96:99], v[168:171], v[200:203], v[96:99]
	s_barrier
	s_add_i32 s45, s40, s17
	s_add_i32 s46, s45, 0x100
	s_mov_b32 s10, s6
	s_mov_b32 s11, s7
	s_mov_b32 m0, s3
	ds_read_b128 v[204:207], v147
	ds_read_b128 v[208:211], v148
	ds_read_b128 v[212:215], v149
	ds_read_b128 v[216:219], v150
	buffer_load_dwordx4 v130, s[8:11], s46 offen lds
	s_mov_b32 m0, s18
	s_nop 0
	buffer_load_dwordx4 v134, s[8:11], s46 offen lds
	s_barrier
	s_waitcnt lgkmcnt(0)
	s_waitcnt lgkmcnt(3)
	v_mfma_f32_16x16x32_bf16 v[92:95], v[204:207], v[172:175], v[92:95]
	s_waitcnt lgkmcnt(1)
	v_mfma_f32_16x16x32_bf16 v[88:91], v[212:215], v[172:175], v[88:91]
	v_mfma_f32_16x16x32_bf16 v[84:87], v[204:207], v[180:183], v[84:87]
	v_mfma_f32_16x16x32_bf16 v[80:83], v[212:215], v[180:183], v[80:83]
	v_mfma_f32_16x16x32_bf16 v[76:79], v[204:207], v[188:191], v[76:79]
	v_mfma_f32_16x16x32_bf16 v[72:75], v[212:215], v[188:191], v[72:75]
	v_mfma_f32_16x16x32_bf16 v[68:71], v[204:207], v[196:199], v[68:71]
	v_mfma_f32_16x16x32_bf16 v[64:67], v[212:215], v[196:199], v[64:67]
	v_mfma_f32_16x16x32_bf16 v[92:95], v[208:211], v[176:179], v[92:95]
	s_waitcnt lgkmcnt(0)
	v_mfma_f32_16x16x32_bf16 v[88:91], v[216:219], v[176:179], v[88:91]
	v_mfma_f32_16x16x32_bf16 v[84:87], v[208:211], v[184:187], v[84:87]
	v_mfma_f32_16x16x32_bf16 v[80:83], v[216:219], v[184:187], v[80:83]
	v_mfma_f32_16x16x32_bf16 v[76:79], v[208:211], v[192:195], v[76:79]
	v_mfma_f32_16x16x32_bf16 v[72:75], v[216:219], v[192:195], v[72:75]
	v_mfma_f32_16x16x32_bf16 v[68:71], v[208:211], v[200:203], v[68:71]
	v_mfma_f32_16x16x32_bf16 v[64:67], v[216:219], v[200:203], v[64:67]
	s_add_i32 s46, s39, s17
	s_add_i32 s47, s46, 0x100
	s_mov_b32 m0, s0
	s_barrier
	ds_read_b128 v[172:175], v131 offset:16384
	ds_read_b128 v[176:179], v131 offset:17408
	ds_read_b128 v[180:183], v138 offset:16384
	ds_read_b128 v[184:187], v138 offset:17408
	ds_read_b128 v[188:191], v137 offset:16384
	ds_read_b128 v[192:195], v137 offset:17408
	ds_read_b128 v[196:199], v135 offset:16384
	ds_read_b128 v[200:203], v135 offset:17408
	buffer_load_dwordx4 v128, s[4:7], s47 offen lds
	s_mov_b32 m0, s19
	s_nop 0
	buffer_load_dwordx4 v132, s[4:7], s47 offen lds
	s_barrier
	s_waitcnt lgkmcnt(0)
	s_waitcnt lgkmcnt(7)
	v_mfma_f32_16x16x32_bf16 v[60:63], v[156:159], v[172:175], v[60:63]
	v_mfma_f32_16x16x32_bf16 v[56:59], v[164:167], v[172:175], v[56:59]
	s_waitcnt lgkmcnt(5)
	v_mfma_f32_16x16x32_bf16 v[52:55], v[156:159], v[180:183], v[52:55]
	v_mfma_f32_16x16x32_bf16 v[48:51], v[164:167], v[180:183], v[48:51]
	s_waitcnt lgkmcnt(3)
	v_mfma_f32_16x16x32_bf16 v[44:47], v[156:159], v[188:191], v[44:47]
	v_mfma_f32_16x16x32_bf16 v[40:43], v[164:167], v[188:191], v[40:43]
	s_waitcnt lgkmcnt(1)
	v_mfma_f32_16x16x32_bf16 v[36:39], v[156:159], v[196:199], v[36:39]
	v_mfma_f32_16x16x32_bf16 v[32:35], v[164:167], v[196:199], v[32:35]
	v_mfma_f32_16x16x32_bf16 v[60:63], v[160:163], v[176:179], v[60:63]
	v_mfma_f32_16x16x32_bf16 v[56:59], v[168:171], v[176:179], v[56:59]
	v_mfma_f32_16x16x32_bf16 v[52:55], v[160:163], v[184:187], v[52:55]
	v_mfma_f32_16x16x32_bf16 v[48:51], v[168:171], v[184:187], v[48:51]
	v_mfma_f32_16x16x32_bf16 v[44:47], v[160:163], v[192:195], v[44:47]
	v_mfma_f32_16x16x32_bf16 v[40:43], v[168:171], v[192:195], v[40:43]
	s_waitcnt lgkmcnt(0)
	v_mfma_f32_16x16x32_bf16 v[36:39], v[160:163], v[200:203], v[36:39]
	v_mfma_f32_16x16x32_bf16 v[32:35], v[168:171], v[200:203], v[32:35]
	s_barrier
	s_add_i32 s47, s41, s17
	s_add_i32 s48, s47, 0x100
	s_mov_b32 m0, s20
	s_nop 0
	buffer_load_dwordx4 v130, s[8:11], s48 offen lds
	s_mov_b32 m0, s21
	s_nop 0
	buffer_load_dwordx4 v134, s[8:11], s48 offen lds
	s_waitcnt vmcnt(6)
	s_barrier
; #define STAGE(P, RS, SOFF, OFF, kt) do { const int _so = (SOFF) + (kt) * (BK * 2); \
;     _Pragma("unroll") for (int _i = 0; _i < 2; ++_i) { \
;       __builtin_amdgcn_raw_ptr_buffer_load_lds(RS, (__attribute__((address_space(3))) void*)((P) + wave * 1024 + _i * 8192), 16, OFF[_i], _so, 0, 0); } } while (0)
; #define LDA(dst, b, h) _Pragma("unroll") for (int m = 0; m < 4; ++m) _Pragma("unroll") for (int k = 0; k < 2; ++k) \
;     dst[m][k] = *reinterpret_cast<const bf16x8*>(SA(b, h) + lds_byte(wr * 64 + m * 16 + fr, k * 32 + fq * 8))
; #define LDB(dst, b, h) _Pragma("unroll") for (int n = 0; n < 2; ++n) _Pragma("unroll") for (int k = 0; k < 2; ++k) \
;     dst[n][k] = *reinterpret_cast<const bf16x8*>(SB(b, h) + lds_byte(wc * 32 + n * 16 + fr, k * 32 + fq * 8))
; #define WAIT_V(n) asm volatile("s_waitcnt vmcnt(" #n ")" ::: "memory")
; #define WAIT_L(n) asm volatile("s_waitcnt lgkmcnt(" #n ")" ::: "memory")
; #define BAR __builtin_amdgcn_s_barrier()
; #define SCHED __builtin_amdgcn_sched_barrier(0)
;     ...
;       WAIT_V(6); BAR; MMA(1, 1, At, B1); BAR;
;       LDB(B0, 1, 0); SCHED; LDA(At, 1, 0); STAGE(SA(0, 1), rsA, sA1, offA, t + 2);
;       WAIT_L(8); BAR; WAIT_L(0); MMA(0, 0, At, B0); BAR; SCHED;
;       LDB(B1, 1, 1); STAGE(SB(1, 0), rsB, sB0, offB, t + 3);
;       BAR; WAIT_L(0); MMA(0, 1, At, B1); BAR;
;       LDA(At, 1, 1); STAGE(SA(1, 0), rsA, sA0, offA, t + 3);
	v_mfma_f32_16x16x32_bf16 v[28:31], v[204:207], v[172:175], v[28:31]
	v_mfma_f32_16x16x32_bf16 v[24:27], v[212:215], v[172:175], v[24:27]
	v_mfma_f32_16x16x32_bf16 v[20:23], v[204:207], v[180:183], v[20:23]
	v_mfma_f32_16x16x32_bf16 v[16:19], v[212:215], v[180:183], v[16:19]
	v_mfma_f32_16x16x32_bf16 v[12:15], v[204:207], v[188:191], v[12:15]
	v_mfma_f32_16x16x32_bf16 v[8:11], v[212:215], v[188:191], v[8:11]
	v_mfma_f32_16x16x32_bf16 v[4:7], v[204:207], v[196:199], v[4:7]
	v_mfma_f32_16x16x32_bf16 v[0:3], v[212:215], v[196:199], v[0:3]
	v_mfma_f32_16x16x32_bf16 v[28:31], v[208:211], v[176:179], v[28:31]
	v_mfma_f32_16x16x32_bf16 v[24:27], v[216:219], v[176:179], v[24:27]
	v_mfma_f32_16x16x32_bf16 v[20:23], v[208:211], v[184:187], v[20:23]
	v_mfma_f32_16x16x32_bf16 v[16:19], v[216:219], v[184:187], v[16:19]
	v_mfma_f32_16x16x32_bf16 v[12:15], v[208:211], v[192:195], v[12:15]
	v_mfma_f32_16x16x32_bf16 v[8:11], v[216:219], v[192:195], v[8:11]
	v_mfma_f32_16x16x32_bf16 v[4:7], v[208:211], v[200:203], v[4:7]
	v_mfma_f32_16x16x32_bf16 v[0:3], v[216:219], v[200:203], v[0:3]
	s_barrier
	ds_read_b128 v[156:159], v143
	ds_read_b128 v[160:163], v144
	ds_read_b128 v[164:167], v145
	ds_read_b128 v[168:171], v146
	s_addk_i32 s44, 0x100
	s_mov_b32 m0, s22
	ds_read_b128 v[172:175], v131 offset:32768
	ds_read_b128 v[176:179], v131 offset:33792
	ds_read_b128 v[180:183], v138 offset:32768
	ds_read_b128 v[184:187], v138 offset:33792
	ds_read_b128 v[188:191], v137 offset:32768
	ds_read_b128 v[192:195], v137 offset:33792
	ds_read_b128 v[196:199], v135 offset:32768
	ds_read_b128 v[200:203], v135 offset:33792
	buffer_load_dwordx4 v128, s[4:7], s44 offen lds
	s_mov_b32 m0, s23
	s_nop 0
	buffer_load_dwordx4 v132, s[4:7], s44 offen lds
	s_waitcnt lgkmcnt(8)
	s_barrier
	s_waitcnt lgkmcnt(0)
	s_waitcnt lgkmcnt(7)
	v_mfma_f32_16x16x32_bf16 v[124:127], v[156:159], v[172:175], v[124:127]
	v_mfma_f32_16x16x32_bf16 v[120:123], v[164:167], v[172:175], v[120:123]
	s_waitcnt lgkmcnt(5)
	v_mfma_f32_16x16x32_bf16 v[116:119], v[156:159], v[180:183], v[116:119]
	v_mfma_f32_16x16x32_bf16 v[112:115], v[164:167], v[180:183], v[112:115]
	s_waitcnt lgkmcnt(3)
	v_mfma_f32_16x16x32_bf16 v[108:111], v[156:159], v[188:191], v[108:111]
	v_mfma_f32_16x16x32_bf16 v[104:107], v[164:167], v[188:191], v[104:107]
	s_waitcnt lgkmcnt(1)
	v_mfma_f32_16x16x32_bf16 v[100:103], v[156:159], v[196:199], v[100:103]
	v_mfma_f32_16x16x32_bf16 v[96:99], v[164:167], v[196:199], v[96:99]
	v_mfma_f32_16x16x32_bf16 v[124:127], v[160:163], v[176:179], v[124:127]
	v_mfma_f32_16x16x32_bf16 v[120:123], v[168:171], v[176:179], v[120:123]
	v_mfma_f32_16x16x32_bf16 v[116:119], v[160:163], v[184:187], v[116:119]
	v_mfma_f32_16x16x32_bf16 v[112:115], v[168:171], v[184:187], v[112:115]
	v_mfma_f32_16x16x32_bf16 v[108:111], v[160:163], v[192:195], v[108:111]
	v_mfma_f32_16x16x32_bf16 v[104:107], v[168:171], v[192:195], v[104:107]
	s_waitcnt lgkmcnt(0)
	v_mfma_f32_16x16x32_bf16 v[100:103], v[160:163], v[200:203], v[100:103]
	v_mfma_f32_16x16x32_bf16 v[96:99], v[168:171], v[200:203], v[96:99]
	s_barrier
	s_addk_i32 s45, 0x180
	s_mov_b32 m0, s24
	ds_read_b128 v[204:207], v139
	ds_read_b128 v[208:211], v140
	ds_read_b128 v[212:215], v141
	ds_read_b128 v[216:219], v142
	buffer_load_dwordx4 v130, s[8:11], s45 offen lds
	s_mov_b32 m0, s25
	s_nop 0
	buffer_load_dwordx4 v134, s[8:11], s45 offen lds
	s_barrier
	s_waitcnt lgkmcnt(0)
	s_waitcnt lgkmcnt(3)
	v_mfma_f32_16x16x32_bf16 v[92:95], v[204:207], v[172:175], v[92:95]
	s_waitcnt lgkmcnt(1)
	v_mfma_f32_16x16x32_bf16 v[88:91], v[212:215], v[172:175], v[88:91]
	v_mfma_f32_16x16x32_bf16 v[84:87], v[204:207], v[180:183], v[84:87]
	v_mfma_f32_16x16x32_bf16 v[80:83], v[212:215], v[180:183], v[80:83]
	v_mfma_f32_16x16x32_bf16 v[76:79], v[204:207], v[188:191], v[76:79]
	v_mfma_f32_16x16x32_bf16 v[72:75], v[212:215], v[188:191], v[72:75]
	v_mfma_f32_16x16x32_bf16 v[68:71], v[204:207], v[196:199], v[68:71]
	v_mfma_f32_16x16x32_bf16 v[64:67], v[212:215], v[196:199], v[64:67]
	v_mfma_f32_16x16x32_bf16 v[92:95], v[208:211], v[176:179], v[92:95]
	s_waitcnt lgkmcnt(0)
	v_mfma_f32_16x16x32_bf16 v[88:91], v[216:219], v[176:179], v[88:91]
	v_mfma_f32_16x16x32_bf16 v[84:87], v[208:211], v[184:187], v[84:87]
	v_mfma_f32_16x16x32_bf16 v[80:83], v[216:219], v[184:187], v[80:83]
	v_mfma_f32_16x16x32_bf16 v[76:79], v[208:211], v[192:195], v[76:79]
	v_mfma_f32_16x16x32_bf16 v[72:75], v[216:219], v[192:195], v[72:75]
	v_mfma_f32_16x16x32_bf16 v[68:71], v[208:211], v[200:203], v[68:71]
	v_mfma_f32_16x16x32_bf16 v[64:67], v[216:219], v[200:203], v[64:67]
	s_addk_i32 s46, 0x180
	s_mov_b32 m0, s26
	s_barrier
	ds_read_b128 v[172:175], v131 offset:49152
	ds_read_b128 v[176:179], v131 offset:50176
	ds_read_b128 v[180:183], v138 offset:49152
	ds_read_b128 v[184:187], v138 offset:50176
	ds_read_b128 v[188:191], v137 offset:49152
	ds_read_b128 v[192:195], v137 offset:50176
	ds_read_b128 v[196:199], v135 offset:49152
	ds_read_b128 v[200:203], v135 offset:50176
	buffer_load_dwordx4 v128, s[4:7], s46 offen lds
	s_mov_b32 m0, s27
	s_nop 0
	buffer_load_dwordx4 v132, s[4:7], s46 offen lds
	s_barrier
; #define STAGE(P, RS, SOFF, OFF, kt) do { const int _so = (SOFF) + (kt) * (BK * 2); \
;     _Pragma("unroll") for (int _i = 0; _i < 2; ++_i) { \
;       __builtin_amdgcn_raw_ptr_buffer_load_lds(RS, (__attribute__((address_space(3))) void*)((P) + wave * 1024 + _i * 8192), 16, OFF[_i], _so, 0, 0); } } while (0)
; #define LDA(dst, b, h) _Pragma("unroll") for (int m = 0; m < 4; ++m) _Pragma("unroll") for (int k = 0; k < 2; ++k) \
;     dst[m][k] = *reinterpret_cast<const bf16x8*>(SA(b, h) + lds_byte(wr * 64 + m * 16 + fr, k * 32 + fq * 8))
; #define LDB(dst, b, h) _Pragma("unroll") for (int n = 0; n < 2; ++n) _Pragma("unroll") for (int k = 0; k < 2; ++k) \
;     dst[n][k] = *reinterpret_cast<const bf16x8*>(SB(b, h) + lds_byte(wc * 32 + n * 16 + fr, k * 32 + fq * 8))
; #define WAIT_V(n) asm volatile("s_waitcnt vmcnt(" #n ")" ::: "memory")
; #define WAIT_L(n) asm volatile("s_waitcnt lgkmcnt(" #n ")" ::: "memory")
; #define BAR __builtin_amdgcn_s_barrier()
; #define SCHED __builtin_amdgcn_sched_barrier(0)
;     ...
;       BAR; WAIT_L(0); MMA(1, 0, At, B0); BAR; SCHED;
;       STAGE(SB(1, 1), rsB, sB1, offB, t + 3);
;       WAIT_V(6); BAR; MMA(1, 1, At, B1); BAR;
;     }
;     { LDB(B0, 0, 0); LDA(At, 0, 0); STAGE(SA(1, 1), rsA, sA1, offA, nt - 1);
;       BAR; WAIT_L(0); MMA(0, 0, At, B0); BAR;
;       LDB(B1, 0, 1); BAR; WAIT_L(0); MMA(0, 1, At, B1); BAR;
	s_waitcnt lgkmcnt(0)
	s_waitcnt lgkmcnt(7)
	v_mfma_f32_16x16x32_bf16 v[60:63], v[156:159], v[172:175], v[60:63]
	v_mfma_f32_16x16x32_bf16 v[56:59], v[164:167], v[172:175], v[56:59]
	s_waitcnt lgkmcnt(5)
	v_mfma_f32_16x16x32_bf16 v[52:55], v[156:159], v[180:183], v[52:55]
	v_mfma_f32_16x16x32_bf16 v[48:51], v[164:167], v[180:183], v[48:51]
	s_waitcnt lgkmcnt(3)
	v_mfma_f32_16x16x32_bf16 v[44:47], v[156:159], v[188:191], v[44:47]
	v_mfma_f32_16x16x32_bf16 v[40:43], v[164:167], v[188:191], v[40:43]
	s_waitcnt lgkmcnt(1)
	v_mfma_f32_16x16x32_bf16 v[36:39], v[156:159], v[196:199], v[36:39]
	v_mfma_f32_16x16x32_bf16 v[32:35], v[164:167], v[196:199], v[32:35]
	v_mfma_f32_16x16x32_bf16 v[60:63], v[160:163], v[176:179], v[60:63]
	v_mfma_f32_16x16x32_bf16 v[56:59], v[168:171], v[176:179], v[56:59]
	v_mfma_f32_16x16x32_bf16 v[52:55], v[160:163], v[184:187], v[52:55]
	v_mfma_f32_16x16x32_bf16 v[48:51], v[168:171], v[184:187], v[48:51]
	v_mfma_f32_16x16x32_bf16 v[44:47], v[160:163], v[192:195], v[44:47]
	v_mfma_f32_16x16x32_bf16 v[40:43], v[168:171], v[192:195], v[40:43]
	s_waitcnt lgkmcnt(0)
	v_mfma_f32_16x16x32_bf16 v[36:39], v[160:163], v[200:203], v[36:39]
	v_mfma_f32_16x16x32_bf16 v[32:35], v[168:171], v[200:203], v[32:35]
	s_barrier
	s_addk_i32 s47, 0x180
	s_mov_b32 m0, s28
	s_nop 0
	buffer_load_dwordx4 v130, s[8:11], s47 offen lds
	s_mov_b32 m0, s29
	s_nop 0
	buffer_load_dwordx4 v134, s[8:11], s47 offen lds
	s_waitcnt vmcnt(6)
	s_barrier
	v_mfma_f32_16x16x32_bf16 v[28:31], v[204:207], v[172:175], v[28:31]
	v_mfma_f32_16x16x32_bf16 v[24:27], v[212:215], v[172:175], v[24:27]
	v_mfma_f32_16x16x32_bf16 v[20:23], v[204:207], v[180:183], v[20:23]
	v_mfma_f32_16x16x32_bf16 v[16:19], v[212:215], v[180:183], v[16:19]
	v_mfma_f32_16x16x32_bf16 v[12:15], v[204:207], v[188:191], v[12:15]
	v_mfma_f32_16x16x32_bf16 v[8:11], v[212:215], v[188:191], v[8:11]
	v_mfma_f32_16x16x32_bf16 v[4:7], v[204:207], v[196:199], v[4:7]
	v_mfma_f32_16x16x32_bf16 v[0:3], v[212:215], v[196:199], v[0:3]
	v_mfma_f32_16x16x32_bf16 v[28:31], v[208:211], v[176:179], v[28:31]
	v_mfma_f32_16x16x32_bf16 v[24:27], v[216:219], v[176:179], v[24:27]
	v_mfma_f32_16x16x32_bf16 v[20:23], v[208:211], v[184:187], v[20:23]
	v_mfma_f32_16x16x32_bf16 v[16:19], v[216:219], v[184:187], v[16:19]
	v_mfma_f32_16x16x32_bf16 v[12:15], v[208:211], v[192:195], v[12:15]
	v_mfma_f32_16x16x32_bf16 v[8:11], v[216:219], v[192:195], v[8:11]
	v_mfma_f32_16x16x32_bf16 v[4:7], v[208:211], v[200:203], v[4:7]
	v_mfma_f32_16x16x32_bf16 v[0:3], v[216:219], v[200:203], v[0:3]
	s_add_i32 s16, s16, 2
	s_addk_i32 s17, 0x100
	s_cmp_gt_u32 s16, 3
	s_barrier
	s_cbranch_scc0 .LBB0_110
	s_add_i32 s10, s38, 0x380
	s_mov_b32 m0, s31
	ds_read_b128 v[156:159], v151
	ds_read_b128 v[160:163], v152
	ds_read_b128 v[164:167], v153
	ds_read_b128 v[152:155], v154
	ds_read_b128 v[168:171], v131
	ds_read_b128 v[172:175], v131 offset:1024
	ds_read_b128 v[176:179], v138
	ds_read_b128 v[180:183], v138 offset:1024
	ds_read_b128 v[184:187], v137
	ds_read_b128 v[188:191], v137 offset:1024
	ds_read_b128 v[192:195], v135
	ds_read_b128 v[196:199], v135 offset:1024
	buffer_load_dwordx4 v128, s[4:7], s10 offen lds
	s_mov_b32 m0, s33
	s_nop 0
	buffer_load_dwordx4 v132, s[4:7], s10 offen lds
	s_barrier
	s_waitcnt lgkmcnt(0)
	s_waitcnt lgkmcnt(7)
	v_mfma_f32_16x16x32_bf16 v[124:127], v[156:159], v[168:171], v[124:127]
	v_mfma_f32_16x16x32_bf16 v[120:123], v[164:167], v[168:171], v[120:123]
	s_waitcnt lgkmcnt(5)
	v_mfma_f32_16x16x32_bf16 v[116:119], v[156:159], v[176:179], v[116:119]
	v_mfma_f32_16x16x32_bf16 v[112:115], v[164:167], v[176:179], v[112:115]
	s_waitcnt lgkmcnt(3)
	v_mfma_f32_16x16x32_bf16 v[108:111], v[156:159], v[184:187], v[108:111]
	v_mfma_f32_16x16x32_bf16 v[104:107], v[164:167], v[184:187], v[104:107]
	s_waitcnt lgkmcnt(1)
	v_mfma_f32_16x16x32_bf16 v[100:103], v[156:159], v[192:195], v[100:103]
	v_mfma_f32_16x16x32_bf16 v[96:99], v[164:167], v[192:195], v[96:99]
	v_mfma_f32_16x16x32_bf16 v[124:127], v[160:163], v[172:175], v[124:127]
	v_mfma_f32_16x16x32_bf16 v[120:123], v[152:155], v[172:175], v[120:123]
	v_mfma_f32_16x16x32_bf16 v[116:119], v[160:163], v[180:183], v[116:119]
	v_mfma_f32_16x16x32_bf16 v[112:115], v[152:155], v[180:183], v[112:115]
	v_mfma_f32_16x16x32_bf16 v[108:111], v[160:163], v[188:191], v[108:111]
	v_mfma_f32_16x16x32_bf16 v[104:107], v[152:155], v[188:191], v[104:107]
	s_waitcnt lgkmcnt(0)
	v_mfma_f32_16x16x32_bf16 v[100:103], v[160:163], v[196:199], v[100:103]
	v_mfma_f32_16x16x32_bf16 v[96:99], v[152:155], v[196:199], v[96:99]
	s_barrier
	ds_read_b128 v[200:203], v147
	ds_read_b128 v[204:207], v148
	ds_read_b128 v[208:211], v149
	ds_read_b128 v[148:151], v150
	s_barrier
	s_waitcnt lgkmcnt(0)
	s_waitcnt lgkmcnt(3)
	v_mfma_f32_16x16x32_bf16 v[92:95], v[200:203], v[168:171], v[92:95]
	s_waitcnt lgkmcnt(1)
	v_mfma_f32_16x16x32_bf16 v[88:91], v[208:211], v[168:171], v[88:91]
	v_mfma_f32_16x16x32_bf16 v[84:87], v[200:203], v[176:179], v[84:87]
	v_mfma_f32_16x16x32_bf16 v[80:83], v[208:211], v[176:179], v[80:83]
	v_mfma_f32_16x16x32_bf16 v[76:79], v[200:203], v[184:187], v[76:79]
	v_mfma_f32_16x16x32_bf16 v[72:75], v[208:211], v[184:187], v[72:75]
	v_mfma_f32_16x16x32_bf16 v[68:71], v[200:203], v[192:195], v[68:71]
	v_mfma_f32_16x16x32_bf16 v[64:67], v[208:211], v[192:195], v[64:67]
	v_mfma_f32_16x16x32_bf16 v[92:95], v[204:207], v[172:175], v[92:95]
	s_waitcnt lgkmcnt(0)
	v_mfma_f32_16x16x32_bf16 v[88:91], v[148:151], v[172:175], v[88:91]
	v_mfma_f32_16x16x32_bf16 v[84:87], v[204:207], v[180:183], v[84:87]
	v_mfma_f32_16x16x32_bf16 v[80:83], v[148:151], v[180:183], v[80:83]
	v_mfma_f32_16x16x32_bf16 v[76:79], v[204:207], v[188:191], v[76:79]
	v_mfma_f32_16x16x32_bf16 v[72:75], v[148:151], v[188:191], v[72:75]
	v_mfma_f32_16x16x32_bf16 v[68:71], v[204:207], v[196:199], v[68:71]
	v_mfma_f32_16x16x32_bf16 v[64:67], v[148:151], v[196:199], v[64:67]
	s_barrier
; #define LDA(dst, b, h) _Pragma("unroll") for (int m = 0; m < 4; ++m) _Pragma("unroll") for (int k = 0; k < 2; ++k) \
;     dst[m][k] = *reinterpret_cast<const bf16x8*>(SA(b, h) + lds_byte(wr * 64 + m * 16 + fr, k * 32 + fq * 8))
; #define LDB(dst, b, h) _Pragma("unroll") for (int n = 0; n < 2; ++n) _Pragma("unroll") for (int k = 0; k < 2; ++k) \
;     dst[n][k] = *reinterpret_cast<const bf16x8*>(SB(b, h) + lds_byte(wc * 32 + n * 16 + fr, k * 32 + fq * 8))
; #define WAIT_V(n) asm volatile("s_waitcnt vmcnt(" #n ")" ::: "memory")
; #define WAIT_L(n) asm volatile("s_waitcnt lgkmcnt(" #n ")" ::: "memory")
; #define BAR __builtin_amdgcn_s_barrier()
;     ...
;       LDA(At, 0, 1); WAIT_V(4); BAR; WAIT_L(0); MMA(1, 0, At, B0); MMA(1, 1, At, B1); BAR; }
;     { LDB(B0, 1, 0); LDA(At, 1, 0); WAIT_V(2); BAR; WAIT_L(0); MMA(0, 0, At, B0); BAR;
	ds_read_b128 v[168:171], v131 offset:16384
	ds_read_b128 v[172:175], v131 offset:17408
	ds_read_b128 v[176:179], v138 offset:16384
	ds_read_b128 v[180:183], v138 offset:17408
	ds_read_b128 v[184:187], v137 offset:16384
	ds_read_b128 v[188:191], v137 offset:17408
	ds_read_b128 v[192:195], v135 offset:16384
	ds_read_b128 v[196:199], v135 offset:17408
	s_waitcnt vmcnt(4)
	s_barrier
	s_waitcnt lgkmcnt(0)
	s_waitcnt lgkmcnt(7)
	v_mfma_f32_16x16x32_bf16 v[60:63], v[156:159], v[168:171], v[60:63]
	v_mfma_f32_16x16x32_bf16 v[56:59], v[164:167], v[168:171], v[56:59]
	s_waitcnt lgkmcnt(5)
	v_mfma_f32_16x16x32_bf16 v[52:55], v[156:159], v[176:179], v[52:55]
	v_mfma_f32_16x16x32_bf16 v[48:51], v[164:167], v[176:179], v[48:51]
	s_waitcnt lgkmcnt(3)
	v_mfma_f32_16x16x32_bf16 v[44:47], v[156:159], v[184:187], v[44:47]
	v_mfma_f32_16x16x32_bf16 v[40:43], v[164:167], v[184:187], v[40:43]
	s_waitcnt lgkmcnt(1)
	v_mfma_f32_16x16x32_bf16 v[36:39], v[156:159], v[192:195], v[36:39]
	v_mfma_f32_16x16x32_bf16 v[32:35], v[164:167], v[192:195], v[32:35]
	v_mfma_f32_16x16x32_bf16 v[60:63], v[160:163], v[172:175], v[60:63]
	v_mfma_f32_16x16x32_bf16 v[56:59], v[152:155], v[172:175], v[56:59]
	v_mfma_f32_16x16x32_bf16 v[52:55], v[160:163], v[180:183], v[52:55]
	v_mfma_f32_16x16x32_bf16 v[48:51], v[152:155], v[180:183], v[48:51]
	v_mfma_f32_16x16x32_bf16 v[44:47], v[160:163], v[188:191], v[44:47]
	v_mfma_f32_16x16x32_bf16 v[40:43], v[152:155], v[188:191], v[40:43]
	s_waitcnt lgkmcnt(0)
	v_mfma_f32_16x16x32_bf16 v[36:39], v[160:163], v[196:199], v[36:39]
	v_mfma_f32_16x16x32_bf16 v[32:35], v[152:155], v[196:199], v[32:35]
	v_mfma_f32_16x16x32_bf16 v[28:31], v[200:203], v[168:171], v[28:31]
	v_mfma_f32_16x16x32_bf16 v[24:27], v[208:211], v[168:171], v[24:27]
	v_mfma_f32_16x16x32_bf16 v[20:23], v[200:203], v[176:179], v[20:23]
	v_mfma_f32_16x16x32_bf16 v[16:19], v[208:211], v[176:179], v[16:19]
	v_mfma_f32_16x16x32_bf16 v[12:15], v[200:203], v[184:187], v[12:15]
	v_mfma_f32_16x16x32_bf16 v[8:11], v[208:211], v[184:187], v[8:11]
	v_mfma_f32_16x16x32_bf16 v[4:7], v[200:203], v[192:195], v[4:7]
	v_mfma_f32_16x16x32_bf16 v[0:3], v[208:211], v[192:195], v[0:3]
	v_mfma_f32_16x16x32_bf16 v[28:31], v[204:207], v[172:175], v[28:31]
	v_mfma_f32_16x16x32_bf16 v[24:27], v[148:151], v[172:175], v[24:27]
	v_mfma_f32_16x16x32_bf16 v[20:23], v[204:207], v[180:183], v[20:23]
	v_mfma_f32_16x16x32_bf16 v[16:19], v[148:151], v[180:183], v[16:19]
	v_mfma_f32_16x16x32_bf16 v[12:15], v[204:207], v[188:191], v[12:15]
	v_mfma_f32_16x16x32_bf16 v[8:11], v[148:151], v[188:191], v[8:11]
	v_mfma_f32_16x16x32_bf16 v[4:7], v[204:207], v[196:199], v[4:7]
	v_mfma_f32_16x16x32_bf16 v[0:3], v[148:151], v[196:199], v[0:3]
	s_barrier
	ds_read_b128 v[148:151], v143
	ds_read_b128 v[152:155], v144
	ds_read_b128 v[156:159], v145
	ds_read_b128 v[144:147], v146
	ds_read_b128 v[160:163], v131 offset:32768
	ds_read_b128 v[164:167], v131 offset:33792
	ds_read_b128 v[168:171], v138 offset:32768
	ds_read_b128 v[172:175], v138 offset:33792
	ds_read_b128 v[176:179], v137 offset:32768
	ds_read_b128 v[180:183], v137 offset:33792
	ds_read_b128 v[184:187], v135 offset:32768
	ds_read_b128 v[188:191], v135 offset:33792
	s_waitcnt vmcnt(2)
	s_barrier
	s_waitcnt lgkmcnt(0)
	s_waitcnt lgkmcnt(7)
	v_mfma_f32_16x16x32_bf16 v[124:127], v[148:151], v[160:163], v[124:127]
	v_mfma_f32_16x16x32_bf16 v[120:123], v[156:159], v[160:163], v[120:123]
	s_waitcnt lgkmcnt(5)
	v_mfma_f32_16x16x32_bf16 v[116:119], v[148:151], v[168:171], v[116:119]
	v_mfma_f32_16x16x32_bf16 v[112:115], v[156:159], v[168:171], v[112:115]
	s_waitcnt lgkmcnt(3)
	v_mfma_f32_16x16x32_bf16 v[108:111], v[148:151], v[176:179], v[108:111]
	v_mfma_f32_16x16x32_bf16 v[104:107], v[156:159], v[176:179], v[104:107]
	s_waitcnt lgkmcnt(1)
	v_mfma_f32_16x16x32_bf16 v[100:103], v[148:151], v[184:187], v[100:103]
	v_mfma_f32_16x16x32_bf16 v[96:99], v[156:159], v[184:187], v[96:99]
	v_mfma_f32_16x16x32_bf16 v[124:127], v[152:155], v[164:167], v[124:127]
	v_mfma_f32_16x16x32_bf16 v[120:123], v[144:147], v[164:167], v[120:123]
	v_mfma_f32_16x16x32_bf16 v[116:119], v[152:155], v[172:175], v[116:119]
	v_mfma_f32_16x16x32_bf16 v[112:115], v[144:147], v[172:175], v[112:115]
	v_mfma_f32_16x16x32_bf16 v[108:111], v[152:155], v[180:183], v[108:111]
	v_mfma_f32_16x16x32_bf16 v[104:107], v[144:147], v[180:183], v[104:107]
	s_waitcnt lgkmcnt(0)
	v_mfma_f32_16x16x32_bf16 v[100:103], v[152:155], v[188:191], v[100:103]
	v_mfma_f32_16x16x32_bf16 v[96:99], v[144:147], v[188:191], v[96:99]
	s_barrier
; #define LDA(dst, b, h) _Pragma("unroll") for (int m = 0; m < 4; ++m) _Pragma("unroll") for (int k = 0; k < 2; ++k) \
;     dst[m][k] = *reinterpret_cast<const bf16x8*>(SA(b, h) + lds_byte(wr * 64 + m * 16 + fr, k * 32 + fq * 8))
; #define LDB(dst, b, h) _Pragma("unroll") for (int n = 0; n < 2; ++n) _Pragma("unroll") for (int k = 0; k < 2; ++k) \
;     dst[n][k] = *reinterpret_cast<const bf16x8*>(SB(b, h) + lds_byte(wc * 32 + n * 16 + fr, k * 32 + fq * 8))
; #define WAIT_V(n) asm volatile("s_waitcnt vmcnt(" #n ")" ::: "memory")
; #define WAIT_L(n) asm volatile("s_waitcnt lgkmcnt(" #n ")" ::: "memory")
; #define BAR __builtin_amdgcn_s_barrier()
;     ...
;     { LDB(B0, 1, 0); LDA(At, 1, 0); WAIT_V(2); BAR; WAIT_L(0); MMA(0, 0, At, B0); BAR;
;       LDB(B1, 1, 1); WAIT_V(0); BAR; WAIT_L(0); MMA(0, 1, At, B1); BAR;
;       LDA(At, 1, 1); BAR; WAIT_L(0); MMA(1, 0, At, B0); MMA(1, 1, At, B1); BAR; }
;     if (wr == 0) BAR;
	ds_read_b128 v[192:195], v139
	ds_read_b128 v[196:199], v140
	ds_read_b128 v[200:203], v141
	ds_read_b128 v[140:143], v142
	s_waitcnt vmcnt(0)
	s_barrier
	s_waitcnt lgkmcnt(0)
	s_waitcnt lgkmcnt(3)
	v_mfma_f32_16x16x32_bf16 v[92:95], v[192:195], v[160:163], v[92:95]
	s_waitcnt lgkmcnt(1)
	v_mfma_f32_16x16x32_bf16 v[88:91], v[200:203], v[160:163], v[88:91]
	v_mfma_f32_16x16x32_bf16 v[84:87], v[192:195], v[168:171], v[84:87]
	v_mfma_f32_16x16x32_bf16 v[80:83], v[200:203], v[168:171], v[80:83]
	v_mfma_f32_16x16x32_bf16 v[76:79], v[192:195], v[176:179], v[76:79]
	v_mfma_f32_16x16x32_bf16 v[72:75], v[200:203], v[176:179], v[72:75]
	v_mfma_f32_16x16x32_bf16 v[68:71], v[192:195], v[184:187], v[68:71]
	v_mfma_f32_16x16x32_bf16 v[64:67], v[200:203], v[184:187], v[64:67]
	v_mfma_f32_16x16x32_bf16 v[92:95], v[196:199], v[164:167], v[92:95]
	s_waitcnt lgkmcnt(0)
	v_mfma_f32_16x16x32_bf16 v[88:91], v[140:143], v[164:167], v[88:91]
	v_mfma_f32_16x16x32_bf16 v[84:87], v[196:199], v[172:175], v[84:87]
	v_mfma_f32_16x16x32_bf16 v[80:83], v[140:143], v[172:175], v[80:83]
	v_mfma_f32_16x16x32_bf16 v[76:79], v[196:199], v[180:183], v[76:79]
	v_mfma_f32_16x16x32_bf16 v[72:75], v[140:143], v[180:183], v[72:75]
	v_mfma_f32_16x16x32_bf16 v[68:71], v[196:199], v[188:191], v[68:71]
	v_mfma_f32_16x16x32_bf16 v[64:67], v[140:143], v[188:191], v[64:67]
	s_barrier
	ds_read_b128 v[160:163], v131 offset:49152
	ds_read_b128 v[164:167], v131 offset:50176
	ds_read_b128 v[168:171], v138 offset:49152
	ds_read_b128 v[172:175], v138 offset:50176
	ds_read_b128 v[176:179], v137 offset:49152
	ds_read_b128 v[180:183], v137 offset:50176
	ds_read_b128 v[184:187], v135 offset:49152
	ds_read_b128 v[188:191], v135 offset:50176
	s_barrier
	s_waitcnt lgkmcnt(0)
	s_waitcnt lgkmcnt(7)
	v_mfma_f32_16x16x32_bf16 v[60:63], v[148:151], v[160:163], v[60:63]
	v_mfma_f32_16x16x32_bf16 v[56:59], v[156:159], v[160:163], v[56:59]
	s_waitcnt lgkmcnt(5)
	v_mfma_f32_16x16x32_bf16 v[52:55], v[148:151], v[168:171], v[52:55]
	v_mfma_f32_16x16x32_bf16 v[48:51], v[156:159], v[168:171], v[48:51]
	s_waitcnt lgkmcnt(3)
	v_mfma_f32_16x16x32_bf16 v[44:47], v[148:151], v[176:179], v[44:47]
	v_mfma_f32_16x16x32_bf16 v[40:43], v[156:159], v[176:179], v[40:43]
	s_waitcnt lgkmcnt(1)
	v_mfma_f32_16x16x32_bf16 v[36:39], v[148:151], v[184:187], v[36:39]
	v_mfma_f32_16x16x32_bf16 v[32:35], v[156:159], v[184:187], v[32:35]
	v_mfma_f32_16x16x32_bf16 v[60:63], v[152:155], v[164:167], v[60:63]
	v_mfma_f32_16x16x32_bf16 v[56:59], v[144:147], v[164:167], v[56:59]
	v_mfma_f32_16x16x32_bf16 v[52:55], v[152:155], v[172:175], v[52:55]
	v_mfma_f32_16x16x32_bf16 v[48:51], v[144:147], v[172:175], v[48:51]
	v_mfma_f32_16x16x32_bf16 v[44:47], v[152:155], v[180:183], v[44:47]
	v_mfma_f32_16x16x32_bf16 v[40:43], v[144:147], v[180:183], v[40:43]
	s_waitcnt lgkmcnt(0)
	v_mfma_f32_16x16x32_bf16 v[36:39], v[152:155], v[188:191], v[36:39]
	v_mfma_f32_16x16x32_bf16 v[32:35], v[144:147], v[188:191], v[32:35]
	v_mfma_f32_16x16x32_bf16 v[28:31], v[192:195], v[160:163], v[28:31]
	v_mfma_f32_16x16x32_bf16 v[24:27], v[200:203], v[160:163], v[24:27]
	v_mfma_f32_16x16x32_bf16 v[20:23], v[192:195], v[168:171], v[20:23]
	v_mfma_f32_16x16x32_bf16 v[16:19], v[200:203], v[168:171], v[16:19]
	v_mfma_f32_16x16x32_bf16 v[12:15], v[192:195], v[176:179], v[12:15]
	v_mfma_f32_16x16x32_bf16 v[8:11], v[200:203], v[176:179], v[8:11]
	v_mfma_f32_16x16x32_bf16 v[4:7], v[192:195], v[184:187], v[4:7]
	v_mfma_f32_16x16x32_bf16 v[0:3], v[200:203], v[184:187], v[0:3]
	v_mfma_f32_16x16x32_bf16 v[28:31], v[196:199], v[164:167], v[28:31]
	v_mfma_f32_16x16x32_bf16 v[24:27], v[140:143], v[164:167], v[24:27]
	v_mfma_f32_16x16x32_bf16 v[20:23], v[196:199], v[172:175], v[20:23]
	v_mfma_f32_16x16x32_bf16 v[16:19], v[140:143], v[172:175], v[16:19]
	v_mfma_f32_16x16x32_bf16 v[12:15], v[196:199], v[180:183], v[12:15]
	v_mfma_f32_16x16x32_bf16 v[8:11], v[140:143], v[180:183], v[8:11]
	v_mfma_f32_16x16x32_bf16 v[4:7], v[196:199], v[188:191], v[4:7]
	v_mfma_f32_16x16x32_bf16 v[0:3], v[140:143], v[188:191], v[0:3]
	v_cmp_gt_u32_e32 vcc, s36, v136
	s_barrier
	s_and_saveexec_b64 s[10:11], vcc
	s_cbranch_execz .LBB0_113
	s_barrier

; #define STAGE(P, RS, SOFF, OFF, kt) do { const int _so = (SOFF) + (kt) * (BK * 2); \
;     _Pragma("unroll") for (int _i = 0; _i < 2; ++_i) { \
;       __builtin_amdgcn_raw_ptr_buffer_load_lds(RS, (__attribute__((address_space(3))) void*)((P) + wave * 1024 + _i * 8192), 16, OFF[_i], _so, 0, 0); } } while (0)
; #define LDA(dst, b, h) _Pragma("unroll") for (int m = 0; m < 4; ++m) _Pragma("unroll") for (int k = 0; k < 2; ++k) \
;     dst[m][k] = *reinterpret_cast<const bf16x8*>(SA(b, h) + lds_byte(wr * 64 + m * 16 + fr, k * 32 + fq * 8))
; #define LDB(dst, b, h) _Pragma("unroll") for (int n = 0; n < 2; ++n) _Pragma("unroll") for (int k = 0; k < 2; ++k) \
;     dst[n][k] = *reinterpret_cast<const bf16x8*>(SB(b, h) + lds_byte(wc * 32 + n * 16 + fr, k * 32 + fq * 8))
; #define WAIT_V(n) asm volatile("s_waitcnt vmcnt(" #n ")" ::: "memory")
; #define WAIT_L(n) asm volatile("s_waitcnt lgkmcnt(" #n ")" ::: "memory")
; #define BAR __builtin_amdgcn_s_barrier()
; #define SCHED __builtin_amdgcn_sched_barrier(0)
;     ...
;       LDB(B0, 0, 0); SCHED; LDA(At, 0, 0); STAGE(SA(1, 1), rsA, sA1, offA, t + 1);
;       WAIT_L(8); BAR; WAIT_L(0); MMA(0, 0, At, B0); BAR; SCHED;
;       LDB(B1, 0, 1); STAGE(SB(0, 0), rsB, sB0, offB, t + 2);
;       BAR; WAIT_L(0); MMA(0, 1, At, B1); BAR;
;       LDA(At, 0, 1); STAGE(SA(0, 0), rsA, sA0, offA, t + 2);
;       BAR; WAIT_L(0); MMA(1, 0, At, B0); BAR; SCHED;
;       STAGE(SB(0, 1), rsB, sB1, offB, t + 2);
;       WAIT_V(6); BAR; MMA(1, 1, At, B1); BAR;
.LBB0_148:
	ds_read_b128 v[152:155], v147
	ds_read_b128 v[156:159], v148
	ds_read_b128 v[160:163], v149
	ds_read_b128 v[164:167], v150
	s_add_i32 s4, s82, s3
	s_add_i32 s5, s4, 0x80
	s_mov_b32 m0, s31
	ds_read_b128 v[168:171], v129
	ds_read_b128 v[172:175], v129 offset:1024
	ds_read_b128 v[176:179], v132
	ds_read_b128 v[180:183], v132 offset:1024
	ds_read_b128 v[184:187], v131
	ds_read_b128 v[188:191], v131 offset:1024
	ds_read_b128 v[192:195], v130
	ds_read_b128 v[196:199], v130 offset:1024
	buffer_load_dwordx4 v141, s[8:11], s5 offen lds
	s_mov_b32 m0, s58
	s_nop 0
	buffer_load_dwordx4 v142, s[8:11], s5 offen lds
	s_waitcnt lgkmcnt(8)
	s_barrier
	s_waitcnt lgkmcnt(0)
	s_waitcnt lgkmcnt(7)
	v_mfma_f32_16x16x32_bf16 v[124:127], v[152:155], v[168:171], v[124:127]
	v_mfma_f32_16x16x32_bf16 v[120:123], v[160:163], v[168:171], v[120:123]
	s_waitcnt lgkmcnt(5)
	v_mfma_f32_16x16x32_bf16 v[116:119], v[152:155], v[176:179], v[116:119]
	v_mfma_f32_16x16x32_bf16 v[112:115], v[160:163], v[176:179], v[112:115]
	s_waitcnt lgkmcnt(3)
	v_mfma_f32_16x16x32_bf16 v[108:111], v[152:155], v[184:187], v[108:111]
	v_mfma_f32_16x16x32_bf16 v[104:107], v[160:163], v[184:187], v[104:107]
	s_waitcnt lgkmcnt(1)
	v_mfma_f32_16x16x32_bf16 v[100:103], v[152:155], v[192:195], v[100:103]
	v_mfma_f32_16x16x32_bf16 v[96:99], v[160:163], v[192:195], v[96:99]
	v_mfma_f32_16x16x32_bf16 v[124:127], v[156:159], v[172:175], v[124:127]
	v_mfma_f32_16x16x32_bf16 v[120:123], v[164:167], v[172:175], v[120:123]
	v_mfma_f32_16x16x32_bf16 v[116:119], v[156:159], v[180:183], v[116:119]
	v_mfma_f32_16x16x32_bf16 v[112:115], v[164:167], v[180:183], v[112:115]
	v_mfma_f32_16x16x32_bf16 v[108:111], v[156:159], v[188:191], v[108:111]
	v_mfma_f32_16x16x32_bf16 v[104:107], v[164:167], v[188:191], v[104:107]
	s_waitcnt lgkmcnt(0)
	v_mfma_f32_16x16x32_bf16 v[100:103], v[156:159], v[196:199], v[100:103]
	v_mfma_f32_16x16x32_bf16 v[96:99], v[164:167], v[196:199], v[96:99]
	s_barrier
	s_add_i32 s5, s84, s3
	s_add_i32 s6, s5, 0x100
	s_mov_b32 s14, s10
	s_mov_b32 s15, s11
	s_mov_b32 m0, s34
	ds_read_b128 v[200:203], v143
	ds_read_b128 v[204:207], v144
	ds_read_b128 v[208:211], v145
	ds_read_b128 v[212:215], v146
	buffer_load_dwordx4 v141, s[12:15], s6 offen lds
	s_mov_b32 m0, s43
	s_nop 0
	buffer_load_dwordx4 v142, s[12:15], s6 offen lds
	s_barrier
	s_waitcnt lgkmcnt(0)
	s_waitcnt lgkmcnt(3)
	v_mfma_f32_16x16x32_bf16 v[92:95], v[200:203], v[168:171], v[92:95]
	s_waitcnt lgkmcnt(1)
	v_mfma_f32_16x16x32_bf16 v[88:91], v[208:211], v[168:171], v[88:91]
	v_mfma_f32_16x16x32_bf16 v[80:83], v[200:203], v[176:179], v[80:83]
	v_mfma_f32_16x16x32_bf16 v[68:71], v[208:211], v[176:179], v[68:71]
	v_mfma_f32_16x16x32_bf16 v[60:63], v[200:203], v[184:187], v[60:63]
	v_mfma_f32_16x16x32_bf16 v[56:59], v[208:211], v[184:187], v[56:59]
	v_mfma_f32_16x16x32_bf16 v[52:55], v[200:203], v[192:195], v[52:55]
	v_mfma_f32_16x16x32_bf16 v[48:51], v[208:211], v[192:195], v[48:51]
	v_mfma_f32_16x16x32_bf16 v[92:95], v[204:207], v[172:175], v[92:95]
	s_waitcnt lgkmcnt(0)
	v_mfma_f32_16x16x32_bf16 v[88:91], v[212:215], v[172:175], v[88:91]
	v_mfma_f32_16x16x32_bf16 v[80:83], v[204:207], v[180:183], v[80:83]
	v_mfma_f32_16x16x32_bf16 v[68:71], v[212:215], v[180:183], v[68:71]
	v_mfma_f32_16x16x32_bf16 v[60:63], v[204:207], v[188:191], v[60:63]
	v_mfma_f32_16x16x32_bf16 v[56:59], v[212:215], v[188:191], v[56:59]
	v_mfma_f32_16x16x32_bf16 v[52:55], v[204:207], v[196:199], v[52:55]
	v_mfma_f32_16x16x32_bf16 v[48:51], v[212:215], v[196:199], v[48:51]
	s_add_i32 s6, s83, s3
	s_add_i32 s7, s6, 0x100
	s_mov_b32 m0, s30
	s_barrier
	ds_read_b128 v[168:171], v129 offset:16384
	ds_read_b128 v[172:175], v129 offset:17408
	ds_read_b128 v[176:179], v132 offset:16384
	ds_read_b128 v[180:183], v132 offset:17408
	ds_read_b128 v[184:187], v131 offset:16384
	ds_read_b128 v[188:191], v131 offset:17408
	ds_read_b128 v[192:195], v130 offset:16384
	ds_read_b128 v[196:199], v130 offset:17408
	buffer_load_dwordx4 v141, s[8:11], s7 offen lds
	s_mov_b32 m0, s44
	s_nop 0
	buffer_load_dwordx4 v142, s[8:11], s7 offen lds
	s_barrier
	s_waitcnt lgkmcnt(0)
	s_waitcnt lgkmcnt(7)
	v_mfma_f32_16x16x32_bf16 v[44:47], v[152:155], v[168:171], v[44:47]
	v_mfma_f32_16x16x32_bf16 v[40:43], v[160:163], v[168:171], v[40:43]
	s_waitcnt lgkmcnt(5)
	v_mfma_f32_16x16x32_bf16 v[36:39], v[152:155], v[176:179], v[36:39]
	v_mfma_f32_16x16x32_bf16 v[32:35], v[160:163], v[176:179], v[32:35]
	s_waitcnt lgkmcnt(3)
	v_mfma_f32_16x16x32_bf16 v[28:31], v[152:155], v[184:187], v[28:31]
	v_mfma_f32_16x16x32_bf16 v[24:27], v[160:163], v[184:187], v[24:27]
	s_waitcnt lgkmcnt(1)
	v_mfma_f32_16x16x32_bf16 v[20:23], v[152:155], v[192:195], v[20:23]
	v_mfma_f32_16x16x32_bf16 v[16:19], v[160:163], v[192:195], v[16:19]
	v_mfma_f32_16x16x32_bf16 v[44:47], v[156:159], v[172:175], v[44:47]
	v_mfma_f32_16x16x32_bf16 v[40:43], v[164:167], v[172:175], v[40:43]
	v_mfma_f32_16x16x32_bf16 v[36:39], v[156:159], v[180:183], v[36:39]
	v_mfma_f32_16x16x32_bf16 v[32:35], v[164:167], v[180:183], v[32:35]
	v_mfma_f32_16x16x32_bf16 v[28:31], v[156:159], v[188:191], v[28:31]
	v_mfma_f32_16x16x32_bf16 v[24:27], v[164:167], v[188:191], v[24:27]
	s_waitcnt lgkmcnt(0)
	v_mfma_f32_16x16x32_bf16 v[20:23], v[156:159], v[196:199], v[20:23]
	v_mfma_f32_16x16x32_bf16 v[16:19], v[164:167], v[196:199], v[16:19]
	s_barrier
	s_add_i32 s7, s85, s3
	s_add_i32 s19, s7, 0x100
	s_mov_b32 m0, s35
	s_nop 0
	buffer_load_dwordx4 v141, s[12:15], s19 offen lds
	s_mov_b32 m0, s45
	s_nop 0
	buffer_load_dwordx4 v142, s[12:15], s19 offen lds
	s_waitcnt vmcnt(6)
	s_barrier
; #define STAGE(P, RS, SOFF, OFF, kt) do { const int _so = (SOFF) + (kt) * (BK * 2); \
;     _Pragma("unroll") for (int _i = 0; _i < 2; ++_i) { \
;       __builtin_amdgcn_raw_ptr_buffer_load_lds(RS, (__attribute__((address_space(3))) void*)((P) + wave * 1024 + _i * 8192), 16, OFF[_i], _so, 0, 0); } } while (0)
; #define LDA(dst, b, h) _Pragma("unroll") for (int m = 0; m < 4; ++m) _Pragma("unroll") for (int k = 0; k < 2; ++k) \
;     dst[m][k] = *reinterpret_cast<const bf16x8*>(SA(b, h) + lds_byte(wr * 64 + m * 16 + fr, k * 32 + fq * 8))
; #define LDB(dst, b, h) _Pragma("unroll") for (int n = 0; n < 2; ++n) _Pragma("unroll") for (int k = 0; k < 2; ++k) \
;     dst[n][k] = *reinterpret_cast<const bf16x8*>(SB(b, h) + lds_byte(wc * 32 + n * 16 + fr, k * 32 + fq * 8))
; #define WAIT_V(n) asm volatile("s_waitcnt vmcnt(" #n ")" ::: "memory")
; #define WAIT_L(n) asm volatile("s_waitcnt lgkmcnt(" #n ")" ::: "memory")
; #define BAR __builtin_amdgcn_s_barrier()
; #define SCHED __builtin_amdgcn_sched_barrier(0)
;     ...
;       WAIT_V(6); BAR; MMA(1, 1, At, B1); BAR;
;       LDB(B0, 1, 0); SCHED; LDA(At, 1, 0); STAGE(SA(0, 1), rsA, sA1, offA, t + 2);
;       WAIT_L(8); BAR; WAIT_L(0); MMA(0, 0, At, B0); BAR; SCHED;
;       LDB(B1, 1, 1); STAGE(SB(1, 0), rsB, sB0, offB, t + 3);
;       BAR; WAIT_L(0); MMA(0, 1, At, B1); BAR;
;       LDA(At, 1, 1); STAGE(SA(1, 0), rsA, sA0, offA, t + 3);
	v_mfma_f32_16x16x32_bf16 v[12:15], v[200:203], v[168:171], v[12:15]
	v_mfma_f32_16x16x32_bf16 v[8:11], v[208:211], v[168:171], v[8:11]
	v_mfma_f32_16x16x32_bf16 v[4:7], v[200:203], v[176:179], v[4:7]
	v_mfma_f32_16x16x32_bf16 v[0:3], v[208:211], v[176:179], v[0:3]
	v_mfma_f32_16x16x32_bf16 v[64:67], v[200:203], v[184:187], v[64:67]
	v_mfma_f32_16x16x32_bf16 v[72:75], v[208:211], v[184:187], v[72:75]
	v_mfma_f32_16x16x32_bf16 v[76:79], v[200:203], v[192:195], v[76:79]
	v_mfma_f32_16x16x32_bf16 v[84:87], v[208:211], v[192:195], v[84:87]
	v_mfma_f32_16x16x32_bf16 v[12:15], v[204:207], v[172:175], v[12:15]
	v_mfma_f32_16x16x32_bf16 v[8:11], v[212:215], v[172:175], v[8:11]
	v_mfma_f32_16x16x32_bf16 v[4:7], v[204:207], v[180:183], v[4:7]
	v_mfma_f32_16x16x32_bf16 v[0:3], v[212:215], v[180:183], v[0:3]
	v_mfma_f32_16x16x32_bf16 v[64:67], v[204:207], v[188:191], v[64:67]
	v_mfma_f32_16x16x32_bf16 v[72:75], v[212:215], v[188:191], v[72:75]
	v_mfma_f32_16x16x32_bf16 v[76:79], v[204:207], v[196:199], v[76:79]
	v_mfma_f32_16x16x32_bf16 v[84:87], v[212:215], v[196:199], v[84:87]
	s_barrier
	ds_read_b128 v[152:155], v137
	ds_read_b128 v[156:159], v138
	ds_read_b128 v[160:163], v139
	ds_read_b128 v[164:167], v140
	s_addk_i32 s4, 0x100
	s_mov_b32 m0, s36
	ds_read_b128 v[168:171], v129 offset:32768
	ds_read_b128 v[172:175], v129 offset:33792
	ds_read_b128 v[176:179], v132 offset:32768
	ds_read_b128 v[180:183], v132 offset:33792
	ds_read_b128 v[184:187], v131 offset:32768
	ds_read_b128 v[188:191], v131 offset:33792
	ds_read_b128 v[192:195], v130 offset:32768
	ds_read_b128 v[196:199], v130 offset:33792
	buffer_load_dwordx4 v141, s[8:11], s4 offen lds
	s_mov_b32 m0, s48
	s_nop 0
	buffer_load_dwordx4 v142, s[8:11], s4 offen lds
	s_waitcnt lgkmcnt(8)
	s_barrier
	s_waitcnt lgkmcnt(0)
	s_waitcnt lgkmcnt(7)
	v_mfma_f32_16x16x32_bf16 v[124:127], v[152:155], v[168:171], v[124:127]
	v_mfma_f32_16x16x32_bf16 v[120:123], v[160:163], v[168:171], v[120:123]
	s_waitcnt lgkmcnt(5)
	v_mfma_f32_16x16x32_bf16 v[116:119], v[152:155], v[176:179], v[116:119]
	v_mfma_f32_16x16x32_bf16 v[112:115], v[160:163], v[176:179], v[112:115]
	s_waitcnt lgkmcnt(3)
	v_mfma_f32_16x16x32_bf16 v[108:111], v[152:155], v[184:187], v[108:111]
	v_mfma_f32_16x16x32_bf16 v[104:107], v[160:163], v[184:187], v[104:107]
	s_waitcnt lgkmcnt(1)
	v_mfma_f32_16x16x32_bf16 v[100:103], v[152:155], v[192:195], v[100:103]
	v_mfma_f32_16x16x32_bf16 v[96:99], v[160:163], v[192:195], v[96:99]
	v_mfma_f32_16x16x32_bf16 v[124:127], v[156:159], v[172:175], v[124:127]
	v_mfma_f32_16x16x32_bf16 v[120:123], v[164:167], v[172:175], v[120:123]
	v_mfma_f32_16x16x32_bf16 v[116:119], v[156:159], v[180:183], v[116:119]
	v_mfma_f32_16x16x32_bf16 v[112:115], v[164:167], v[180:183], v[112:115]
	v_mfma_f32_16x16x32_bf16 v[108:111], v[156:159], v[188:191], v[108:111]
	v_mfma_f32_16x16x32_bf16 v[104:107], v[164:167], v[188:191], v[104:107]
	s_waitcnt lgkmcnt(0)
	v_mfma_f32_16x16x32_bf16 v[100:103], v[156:159], v[196:199], v[100:103]
	v_mfma_f32_16x16x32_bf16 v[96:99], v[164:167], v[196:199], v[96:99]
	s_barrier
	s_addk_i32 s5, 0x180
	s_mov_b32 m0, s37
	ds_read_b128 v[200:203], v133
	ds_read_b128 v[204:207], v134
	ds_read_b128 v[208:211], v135
	ds_read_b128 v[212:215], v136
	buffer_load_dwordx4 v141, s[12:15], s5 offen lds
	s_mov_b32 m0, s49
	s_nop 0
	buffer_load_dwordx4 v142, s[12:15], s5 offen lds
	s_barrier
	s_waitcnt lgkmcnt(0)
	s_waitcnt lgkmcnt(3)
	v_mfma_f32_16x16x32_bf16 v[92:95], v[200:203], v[168:171], v[92:95]
	s_waitcnt lgkmcnt(1)
	v_mfma_f32_16x16x32_bf16 v[88:91], v[208:211], v[168:171], v[88:91]
	v_mfma_f32_16x16x32_bf16 v[80:83], v[200:203], v[176:179], v[80:83]
	v_mfma_f32_16x16x32_bf16 v[68:71], v[208:211], v[176:179], v[68:71]
	v_mfma_f32_16x16x32_bf16 v[60:63], v[200:203], v[184:187], v[60:63]
	v_mfma_f32_16x16x32_bf16 v[56:59], v[208:211], v[184:187], v[56:59]
	v_mfma_f32_16x16x32_bf16 v[52:55], v[200:203], v[192:195], v[52:55]
	v_mfma_f32_16x16x32_bf16 v[48:51], v[208:211], v[192:195], v[48:51]
	v_mfma_f32_16x16x32_bf16 v[92:95], v[204:207], v[172:175], v[92:95]
	s_waitcnt lgkmcnt(0)
	v_mfma_f32_16x16x32_bf16 v[88:91], v[212:215], v[172:175], v[88:91]
	v_mfma_f32_16x16x32_bf16 v[80:83], v[204:207], v[180:183], v[80:83]
	v_mfma_f32_16x16x32_bf16 v[68:71], v[212:215], v[180:183], v[68:71]
	v_mfma_f32_16x16x32_bf16 v[60:63], v[204:207], v[188:191], v[60:63]
	v_mfma_f32_16x16x32_bf16 v[56:59], v[212:215], v[188:191], v[56:59]
	v_mfma_f32_16x16x32_bf16 v[52:55], v[204:207], v[196:199], v[52:55]
	v_mfma_f32_16x16x32_bf16 v[48:51], v[212:215], v[196:199], v[48:51]
	s_addk_i32 s6, 0x180
	s_mov_b32 m0, s38
	s_barrier
	ds_read_b128 v[168:171], v129 offset:49152
	ds_read_b128 v[172:175], v129 offset:50176
	ds_read_b128 v[176:179], v132 offset:49152
	ds_read_b128 v[180:183], v132 offset:50176
	ds_read_b128 v[184:187], v131 offset:49152
	ds_read_b128 v[188:191], v131 offset:50176
	ds_read_b128 v[192:195], v130 offset:49152
	ds_read_b128 v[196:199], v130 offset:50176
	buffer_load_dwordx4 v141, s[8:11], s6 offen lds
	s_mov_b32 m0, s54
	s_nop 0
	buffer_load_dwordx4 v142, s[8:11], s6 offen lds
	s_barrier
; #define STAGE(P, RS, SOFF, OFF, kt) do { const int _so = (SOFF) + (kt) * (BK * 2); \
;     _Pragma("unroll") for (int _i = 0; _i < 2; ++_i) { \
;       __builtin_amdgcn_raw_ptr_buffer_load_lds(RS, (__attribute__((address_space(3))) void*)((P) + wave * 1024 + _i * 8192), 16, OFF[_i], _so, 0, 0); } } while (0)
; #define LDA(dst, b, h) _Pragma("unroll") for (int m = 0; m < 4; ++m) _Pragma("unroll") for (int k = 0; k < 2; ++k) \
;     dst[m][k] = *reinterpret_cast<const bf16x8*>(SA(b, h) + lds_byte(wr * 64 + m * 16 + fr, k * 32 + fq * 8))
; #define LDB(dst, b, h) _Pragma("unroll") for (int n = 0; n < 2; ++n) _Pragma("unroll") for (int k = 0; k < 2; ++k) \
;     dst[n][k] = *reinterpret_cast<const bf16x8*>(SB(b, h) + lds_byte(wc * 32 + n * 16 + fr, k * 32 + fq * 8))
; #define WAIT_V(n) asm volatile("s_waitcnt vmcnt(" #n ")" ::: "memory")
; #define WAIT_L(n) asm volatile("s_waitcnt lgkmcnt(" #n ")" ::: "memory")
; #define BAR __builtin_amdgcn_s_barrier()
; #define SCHED __builtin_amdgcn_sched_barrier(0)
;     ...
;       BAR; WAIT_L(0); MMA(1, 0, At, B0); BAR; SCHED;
;       STAGE(SB(1, 1), rsB, sB1, offB, t + 3);
;       WAIT_V(6); BAR; MMA(1, 1, At, B1); BAR;
;     }
;     { LDB(B0, 0, 0); LDA(At, 0, 0); STAGE(SA(1, 1), rsA, sA1, offA, nt - 1);
;       BAR; WAIT_L(0); MMA(0, 0, At, B0); BAR;
;       LDB(B1, 0, 1); BAR; WAIT_L(0); MMA(0, 1, At, B1); BAR;
	s_waitcnt lgkmcnt(0)
	s_waitcnt lgkmcnt(7)
	v_mfma_f32_16x16x32_bf16 v[44:47], v[152:155], v[168:171], v[44:47]
	v_mfma_f32_16x16x32_bf16 v[40:43], v[160:163], v[168:171], v[40:43]
	s_waitcnt lgkmcnt(5)
	v_mfma_f32_16x16x32_bf16 v[36:39], v[152:155], v[176:179], v[36:39]
	v_mfma_f32_16x16x32_bf16 v[32:35], v[160:163], v[176:179], v[32:35]
	s_waitcnt lgkmcnt(3)
	v_mfma_f32_16x16x32_bf16 v[28:31], v[152:155], v[184:187], v[28:31]
	v_mfma_f32_16x16x32_bf16 v[24:27], v[160:163], v[184:187], v[24:27]
	s_waitcnt lgkmcnt(1)
	v_mfma_f32_16x16x32_bf16 v[20:23], v[152:155], v[192:195], v[20:23]
	v_mfma_f32_16x16x32_bf16 v[16:19], v[160:163], v[192:195], v[16:19]
	v_mfma_f32_16x16x32_bf16 v[44:47], v[156:159], v[172:175], v[44:47]
	v_mfma_f32_16x16x32_bf16 v[40:43], v[164:167], v[172:175], v[40:43]
	v_mfma_f32_16x16x32_bf16 v[36:39], v[156:159], v[180:183], v[36:39]
	v_mfma_f32_16x16x32_bf16 v[32:35], v[164:167], v[180:183], v[32:35]
	v_mfma_f32_16x16x32_bf16 v[28:31], v[156:159], v[188:191], v[28:31]
	v_mfma_f32_16x16x32_bf16 v[24:27], v[164:167], v[188:191], v[24:27]
	s_waitcnt lgkmcnt(0)
	v_mfma_f32_16x16x32_bf16 v[20:23], v[156:159], v[196:199], v[20:23]
	v_mfma_f32_16x16x32_bf16 v[16:19], v[164:167], v[196:199], v[16:19]
	s_barrier
	s_addk_i32 s7, 0x180
	s_mov_b32 m0, s39
	s_nop 0
	buffer_load_dwordx4 v141, s[12:15], s7 offen lds
	s_mov_b32 m0, s55
	s_nop 0
	buffer_load_dwordx4 v142, s[12:15], s7 offen lds
	s_waitcnt vmcnt(6)
	s_barrier
	v_mfma_f32_16x16x32_bf16 v[12:15], v[200:203], v[168:171], v[12:15]
	v_mfma_f32_16x16x32_bf16 v[8:11], v[208:211], v[168:171], v[8:11]
	v_mfma_f32_16x16x32_bf16 v[4:7], v[200:203], v[176:179], v[4:7]
	v_mfma_f32_16x16x32_bf16 v[0:3], v[208:211], v[176:179], v[0:3]
	v_mfma_f32_16x16x32_bf16 v[64:67], v[200:203], v[184:187], v[64:67]
	v_mfma_f32_16x16x32_bf16 v[72:75], v[208:211], v[184:187], v[72:75]
	v_mfma_f32_16x16x32_bf16 v[76:79], v[200:203], v[192:195], v[76:79]
	v_mfma_f32_16x16x32_bf16 v[84:87], v[208:211], v[192:195], v[84:87]
	v_mfma_f32_16x16x32_bf16 v[12:15], v[204:207], v[172:175], v[12:15]
	v_mfma_f32_16x16x32_bf16 v[8:11], v[212:215], v[172:175], v[8:11]
	v_mfma_f32_16x16x32_bf16 v[4:7], v[204:207], v[180:183], v[4:7]
	v_mfma_f32_16x16x32_bf16 v[0:3], v[212:215], v[180:183], v[0:3]
	v_mfma_f32_16x16x32_bf16 v[64:67], v[204:207], v[188:191], v[64:67]
	v_mfma_f32_16x16x32_bf16 v[72:75], v[212:215], v[188:191], v[72:75]
	v_mfma_f32_16x16x32_bf16 v[76:79], v[204:207], v[196:199], v[76:79]
	v_mfma_f32_16x16x32_bf16 v[84:87], v[212:215], v[196:199], v[84:87]
	s_add_i32 s1, s1, 2
	s_addk_i32 s3, 0x100
	s_cmp_gt_u32 s1, 59
	s_barrier
	s_cbranch_scc0 .LBB0_148
	s_add_i32 s1, s82, 0x1f80
	s_mov_b32 m0, s31
	ds_read_b128 v[152:155], v147
	ds_read_b128 v[156:159], v148
	ds_read_b128 v[160:163], v149
	ds_read_b128 v[148:151], v150
	ds_read_b128 v[164:167], v129
	ds_read_b128 v[168:171], v129 offset:1024
	ds_read_b128 v[172:175], v132
	ds_read_b128 v[176:179], v132 offset:1024
	ds_read_b128 v[180:183], v131
	ds_read_b128 v[184:187], v131 offset:1024
	ds_read_b128 v[188:191], v130
	ds_read_b128 v[192:195], v130 offset:1024
	buffer_load_dwordx4 v141, s[8:11], s1 offen lds
	s_mov_b32 m0, s58
	s_nop 0
	buffer_load_dwordx4 v142, s[8:11], s1 offen lds
	s_barrier
	s_waitcnt lgkmcnt(0)
	s_waitcnt lgkmcnt(7)
	v_mfma_f32_16x16x32_bf16 v[124:127], v[152:155], v[164:167], v[124:127]
	v_mfma_f32_16x16x32_bf16 v[120:123], v[160:163], v[164:167], v[120:123]
	s_waitcnt lgkmcnt(5)
	v_mfma_f32_16x16x32_bf16 v[116:119], v[152:155], v[172:175], v[116:119]
	v_mfma_f32_16x16x32_bf16 v[112:115], v[160:163], v[172:175], v[112:115]
	s_waitcnt lgkmcnt(3)
	v_mfma_f32_16x16x32_bf16 v[108:111], v[152:155], v[180:183], v[108:111]
	v_mfma_f32_16x16x32_bf16 v[104:107], v[160:163], v[180:183], v[104:107]
	s_waitcnt lgkmcnt(1)
	v_mfma_f32_16x16x32_bf16 v[100:103], v[152:155], v[188:191], v[100:103]
	v_mfma_f32_16x16x32_bf16 v[96:99], v[160:163], v[188:191], v[96:99]
	v_mfma_f32_16x16x32_bf16 v[124:127], v[156:159], v[168:171], v[124:127]
	v_mfma_f32_16x16x32_bf16 v[120:123], v[148:151], v[168:171], v[120:123]
	v_mfma_f32_16x16x32_bf16 v[116:119], v[156:159], v[176:179], v[116:119]
	v_mfma_f32_16x16x32_bf16 v[112:115], v[148:151], v[176:179], v[112:115]
	v_mfma_f32_16x16x32_bf16 v[108:111], v[156:159], v[184:187], v[108:111]
	v_mfma_f32_16x16x32_bf16 v[104:107], v[148:151], v[184:187], v[104:107]
	s_waitcnt lgkmcnt(0)
	v_mfma_f32_16x16x32_bf16 v[100:103], v[156:159], v[192:195], v[100:103]
	v_mfma_f32_16x16x32_bf16 v[96:99], v[148:151], v[192:195], v[96:99]
	s_barrier
	ds_read_b128 v[196:199], v143
	ds_read_b128 v[200:203], v144
	ds_read_b128 v[142:145], v145
	ds_read_b128 v[204:207], v146
	s_barrier
	s_waitcnt lgkmcnt(0)
	s_waitcnt lgkmcnt(1)
	v_mfma_f32_16x16x32_bf16 v[88:91], v[142:145], v[164:167], v[88:91]
	v_mfma_f32_16x16x32_bf16 v[80:83], v[196:199], v[172:175], v[80:83]
	v_mfma_f32_16x16x32_bf16 v[60:63], v[196:199], v[180:183], v[60:63]
	v_mfma_f32_16x16x32_bf16 v[56:59], v[142:145], v[180:183], v[56:59]
	v_mfma_f32_16x16x32_bf16 v[52:55], v[196:199], v[188:191], v[52:55]
	v_mfma_f32_16x16x32_bf16 v[48:51], v[142:145], v[188:191], v[48:51]
	v_mfma_f32_16x16x32_bf16 v[92:95], v[196:199], v[164:167], v[92:95]
	v_mfma_f32_16x16x32_bf16 v[68:71], v[142:145], v[172:175], v[68:71]
	s_waitcnt lgkmcnt(0)
	v_mfma_f32_16x16x32_bf16 v[88:91], v[204:207], v[168:171], v[88:91]
	v_mfma_f32_16x16x32_bf16 v[80:83], v[200:203], v[176:179], v[80:83]
	v_mfma_f32_16x16x32_bf16 v[60:63], v[200:203], v[184:187], v[60:63]
	v_mfma_f32_16x16x32_bf16 v[56:59], v[204:207], v[184:187], v[56:59]
	v_mfma_f32_16x16x32_bf16 v[52:55], v[200:203], v[192:195], v[52:55]
	v_mfma_f32_16x16x32_bf16 v[48:51], v[204:207], v[192:195], v[48:51]
	v_mfma_f32_16x16x32_bf16 v[164:167], v[200:203], v[168:171], v[92:95]
	v_mfma_f32_16x16x32_bf16 v[168:171], v[204:207], v[176:179], v[68:71]
	s_barrier
; #define LDA(dst, b, h) _Pragma("unroll") for (int m = 0; m < 4; ++m) _Pragma("unroll") for (int k = 0; k < 2; ++k) \
;     dst[m][k] = *reinterpret_cast<const bf16x8*>(SA(b, h) + lds_byte(wr * 64 + m * 16 + fr, k * 32 + fq * 8))
; #define LDB(dst, b, h) _Pragma("unroll") for (int n = 0; n < 2; ++n) _Pragma("unroll") for (int k = 0; k < 2; ++k) \
;     dst[n][k] = *reinterpret_cast<const bf16x8*>(SB(b, h) + lds_byte(wc * 32 + n * 16 + fr, k * 32 + fq * 8))
; #define WAIT_V(n) asm volatile("s_waitcnt vmcnt(" #n ")" ::: "memory")
; #define WAIT_L(n) asm volatile("s_waitcnt lgkmcnt(" #n ")" ::: "memory")
; #define BAR __builtin_amdgcn_s_barrier()
;     ...
;       LDA(At, 0, 1); WAIT_V(4); BAR; WAIT_L(0); MMA(1, 0, At, B0); MMA(1, 1, At, B1); BAR; }
;     { LDB(B0, 1, 0); LDA(At, 1, 0); WAIT_V(2); BAR; WAIT_L(0); MMA(0, 0, At, B0); BAR;
	s_nop 0
	ds_read_b128 v[68:71], v129 offset:16384
	ds_read_b128 v[92:95], v129 offset:17408
	ds_read_b128 v[172:175], v132 offset:16384
	ds_read_b128 v[176:179], v132 offset:17408
	ds_read_b128 v[180:183], v131 offset:16384
	ds_read_b128 v[184:187], v131 offset:17408
	ds_read_b128 v[188:191], v130 offset:16384
	ds_read_b128 v[192:195], v130 offset:17408
	s_waitcnt vmcnt(4)
	s_barrier
	s_waitcnt lgkmcnt(0)
	s_waitcnt lgkmcnt(7)
	v_mfma_f32_16x16x32_bf16 v[44:47], v[152:155], v[68:71], v[44:47]
	v_mfma_f32_16x16x32_bf16 v[40:43], v[160:163], v[68:71], v[40:43]
	s_waitcnt lgkmcnt(5)
	v_mfma_f32_16x16x32_bf16 v[36:39], v[152:155], v[172:175], v[36:39]
	v_mfma_f32_16x16x32_bf16 v[32:35], v[160:163], v[172:175], v[32:35]
	s_waitcnt lgkmcnt(3)
	v_mfma_f32_16x16x32_bf16 v[28:31], v[152:155], v[180:183], v[28:31]
	v_mfma_f32_16x16x32_bf16 v[24:27], v[160:163], v[180:183], v[24:27]
	s_waitcnt lgkmcnt(1)
	v_mfma_f32_16x16x32_bf16 v[20:23], v[152:155], v[188:191], v[20:23]
	v_mfma_f32_16x16x32_bf16 v[16:19], v[160:163], v[188:191], v[16:19]
	v_mfma_f32_16x16x32_bf16 v[44:47], v[156:159], v[92:95], v[44:47]
	v_mfma_f32_16x16x32_bf16 v[40:43], v[148:151], v[92:95], v[40:43]
	v_mfma_f32_16x16x32_bf16 v[36:39], v[156:159], v[176:179], v[36:39]
	v_mfma_f32_16x16x32_bf16 v[32:35], v[148:151], v[176:179], v[32:35]
	v_mfma_f32_16x16x32_bf16 v[28:31], v[156:159], v[184:187], v[28:31]
	v_mfma_f32_16x16x32_bf16 v[24:27], v[148:151], v[184:187], v[24:27]
	s_waitcnt lgkmcnt(0)
	v_mfma_f32_16x16x32_bf16 v[20:23], v[156:159], v[192:195], v[20:23]
	v_mfma_f32_16x16x32_bf16 v[16:19], v[148:151], v[192:195], v[16:19]
	v_mfma_f32_16x16x32_bf16 v[8:11], v[142:145], v[68:71], v[8:11]
	v_mfma_f32_16x16x32_bf16 v[0:3], v[142:145], v[172:175], v[0:3]
	v_mfma_f32_16x16x32_bf16 v[12:15], v[196:199], v[68:71], v[12:15]
	v_mfma_f32_16x16x32_bf16 v[4:7], v[196:199], v[172:175], v[4:7]
	v_mfma_f32_16x16x32_bf16 v[64:67], v[196:199], v[180:183], v[64:67]
	v_mfma_f32_16x16x32_bf16 v[68:71], v[142:145], v[180:183], v[72:75]
	v_mfma_f32_16x16x32_bf16 v[72:75], v[196:199], v[188:191], v[76:79]
	v_mfma_f32_16x16x32_bf16 v[76:79], v[142:145], v[188:191], v[84:87]
	v_mfma_f32_16x16x32_bf16 v[8:11], v[204:207], v[92:95], v[8:11]
	v_mfma_f32_16x16x32_bf16 v[0:3], v[204:207], v[176:179], v[0:3]
	v_mfma_f32_16x16x32_bf16 v[160:163], v[200:203], v[92:95], v[12:15]
	v_mfma_f32_16x16x32_bf16 v[172:175], v[200:203], v[176:179], v[4:7]
	v_mfma_f32_16x16x32_bf16 v[176:179], v[200:203], v[184:187], v[64:67]
	v_mfma_f32_16x16x32_bf16 v[180:183], v[204:207], v[184:187], v[68:71]
	v_mfma_f32_16x16x32_bf16 v[184:187], v[200:203], v[192:195], v[72:75]
	v_mfma_f32_16x16x32_bf16 v[188:191], v[204:207], v[192:195], v[76:79]
	s_barrier
	ds_read_b128 v[4:7], v137
	ds_read_b128 v[12:15], v138
	ds_read_b128 v[192:195], v139
	ds_read_b128 v[138:141], v140
	ds_read_b128 v[72:75], v129 offset:32768
	ds_read_b128 v[142:145], v129 offset:33792
	ds_read_b128 v[76:79], v132 offset:32768
	ds_read_b128 v[196:199], v132 offset:33792
	ds_read_b128 v[152:155], v131 offset:32768
	ds_read_b128 v[200:203], v131 offset:33792
	ds_read_b128 v[204:207], v130 offset:32768
	ds_read_b128 v[208:211], v130 offset:33792
	s_waitcnt vmcnt(2)
	s_barrier
	s_waitcnt lgkmcnt(0)
	s_waitcnt lgkmcnt(7)
	v_mfma_f32_16x16x32_bf16 v[64:67], v[4:7], v[72:75], v[124:127]
	v_mfma_f32_16x16x32_bf16 v[84:87], v[192:195], v[72:75], v[120:123]
	s_waitcnt lgkmcnt(5)
	v_mfma_f32_16x16x32_bf16 v[92:95], v[4:7], v[76:79], v[116:119]
	v_mfma_f32_16x16x32_bf16 v[112:115], v[192:195], v[76:79], v[112:115]
	s_waitcnt lgkmcnt(3)
	v_mfma_f32_16x16x32_bf16 v[108:111], v[4:7], v[152:155], v[108:111]
	v_mfma_f32_16x16x32_bf16 v[104:107], v[192:195], v[152:155], v[104:107]
	s_waitcnt lgkmcnt(1)
	v_mfma_f32_16x16x32_bf16 v[100:103], v[4:7], v[204:207], v[100:103]
	v_mfma_f32_16x16x32_bf16 v[96:99], v[192:195], v[204:207], v[96:99]
	v_mfma_f32_16x16x32_bf16 v[68:71], v[12:15], v[142:145], v[64:67]
	v_mfma_f32_16x16x32_bf16 v[64:67], v[138:141], v[142:145], v[84:87]
	v_mfma_f32_16x16x32_bf16 v[156:159], v[12:15], v[196:199], v[92:95]
	v_mfma_f32_16x16x32_bf16 v[148:151], v[138:141], v[196:199], v[112:115]
	v_mfma_f32_16x16x32_bf16 v[124:127], v[12:15], v[200:203], v[108:111]
	v_mfma_f32_16x16x32_bf16 v[116:119], v[138:141], v[200:203], v[104:107]
	s_waitcnt lgkmcnt(0)
	v_mfma_f32_16x16x32_bf16 v[92:95], v[12:15], v[208:211], v[100:103]
	v_mfma_f32_16x16x32_bf16 v[84:87], v[138:141], v[208:211], v[96:99]
	s_barrier
; #define LDA(dst, b, h) _Pragma("unroll") for (int m = 0; m < 4; ++m) _Pragma("unroll") for (int k = 0; k < 2; ++k) \
;     dst[m][k] = *reinterpret_cast<const bf16x8*>(SA(b, h) + lds_byte(wr * 64 + m * 16 + fr, k * 32 + fq * 8))
; #define LDB(dst, b, h) _Pragma("unroll") for (int n = 0; n < 2; ++n) _Pragma("unroll") for (int k = 0; k < 2; ++k) \
;     dst[n][k] = *reinterpret_cast<const bf16x8*>(SB(b, h) + lds_byte(wc * 32 + n * 16 + fr, k * 32 + fq * 8))
; #define WAIT_V(n) asm volatile("s_waitcnt vmcnt(" #n ")" ::: "memory")
; #define WAIT_L(n) asm volatile("s_waitcnt lgkmcnt(" #n ")" ::: "memory")
; #define BAR __builtin_amdgcn_s_barrier()
;     ...
;       LDB(B1, 1, 1); WAIT_V(0); BAR; WAIT_L(0); MMA(0, 1, At, B1); BAR;
;       LDA(At, 1, 1); BAR; WAIT_L(0); MMA(1, 0, At, B0); MMA(1, 1, At, B1); BAR; }
;     if (wr == 0) BAR;
	s_nop 0
	ds_read_b128 v[96:99], v133
	ds_read_b128 v[100:103], v134
	ds_read_b128 v[104:107], v135
	ds_read_b128 v[108:111], v136
	s_waitcnt vmcnt(0)
	s_barrier
	s_waitcnt lgkmcnt(0)
	s_waitcnt lgkmcnt(3)
	v_mfma_f32_16x16x32_bf16 v[112:115], v[96:99], v[72:75], v[164:167]
	s_waitcnt lgkmcnt(1)
	v_mfma_f32_16x16x32_bf16 v[72:75], v[104:107], v[72:75], v[88:91]
	v_mfma_f32_16x16x32_bf16 v[80:83], v[96:99], v[76:79], v[80:83]
	v_mfma_f32_16x16x32_bf16 v[88:91], v[104:107], v[76:79], v[168:171]
	v_mfma_f32_16x16x32_bf16 v[60:63], v[96:99], v[152:155], v[60:63]
	v_mfma_f32_16x16x32_bf16 v[56:59], v[104:107], v[152:155], v[56:59]
	v_mfma_f32_16x16x32_bf16 v[52:55], v[96:99], v[204:207], v[52:55]
	v_mfma_f32_16x16x32_bf16 v[48:51], v[104:107], v[204:207], v[48:51]
	v_mfma_f32_16x16x32_bf16 v[76:79], v[100:103], v[142:145], v[112:115]
	s_waitcnt lgkmcnt(0)
	v_mfma_f32_16x16x32_bf16 v[72:75], v[108:111], v[142:145], v[72:75]
	v_mfma_f32_16x16x32_bf16 v[152:155], v[100:103], v[196:199], v[80:83]
	v_mfma_f32_16x16x32_bf16 v[144:147], v[108:111], v[196:199], v[88:91]
	v_mfma_f32_16x16x32_bf16 v[120:123], v[100:103], v[200:203], v[60:63]
	v_mfma_f32_16x16x32_bf16 v[112:115], v[108:111], v[200:203], v[56:59]
	v_mfma_f32_16x16x32_bf16 v[88:91], v[100:103], v[208:211], v[52:55]
	v_mfma_f32_16x16x32_bf16 v[80:83], v[108:111], v[208:211], v[48:51]
	s_barrier
	s_nop 0
	ds_read_b128 v[48:51], v129 offset:49152
	ds_read_b128 v[134:137], v129 offset:50176
	ds_read_b128 v[56:59], v132 offset:49152
	ds_read_b128 v[164:167], v132 offset:50176
	ds_read_b128 v[168:171], v131 offset:49152
	ds_read_b128 v[196:199], v131 offset:50176
	ds_read_b128 v[200:203], v130 offset:49152
	ds_read_b128 v[130:133], v130 offset:50176
	s_barrier
	s_waitcnt lgkmcnt(0)
	s_waitcnt lgkmcnt(7)
	v_mfma_f32_16x16x32_bf16 v[44:47], v[4:7], v[48:51], v[44:47]
	v_mfma_f32_16x16x32_bf16 v[40:43], v[192:195], v[48:51], v[40:43]
	s_waitcnt lgkmcnt(5)
	v_mfma_f32_16x16x32_bf16 v[36:39], v[4:7], v[56:59], v[36:39]
	v_mfma_f32_16x16x32_bf16 v[32:35], v[192:195], v[56:59], v[32:35]
	s_waitcnt lgkmcnt(3)
	v_mfma_f32_16x16x32_bf16 v[28:31], v[4:7], v[168:171], v[28:31]
	v_mfma_f32_16x16x32_bf16 v[24:27], v[192:195], v[168:171], v[24:27]
	s_waitcnt lgkmcnt(1)
	v_mfma_f32_16x16x32_bf16 v[4:7], v[4:7], v[200:203], v[20:23]
	v_mfma_f32_16x16x32_bf16 v[16:19], v[192:195], v[200:203], v[16:19]
	v_mfma_f32_16x16x32_bf16 v[60:63], v[12:15], v[134:137], v[44:47]
	v_mfma_f32_16x16x32_bf16 v[52:55], v[138:141], v[134:137], v[40:43]
	v_mfma_f32_16x16x32_bf16 v[44:47], v[12:15], v[164:167], v[36:39]
	v_mfma_f32_16x16x32_bf16 v[36:39], v[138:141], v[164:167], v[32:35]
	v_mfma_f32_16x16x32_bf16 v[28:31], v[12:15], v[196:199], v[28:31]
	v_mfma_f32_16x16x32_bf16 v[20:23], v[138:141], v[196:199], v[24:27]
	s_waitcnt lgkmcnt(0)
	v_mfma_f32_16x16x32_bf16 v[12:15], v[12:15], v[130:133], v[4:7]
	v_mfma_f32_16x16x32_bf16 v[4:7], v[138:141], v[130:133], v[16:19]
	v_mfma_f32_16x16x32_bf16 v[16:19], v[96:99], v[48:51], v[160:163]
	v_mfma_f32_16x16x32_bf16 v[8:11], v[104:107], v[48:51], v[8:11]
	v_mfma_f32_16x16x32_bf16 v[24:27], v[96:99], v[56:59], v[172:175]
	v_mfma_f32_16x16x32_bf16 v[0:3], v[104:107], v[56:59], v[0:3]
	v_mfma_f32_16x16x32_bf16 v[138:141], v[96:99], v[168:171], v[176:179]
	v_mfma_f32_16x16x32_bf16 v[160:163], v[104:107], v[168:171], v[180:183]
	v_mfma_f32_16x16x32_bf16 v[96:99], v[96:99], v[200:203], v[184:187]
	v_mfma_f32_16x16x32_bf16 v[104:107], v[104:107], v[200:203], v[188:191]
	v_mfma_f32_16x16x32_bf16 v[56:59], v[100:103], v[134:137], v[16:19]
	v_mfma_f32_16x16x32_bf16 v[48:51], v[108:111], v[134:137], v[8:11]
	v_mfma_f32_16x16x32_bf16 v[40:43], v[100:103], v[164:167], v[24:27]
	v_mfma_f32_16x16x32_bf16 v[32:35], v[108:111], v[164:167], v[0:3]
	v_mfma_f32_16x16x32_bf16 v[24:27], v[100:103], v[196:199], v[138:141]
	v_mfma_f32_16x16x32_bf16 v[16:19], v[108:111], v[196:199], v[160:163]
	v_mfma_f32_16x16x32_bf16 v[8:11], v[100:103], v[130:133], v[96:99]
	v_mfma_f32_16x16x32_bf16 v[0:3], v[108:111], v[130:133], v[104:107]
	v_cmp_gt_u32_e32 vcc, s60, v128
	s_barrier
	s_and_saveexec_b64 s[4:5], vcc
	s_cbranch_execz .LBB0_151
	s_barrier

; #define STAGE(P, RS, SOFF, OFF, kt) do { const int _so = (SOFF) + (kt) * (BK * 2); \
;     _Pragma("unroll") for (int _i = 0; _i < 2; ++_i) { \
;       __builtin_amdgcn_raw_ptr_buffer_load_lds(RS, (__attribute__((address_space(3))) void*)((P) + wave * 1024 + _i * 8192), 16, OFF[_i], _so, 0, 0); } } while (0)
; #define LDA(dst, b, h) _Pragma("unroll") for (int m = 0; m < 4; ++m) _Pragma("unroll") for (int k = 0; k < 2; ++k) \
;     dst[m][k] = *reinterpret_cast<const bf16x8*>(SA(b, h) + lds_byte(wr * 64 + m * 16 + fr, k * 32 + fq * 8))
; #define LDB(dst, b, h) _Pragma("unroll") for (int n = 0; n < 2; ++n) _Pragma("unroll") for (int k = 0; k < 2; ++k) \
;     dst[n][k] = *reinterpret_cast<const bf16x8*>(SB(b, h) + lds_byte(wc * 32 + n * 16 + fr, k * 32 + fq * 8))
; #define WAIT_V(n) asm volatile("s_waitcnt vmcnt(" #n ")" ::: "memory")
; #define WAIT_L(n) asm volatile("s_waitcnt lgkmcnt(" #n ")" ::: "memory")
; #define BAR __builtin_amdgcn_s_barrier()
; #define SCHED __builtin_amdgcn_sched_barrier(0)
;     ...
;       LDB(B0, 0, 0); SCHED; LDA(At, 0, 0); STAGE(SA(1, 1), rsA, sA1, offA, t + 1);
;       WAIT_L(8); BAR; WAIT_L(0); MMA(0, 0, At, B0); BAR; SCHED;
;       LDB(B1, 0, 1); STAGE(SB(0, 0), rsB, sB0, offB, t + 2);
;       BAR; WAIT_L(0); MMA(0, 1, At, B1); BAR;
;       LDA(At, 0, 1); STAGE(SA(0, 0), rsA, sA0, offA, t + 2);
;       BAR; WAIT_L(0); MMA(1, 0, At, B0); BAR; SCHED;
;       STAGE(SB(0, 1), rsB, sB1, offB, t + 2);
;       WAIT_V(6); BAR; MMA(1, 1, At, B1); BAR;
.LBB0_210:
	ds_read_b128 v[154:157], v149
	ds_read_b128 v[158:161], v150
	ds_read_b128 v[162:165], v151
	ds_read_b128 v[166:169], v152
	s_add_i32 s44, s38, s17
	s_add_i32 s10, s44, 0x80
	s_mov_b32 m0, s30
	ds_read_b128 v[170:173], v131
	ds_read_b128 v[174:177], v131 offset:1024
	ds_read_b128 v[178:181], v134
	ds_read_b128 v[182:185], v134 offset:1024
	ds_read_b128 v[186:189], v133
	ds_read_b128 v[190:193], v133 offset:1024
	ds_read_b128 v[194:197], v132
	ds_read_b128 v[198:201], v132 offset:1024
	buffer_load_dwordx4 v143, s[4:7], s10 offen lds
	s_mov_b32 m0, s31
	s_nop 0
	buffer_load_dwordx4 v144, s[4:7], s10 offen lds
	s_waitcnt lgkmcnt(8)
	s_barrier
	s_waitcnt lgkmcnt(0)
	s_waitcnt lgkmcnt(7)
	v_mfma_f32_16x16x32_bf16 v[124:127], v[154:157], v[170:173], v[124:127]
	v_mfma_f32_16x16x32_bf16 v[120:123], v[162:165], v[170:173], v[120:123]
	s_waitcnt lgkmcnt(5)
	v_mfma_f32_16x16x32_bf16 v[116:119], v[154:157], v[178:181], v[116:119]
	v_mfma_f32_16x16x32_bf16 v[112:115], v[162:165], v[178:181], v[112:115]
	s_waitcnt lgkmcnt(3)
	v_mfma_f32_16x16x32_bf16 v[108:111], v[154:157], v[186:189], v[108:111]
	v_mfma_f32_16x16x32_bf16 v[104:107], v[162:165], v[186:189], v[104:107]
	s_waitcnt lgkmcnt(1)
	v_mfma_f32_16x16x32_bf16 v[100:103], v[154:157], v[194:197], v[100:103]
	v_mfma_f32_16x16x32_bf16 v[96:99], v[162:165], v[194:197], v[96:99]
	v_mfma_f32_16x16x32_bf16 v[124:127], v[158:161], v[174:177], v[124:127]
	v_mfma_f32_16x16x32_bf16 v[120:123], v[166:169], v[174:177], v[120:123]
	v_mfma_f32_16x16x32_bf16 v[116:119], v[158:161], v[182:185], v[116:119]
	v_mfma_f32_16x16x32_bf16 v[112:115], v[166:169], v[182:185], v[112:115]
	v_mfma_f32_16x16x32_bf16 v[108:111], v[158:161], v[190:193], v[108:111]
	v_mfma_f32_16x16x32_bf16 v[104:107], v[166:169], v[190:193], v[104:107]
	s_waitcnt lgkmcnt(0)
	v_mfma_f32_16x16x32_bf16 v[100:103], v[158:161], v[198:201], v[100:103]
	v_mfma_f32_16x16x32_bf16 v[96:99], v[166:169], v[198:201], v[96:99]
	s_barrier
	s_add_i32 s45, s40, s17
	s_add_i32 s46, s45, 0x100
	s_mov_b32 s10, s6
	s_mov_b32 s11, s7
	s_mov_b32 m0, s1
	ds_read_b128 v[202:205], v145
	ds_read_b128 v[206:209], v146
	ds_read_b128 v[210:213], v147
	ds_read_b128 v[214:217], v148
	buffer_load_dwordx4 v143, s[8:11], s46 offen lds
	s_mov_b32 m0, s3
	s_nop 0
	buffer_load_dwordx4 v144, s[8:11], s46 offen lds
	s_barrier
	s_waitcnt lgkmcnt(0)
	s_waitcnt lgkmcnt(3)
	v_mfma_f32_16x16x32_bf16 v[92:95], v[202:205], v[170:173], v[92:95]
	s_waitcnt lgkmcnt(1)
	v_mfma_f32_16x16x32_bf16 v[88:91], v[210:213], v[170:173], v[88:91]
	v_mfma_f32_16x16x32_bf16 v[84:87], v[202:205], v[178:181], v[84:87]
	v_mfma_f32_16x16x32_bf16 v[80:83], v[210:213], v[178:181], v[80:83]
	v_mfma_f32_16x16x32_bf16 v[76:79], v[202:205], v[186:189], v[76:79]
	v_mfma_f32_16x16x32_bf16 v[72:75], v[210:213], v[186:189], v[72:75]
	v_mfma_f32_16x16x32_bf16 v[68:71], v[202:205], v[194:197], v[68:71]
	v_mfma_f32_16x16x32_bf16 v[64:67], v[210:213], v[194:197], v[64:67]
	v_mfma_f32_16x16x32_bf16 v[92:95], v[206:209], v[174:177], v[92:95]
	s_waitcnt lgkmcnt(0)
	v_mfma_f32_16x16x32_bf16 v[88:91], v[214:217], v[174:177], v[88:91]
	v_mfma_f32_16x16x32_bf16 v[84:87], v[206:209], v[182:185], v[84:87]
	v_mfma_f32_16x16x32_bf16 v[80:83], v[214:217], v[182:185], v[80:83]
	v_mfma_f32_16x16x32_bf16 v[76:79], v[206:209], v[190:193], v[76:79]
	v_mfma_f32_16x16x32_bf16 v[72:75], v[214:217], v[190:193], v[72:75]
	v_mfma_f32_16x16x32_bf16 v[68:71], v[206:209], v[198:201], v[68:71]
	v_mfma_f32_16x16x32_bf16 v[64:67], v[214:217], v[198:201], v[64:67]
	s_add_i32 s46, s39, s17
	s_add_i32 s47, s46, 0x100
	s_mov_b32 m0, s0
	s_barrier
	ds_read_b128 v[170:173], v131 offset:16384
	ds_read_b128 v[174:177], v131 offset:17408
	ds_read_b128 v[178:181], v134 offset:16384
	ds_read_b128 v[182:185], v134 offset:17408
	ds_read_b128 v[186:189], v133 offset:16384
	ds_read_b128 v[190:193], v133 offset:17408
	ds_read_b128 v[194:197], v132 offset:16384
	ds_read_b128 v[198:201], v132 offset:17408
	buffer_load_dwordx4 v143, s[4:7], s47 offen lds
	s_mov_b32 m0, s18
	s_nop 0
	buffer_load_dwordx4 v144, s[4:7], s47 offen lds
	s_barrier
	s_waitcnt lgkmcnt(0)
	s_waitcnt lgkmcnt(7)
	v_mfma_f32_16x16x32_bf16 v[60:63], v[154:157], v[170:173], v[60:63]
	v_mfma_f32_16x16x32_bf16 v[56:59], v[162:165], v[170:173], v[56:59]
	s_waitcnt lgkmcnt(5)
	v_mfma_f32_16x16x32_bf16 v[52:55], v[154:157], v[178:181], v[52:55]
	v_mfma_f32_16x16x32_bf16 v[48:51], v[162:165], v[178:181], v[48:51]
	s_waitcnt lgkmcnt(3)
	v_mfma_f32_16x16x32_bf16 v[44:47], v[154:157], v[186:189], v[44:47]
	v_mfma_f32_16x16x32_bf16 v[40:43], v[162:165], v[186:189], v[40:43]
	s_waitcnt lgkmcnt(1)
	v_mfma_f32_16x16x32_bf16 v[36:39], v[154:157], v[194:197], v[36:39]
	v_mfma_f32_16x16x32_bf16 v[32:35], v[162:165], v[194:197], v[32:35]
	v_mfma_f32_16x16x32_bf16 v[60:63], v[158:161], v[174:177], v[60:63]
	v_mfma_f32_16x16x32_bf16 v[56:59], v[166:169], v[174:177], v[56:59]
	v_mfma_f32_16x16x32_bf16 v[52:55], v[158:161], v[182:185], v[52:55]
	v_mfma_f32_16x16x32_bf16 v[48:51], v[166:169], v[182:185], v[48:51]
	v_mfma_f32_16x16x32_bf16 v[44:47], v[158:161], v[190:193], v[44:47]
	v_mfma_f32_16x16x32_bf16 v[40:43], v[166:169], v[190:193], v[40:43]
	s_waitcnt lgkmcnt(0)
	v_mfma_f32_16x16x32_bf16 v[36:39], v[158:161], v[198:201], v[36:39]
	v_mfma_f32_16x16x32_bf16 v[32:35], v[166:169], v[198:201], v[32:35]
	s_barrier
	s_add_i32 s47, s41, s17
	s_add_i32 s48, s47, 0x100
	s_mov_b32 m0, s19
	s_nop 0
	buffer_load_dwordx4 v143, s[8:11], s48 offen lds
	s_mov_b32 m0, s20
	s_nop 0
	buffer_load_dwordx4 v144, s[8:11], s48 offen lds
	s_waitcnt vmcnt(6)
	s_barrier
; #define STAGE(P, RS, SOFF, OFF, kt) do { const int _so = (SOFF) + (kt) * (BK * 2); \
;     _Pragma("unroll") for (int _i = 0; _i < 2; ++_i) { \
;       __builtin_amdgcn_raw_ptr_buffer_load_lds(RS, (__attribute__((address_space(3))) void*)((P) + wave * 1024 + _i * 8192), 16, OFF[_i], _so, 0, 0); } } while (0)
; #define LDA(dst, b, h) _Pragma("unroll") for (int m = 0; m < 4; ++m) _Pragma("unroll") for (int k = 0; k < 2; ++k) \
;     dst[m][k] = *reinterpret_cast<const bf16x8*>(SA(b, h) + lds_byte(wr * 64 + m * 16 + fr, k * 32 + fq * 8))
; #define LDB(dst, b, h) _Pragma("unroll") for (int n = 0; n < 2; ++n) _Pragma("unroll") for (int k = 0; k < 2; ++k) \
;     dst[n][k] = *reinterpret_cast<const bf16x8*>(SB(b, h) + lds_byte(wc * 32 + n * 16 + fr, k * 32 + fq * 8))
; #define WAIT_V(n) asm volatile("s_waitcnt vmcnt(" #n ")" ::: "memory")
; #define WAIT_L(n) asm volatile("s_waitcnt lgkmcnt(" #n ")" ::: "memory")
; #define BAR __builtin_amdgcn_s_barrier()
; #define SCHED __builtin_amdgcn_sched_barrier(0)
;     ...
;       WAIT_V(6); BAR; MMA(1, 1, At, B1); BAR;
;       LDB(B0, 1, 0); SCHED; LDA(At, 1, 0); STAGE(SA(0, 1), rsA, sA1, offA, t + 2);
;       WAIT_L(8); BAR; WAIT_L(0); MMA(0, 0, At, B0); BAR; SCHED;
;       LDB(B1, 1, 1); STAGE(SB(1, 0), rsB, sB0, offB, t + 3);
;       BAR; WAIT_L(0); MMA(0, 1, At, B1); BAR;
;       LDA(At, 1, 1); STAGE(SA(1, 0), rsA, sA0, offA, t + 3);
	v_mfma_f32_16x16x32_bf16 v[28:31], v[202:205], v[170:173], v[28:31]
	v_mfma_f32_16x16x32_bf16 v[24:27], v[210:213], v[170:173], v[24:27]
	v_mfma_f32_16x16x32_bf16 v[20:23], v[202:205], v[178:181], v[20:23]
	v_mfma_f32_16x16x32_bf16 v[16:19], v[210:213], v[178:181], v[16:19]
	v_mfma_f32_16x16x32_bf16 v[12:15], v[202:205], v[186:189], v[12:15]
	v_mfma_f32_16x16x32_bf16 v[8:11], v[210:213], v[186:189], v[8:11]
	v_mfma_f32_16x16x32_bf16 v[4:7], v[202:205], v[194:197], v[4:7]
	v_mfma_f32_16x16x32_bf16 v[0:3], v[210:213], v[194:197], v[0:3]
	v_mfma_f32_16x16x32_bf16 v[28:31], v[206:209], v[174:177], v[28:31]
	v_mfma_f32_16x16x32_bf16 v[24:27], v[214:217], v[174:177], v[24:27]
	v_mfma_f32_16x16x32_bf16 v[20:23], v[206:209], v[182:185], v[20:23]
	v_mfma_f32_16x16x32_bf16 v[16:19], v[214:217], v[182:185], v[16:19]
	v_mfma_f32_16x16x32_bf16 v[12:15], v[206:209], v[190:193], v[12:15]
	v_mfma_f32_16x16x32_bf16 v[8:11], v[214:217], v[190:193], v[8:11]
	v_mfma_f32_16x16x32_bf16 v[4:7], v[206:209], v[198:201], v[4:7]
	v_mfma_f32_16x16x32_bf16 v[0:3], v[214:217], v[198:201], v[0:3]
	s_barrier
	ds_read_b128 v[154:157], v139
	ds_read_b128 v[158:161], v140
	ds_read_b128 v[162:165], v141
	ds_read_b128 v[166:169], v142
	s_addk_i32 s44, 0x100
	s_mov_b32 m0, s21
	ds_read_b128 v[170:173], v131 offset:32768
	ds_read_b128 v[174:177], v131 offset:33792
	ds_read_b128 v[178:181], v134 offset:32768
	ds_read_b128 v[182:185], v134 offset:33792
	ds_read_b128 v[186:189], v133 offset:32768
	ds_read_b128 v[190:193], v133 offset:33792
	ds_read_b128 v[194:197], v132 offset:32768
	ds_read_b128 v[198:201], v132 offset:33792
	buffer_load_dwordx4 v143, s[4:7], s44 offen lds
	s_mov_b32 m0, s22
	s_nop 0
	buffer_load_dwordx4 v144, s[4:7], s44 offen lds
	s_waitcnt lgkmcnt(8)
	s_barrier
	s_waitcnt lgkmcnt(0)
	s_waitcnt lgkmcnt(7)
	v_mfma_f32_16x16x32_bf16 v[124:127], v[154:157], v[170:173], v[124:127]
	v_mfma_f32_16x16x32_bf16 v[120:123], v[162:165], v[170:173], v[120:123]
	s_waitcnt lgkmcnt(5)
	v_mfma_f32_16x16x32_bf16 v[116:119], v[154:157], v[178:181], v[116:119]
	v_mfma_f32_16x16x32_bf16 v[112:115], v[162:165], v[178:181], v[112:115]
	s_waitcnt lgkmcnt(3)
	v_mfma_f32_16x16x32_bf16 v[108:111], v[154:157], v[186:189], v[108:111]
	v_mfma_f32_16x16x32_bf16 v[104:107], v[162:165], v[186:189], v[104:107]
	s_waitcnt lgkmcnt(1)
	v_mfma_f32_16x16x32_bf16 v[100:103], v[154:157], v[194:197], v[100:103]
	v_mfma_f32_16x16x32_bf16 v[96:99], v[162:165], v[194:197], v[96:99]
	v_mfma_f32_16x16x32_bf16 v[124:127], v[158:161], v[174:177], v[124:127]
	v_mfma_f32_16x16x32_bf16 v[120:123], v[166:169], v[174:177], v[120:123]
	v_mfma_f32_16x16x32_bf16 v[116:119], v[158:161], v[182:185], v[116:119]
	v_mfma_f32_16x16x32_bf16 v[112:115], v[166:169], v[182:185], v[112:115]
	v_mfma_f32_16x16x32_bf16 v[108:111], v[158:161], v[190:193], v[108:111]
	v_mfma_f32_16x16x32_bf16 v[104:107], v[166:169], v[190:193], v[104:107]
	s_waitcnt lgkmcnt(0)
	v_mfma_f32_16x16x32_bf16 v[100:103], v[158:161], v[198:201], v[100:103]
	v_mfma_f32_16x16x32_bf16 v[96:99], v[166:169], v[198:201], v[96:99]
	s_barrier
	s_addk_i32 s45, 0x180
	s_mov_b32 m0, s23
	ds_read_b128 v[202:205], v135
	ds_read_b128 v[206:209], v136
	ds_read_b128 v[210:213], v137
	ds_read_b128 v[214:217], v138
	buffer_load_dwordx4 v143, s[8:11], s45 offen lds
	s_mov_b32 m0, s24
	s_nop 0
	buffer_load_dwordx4 v144, s[8:11], s45 offen lds
	s_barrier
	s_waitcnt lgkmcnt(0)
	s_waitcnt lgkmcnt(3)
	v_mfma_f32_16x16x32_bf16 v[92:95], v[202:205], v[170:173], v[92:95]
	s_waitcnt lgkmcnt(1)
	v_mfma_f32_16x16x32_bf16 v[88:91], v[210:213], v[170:173], v[88:91]
	v_mfma_f32_16x16x32_bf16 v[84:87], v[202:205], v[178:181], v[84:87]
	v_mfma_f32_16x16x32_bf16 v[80:83], v[210:213], v[178:181], v[80:83]
	v_mfma_f32_16x16x32_bf16 v[76:79], v[202:205], v[186:189], v[76:79]
	v_mfma_f32_16x16x32_bf16 v[72:75], v[210:213], v[186:189], v[72:75]
	v_mfma_f32_16x16x32_bf16 v[68:71], v[202:205], v[194:197], v[68:71]
	v_mfma_f32_16x16x32_bf16 v[64:67], v[210:213], v[194:197], v[64:67]
	v_mfma_f32_16x16x32_bf16 v[92:95], v[206:209], v[174:177], v[92:95]
	s_waitcnt lgkmcnt(0)
	v_mfma_f32_16x16x32_bf16 v[88:91], v[214:217], v[174:177], v[88:91]
	v_mfma_f32_16x16x32_bf16 v[84:87], v[206:209], v[182:185], v[84:87]
	v_mfma_f32_16x16x32_bf16 v[80:83], v[214:217], v[182:185], v[80:83]
	v_mfma_f32_16x16x32_bf16 v[76:79], v[206:209], v[190:193], v[76:79]
	v_mfma_f32_16x16x32_bf16 v[72:75], v[214:217], v[190:193], v[72:75]
	v_mfma_f32_16x16x32_bf16 v[68:71], v[206:209], v[198:201], v[68:71]
	v_mfma_f32_16x16x32_bf16 v[64:67], v[214:217], v[198:201], v[64:67]
	s_addk_i32 s46, 0x180
	s_mov_b32 m0, s25
	s_barrier
	ds_read_b128 v[170:173], v131 offset:49152
	ds_read_b128 v[174:177], v131 offset:50176
	ds_read_b128 v[178:181], v134 offset:49152
	ds_read_b128 v[182:185], v134 offset:50176
	ds_read_b128 v[186:189], v133 offset:49152
	ds_read_b128 v[190:193], v133 offset:50176
	ds_read_b128 v[194:197], v132 offset:49152
	ds_read_b128 v[198:201], v132 offset:50176
	buffer_load_dwordx4 v143, s[4:7], s46 offen lds
	s_mov_b32 m0, s26
	s_nop 0
	buffer_load_dwordx4 v144, s[4:7], s46 offen lds
	s_barrier
; #define STAGE(P, RS, SOFF, OFF, kt) do { const int _so = (SOFF) + (kt) * (BK * 2); \
;     _Pragma("unroll") for (int _i = 0; _i < 2; ++_i) { \
;       __builtin_amdgcn_raw_ptr_buffer_load_lds(RS, (__attribute__((address_space(3))) void*)((P) + wave * 1024 + _i * 8192), 16, OFF[_i], _so, 0, 0); } } while (0)
; #define LDA(dst, b, h) _Pragma("unroll") for (int m = 0; m < 4; ++m) _Pragma("unroll") for (int k = 0; k < 2; ++k) \
;     dst[m][k] = *reinterpret_cast<const bf16x8*>(SA(b, h) + lds_byte(wr * 64 + m * 16 + fr, k * 32 + fq * 8))
; #define LDB(dst, b, h) _Pragma("unroll") for (int n = 0; n < 2; ++n) _Pragma("unroll") for (int k = 0; k < 2; ++k) \
;     dst[n][k] = *reinterpret_cast<const bf16x8*>(SB(b, h) + lds_byte(wc * 32 + n * 16 + fr, k * 32 + fq * 8))
; #define WAIT_V(n) asm volatile("s_waitcnt vmcnt(" #n ")" ::: "memory")
; #define WAIT_L(n) asm volatile("s_waitcnt lgkmcnt(" #n ")" ::: "memory")
; #define BAR __builtin_amdgcn_s_barrier()
; #define SCHED __builtin_amdgcn_sched_barrier(0)
;     ...
;       BAR; WAIT_L(0); MMA(1, 0, At, B0); BAR; SCHED;
;       STAGE(SB(1, 1), rsB, sB1, offB, t + 3);
;       WAIT_V(6); BAR; MMA(1, 1, At, B1); BAR;
;     }
;     { LDB(B0, 0, 0); LDA(At, 0, 0); STAGE(SA(1, 1), rsA, sA1, offA, nt - 1);
;       BAR; WAIT_L(0); MMA(0, 0, At, B0); BAR;
;       LDB(B1, 0, 1); BAR; WAIT_L(0); MMA(0, 1, At, B1); BAR;
	s_waitcnt lgkmcnt(0)
	s_waitcnt lgkmcnt(7)
	v_mfma_f32_16x16x32_bf16 v[60:63], v[154:157], v[170:173], v[60:63]
	v_mfma_f32_16x16x32_bf16 v[56:59], v[162:165], v[170:173], v[56:59]
	s_waitcnt lgkmcnt(5)
	v_mfma_f32_16x16x32_bf16 v[52:55], v[154:157], v[178:181], v[52:55]
	v_mfma_f32_16x16x32_bf16 v[48:51], v[162:165], v[178:181], v[48:51]
	s_waitcnt lgkmcnt(3)
	v_mfma_f32_16x16x32_bf16 v[44:47], v[154:157], v[186:189], v[44:47]
	v_mfma_f32_16x16x32_bf16 v[40:43], v[162:165], v[186:189], v[40:43]
	s_waitcnt lgkmcnt(1)
	v_mfma_f32_16x16x32_bf16 v[36:39], v[154:157], v[194:197], v[36:39]
	v_mfma_f32_16x16x32_bf16 v[32:35], v[162:165], v[194:197], v[32:35]
	v_mfma_f32_16x16x32_bf16 v[60:63], v[158:161], v[174:177], v[60:63]
	v_mfma_f32_16x16x32_bf16 v[56:59], v[166:169], v[174:177], v[56:59]
	v_mfma_f32_16x16x32_bf16 v[52:55], v[158:161], v[182:185], v[52:55]
	v_mfma_f32_16x16x32_bf16 v[48:51], v[166:169], v[182:185], v[48:51]
	v_mfma_f32_16x16x32_bf16 v[44:47], v[158:161], v[190:193], v[44:47]
	v_mfma_f32_16x16x32_bf16 v[40:43], v[166:169], v[190:193], v[40:43]
	s_waitcnt lgkmcnt(0)
	v_mfma_f32_16x16x32_bf16 v[36:39], v[158:161], v[198:201], v[36:39]
	v_mfma_f32_16x16x32_bf16 v[32:35], v[166:169], v[198:201], v[32:35]
	s_barrier
	s_addk_i32 s47, 0x180
	s_mov_b32 m0, s27
	s_nop 0
	buffer_load_dwordx4 v143, s[8:11], s47 offen lds
	s_mov_b32 m0, s28
	s_nop 0
	buffer_load_dwordx4 v144, s[8:11], s47 offen lds
	s_waitcnt vmcnt(6)
	s_barrier
	v_mfma_f32_16x16x32_bf16 v[28:31], v[202:205], v[170:173], v[28:31]
	v_mfma_f32_16x16x32_bf16 v[24:27], v[210:213], v[170:173], v[24:27]
	v_mfma_f32_16x16x32_bf16 v[20:23], v[202:205], v[178:181], v[20:23]
	v_mfma_f32_16x16x32_bf16 v[16:19], v[210:213], v[178:181], v[16:19]
	v_mfma_f32_16x16x32_bf16 v[12:15], v[202:205], v[186:189], v[12:15]
	v_mfma_f32_16x16x32_bf16 v[8:11], v[210:213], v[186:189], v[8:11]
	v_mfma_f32_16x16x32_bf16 v[4:7], v[202:205], v[194:197], v[4:7]
	v_mfma_f32_16x16x32_bf16 v[0:3], v[210:213], v[194:197], v[0:3]
	v_mfma_f32_16x16x32_bf16 v[28:31], v[206:209], v[174:177], v[28:31]
	v_mfma_f32_16x16x32_bf16 v[24:27], v[214:217], v[174:177], v[24:27]
	v_mfma_f32_16x16x32_bf16 v[20:23], v[206:209], v[182:185], v[20:23]
	v_mfma_f32_16x16x32_bf16 v[16:19], v[214:217], v[182:185], v[16:19]
	v_mfma_f32_16x16x32_bf16 v[12:15], v[206:209], v[190:193], v[12:15]
	v_mfma_f32_16x16x32_bf16 v[8:11], v[214:217], v[190:193], v[8:11]
	v_mfma_f32_16x16x32_bf16 v[4:7], v[206:209], v[198:201], v[4:7]
	v_mfma_f32_16x16x32_bf16 v[0:3], v[214:217], v[198:201], v[0:3]
	s_add_i32 s16, s16, 2
	s_addk_i32 s17, 0x100
	s_cmp_gt_u32 s16, 27
	s_barrier
	s_cbranch_scc0 .LBB0_210
	s_add_i32 s10, s38, 0xf80
	s_mov_b32 m0, s30
	ds_read_b128 v[154:157], v149
	ds_read_b128 v[158:161], v150
	ds_read_b128 v[162:165], v151
	ds_read_b128 v[150:153], v152
	ds_read_b128 v[166:169], v131
	ds_read_b128 v[170:173], v131 offset:1024
	ds_read_b128 v[174:177], v134
	ds_read_b128 v[178:181], v134 offset:1024
	ds_read_b128 v[182:185], v133
	ds_read_b128 v[186:189], v133 offset:1024
	ds_read_b128 v[190:193], v132
	ds_read_b128 v[194:197], v132 offset:1024
	buffer_load_dwordx4 v143, s[4:7], s10 offen lds
	s_mov_b32 m0, s31
	s_nop 0
	buffer_load_dwordx4 v144, s[4:7], s10 offen lds
	s_barrier
	s_waitcnt lgkmcnt(0)
	s_waitcnt lgkmcnt(7)
	v_mfma_f32_16x16x32_bf16 v[124:127], v[154:157], v[166:169], v[124:127]
	v_mfma_f32_16x16x32_bf16 v[120:123], v[162:165], v[166:169], v[120:123]
	s_waitcnt lgkmcnt(5)
	v_mfma_f32_16x16x32_bf16 v[116:119], v[154:157], v[174:177], v[116:119]
	v_mfma_f32_16x16x32_bf16 v[112:115], v[162:165], v[174:177], v[112:115]
	s_waitcnt lgkmcnt(3)
	v_mfma_f32_16x16x32_bf16 v[108:111], v[154:157], v[182:185], v[108:111]
	v_mfma_f32_16x16x32_bf16 v[104:107], v[162:165], v[182:185], v[104:107]
	s_waitcnt lgkmcnt(1)
	v_mfma_f32_16x16x32_bf16 v[100:103], v[154:157], v[190:193], v[100:103]
	v_mfma_f32_16x16x32_bf16 v[96:99], v[162:165], v[190:193], v[96:99]
	v_mfma_f32_16x16x32_bf16 v[124:127], v[158:161], v[170:173], v[124:127]
	v_mfma_f32_16x16x32_bf16 v[120:123], v[150:153], v[170:173], v[120:123]
	v_mfma_f32_16x16x32_bf16 v[116:119], v[158:161], v[178:181], v[116:119]
	v_mfma_f32_16x16x32_bf16 v[112:115], v[150:153], v[178:181], v[112:115]
	v_mfma_f32_16x16x32_bf16 v[108:111], v[158:161], v[186:189], v[108:111]
	v_mfma_f32_16x16x32_bf16 v[104:107], v[150:153], v[186:189], v[104:107]
	s_waitcnt lgkmcnt(0)
	v_mfma_f32_16x16x32_bf16 v[100:103], v[158:161], v[194:197], v[100:103]
	v_mfma_f32_16x16x32_bf16 v[96:99], v[150:153], v[194:197], v[96:99]
	s_barrier
	ds_read_b128 v[198:201], v145
	ds_read_b128 v[202:205], v146
	ds_read_b128 v[144:147], v147
	ds_read_b128 v[206:209], v148
	s_barrier
	s_waitcnt lgkmcnt(0)
	s_waitcnt lgkmcnt(3)
	v_mfma_f32_16x16x32_bf16 v[92:95], v[198:201], v[166:169], v[92:95]
	s_waitcnt lgkmcnt(1)
	v_mfma_f32_16x16x32_bf16 v[88:91], v[144:147], v[166:169], v[88:91]
	v_mfma_f32_16x16x32_bf16 v[84:87], v[198:201], v[174:177], v[84:87]
	v_mfma_f32_16x16x32_bf16 v[80:83], v[144:147], v[174:177], v[80:83]
	v_mfma_f32_16x16x32_bf16 v[76:79], v[198:201], v[182:185], v[76:79]
	v_mfma_f32_16x16x32_bf16 v[72:75], v[144:147], v[182:185], v[72:75]
	v_mfma_f32_16x16x32_bf16 v[68:71], v[198:201], v[190:193], v[68:71]
	v_mfma_f32_16x16x32_bf16 v[64:67], v[144:147], v[190:193], v[64:67]
	v_mfma_f32_16x16x32_bf16 v[92:95], v[202:205], v[170:173], v[92:95]
	s_waitcnt lgkmcnt(0)
	v_mfma_f32_16x16x32_bf16 v[88:91], v[206:209], v[170:173], v[88:91]
	v_mfma_f32_16x16x32_bf16 v[84:87], v[202:205], v[178:181], v[84:87]
	v_mfma_f32_16x16x32_bf16 v[80:83], v[206:209], v[178:181], v[80:83]
	v_mfma_f32_16x16x32_bf16 v[76:79], v[202:205], v[186:189], v[76:79]
	v_mfma_f32_16x16x32_bf16 v[72:75], v[206:209], v[186:189], v[72:75]
	v_mfma_f32_16x16x32_bf16 v[68:71], v[202:205], v[194:197], v[68:71]
	v_mfma_f32_16x16x32_bf16 v[64:67], v[206:209], v[194:197], v[64:67]
	s_barrier
; #define LDA(dst, b, h) _Pragma("unroll") for (int m = 0; m < 4; ++m) _Pragma("unroll") for (int k = 0; k < 2; ++k) \
;     dst[m][k] = *reinterpret_cast<const bf16x8*>(SA(b, h) + lds_byte(wr * 64 + m * 16 + fr, k * 32 + fq * 8))
; #define LDB(dst, b, h) _Pragma("unroll") for (int n = 0; n < 2; ++n) _Pragma("unroll") for (int k = 0; k < 2; ++k) \
;     dst[n][k] = *reinterpret_cast<const bf16x8*>(SB(b, h) + lds_byte(wc * 32 + n * 16 + fr, k * 32 + fq * 8))
; #define WAIT_V(n) asm volatile("s_waitcnt vmcnt(" #n ")" ::: "memory")
; #define WAIT_L(n) asm volatile("s_waitcnt lgkmcnt(" #n ")" ::: "memory")
; #define BAR __builtin_amdgcn_s_barrier()
;     ...
;       LDA(At, 0, 1); WAIT_V(4); BAR; WAIT_L(0); MMA(1, 0, At, B0); MMA(1, 1, At, B1); BAR; }
;     { LDB(B0, 1, 0); LDA(At, 1, 0); WAIT_V(2); BAR; WAIT_L(0); MMA(0, 0, At, B0); BAR;
	ds_read_b128 v[166:169], v131 offset:16384
	ds_read_b128 v[170:173], v131 offset:17408
	ds_read_b128 v[174:177], v134 offset:16384
	ds_read_b128 v[178:181], v134 offset:17408
	ds_read_b128 v[182:185], v133 offset:16384
	ds_read_b128 v[186:189], v133 offset:17408
	ds_read_b128 v[190:193], v132 offset:16384
	ds_read_b128 v[194:197], v132 offset:17408
	s_waitcnt vmcnt(4)
	s_barrier
	s_waitcnt lgkmcnt(0)
	s_waitcnt lgkmcnt(7)
	v_mfma_f32_16x16x32_bf16 v[60:63], v[154:157], v[166:169], v[60:63]
	v_mfma_f32_16x16x32_bf16 v[56:59], v[162:165], v[166:169], v[56:59]
	s_waitcnt lgkmcnt(5)
	v_mfma_f32_16x16x32_bf16 v[52:55], v[154:157], v[174:177], v[52:55]
	v_mfma_f32_16x16x32_bf16 v[48:51], v[162:165], v[174:177], v[48:51]
	s_waitcnt lgkmcnt(3)
	v_mfma_f32_16x16x32_bf16 v[44:47], v[154:157], v[182:185], v[44:47]
	v_mfma_f32_16x16x32_bf16 v[40:43], v[162:165], v[182:185], v[40:43]
	s_waitcnt lgkmcnt(1)
	v_mfma_f32_16x16x32_bf16 v[36:39], v[154:157], v[190:193], v[36:39]
	v_mfma_f32_16x16x32_bf16 v[32:35], v[162:165], v[190:193], v[32:35]
	v_mfma_f32_16x16x32_bf16 v[60:63], v[158:161], v[170:173], v[60:63]
	v_mfma_f32_16x16x32_bf16 v[56:59], v[150:153], v[170:173], v[56:59]
	v_mfma_f32_16x16x32_bf16 v[52:55], v[158:161], v[178:181], v[52:55]
	v_mfma_f32_16x16x32_bf16 v[48:51], v[150:153], v[178:181], v[48:51]
	v_mfma_f32_16x16x32_bf16 v[44:47], v[158:161], v[186:189], v[44:47]
	v_mfma_f32_16x16x32_bf16 v[40:43], v[150:153], v[186:189], v[40:43]
	s_waitcnt lgkmcnt(0)
	v_mfma_f32_16x16x32_bf16 v[36:39], v[158:161], v[194:197], v[36:39]
	v_mfma_f32_16x16x32_bf16 v[32:35], v[150:153], v[194:197], v[32:35]
	v_mfma_f32_16x16x32_bf16 v[28:31], v[198:201], v[166:169], v[28:31]
	v_mfma_f32_16x16x32_bf16 v[24:27], v[144:147], v[166:169], v[24:27]
	v_mfma_f32_16x16x32_bf16 v[20:23], v[198:201], v[174:177], v[20:23]
	v_mfma_f32_16x16x32_bf16 v[16:19], v[144:147], v[174:177], v[16:19]
	v_mfma_f32_16x16x32_bf16 v[12:15], v[198:201], v[182:185], v[12:15]
	v_mfma_f32_16x16x32_bf16 v[8:11], v[144:147], v[182:185], v[8:11]
	v_mfma_f32_16x16x32_bf16 v[4:7], v[198:201], v[190:193], v[4:7]
	v_mfma_f32_16x16x32_bf16 v[0:3], v[144:147], v[190:193], v[0:3]
	v_mfma_f32_16x16x32_bf16 v[28:31], v[202:205], v[170:173], v[28:31]
	v_mfma_f32_16x16x32_bf16 v[24:27], v[206:209], v[170:173], v[24:27]
	v_mfma_f32_16x16x32_bf16 v[20:23], v[202:205], v[178:181], v[20:23]
	v_mfma_f32_16x16x32_bf16 v[16:19], v[206:209], v[178:181], v[16:19]
	v_mfma_f32_16x16x32_bf16 v[12:15], v[202:205], v[186:189], v[12:15]
	v_mfma_f32_16x16x32_bf16 v[8:11], v[206:209], v[186:189], v[8:11]
	v_mfma_f32_16x16x32_bf16 v[4:7], v[202:205], v[194:197], v[4:7]
	v_mfma_f32_16x16x32_bf16 v[0:3], v[206:209], v[194:197], v[0:3]
	s_barrier
	ds_read_b128 v[144:147], v139
	ds_read_b128 v[148:151], v140
	ds_read_b128 v[152:155], v141
	ds_read_b128 v[140:143], v142
	ds_read_b128 v[156:159], v131 offset:32768
	ds_read_b128 v[160:163], v131 offset:33792
	ds_read_b128 v[164:167], v134 offset:32768
	ds_read_b128 v[168:171], v134 offset:33792
	ds_read_b128 v[172:175], v133 offset:32768
	ds_read_b128 v[176:179], v133 offset:33792
	ds_read_b128 v[180:183], v132 offset:32768
	ds_read_b128 v[184:187], v132 offset:33792
	s_waitcnt vmcnt(2)
	s_barrier
	s_waitcnt lgkmcnt(0)
	s_waitcnt lgkmcnt(7)
	v_mfma_f32_16x16x32_bf16 v[124:127], v[144:147], v[156:159], v[124:127]
	v_mfma_f32_16x16x32_bf16 v[120:123], v[152:155], v[156:159], v[120:123]
	s_waitcnt lgkmcnt(5)
	v_mfma_f32_16x16x32_bf16 v[116:119], v[144:147], v[164:167], v[116:119]
	v_mfma_f32_16x16x32_bf16 v[112:115], v[152:155], v[164:167], v[112:115]
	s_waitcnt lgkmcnt(3)
	v_mfma_f32_16x16x32_bf16 v[108:111], v[144:147], v[172:175], v[108:111]
	v_mfma_f32_16x16x32_bf16 v[104:107], v[152:155], v[172:175], v[104:107]
	s_waitcnt lgkmcnt(1)
	v_mfma_f32_16x16x32_bf16 v[100:103], v[144:147], v[180:183], v[100:103]
	v_mfma_f32_16x16x32_bf16 v[96:99], v[152:155], v[180:183], v[96:99]
	v_mfma_f32_16x16x32_bf16 v[124:127], v[148:151], v[160:163], v[124:127]
	v_mfma_f32_16x16x32_bf16 v[120:123], v[140:143], v[160:163], v[120:123]
	v_mfma_f32_16x16x32_bf16 v[116:119], v[148:151], v[168:171], v[116:119]
	v_mfma_f32_16x16x32_bf16 v[112:115], v[140:143], v[168:171], v[112:115]
	v_mfma_f32_16x16x32_bf16 v[108:111], v[148:151], v[176:179], v[108:111]
	v_mfma_f32_16x16x32_bf16 v[104:107], v[140:143], v[176:179], v[104:107]
	s_waitcnt lgkmcnt(0)
	v_mfma_f32_16x16x32_bf16 v[100:103], v[148:151], v[184:187], v[100:103]
	v_mfma_f32_16x16x32_bf16 v[96:99], v[140:143], v[184:187], v[96:99]
	s_barrier
; #define LDA(dst, b, h) _Pragma("unroll") for (int m = 0; m < 4; ++m) _Pragma("unroll") for (int k = 0; k < 2; ++k) \
;     dst[m][k] = *reinterpret_cast<const bf16x8*>(SA(b, h) + lds_byte(wr * 64 + m * 16 + fr, k * 32 + fq * 8))
; #define LDB(dst, b, h) _Pragma("unroll") for (int n = 0; n < 2; ++n) _Pragma("unroll") for (int k = 0; k < 2; ++k) \
;     dst[n][k] = *reinterpret_cast<const bf16x8*>(SB(b, h) + lds_byte(wc * 32 + n * 16 + fr, k * 32 + fq * 8))
; #define WAIT_V(n) asm volatile("s_waitcnt vmcnt(" #n ")" ::: "memory")
; #define WAIT_L(n) asm volatile("s_waitcnt lgkmcnt(" #n ")" ::: "memory")
; #define BAR __builtin_amdgcn_s_barrier()
;     ...
;       LDB(B1, 1, 1); WAIT_V(0); BAR; WAIT_L(0); MMA(0, 1, At, B1); BAR;
;       LDA(At, 1, 1); BAR; WAIT_L(0); MMA(1, 0, At, B0); MMA(1, 1, At, B1); BAR; }
;     if (wr == 0) BAR;
	ds_read_b128 v[188:191], v135
	ds_read_b128 v[192:195], v136
	ds_read_b128 v[196:199], v137
	ds_read_b128 v[136:139], v138
	s_waitcnt vmcnt(0)
	s_barrier
	s_waitcnt lgkmcnt(0)
	s_waitcnt lgkmcnt(3)
	v_mfma_f32_16x16x32_bf16 v[92:95], v[188:191], v[156:159], v[92:95]
	s_waitcnt lgkmcnt(1)
	v_mfma_f32_16x16x32_bf16 v[88:91], v[196:199], v[156:159], v[88:91]
	v_mfma_f32_16x16x32_bf16 v[84:87], v[188:191], v[164:167], v[84:87]
	v_mfma_f32_16x16x32_bf16 v[80:83], v[196:199], v[164:167], v[80:83]
	v_mfma_f32_16x16x32_bf16 v[76:79], v[188:191], v[172:175], v[76:79]
	v_mfma_f32_16x16x32_bf16 v[72:75], v[196:199], v[172:175], v[72:75]
	v_mfma_f32_16x16x32_bf16 v[68:71], v[188:191], v[180:183], v[68:71]
	v_mfma_f32_16x16x32_bf16 v[64:67], v[196:199], v[180:183], v[64:67]
	v_mfma_f32_16x16x32_bf16 v[92:95], v[192:195], v[160:163], v[92:95]
	s_waitcnt lgkmcnt(0)
	v_mfma_f32_16x16x32_bf16 v[88:91], v[136:139], v[160:163], v[88:91]
	v_mfma_f32_16x16x32_bf16 v[84:87], v[192:195], v[168:171], v[84:87]
	v_mfma_f32_16x16x32_bf16 v[80:83], v[136:139], v[168:171], v[80:83]
	v_mfma_f32_16x16x32_bf16 v[76:79], v[192:195], v[176:179], v[76:79]
	v_mfma_f32_16x16x32_bf16 v[72:75], v[136:139], v[176:179], v[72:75]
	v_mfma_f32_16x16x32_bf16 v[68:71], v[192:195], v[184:187], v[68:71]
	v_mfma_f32_16x16x32_bf16 v[64:67], v[136:139], v[184:187], v[64:67]
	s_barrier
	ds_read_b128 v[156:159], v131 offset:49152
	ds_read_b128 v[160:163], v131 offset:50176
	ds_read_b128 v[164:167], v134 offset:49152
	ds_read_b128 v[168:171], v134 offset:50176
	ds_read_b128 v[172:175], v133 offset:49152
	ds_read_b128 v[176:179], v133 offset:50176
	ds_read_b128 v[180:183], v132 offset:49152
	ds_read_b128 v[132:135], v132 offset:50176
	s_barrier
	s_waitcnt lgkmcnt(0)
	s_waitcnt lgkmcnt(7)
	v_mfma_f32_16x16x32_bf16 v[60:63], v[144:147], v[156:159], v[60:63]
	v_mfma_f32_16x16x32_bf16 v[56:59], v[152:155], v[156:159], v[56:59]
	s_waitcnt lgkmcnt(5)
	v_mfma_f32_16x16x32_bf16 v[52:55], v[144:147], v[164:167], v[52:55]
	v_mfma_f32_16x16x32_bf16 v[48:51], v[152:155], v[164:167], v[48:51]
	s_waitcnt lgkmcnt(3)
	v_mfma_f32_16x16x32_bf16 v[44:47], v[144:147], v[172:175], v[44:47]
	v_mfma_f32_16x16x32_bf16 v[40:43], v[152:155], v[172:175], v[40:43]
	s_waitcnt lgkmcnt(1)
	v_mfma_f32_16x16x32_bf16 v[36:39], v[144:147], v[180:183], v[36:39]
	v_mfma_f32_16x16x32_bf16 v[32:35], v[152:155], v[180:183], v[32:35]
	v_mfma_f32_16x16x32_bf16 v[60:63], v[148:151], v[160:163], v[60:63]
	v_mfma_f32_16x16x32_bf16 v[56:59], v[140:143], v[160:163], v[56:59]
	v_mfma_f32_16x16x32_bf16 v[52:55], v[148:151], v[168:171], v[52:55]
	v_mfma_f32_16x16x32_bf16 v[48:51], v[140:143], v[168:171], v[48:51]
	v_mfma_f32_16x16x32_bf16 v[44:47], v[148:151], v[176:179], v[44:47]
	v_mfma_f32_16x16x32_bf16 v[40:43], v[140:143], v[176:179], v[40:43]
	s_waitcnt lgkmcnt(0)
	v_mfma_f32_16x16x32_bf16 v[36:39], v[148:151], v[132:135], v[36:39]
	v_mfma_f32_16x16x32_bf16 v[32:35], v[140:143], v[132:135], v[32:35]
	v_mfma_f32_16x16x32_bf16 v[28:31], v[188:191], v[156:159], v[28:31]
	v_mfma_f32_16x16x32_bf16 v[24:27], v[196:199], v[156:159], v[24:27]
	v_mfma_f32_16x16x32_bf16 v[20:23], v[188:191], v[164:167], v[20:23]
	v_mfma_f32_16x16x32_bf16 v[16:19], v[196:199], v[164:167], v[16:19]
	v_mfma_f32_16x16x32_bf16 v[12:15], v[188:191], v[172:175], v[12:15]
	v_mfma_f32_16x16x32_bf16 v[8:11], v[196:199], v[172:175], v[8:11]
	v_mfma_f32_16x16x32_bf16 v[4:7], v[188:191], v[180:183], v[4:7]
	v_mfma_f32_16x16x32_bf16 v[0:3], v[196:199], v[180:183], v[0:3]
	v_mfma_f32_16x16x32_bf16 v[28:31], v[192:195], v[160:163], v[28:31]
	v_mfma_f32_16x16x32_bf16 v[24:27], v[136:139], v[160:163], v[24:27]
	v_mfma_f32_16x16x32_bf16 v[20:23], v[192:195], v[168:171], v[20:23]
	v_mfma_f32_16x16x32_bf16 v[16:19], v[136:139], v[168:171], v[16:19]
	v_mfma_f32_16x16x32_bf16 v[12:15], v[192:195], v[176:179], v[12:15]
	v_mfma_f32_16x16x32_bf16 v[8:11], v[136:139], v[176:179], v[8:11]
	v_mfma_f32_16x16x32_bf16 v[4:7], v[192:195], v[132:135], v[4:7]
	v_mfma_f32_16x16x32_bf16 v[0:3], v[136:139], v[132:135], v[0:3]
	v_cmp_gt_u32_e32 vcc, s35, v130
	s_barrier
	s_and_saveexec_b64 s[10:11], vcc
	s_cbranch_execz .LBB0_213
	s_barrier

; #define STAGE(P, RS, SOFF, OFF, kt) do { const int _so = (SOFF) + (kt) * (BK * 2); \
;     _Pragma("unroll") for (int _i = 0; _i < 2; ++_i) { \
;       __builtin_amdgcn_raw_ptr_buffer_load_lds(RS, (__attribute__((address_space(3))) void*)((P) + wave * 1024 + _i * 8192), 16, OFF[_i], _so, 0, 0); } } while (0)
; #define LDA(dst, b, h) _Pragma("unroll") for (int m = 0; m < 4; ++m) _Pragma("unroll") for (int k = 0; k < 2; ++k) \
;     dst[m][k] = *reinterpret_cast<const bf16x8*>(SA(b, h) + lds_byte(wr * 64 + m * 16 + fr, k * 32 + fq * 8))
; #define LDB(dst, b, h) _Pragma("unroll") for (int n = 0; n < 2; ++n) _Pragma("unroll") for (int k = 0; k < 2; ++k) \
;     dst[n][k] = *reinterpret_cast<const bf16x8*>(SB(b, h) + lds_byte(wc * 32 + n * 16 + fr, k * 32 + fq * 8))
; #define WAIT_V(n) asm volatile("s_waitcnt vmcnt(" #n ")" ::: "memory")
; #define WAIT_L(n) asm volatile("s_waitcnt lgkmcnt(" #n ")" ::: "memory")
; #define BAR __builtin_amdgcn_s_barrier()
; #define SCHED __builtin_amdgcn_sched_barrier(0)
;     ...
;       LDB(B0, 0, 0); SCHED; LDA(At, 0, 0); STAGE(SA(1, 1), rsA, sA1, offA, t + 1);
;       WAIT_L(8); BAR; WAIT_L(0); MMA(0, 0, At, B0); BAR; SCHED;
;       LDB(B1, 0, 1); STAGE(SB(0, 0), rsB, sB0, offB, t + 2);
;       BAR; WAIT_L(0); MMA(0, 1, At, B1); BAR;
;       LDA(At, 0, 1); STAGE(SA(0, 0), rsA, sA0, offA, t + 2);
;       BAR; WAIT_L(0); MMA(1, 0, At, B0); BAR; SCHED;
;       STAGE(SB(0, 1), rsB, sB1, offB, t + 2);
;       WAIT_V(6); BAR; MMA(1, 1, At, B1); BAR;
.LBB0_225:
	ds_read_b128 v[152:155], v148
	ds_read_b128 v[156:159], v149
	ds_read_b128 v[160:163], v150
	ds_read_b128 v[164:167], v151
	s_add_i32 s18, s41, s17
	s_add_i32 s19, s18, 0x80
	s_mov_b32 m0, s33
	ds_read_b128 v[168:171], v130
	ds_read_b128 v[172:175], v130 offset:1024
	ds_read_b128 v[176:179], v133
	ds_read_b128 v[180:183], v133 offset:1024
	ds_read_b128 v[184:187], v132
	ds_read_b128 v[188:191], v132 offset:1024
	ds_read_b128 v[192:195], v131
	ds_read_b128 v[196:199], v131 offset:1024
	buffer_load_dwordx4 v142, s[4:7], s19 offen lds
	s_mov_b32 m0, s34
	s_nop 0
	buffer_load_dwordx4 v143, s[4:7], s19 offen lds
	s_waitcnt lgkmcnt(8)
	s_barrier
	s_waitcnt lgkmcnt(0)
	s_waitcnt lgkmcnt(7)
	v_mfma_f32_16x16x32_bf16 v[124:127], v[168:171], v[152:155], v[124:127]
	v_mfma_f32_16x16x32_bf16 v[120:123], v[168:171], v[160:163], v[120:123]
	s_waitcnt lgkmcnt(5)
	v_mfma_f32_16x16x32_bf16 v[116:119], v[176:179], v[152:155], v[116:119]
	v_mfma_f32_16x16x32_bf16 v[112:115], v[176:179], v[160:163], v[112:115]
	s_waitcnt lgkmcnt(3)
	v_mfma_f32_16x16x32_bf16 v[108:111], v[184:187], v[152:155], v[108:111]
	v_mfma_f32_16x16x32_bf16 v[104:107], v[184:187], v[160:163], v[104:107]
	s_waitcnt lgkmcnt(1)
	v_mfma_f32_16x16x32_bf16 v[100:103], v[192:195], v[152:155], v[100:103]
	v_mfma_f32_16x16x32_bf16 v[96:99], v[192:195], v[160:163], v[96:99]
	v_mfma_f32_16x16x32_bf16 v[124:127], v[172:175], v[156:159], v[124:127]
	v_mfma_f32_16x16x32_bf16 v[120:123], v[172:175], v[164:167], v[120:123]
	v_mfma_f32_16x16x32_bf16 v[116:119], v[180:183], v[156:159], v[116:119]
	v_mfma_f32_16x16x32_bf16 v[112:115], v[180:183], v[164:167], v[112:115]
	v_mfma_f32_16x16x32_bf16 v[108:111], v[188:191], v[156:159], v[108:111]
	v_mfma_f32_16x16x32_bf16 v[104:107], v[188:191], v[164:167], v[104:107]
	s_waitcnt lgkmcnt(0)
	v_mfma_f32_16x16x32_bf16 v[100:103], v[196:199], v[156:159], v[100:103]
	v_mfma_f32_16x16x32_bf16 v[96:99], v[196:199], v[164:167], v[96:99]
	s_barrier
	s_add_i32 s19, s43, s17
	s_add_i32 s47, s19, 0x100
	s_mov_b32 m0, s1
	ds_read_b128 v[200:203], v144
	ds_read_b128 v[204:207], v145
	ds_read_b128 v[208:211], v146
	ds_read_b128 v[212:215], v147
	buffer_load_dwordx4 v142, s[8:11], s47 offen lds
	s_mov_b32 m0, s3
	s_nop 0
	buffer_load_dwordx4 v143, s[8:11], s47 offen lds
	s_barrier
	s_waitcnt lgkmcnt(0)
	s_waitcnt lgkmcnt(3)
	v_mfma_f32_16x16x32_bf16 v[92:95], v[168:171], v[200:203], v[92:95]
	s_waitcnt lgkmcnt(1)
	v_mfma_f32_16x16x32_bf16 v[88:91], v[168:171], v[208:211], v[88:91]
	v_mfma_f32_16x16x32_bf16 v[84:87], v[176:179], v[200:203], v[84:87]
	v_mfma_f32_16x16x32_bf16 v[80:83], v[176:179], v[208:211], v[80:83]
	v_mfma_f32_16x16x32_bf16 v[76:79], v[184:187], v[200:203], v[76:79]
	v_mfma_f32_16x16x32_bf16 v[72:75], v[184:187], v[208:211], v[72:75]
	v_mfma_f32_16x16x32_bf16 v[68:71], v[192:195], v[200:203], v[68:71]
	v_mfma_f32_16x16x32_bf16 v[64:67], v[192:195], v[208:211], v[64:67]
	v_mfma_f32_16x16x32_bf16 v[92:95], v[172:175], v[204:207], v[92:95]
	s_waitcnt lgkmcnt(0)
	v_mfma_f32_16x16x32_bf16 v[88:91], v[172:175], v[212:215], v[88:91]
	v_mfma_f32_16x16x32_bf16 v[84:87], v[180:183], v[204:207], v[84:87]
	v_mfma_f32_16x16x32_bf16 v[80:83], v[180:183], v[212:215], v[80:83]
	v_mfma_f32_16x16x32_bf16 v[76:79], v[188:191], v[204:207], v[76:79]
	v_mfma_f32_16x16x32_bf16 v[72:75], v[188:191], v[212:215], v[72:75]
	v_mfma_f32_16x16x32_bf16 v[68:71], v[196:199], v[204:207], v[68:71]
	v_mfma_f32_16x16x32_bf16 v[64:67], v[196:199], v[212:215], v[64:67]
	s_add_i32 s47, s42, s17
	s_add_i32 s48, s47, 0x100
	s_mov_b32 m0, s0
	s_barrier
	ds_read_b128 v[168:171], v130 offset:16384
	ds_read_b128 v[172:175], v130 offset:17408
	ds_read_b128 v[176:179], v133 offset:16384
	ds_read_b128 v[180:183], v133 offset:17408
	ds_read_b128 v[184:187], v132 offset:16384
	ds_read_b128 v[188:191], v132 offset:17408
	ds_read_b128 v[192:195], v131 offset:16384
	ds_read_b128 v[196:199], v131 offset:17408
	buffer_load_dwordx4 v142, s[4:7], s48 offen lds
	s_mov_b32 m0, s20
	s_nop 0
	buffer_load_dwordx4 v143, s[4:7], s48 offen lds
	s_barrier
	s_waitcnt lgkmcnt(0)
	s_waitcnt lgkmcnt(7)
	v_mfma_f32_16x16x32_bf16 v[60:63], v[168:171], v[152:155], v[60:63]
	v_mfma_f32_16x16x32_bf16 v[56:59], v[168:171], v[160:163], v[56:59]
	s_waitcnt lgkmcnt(5)
	v_mfma_f32_16x16x32_bf16 v[52:55], v[176:179], v[152:155], v[52:55]
	v_mfma_f32_16x16x32_bf16 v[48:51], v[176:179], v[160:163], v[48:51]
	s_waitcnt lgkmcnt(3)
	v_mfma_f32_16x16x32_bf16 v[44:47], v[184:187], v[152:155], v[44:47]
	v_mfma_f32_16x16x32_bf16 v[40:43], v[184:187], v[160:163], v[40:43]
	s_waitcnt lgkmcnt(1)
	v_mfma_f32_16x16x32_bf16 v[36:39], v[192:195], v[152:155], v[36:39]
	v_mfma_f32_16x16x32_bf16 v[32:35], v[192:195], v[160:163], v[32:35]
	v_mfma_f32_16x16x32_bf16 v[60:63], v[172:175], v[156:159], v[60:63]
	v_mfma_f32_16x16x32_bf16 v[56:59], v[172:175], v[164:167], v[56:59]
	v_mfma_f32_16x16x32_bf16 v[52:55], v[180:183], v[156:159], v[52:55]
	v_mfma_f32_16x16x32_bf16 v[48:51], v[180:183], v[164:167], v[48:51]
	v_mfma_f32_16x16x32_bf16 v[44:47], v[188:191], v[156:159], v[44:47]
	v_mfma_f32_16x16x32_bf16 v[40:43], v[188:191], v[164:167], v[40:43]
	s_waitcnt lgkmcnt(0)
	v_mfma_f32_16x16x32_bf16 v[36:39], v[196:199], v[156:159], v[36:39]
	v_mfma_f32_16x16x32_bf16 v[32:35], v[196:199], v[164:167], v[32:35]
	s_barrier
	s_add_i32 s48, s44, s17
	s_add_i32 s49, s48, 0x100
	s_mov_b32 m0, s21
	s_nop 0
	buffer_load_dwordx4 v142, s[8:11], s49 offen lds
	s_mov_b32 m0, s22
	s_nop 0
	buffer_load_dwordx4 v143, s[8:11], s49 offen lds
	s_waitcnt vmcnt(6)
	s_barrier
; #define STAGE(P, RS, SOFF, OFF, kt) do { const int _so = (SOFF) + (kt) * (BK * 2); \
;     _Pragma("unroll") for (int _i = 0; _i < 2; ++_i) { \
;       __builtin_amdgcn_raw_ptr_buffer_load_lds(RS, (__attribute__((address_space(3))) void*)((P) + wave * 1024 + _i * 8192), 16, OFF[_i], _so, 0, 0); } } while (0)
; #define LDA(dst, b, h) _Pragma("unroll") for (int m = 0; m < 4; ++m) _Pragma("unroll") for (int k = 0; k < 2; ++k) \
;     dst[m][k] = *reinterpret_cast<const bf16x8*>(SA(b, h) + lds_byte(wr * 64 + m * 16 + fr, k * 32 + fq * 8))
; #define LDB(dst, b, h) _Pragma("unroll") for (int n = 0; n < 2; ++n) _Pragma("unroll") for (int k = 0; k < 2; ++k) \
;     dst[n][k] = *reinterpret_cast<const bf16x8*>(SB(b, h) + lds_byte(wc * 32 + n * 16 + fr, k * 32 + fq * 8))
; #define WAIT_V(n) asm volatile("s_waitcnt vmcnt(" #n ")" ::: "memory")
; #define WAIT_L(n) asm volatile("s_waitcnt lgkmcnt(" #n ")" ::: "memory")
; #define BAR __builtin_amdgcn_s_barrier()
; #define SCHED __builtin_amdgcn_sched_barrier(0)
;     ...
;       WAIT_V(6); BAR; MMA(1, 1, At, B1); BAR;
;       LDB(B0, 1, 0); SCHED; LDA(At, 1, 0); STAGE(SA(0, 1), rsA, sA1, offA, t + 2);
;       WAIT_L(8); BAR; WAIT_L(0); MMA(0, 0, At, B0); BAR; SCHED;
;       LDB(B1, 1, 1); STAGE(SB(1, 0), rsB, sB0, offB, t + 3);
;       BAR; WAIT_L(0); MMA(0, 1, At, B1); BAR;
;       LDA(At, 1, 1); STAGE(SA(1, 0), rsA, sA0, offA, t + 3);
	v_mfma_f32_16x16x32_bf16 v[28:31], v[168:171], v[200:203], v[28:31]
	v_mfma_f32_16x16x32_bf16 v[24:27], v[168:171], v[208:211], v[24:27]
	v_mfma_f32_16x16x32_bf16 v[20:23], v[176:179], v[200:203], v[20:23]
	v_mfma_f32_16x16x32_bf16 v[16:19], v[176:179], v[208:211], v[16:19]
	v_mfma_f32_16x16x32_bf16 v[12:15], v[184:187], v[200:203], v[12:15]
	v_mfma_f32_16x16x32_bf16 v[8:11], v[184:187], v[208:211], v[8:11]
	v_mfma_f32_16x16x32_bf16 v[4:7], v[192:195], v[200:203], v[4:7]
	v_mfma_f32_16x16x32_bf16 v[0:3], v[192:195], v[208:211], v[0:3]
	v_mfma_f32_16x16x32_bf16 v[28:31], v[172:175], v[204:207], v[28:31]
	v_mfma_f32_16x16x32_bf16 v[24:27], v[172:175], v[212:215], v[24:27]
	v_mfma_f32_16x16x32_bf16 v[20:23], v[180:183], v[204:207], v[20:23]
	v_mfma_f32_16x16x32_bf16 v[16:19], v[180:183], v[212:215], v[16:19]
	v_mfma_f32_16x16x32_bf16 v[12:15], v[188:191], v[204:207], v[12:15]
	v_mfma_f32_16x16x32_bf16 v[8:11], v[188:191], v[212:215], v[8:11]
	v_mfma_f32_16x16x32_bf16 v[4:7], v[196:199], v[204:207], v[4:7]
	v_mfma_f32_16x16x32_bf16 v[0:3], v[196:199], v[212:215], v[0:3]
	s_barrier
	ds_read_b128 v[152:155], v138
	ds_read_b128 v[156:159], v139
	ds_read_b128 v[160:163], v140
	ds_read_b128 v[164:167], v141
	s_addk_i32 s18, 0x100
	s_mov_b32 m0, s23
	ds_read_b128 v[168:171], v130 offset:32768
	ds_read_b128 v[172:175], v130 offset:33792
	ds_read_b128 v[176:179], v133 offset:32768
	ds_read_b128 v[180:183], v133 offset:33792
	ds_read_b128 v[184:187], v132 offset:32768
	ds_read_b128 v[188:191], v132 offset:33792
	ds_read_b128 v[192:195], v131 offset:32768
	ds_read_b128 v[196:199], v131 offset:33792
	buffer_load_dwordx4 v142, s[4:7], s18 offen lds
	s_mov_b32 m0, s24
	s_nop 0
	buffer_load_dwordx4 v143, s[4:7], s18 offen lds
	s_waitcnt lgkmcnt(8)
	s_barrier
	s_waitcnt lgkmcnt(0)
	s_waitcnt lgkmcnt(7)
	v_mfma_f32_16x16x32_bf16 v[124:127], v[168:171], v[152:155], v[124:127]
	v_mfma_f32_16x16x32_bf16 v[120:123], v[168:171], v[160:163], v[120:123]
	s_waitcnt lgkmcnt(5)
	v_mfma_f32_16x16x32_bf16 v[116:119], v[176:179], v[152:155], v[116:119]
	v_mfma_f32_16x16x32_bf16 v[112:115], v[176:179], v[160:163], v[112:115]
	s_waitcnt lgkmcnt(3)
	v_mfma_f32_16x16x32_bf16 v[108:111], v[184:187], v[152:155], v[108:111]
	v_mfma_f32_16x16x32_bf16 v[104:107], v[184:187], v[160:163], v[104:107]
	s_waitcnt lgkmcnt(1)
	v_mfma_f32_16x16x32_bf16 v[100:103], v[192:195], v[152:155], v[100:103]
	v_mfma_f32_16x16x32_bf16 v[96:99], v[192:195], v[160:163], v[96:99]
	v_mfma_f32_16x16x32_bf16 v[124:127], v[172:175], v[156:159], v[124:127]
	v_mfma_f32_16x16x32_bf16 v[120:123], v[172:175], v[164:167], v[120:123]
	v_mfma_f32_16x16x32_bf16 v[116:119], v[180:183], v[156:159], v[116:119]
	v_mfma_f32_16x16x32_bf16 v[112:115], v[180:183], v[164:167], v[112:115]
	v_mfma_f32_16x16x32_bf16 v[108:111], v[188:191], v[156:159], v[108:111]
	v_mfma_f32_16x16x32_bf16 v[104:107], v[188:191], v[164:167], v[104:107]
	s_waitcnt lgkmcnt(0)
	v_mfma_f32_16x16x32_bf16 v[100:103], v[196:199], v[156:159], v[100:103]
	v_mfma_f32_16x16x32_bf16 v[96:99], v[196:199], v[164:167], v[96:99]
	s_barrier
	s_addk_i32 s19, 0x180
	s_mov_b32 m0, s25
	ds_read_b128 v[200:203], v134
	ds_read_b128 v[204:207], v135
	ds_read_b128 v[208:211], v136
	ds_read_b128 v[212:215], v137
	buffer_load_dwordx4 v142, s[8:11], s19 offen lds
	s_mov_b32 m0, s26
	s_nop 0
	buffer_load_dwordx4 v143, s[8:11], s19 offen lds
	s_barrier
	s_waitcnt lgkmcnt(0)
	s_waitcnt lgkmcnt(3)
	v_mfma_f32_16x16x32_bf16 v[92:95], v[168:171], v[200:203], v[92:95]
	s_waitcnt lgkmcnt(1)
	v_mfma_f32_16x16x32_bf16 v[88:91], v[168:171], v[208:211], v[88:91]
	v_mfma_f32_16x16x32_bf16 v[84:87], v[176:179], v[200:203], v[84:87]
	v_mfma_f32_16x16x32_bf16 v[80:83], v[176:179], v[208:211], v[80:83]
	v_mfma_f32_16x16x32_bf16 v[76:79], v[184:187], v[200:203], v[76:79]
	v_mfma_f32_16x16x32_bf16 v[72:75], v[184:187], v[208:211], v[72:75]
	v_mfma_f32_16x16x32_bf16 v[68:71], v[192:195], v[200:203], v[68:71]
	v_mfma_f32_16x16x32_bf16 v[64:67], v[192:195], v[208:211], v[64:67]
	v_mfma_f32_16x16x32_bf16 v[92:95], v[172:175], v[204:207], v[92:95]
	s_waitcnt lgkmcnt(0)
	v_mfma_f32_16x16x32_bf16 v[88:91], v[172:175], v[212:215], v[88:91]
	v_mfma_f32_16x16x32_bf16 v[84:87], v[180:183], v[204:207], v[84:87]
	v_mfma_f32_16x16x32_bf16 v[80:83], v[180:183], v[212:215], v[80:83]
	v_mfma_f32_16x16x32_bf16 v[76:79], v[188:191], v[204:207], v[76:79]
	v_mfma_f32_16x16x32_bf16 v[72:75], v[188:191], v[212:215], v[72:75]
	v_mfma_f32_16x16x32_bf16 v[68:71], v[196:199], v[204:207], v[68:71]
	v_mfma_f32_16x16x32_bf16 v[64:67], v[196:199], v[212:215], v[64:67]
	s_addk_i32 s47, 0x180
	s_mov_b32 m0, s27
	s_barrier
	ds_read_b128 v[168:171], v130 offset:49152
	ds_read_b128 v[172:175], v130 offset:50176
	ds_read_b128 v[176:179], v133 offset:49152
	ds_read_b128 v[180:183], v133 offset:50176
	ds_read_b128 v[184:187], v132 offset:49152
	ds_read_b128 v[188:191], v132 offset:50176
	ds_read_b128 v[192:195], v131 offset:49152
	ds_read_b128 v[196:199], v131 offset:50176
	buffer_load_dwordx4 v142, s[4:7], s47 offen lds
	s_mov_b32 m0, s28
	s_nop 0
	buffer_load_dwordx4 v143, s[4:7], s47 offen lds
	s_barrier
; #define STAGE(P, RS, SOFF, OFF, kt) do { const int _so = (SOFF) + (kt) * (BK * 2); \
;     _Pragma("unroll") for (int _i = 0; _i < 2; ++_i) { \
;       __builtin_amdgcn_raw_ptr_buffer_load_lds(RS, (__attribute__((address_space(3))) void*)((P) + wave * 1024 + _i * 8192), 16, OFF[_i], _so, 0, 0); } } while (0)
; #define LDA(dst, b, h) _Pragma("unroll") for (int m = 0; m < 4; ++m) _Pragma("unroll") for (int k = 0; k < 2; ++k) \
;     dst[m][k] = *reinterpret_cast<const bf16x8*>(SA(b, h) + lds_byte(wr * 64 + m * 16 + fr, k * 32 + fq * 8))
; #define LDB(dst, b, h) _Pragma("unroll") for (int n = 0; n < 2; ++n) _Pragma("unroll") for (int k = 0; k < 2; ++k) \
;     dst[n][k] = *reinterpret_cast<const bf16x8*>(SB(b, h) + lds_byte(wc * 32 + n * 16 + fr, k * 32 + fq * 8))
; #define WAIT_V(n) asm volatile("s_waitcnt vmcnt(" #n ")" ::: "memory")
; #define WAIT_L(n) asm volatile("s_waitcnt lgkmcnt(" #n ")" ::: "memory")
; #define BAR __builtin_amdgcn_s_barrier()
; #define SCHED __builtin_amdgcn_sched_barrier(0)
;     ...
;       BAR; WAIT_L(0); MMA(1, 0, At, B0); BAR; SCHED;
;       STAGE(SB(1, 1), rsB, sB1, offB, t + 3);
;       WAIT_V(6); BAR; MMA(1, 1, At, B1); BAR;
;     }
;     { LDB(B0, 0, 0); LDA(At, 0, 0); STAGE(SA(1, 1), rsA, sA1, offA, nt - 1);
;       BAR; WAIT_L(0); MMA(0, 0, At, B0); BAR;
;       LDB(B1, 0, 1); BAR; WAIT_L(0); MMA(0, 1, At, B1); BAR;
	s_waitcnt lgkmcnt(0)
	s_waitcnt lgkmcnt(7)
	v_mfma_f32_16x16x32_bf16 v[60:63], v[168:171], v[152:155], v[60:63]
	v_mfma_f32_16x16x32_bf16 v[56:59], v[168:171], v[160:163], v[56:59]
	s_waitcnt lgkmcnt(5)
	v_mfma_f32_16x16x32_bf16 v[52:55], v[176:179], v[152:155], v[52:55]
	v_mfma_f32_16x16x32_bf16 v[48:51], v[176:179], v[160:163], v[48:51]
	s_waitcnt lgkmcnt(3)
	v_mfma_f32_16x16x32_bf16 v[44:47], v[184:187], v[152:155], v[44:47]
	v_mfma_f32_16x16x32_bf16 v[40:43], v[184:187], v[160:163], v[40:43]
	s_waitcnt lgkmcnt(1)
	v_mfma_f32_16x16x32_bf16 v[36:39], v[192:195], v[152:155], v[36:39]
	v_mfma_f32_16x16x32_bf16 v[32:35], v[192:195], v[160:163], v[32:35]
	v_mfma_f32_16x16x32_bf16 v[60:63], v[172:175], v[156:159], v[60:63]
	v_mfma_f32_16x16x32_bf16 v[56:59], v[172:175], v[164:167], v[56:59]
	v_mfma_f32_16x16x32_bf16 v[52:55], v[180:183], v[156:159], v[52:55]
	v_mfma_f32_16x16x32_bf16 v[48:51], v[180:183], v[164:167], v[48:51]
	v_mfma_f32_16x16x32_bf16 v[44:47], v[188:191], v[156:159], v[44:47]
	v_mfma_f32_16x16x32_bf16 v[40:43], v[188:191], v[164:167], v[40:43]
	s_waitcnt lgkmcnt(0)
	v_mfma_f32_16x16x32_bf16 v[36:39], v[196:199], v[156:159], v[36:39]
	v_mfma_f32_16x16x32_bf16 v[32:35], v[196:199], v[164:167], v[32:35]
	s_barrier
	s_addk_i32 s48, 0x180
	s_mov_b32 m0, s29
	s_nop 0
	buffer_load_dwordx4 v142, s[8:11], s48 offen lds
	s_mov_b32 m0, s30
	s_nop 0
	buffer_load_dwordx4 v143, s[8:11], s48 offen lds
	s_waitcnt vmcnt(6)
	s_barrier
	v_mfma_f32_16x16x32_bf16 v[28:31], v[168:171], v[200:203], v[28:31]
	v_mfma_f32_16x16x32_bf16 v[24:27], v[168:171], v[208:211], v[24:27]
	v_mfma_f32_16x16x32_bf16 v[20:23], v[176:179], v[200:203], v[20:23]
	v_mfma_f32_16x16x32_bf16 v[16:19], v[176:179], v[208:211], v[16:19]
	v_mfma_f32_16x16x32_bf16 v[12:15], v[184:187], v[200:203], v[12:15]
	v_mfma_f32_16x16x32_bf16 v[8:11], v[184:187], v[208:211], v[8:11]
	v_mfma_f32_16x16x32_bf16 v[4:7], v[192:195], v[200:203], v[4:7]
	v_mfma_f32_16x16x32_bf16 v[0:3], v[192:195], v[208:211], v[0:3]
	v_mfma_f32_16x16x32_bf16 v[28:31], v[172:175], v[204:207], v[28:31]
	v_mfma_f32_16x16x32_bf16 v[24:27], v[172:175], v[212:215], v[24:27]
	v_mfma_f32_16x16x32_bf16 v[20:23], v[180:183], v[204:207], v[20:23]
	v_mfma_f32_16x16x32_bf16 v[16:19], v[180:183], v[212:215], v[16:19]
	v_mfma_f32_16x16x32_bf16 v[12:15], v[188:191], v[204:207], v[12:15]
	v_mfma_f32_16x16x32_bf16 v[8:11], v[188:191], v[212:215], v[8:11]
	v_mfma_f32_16x16x32_bf16 v[4:7], v[196:199], v[204:207], v[4:7]
	v_mfma_f32_16x16x32_bf16 v[0:3], v[196:199], v[212:215], v[0:3]
	s_add_i32 s16, s16, 2
	s_addk_i32 s17, 0x100
	s_cmp_gt_u32 s16, 27
	s_barrier
	s_cbranch_scc0 .LBB0_225
	s_add_i32 s16, s41, 0xf80
	s_mov_b32 m0, s33
	ds_read_b128 v[152:155], v148
	ds_read_b128 v[156:159], v149
	ds_read_b128 v[160:163], v150
	ds_read_b128 v[148:151], v151
	ds_read_b128 v[164:167], v130
	ds_read_b128 v[168:171], v130 offset:1024
	ds_read_b128 v[172:175], v133
	ds_read_b128 v[176:179], v133 offset:1024
	ds_read_b128 v[180:183], v132
	ds_read_b128 v[184:187], v132 offset:1024
	ds_read_b128 v[188:191], v131
	ds_read_b128 v[192:195], v131 offset:1024
	buffer_load_dwordx4 v142, s[4:7], s16 offen lds
	s_mov_b32 m0, s34
	s_nop 0
	buffer_load_dwordx4 v143, s[4:7], s16 offen lds
	s_barrier
	s_waitcnt lgkmcnt(0)
	s_waitcnt lgkmcnt(7)
	v_mfma_f32_16x16x32_bf16 v[124:127], v[164:167], v[152:155], v[124:127]
	v_mfma_f32_16x16x32_bf16 v[120:123], v[164:167], v[160:163], v[120:123]
	s_waitcnt lgkmcnt(5)
	v_mfma_f32_16x16x32_bf16 v[116:119], v[172:175], v[152:155], v[116:119]
	v_mfma_f32_16x16x32_bf16 v[112:115], v[172:175], v[160:163], v[112:115]
	s_waitcnt lgkmcnt(3)
	v_mfma_f32_16x16x32_bf16 v[108:111], v[180:183], v[152:155], v[108:111]
	v_mfma_f32_16x16x32_bf16 v[104:107], v[180:183], v[160:163], v[104:107]
	s_waitcnt lgkmcnt(1)
	v_mfma_f32_16x16x32_bf16 v[100:103], v[188:191], v[152:155], v[100:103]
	v_mfma_f32_16x16x32_bf16 v[96:99], v[188:191], v[160:163], v[96:99]
	v_mfma_f32_16x16x32_bf16 v[124:127], v[168:171], v[156:159], v[124:127]
	v_mfma_f32_16x16x32_bf16 v[120:123], v[168:171], v[148:151], v[120:123]
	v_mfma_f32_16x16x32_bf16 v[116:119], v[176:179], v[156:159], v[116:119]
	v_mfma_f32_16x16x32_bf16 v[112:115], v[176:179], v[148:151], v[112:115]
	v_mfma_f32_16x16x32_bf16 v[108:111], v[184:187], v[156:159], v[108:111]
	v_mfma_f32_16x16x32_bf16 v[104:107], v[184:187], v[148:151], v[104:107]
	s_waitcnt lgkmcnt(0)
	v_mfma_f32_16x16x32_bf16 v[100:103], v[192:195], v[156:159], v[100:103]
	v_mfma_f32_16x16x32_bf16 v[96:99], v[192:195], v[148:151], v[96:99]
	s_barrier
	ds_read_b128 v[196:199], v144
	ds_read_b128 v[142:145], v145
	ds_read_b128 v[200:203], v146
	ds_read_b128 v[204:207], v147
	s_barrier
	s_waitcnt lgkmcnt(0)
	s_waitcnt lgkmcnt(1)
	v_mfma_f32_16x16x32_bf16 v[88:91], v[164:167], v[200:203], v[88:91]
	v_mfma_f32_16x16x32_bf16 v[84:87], v[172:175], v[196:199], v[84:87]
	v_mfma_f32_16x16x32_bf16 v[80:83], v[172:175], v[200:203], v[80:83]
	v_mfma_f32_16x16x32_bf16 v[76:79], v[180:183], v[196:199], v[76:79]
	v_mfma_f32_16x16x32_bf16 v[72:75], v[180:183], v[200:203], v[72:75]
	v_mfma_f32_16x16x32_bf16 v[68:71], v[188:191], v[196:199], v[68:71]
	v_mfma_f32_16x16x32_bf16 v[64:67], v[188:191], v[200:203], v[64:67]
	v_mfma_f32_16x16x32_bf16 v[92:95], v[164:167], v[196:199], v[92:95]
	s_waitcnt lgkmcnt(0)
	v_mfma_f32_16x16x32_bf16 v[88:91], v[168:171], v[204:207], v[88:91]
	v_mfma_f32_16x16x32_bf16 v[84:87], v[176:179], v[142:145], v[84:87]
	v_mfma_f32_16x16x32_bf16 v[80:83], v[176:179], v[204:207], v[80:83]
	v_mfma_f32_16x16x32_bf16 v[76:79], v[184:187], v[142:145], v[76:79]
	v_mfma_f32_16x16x32_bf16 v[72:75], v[184:187], v[204:207], v[72:75]
	v_mfma_f32_16x16x32_bf16 v[68:71], v[192:195], v[142:145], v[68:71]
	v_mfma_f32_16x16x32_bf16 v[64:67], v[192:195], v[204:207], v[64:67]
	v_mfma_f32_16x16x32_bf16 v[164:167], v[168:171], v[142:145], v[92:95]
	s_barrier
; #define LDA(dst, b, h) _Pragma("unroll") for (int m = 0; m < 4; ++m) _Pragma("unroll") for (int k = 0; k < 2; ++k) \
;     dst[m][k] = *reinterpret_cast<const bf16x8*>(SA(b, h) + lds_byte(wr * 64 + m * 16 + fr, k * 32 + fq * 8))
; #define LDB(dst, b, h) _Pragma("unroll") for (int n = 0; n < 2; ++n) _Pragma("unroll") for (int k = 0; k < 2; ++k) \
;     dst[n][k] = *reinterpret_cast<const bf16x8*>(SB(b, h) + lds_byte(wc * 32 + n * 16 + fr, k * 32 + fq * 8))
; #define WAIT_V(n) asm volatile("s_waitcnt vmcnt(" #n ")" ::: "memory")
; #define WAIT_L(n) asm volatile("s_waitcnt lgkmcnt(" #n ")" ::: "memory")
; #define BAR __builtin_amdgcn_s_barrier()
;     ...
;       LDA(At, 0, 1); WAIT_V(4); BAR; WAIT_L(0); MMA(1, 0, At, B0); MMA(1, 1, At, B1); BAR; }
;     { LDB(B0, 1, 0); LDA(At, 1, 0); WAIT_V(2); BAR; WAIT_L(0); MMA(0, 0, At, B0); BAR;
	s_nop 0
	ds_read_b128 v[92:95], v130 offset:16384
	ds_read_b128 v[168:171], v130 offset:17408
	ds_read_b128 v[172:175], v133 offset:16384
	ds_read_b128 v[176:179], v133 offset:17408
	ds_read_b128 v[180:183], v132 offset:16384
	ds_read_b128 v[184:187], v132 offset:17408
	ds_read_b128 v[188:191], v131 offset:16384
	ds_read_b128 v[192:195], v131 offset:17408
	s_waitcnt vmcnt(4)
	s_barrier
	s_waitcnt lgkmcnt(0)
	s_waitcnt lgkmcnt(7)
	v_mfma_f32_16x16x32_bf16 v[60:63], v[92:95], v[152:155], v[60:63]
	v_mfma_f32_16x16x32_bf16 v[56:59], v[92:95], v[160:163], v[56:59]
	s_waitcnt lgkmcnt(5)
	v_mfma_f32_16x16x32_bf16 v[52:55], v[172:175], v[152:155], v[52:55]
	v_mfma_f32_16x16x32_bf16 v[48:51], v[172:175], v[160:163], v[48:51]
	s_waitcnt lgkmcnt(3)
	v_mfma_f32_16x16x32_bf16 v[44:47], v[180:183], v[152:155], v[44:47]
	v_mfma_f32_16x16x32_bf16 v[40:43], v[180:183], v[160:163], v[40:43]
	s_waitcnt lgkmcnt(1)
	v_mfma_f32_16x16x32_bf16 v[36:39], v[188:191], v[152:155], v[36:39]
	v_mfma_f32_16x16x32_bf16 v[32:35], v[188:191], v[160:163], v[32:35]
	v_mfma_f32_16x16x32_bf16 v[60:63], v[168:171], v[156:159], v[60:63]
	v_mfma_f32_16x16x32_bf16 v[56:59], v[168:171], v[148:151], v[56:59]
	v_mfma_f32_16x16x32_bf16 v[52:55], v[176:179], v[156:159], v[52:55]
	v_mfma_f32_16x16x32_bf16 v[48:51], v[176:179], v[148:151], v[48:51]
	v_mfma_f32_16x16x32_bf16 v[44:47], v[184:187], v[156:159], v[44:47]
	v_mfma_f32_16x16x32_bf16 v[40:43], v[184:187], v[148:151], v[40:43]
	s_waitcnt lgkmcnt(0)
	v_mfma_f32_16x16x32_bf16 v[36:39], v[192:195], v[156:159], v[36:39]
	v_mfma_f32_16x16x32_bf16 v[32:35], v[192:195], v[148:151], v[32:35]
	v_mfma_f32_16x16x32_bf16 v[28:31], v[92:95], v[196:199], v[28:31]
	v_mfma_f32_16x16x32_bf16 v[24:27], v[92:95], v[200:203], v[24:27]
	v_mfma_f32_16x16x32_bf16 v[20:23], v[172:175], v[196:199], v[20:23]
	v_mfma_f32_16x16x32_bf16 v[16:19], v[172:175], v[200:203], v[16:19]
	v_mfma_f32_16x16x32_bf16 v[12:15], v[180:183], v[196:199], v[12:15]
	v_mfma_f32_16x16x32_bf16 v[8:11], v[180:183], v[200:203], v[8:11]
	v_mfma_f32_16x16x32_bf16 v[4:7], v[188:191], v[196:199], v[4:7]
	v_mfma_f32_16x16x32_bf16 v[0:3], v[188:191], v[200:203], v[0:3]
	v_mfma_f32_16x16x32_bf16 v[28:31], v[168:171], v[142:145], v[28:31]
	v_mfma_f32_16x16x32_bf16 v[24:27], v[168:171], v[204:207], v[24:27]
	v_mfma_f32_16x16x32_bf16 v[20:23], v[176:179], v[142:145], v[20:23]
	v_mfma_f32_16x16x32_bf16 v[16:19], v[176:179], v[204:207], v[16:19]
	v_mfma_f32_16x16x32_bf16 v[12:15], v[184:187], v[142:145], v[12:15]
	v_mfma_f32_16x16x32_bf16 v[8:11], v[184:187], v[204:207], v[8:11]
	v_mfma_f32_16x16x32_bf16 v[4:7], v[192:195], v[142:145], v[4:7]
	v_mfma_f32_16x16x32_bf16 v[0:3], v[192:195], v[204:207], v[0:3]
	s_barrier
	ds_read_b128 v[142:145], v138
	ds_read_b128 v[146:149], v139
	ds_read_b128 v[150:153], v140
	ds_read_b128 v[138:141], v141
	ds_read_b128 v[154:157], v130 offset:32768
	ds_read_b128 v[158:161], v130 offset:33792
	ds_read_b128 v[168:171], v133 offset:32768
	ds_read_b128 v[172:175], v133 offset:33792
	ds_read_b128 v[176:179], v132 offset:32768
	ds_read_b128 v[180:183], v132 offset:33792
	ds_read_b128 v[184:187], v131 offset:32768
	ds_read_b128 v[188:191], v131 offset:33792
	s_waitcnt vmcnt(2)
	s_barrier
	s_waitcnt lgkmcnt(0)
	s_waitcnt lgkmcnt(7)
	v_mfma_f32_16x16x32_bf16 v[92:95], v[154:157], v[142:145], v[124:127]
	v_mfma_f32_16x16x32_bf16 v[120:123], v[154:157], v[150:153], v[120:123]
	s_waitcnt lgkmcnt(5)
	v_mfma_f32_16x16x32_bf16 v[116:119], v[168:171], v[142:145], v[116:119]
	v_mfma_f32_16x16x32_bf16 v[112:115], v[168:171], v[150:153], v[112:115]
	s_waitcnt lgkmcnt(3)
	v_mfma_f32_16x16x32_bf16 v[108:111], v[176:179], v[142:145], v[108:111]
	v_mfma_f32_16x16x32_bf16 v[104:107], v[176:179], v[150:153], v[104:107]
	s_waitcnt lgkmcnt(1)
	v_mfma_f32_16x16x32_bf16 v[100:103], v[184:187], v[142:145], v[100:103]
	v_mfma_f32_16x16x32_bf16 v[96:99], v[184:187], v[150:153], v[96:99]
	v_mfma_f32_16x16x32_bf16 v[124:127], v[158:161], v[146:149], v[92:95]
	v_mfma_f32_16x16x32_bf16 v[120:123], v[158:161], v[138:141], v[120:123]
	v_mfma_f32_16x16x32_bf16 v[116:119], v[172:175], v[146:149], v[116:119]
	v_mfma_f32_16x16x32_bf16 v[112:115], v[172:175], v[138:141], v[112:115]
	v_mfma_f32_16x16x32_bf16 v[108:111], v[180:183], v[146:149], v[108:111]
	v_mfma_f32_16x16x32_bf16 v[104:107], v[180:183], v[138:141], v[104:107]
	s_waitcnt lgkmcnt(0)
	v_mfma_f32_16x16x32_bf16 v[100:103], v[188:191], v[146:149], v[100:103]
	v_mfma_f32_16x16x32_bf16 v[92:95], v[188:191], v[138:141], v[96:99]
	s_barrier
; #define LDA(dst, b, h) _Pragma("unroll") for (int m = 0; m < 4; ++m) _Pragma("unroll") for (int k = 0; k < 2; ++k) \
;     dst[m][k] = *reinterpret_cast<const bf16x8*>(SA(b, h) + lds_byte(wr * 64 + m * 16 + fr, k * 32 + fq * 8))
; #define LDB(dst, b, h) _Pragma("unroll") for (int n = 0; n < 2; ++n) _Pragma("unroll") for (int k = 0; k < 2; ++k) \
;     dst[n][k] = *reinterpret_cast<const bf16x8*>(SB(b, h) + lds_byte(wc * 32 + n * 16 + fr, k * 32 + fq * 8))
; #define WAIT_V(n) asm volatile("s_waitcnt vmcnt(" #n ")" ::: "memory")
; #define WAIT_L(n) asm volatile("s_waitcnt lgkmcnt(" #n ")" ::: "memory")
; #define BAR __builtin_amdgcn_s_barrier()
;     ...
;       LDB(B1, 1, 1); WAIT_V(0); BAR; WAIT_L(0); MMA(0, 1, At, B1); BAR;
;       LDA(At, 1, 1); BAR; WAIT_L(0); MMA(1, 0, At, B0); MMA(1, 1, At, B1); BAR; }
;     if (wr == 0) BAR;
	ds_read_b128 v[192:195], v134
	ds_read_b128 v[196:199], v135
	ds_read_b128 v[200:203], v136
	ds_read_b128 v[134:137], v137
	s_waitcnt vmcnt(0)
	s_barrier
	s_waitcnt lgkmcnt(0)
	s_waitcnt lgkmcnt(3)
	v_mfma_f32_16x16x32_bf16 v[96:99], v[154:157], v[192:195], v[164:167]
	s_waitcnt lgkmcnt(1)
	v_mfma_f32_16x16x32_bf16 v[88:91], v[154:157], v[200:203], v[88:91]
	v_mfma_f32_16x16x32_bf16 v[84:87], v[168:171], v[192:195], v[84:87]
	v_mfma_f32_16x16x32_bf16 v[80:83], v[168:171], v[200:203], v[80:83]
	v_mfma_f32_16x16x32_bf16 v[76:79], v[176:179], v[192:195], v[76:79]
	v_mfma_f32_16x16x32_bf16 v[72:75], v[176:179], v[200:203], v[72:75]
	v_mfma_f32_16x16x32_bf16 v[68:71], v[184:187], v[192:195], v[68:71]
	v_mfma_f32_16x16x32_bf16 v[64:67], v[184:187], v[200:203], v[64:67]
	v_mfma_f32_16x16x32_bf16 v[96:99], v[158:161], v[196:199], v[96:99]
	s_waitcnt lgkmcnt(0)
	v_mfma_f32_16x16x32_bf16 v[88:91], v[158:161], v[134:137], v[88:91]
	v_mfma_f32_16x16x32_bf16 v[84:87], v[172:175], v[196:199], v[84:87]
	v_mfma_f32_16x16x32_bf16 v[80:83], v[172:175], v[134:137], v[80:83]
	v_mfma_f32_16x16x32_bf16 v[76:79], v[180:183], v[196:199], v[76:79]
	v_mfma_f32_16x16x32_bf16 v[72:75], v[180:183], v[134:137], v[72:75]
	v_mfma_f32_16x16x32_bf16 v[68:71], v[188:191], v[196:199], v[68:71]
	v_mfma_f32_16x16x32_bf16 v[64:67], v[188:191], v[134:137], v[64:67]
	s_barrier
	ds_read_b128 v[154:157], v130 offset:49152
	ds_read_b128 v[158:161], v130 offset:50176
	ds_read_b128 v[162:165], v133 offset:49152
	ds_read_b128 v[166:169], v133 offset:50176
	ds_read_b128 v[170:173], v132 offset:49152
	ds_read_b128 v[174:177], v132 offset:50176
	ds_read_b128 v[178:181], v131 offset:49152
	ds_read_b128 v[130:133], v131 offset:50176
	s_barrier
	s_waitcnt lgkmcnt(0)
	s_waitcnt lgkmcnt(7)
	v_mfma_f32_16x16x32_bf16 v[60:63], v[154:157], v[142:145], v[60:63]
	v_mfma_f32_16x16x32_bf16 v[56:59], v[154:157], v[150:153], v[56:59]
	s_waitcnt lgkmcnt(5)
	v_mfma_f32_16x16x32_bf16 v[52:55], v[162:165], v[142:145], v[52:55]
	v_mfma_f32_16x16x32_bf16 v[48:51], v[162:165], v[150:153], v[48:51]
	s_waitcnt lgkmcnt(3)
	v_mfma_f32_16x16x32_bf16 v[44:47], v[170:173], v[142:145], v[44:47]
	v_mfma_f32_16x16x32_bf16 v[40:43], v[170:173], v[150:153], v[40:43]
	s_waitcnt lgkmcnt(1)
	v_mfma_f32_16x16x32_bf16 v[36:39], v[178:181], v[142:145], v[36:39]
	v_mfma_f32_16x16x32_bf16 v[32:35], v[178:181], v[150:153], v[32:35]
	v_mfma_f32_16x16x32_bf16 v[60:63], v[158:161], v[146:149], v[60:63]
	v_mfma_f32_16x16x32_bf16 v[56:59], v[158:161], v[138:141], v[56:59]
	v_mfma_f32_16x16x32_bf16 v[52:55], v[166:169], v[146:149], v[52:55]
	v_mfma_f32_16x16x32_bf16 v[48:51], v[166:169], v[138:141], v[48:51]
	v_mfma_f32_16x16x32_bf16 v[44:47], v[174:177], v[146:149], v[44:47]
	v_mfma_f32_16x16x32_bf16 v[40:43], v[174:177], v[138:141], v[40:43]
	s_waitcnt lgkmcnt(0)
	v_mfma_f32_16x16x32_bf16 v[36:39], v[130:133], v[146:149], v[36:39]
	v_mfma_f32_16x16x32_bf16 v[32:35], v[130:133], v[138:141], v[32:35]
	v_mfma_f32_16x16x32_bf16 v[28:31], v[154:157], v[192:195], v[28:31]
	v_mfma_f32_16x16x32_bf16 v[24:27], v[154:157], v[200:203], v[24:27]
	v_mfma_f32_16x16x32_bf16 v[20:23], v[162:165], v[192:195], v[20:23]
	v_mfma_f32_16x16x32_bf16 v[16:19], v[162:165], v[200:203], v[16:19]
	v_mfma_f32_16x16x32_bf16 v[12:15], v[170:173], v[192:195], v[12:15]
	v_mfma_f32_16x16x32_bf16 v[8:11], v[170:173], v[200:203], v[8:11]
	v_mfma_f32_16x16x32_bf16 v[4:7], v[178:181], v[192:195], v[4:7]
	v_mfma_f32_16x16x32_bf16 v[0:3], v[178:181], v[200:203], v[0:3]
	v_mfma_f32_16x16x32_bf16 v[28:31], v[158:161], v[196:199], v[28:31]
	v_mfma_f32_16x16x32_bf16 v[24:27], v[158:161], v[134:137], v[24:27]
	v_mfma_f32_16x16x32_bf16 v[20:23], v[166:169], v[196:199], v[20:23]
	v_mfma_f32_16x16x32_bf16 v[16:19], v[166:169], v[134:137], v[16:19]
	v_mfma_f32_16x16x32_bf16 v[12:15], v[174:177], v[196:199], v[12:15]
	v_mfma_f32_16x16x32_bf16 v[8:11], v[174:177], v[134:137], v[8:11]
	v_mfma_f32_16x16x32_bf16 v[4:7], v[130:133], v[196:199], v[4:7]
	v_mfma_f32_16x16x32_bf16 v[0:3], v[130:133], v[134:137], v[0:3]
	v_cmp_gt_u32_e32 vcc, s37, v129
	s_barrier
	s_and_saveexec_b64 s[16:17], vcc
	s_cbranch_execz .LBB0_228
	s_barrier

; #define STAGE(P, RS, SOFF, OFF, kt) do { const int _so = (SOFF) + (kt) * (BK * 2); \
;     _Pragma("unroll") for (int _i = 0; _i < 2; ++_i) { \
;       __builtin_amdgcn_raw_ptr_buffer_load_lds(RS, (__attribute__((address_space(3))) void*)((P) + wave * 1024 + _i * 8192), 16, OFF[_i], _so, 0, 0); } } while (0)
; #define LDA(dst, b, h) _Pragma("unroll") for (int m = 0; m < 4; ++m) _Pragma("unroll") for (int k = 0; k < 2; ++k) \
;     dst[m][k] = *reinterpret_cast<const bf16x8*>(SA(b, h) + lds_byte(wr * 64 + m * 16 + fr, k * 32 + fq * 8))
; #define LDB(dst, b, h) _Pragma("unroll") for (int n = 0; n < 2; ++n) _Pragma("unroll") for (int k = 0; k < 2; ++k) \
;     dst[n][k] = *reinterpret_cast<const bf16x8*>(SB(b, h) + lds_byte(wc * 32 + n * 16 + fr, k * 32 + fq * 8))
; #define WAIT_V(n) asm volatile("s_waitcnt vmcnt(" #n ")" ::: "memory")
; #define WAIT_L(n) asm volatile("s_waitcnt lgkmcnt(" #n ")" ::: "memory")
; #define BAR __builtin_amdgcn_s_barrier()
; #define SCHED __builtin_amdgcn_sched_barrier(0)
;     ...
;       LDB(B0, 0, 0); SCHED; LDA(At, 0, 0); STAGE(SA(1, 1), rsA, sA1, offA, t + 1);
;       WAIT_L(8); BAR; WAIT_L(0); MMA(0, 0, At, B0); BAR; SCHED;
;       LDB(B1, 0, 1); STAGE(SB(0, 0), rsB, sB0, offB, t + 2);
;       BAR; WAIT_L(0); MMA(0, 1, At, B1); BAR;
;       LDA(At, 0, 1); STAGE(SA(0, 0), rsA, sA0, offA, t + 2);
;       BAR; WAIT_L(0); MMA(1, 0, At, B0); BAR; SCHED;
;       STAGE(SB(0, 1), rsB, sB1, offB, t + 2);
;       WAIT_V(6); BAR; MMA(1, 1, At, B1); BAR;
.LBB0_291:
	ds_read_b128 v[152:155], v147
	ds_read_b128 v[156:159], v148
	ds_read_b128 v[160:163], v149
	ds_read_b128 v[164:167], v150
	s_add_i32 s5, s94, s3
	s_add_i32 s6, s5, 0x80
	s_mov_b32 m0, s36
	ds_read_b128 v[168:171], v129
	ds_read_b128 v[172:175], v129 offset:1024
	ds_read_b128 v[176:179], v132
	ds_read_b128 v[180:183], v132 offset:1024
	ds_read_b128 v[184:187], v131
	ds_read_b128 v[188:191], v131 offset:1024
	ds_read_b128 v[192:195], v130
	ds_read_b128 v[196:199], v130 offset:1024
	buffer_load_dwordx4 v141, s[8:11], s6 offen lds
	s_mov_b32 m0, s61
	s_nop 0
	buffer_load_dwordx4 v142, s[8:11], s6 offen lds
	s_waitcnt lgkmcnt(8)
	s_barrier
	s_waitcnt lgkmcnt(0)
	s_waitcnt lgkmcnt(7)
	v_mfma_f32_16x16x32_bf16 v[124:127], v[152:155], v[168:171], v[124:127]
	v_mfma_f32_16x16x32_bf16 v[120:123], v[160:163], v[168:171], v[120:123]
	s_waitcnt lgkmcnt(5)
	v_mfma_f32_16x16x32_bf16 v[116:119], v[152:155], v[176:179], v[116:119]
	v_mfma_f32_16x16x32_bf16 v[112:115], v[160:163], v[176:179], v[112:115]
	s_waitcnt lgkmcnt(3)
	v_mfma_f32_16x16x32_bf16 v[108:111], v[152:155], v[184:187], v[108:111]
	v_mfma_f32_16x16x32_bf16 v[104:107], v[160:163], v[184:187], v[104:107]
	s_waitcnt lgkmcnt(1)
	v_mfma_f32_16x16x32_bf16 v[100:103], v[152:155], v[192:195], v[100:103]
	v_mfma_f32_16x16x32_bf16 v[96:99], v[160:163], v[192:195], v[96:99]
	v_mfma_f32_16x16x32_bf16 v[124:127], v[156:159], v[172:175], v[124:127]
	v_mfma_f32_16x16x32_bf16 v[120:123], v[164:167], v[172:175], v[120:123]
	v_mfma_f32_16x16x32_bf16 v[116:119], v[156:159], v[180:183], v[116:119]
	v_mfma_f32_16x16x32_bf16 v[112:115], v[164:167], v[180:183], v[112:115]
	v_mfma_f32_16x16x32_bf16 v[108:111], v[156:159], v[188:191], v[108:111]
	v_mfma_f32_16x16x32_bf16 v[104:107], v[164:167], v[188:191], v[104:107]
	s_waitcnt lgkmcnt(0)
	v_mfma_f32_16x16x32_bf16 v[100:103], v[156:159], v[196:199], v[100:103]
	v_mfma_f32_16x16x32_bf16 v[96:99], v[164:167], v[196:199], v[96:99]
	s_barrier
	s_add_i32 s6, s96, s3
	s_add_i32 s7, s6, 0x100
	s_mov_b32 s14, s10
	s_mov_b32 s15, s11
	s_mov_b32 m0, s37
	ds_read_b128 v[200:203], v143
	ds_read_b128 v[204:207], v144
	ds_read_b128 v[208:211], v145
	ds_read_b128 v[212:215], v146
	buffer_load_dwordx4 v141, s[12:15], s7 offen lds
	s_mov_b32 m0, s48
	s_nop 0
	buffer_load_dwordx4 v142, s[12:15], s7 offen lds
	s_barrier
	s_waitcnt lgkmcnt(0)
	s_waitcnt lgkmcnt(3)
	v_mfma_f32_16x16x32_bf16 v[92:95], v[200:203], v[168:171], v[92:95]
	s_waitcnt lgkmcnt(1)
	v_mfma_f32_16x16x32_bf16 v[88:91], v[208:211], v[168:171], v[88:91]
	v_mfma_f32_16x16x32_bf16 v[80:83], v[200:203], v[176:179], v[80:83]
	v_mfma_f32_16x16x32_bf16 v[68:71], v[208:211], v[176:179], v[68:71]
	v_mfma_f32_16x16x32_bf16 v[60:63], v[200:203], v[184:187], v[60:63]
	v_mfma_f32_16x16x32_bf16 v[56:59], v[208:211], v[184:187], v[56:59]
	v_mfma_f32_16x16x32_bf16 v[52:55], v[200:203], v[192:195], v[52:55]
	v_mfma_f32_16x16x32_bf16 v[48:51], v[208:211], v[192:195], v[48:51]
	v_mfma_f32_16x16x32_bf16 v[92:95], v[204:207], v[172:175], v[92:95]
	s_waitcnt lgkmcnt(0)
	v_mfma_f32_16x16x32_bf16 v[88:91], v[212:215], v[172:175], v[88:91]
	v_mfma_f32_16x16x32_bf16 v[80:83], v[204:207], v[180:183], v[80:83]
	v_mfma_f32_16x16x32_bf16 v[68:71], v[212:215], v[180:183], v[68:71]
	v_mfma_f32_16x16x32_bf16 v[60:63], v[204:207], v[188:191], v[60:63]
	v_mfma_f32_16x16x32_bf16 v[56:59], v[212:215], v[188:191], v[56:59]
	v_mfma_f32_16x16x32_bf16 v[52:55], v[204:207], v[196:199], v[52:55]
	v_mfma_f32_16x16x32_bf16 v[48:51], v[212:215], v[196:199], v[48:51]
	s_add_i32 s7, s95, s3
	s_add_i32 s22, s7, 0x100
	s_mov_b32 m0, s35
	s_barrier
	ds_read_b128 v[168:171], v129 offset:16384
	ds_read_b128 v[172:175], v129 offset:17408
	ds_read_b128 v[176:179], v132 offset:16384
	ds_read_b128 v[180:183], v132 offset:17408
	ds_read_b128 v[184:187], v131 offset:16384
	ds_read_b128 v[188:191], v131 offset:17408
	ds_read_b128 v[192:195], v130 offset:16384
	ds_read_b128 v[196:199], v130 offset:17408
	buffer_load_dwordx4 v141, s[8:11], s22 offen lds
	s_mov_b32 m0, s49
	s_nop 0
	buffer_load_dwordx4 v142, s[8:11], s22 offen lds
	s_barrier
	s_waitcnt lgkmcnt(0)
	s_waitcnt lgkmcnt(7)
	v_mfma_f32_16x16x32_bf16 v[44:47], v[152:155], v[168:171], v[44:47]
	v_mfma_f32_16x16x32_bf16 v[40:43], v[160:163], v[168:171], v[40:43]
	s_waitcnt lgkmcnt(5)
	v_mfma_f32_16x16x32_bf16 v[36:39], v[152:155], v[176:179], v[36:39]
	v_mfma_f32_16x16x32_bf16 v[32:35], v[160:163], v[176:179], v[32:35]
	s_waitcnt lgkmcnt(3)
	v_mfma_f32_16x16x32_bf16 v[28:31], v[152:155], v[184:187], v[28:31]
	v_mfma_f32_16x16x32_bf16 v[24:27], v[160:163], v[184:187], v[24:27]
	s_waitcnt lgkmcnt(1)
	v_mfma_f32_16x16x32_bf16 v[20:23], v[152:155], v[192:195], v[20:23]
	v_mfma_f32_16x16x32_bf16 v[16:19], v[160:163], v[192:195], v[16:19]
	v_mfma_f32_16x16x32_bf16 v[44:47], v[156:159], v[172:175], v[44:47]
	v_mfma_f32_16x16x32_bf16 v[40:43], v[164:167], v[172:175], v[40:43]
	v_mfma_f32_16x16x32_bf16 v[36:39], v[156:159], v[180:183], v[36:39]
	v_mfma_f32_16x16x32_bf16 v[32:35], v[164:167], v[180:183], v[32:35]
	v_mfma_f32_16x16x32_bf16 v[28:31], v[156:159], v[188:191], v[28:31]
	v_mfma_f32_16x16x32_bf16 v[24:27], v[164:167], v[188:191], v[24:27]
	s_waitcnt lgkmcnt(0)
	v_mfma_f32_16x16x32_bf16 v[20:23], v[156:159], v[196:199], v[20:23]
	v_mfma_f32_16x16x32_bf16 v[16:19], v[164:167], v[196:199], v[16:19]
	s_barrier
	s_add_i32 s22, s97, s3
	s_add_i32 s23, s22, 0x100
	s_mov_b32 m0, s38
	s_nop 0
	buffer_load_dwordx4 v141, s[12:15], s23 offen lds
	s_mov_b32 m0, s54
	s_nop 0
	buffer_load_dwordx4 v142, s[12:15], s23 offen lds
	s_waitcnt vmcnt(6)
	s_barrier
; #define STAGE(P, RS, SOFF, OFF, kt) do { const int _so = (SOFF) + (kt) * (BK * 2); \
;     _Pragma("unroll") for (int _i = 0; _i < 2; ++_i) { \
;       __builtin_amdgcn_raw_ptr_buffer_load_lds(RS, (__attribute__((address_space(3))) void*)((P) + wave * 1024 + _i * 8192), 16, OFF[_i], _so, 0, 0); } } while (0)
; #define LDA(dst, b, h) _Pragma("unroll") for (int m = 0; m < 4; ++m) _Pragma("unroll") for (int k = 0; k < 2; ++k) \
;     dst[m][k] = *reinterpret_cast<const bf16x8*>(SA(b, h) + lds_byte(wr * 64 + m * 16 + fr, k * 32 + fq * 8))
; #define LDB(dst, b, h) _Pragma("unroll") for (int n = 0; n < 2; ++n) _Pragma("unroll") for (int k = 0; k < 2; ++k) \
;     dst[n][k] = *reinterpret_cast<const bf16x8*>(SB(b, h) + lds_byte(wc * 32 + n * 16 + fr, k * 32 + fq * 8))
; #define WAIT_V(n) asm volatile("s_waitcnt vmcnt(" #n ")" ::: "memory")
; #define WAIT_L(n) asm volatile("s_waitcnt lgkmcnt(" #n ")" ::: "memory")
; #define BAR __builtin_amdgcn_s_barrier()
; #define SCHED __builtin_amdgcn_sched_barrier(0)
;     ...
;       WAIT_V(6); BAR; MMA(1, 1, At, B1); BAR;
;       LDB(B0, 1, 0); SCHED; LDA(At, 1, 0); STAGE(SA(0, 1), rsA, sA1, offA, t + 2);
;       WAIT_L(8); BAR; WAIT_L(0); MMA(0, 0, At, B0); BAR; SCHED;
;       LDB(B1, 1, 1); STAGE(SB(1, 0), rsB, sB0, offB, t + 3);
;       BAR; WAIT_L(0); MMA(0, 1, At, B1); BAR;
;       LDA(At, 1, 1); STAGE(SA(1, 0), rsA, sA0, offA, t + 3);
;       BAR; WAIT_L(0); MMA(1, 0, At, B0); BAR; SCHED;
;       STAGE(SB(1, 1), rsB, sB1, offB, t + 3);
	v_mfma_f32_16x16x32_bf16 v[12:15], v[200:203], v[168:171], v[12:15]
	v_mfma_f32_16x16x32_bf16 v[8:11], v[208:211], v[168:171], v[8:11]
	v_mfma_f32_16x16x32_bf16 v[4:7], v[200:203], v[176:179], v[4:7]
	v_mfma_f32_16x16x32_bf16 v[0:3], v[208:211], v[176:179], v[0:3]
	v_mfma_f32_16x16x32_bf16 v[64:67], v[200:203], v[184:187], v[64:67]
	v_mfma_f32_16x16x32_bf16 v[72:75], v[208:211], v[184:187], v[72:75]
	v_mfma_f32_16x16x32_bf16 v[76:79], v[200:203], v[192:195], v[76:79]
	v_mfma_f32_16x16x32_bf16 v[84:87], v[208:211], v[192:195], v[84:87]
	v_mfma_f32_16x16x32_bf16 v[12:15], v[204:207], v[172:175], v[12:15]
	v_mfma_f32_16x16x32_bf16 v[8:11], v[212:215], v[172:175], v[8:11]
	v_mfma_f32_16x16x32_bf16 v[4:7], v[204:207], v[180:183], v[4:7]
	v_mfma_f32_16x16x32_bf16 v[0:3], v[212:215], v[180:183], v[0:3]
	v_mfma_f32_16x16x32_bf16 v[64:67], v[204:207], v[188:191], v[64:67]
	v_mfma_f32_16x16x32_bf16 v[72:75], v[212:215], v[188:191], v[72:75]
	v_mfma_f32_16x16x32_bf16 v[76:79], v[204:207], v[196:199], v[76:79]
	v_mfma_f32_16x16x32_bf16 v[84:87], v[212:215], v[196:199], v[84:87]
	s_barrier
	ds_read_b128 v[152:155], v137
	ds_read_b128 v[156:159], v138
	ds_read_b128 v[160:163], v139
	ds_read_b128 v[164:167], v140
	s_addk_i32 s5, 0x100
	s_mov_b32 m0, s39
	ds_read_b128 v[168:171], v129 offset:32768
	ds_read_b128 v[172:175], v129 offset:33792
	ds_read_b128 v[176:179], v132 offset:32768
	ds_read_b128 v[180:183], v132 offset:33792
	ds_read_b128 v[184:187], v131 offset:32768
	ds_read_b128 v[188:191], v131 offset:33792
	ds_read_b128 v[192:195], v130 offset:32768
	ds_read_b128 v[196:199], v130 offset:33792
	buffer_load_dwordx4 v141, s[8:11], s5 offen lds
	s_mov_b32 m0, s55
	s_nop 0
	buffer_load_dwordx4 v142, s[8:11], s5 offen lds
	s_waitcnt lgkmcnt(8)
	s_barrier
	s_waitcnt lgkmcnt(0)
	s_waitcnt lgkmcnt(7)
	v_mfma_f32_16x16x32_bf16 v[124:127], v[152:155], v[168:171], v[124:127]
	v_mfma_f32_16x16x32_bf16 v[120:123], v[160:163], v[168:171], v[120:123]
	s_waitcnt lgkmcnt(5)
	v_mfma_f32_16x16x32_bf16 v[116:119], v[152:155], v[176:179], v[116:119]
	v_mfma_f32_16x16x32_bf16 v[112:115], v[160:163], v[176:179], v[112:115]
	s_waitcnt lgkmcnt(3)
	v_mfma_f32_16x16x32_bf16 v[108:111], v[152:155], v[184:187], v[108:111]
	v_mfma_f32_16x16x32_bf16 v[104:107], v[160:163], v[184:187], v[104:107]
	s_waitcnt lgkmcnt(1)
	v_mfma_f32_16x16x32_bf16 v[100:103], v[152:155], v[192:195], v[100:103]
	v_mfma_f32_16x16x32_bf16 v[96:99], v[160:163], v[192:195], v[96:99]
	v_mfma_f32_16x16x32_bf16 v[124:127], v[156:159], v[172:175], v[124:127]
	v_mfma_f32_16x16x32_bf16 v[120:123], v[164:167], v[172:175], v[120:123]
	v_mfma_f32_16x16x32_bf16 v[116:119], v[156:159], v[180:183], v[116:119]
	v_mfma_f32_16x16x32_bf16 v[112:115], v[164:167], v[180:183], v[112:115]
	v_mfma_f32_16x16x32_bf16 v[108:111], v[156:159], v[188:191], v[108:111]
	v_mfma_f32_16x16x32_bf16 v[104:107], v[164:167], v[188:191], v[104:107]
	s_waitcnt lgkmcnt(0)
	v_mfma_f32_16x16x32_bf16 v[100:103], v[156:159], v[196:199], v[100:103]
	v_mfma_f32_16x16x32_bf16 v[96:99], v[164:167], v[196:199], v[96:99]
	s_barrier
	s_addk_i32 s6, 0x180
	s_mov_b32 m0, s42
	ds_read_b128 v[200:203], v133
	ds_read_b128 v[204:207], v134
	ds_read_b128 v[208:211], v135
	ds_read_b128 v[212:215], v136
	buffer_load_dwordx4 v141, s[12:15], s6 offen lds
	s_mov_b32 m0, s58
	s_nop 0
	buffer_load_dwordx4 v142, s[12:15], s6 offen lds
	s_barrier
	s_waitcnt lgkmcnt(0)
	s_waitcnt lgkmcnt(3)
	v_mfma_f32_16x16x32_bf16 v[92:95], v[200:203], v[168:171], v[92:95]
	s_waitcnt lgkmcnt(1)
	v_mfma_f32_16x16x32_bf16 v[88:91], v[208:211], v[168:171], v[88:91]
	v_mfma_f32_16x16x32_bf16 v[80:83], v[200:203], v[176:179], v[80:83]
	v_mfma_f32_16x16x32_bf16 v[68:71], v[208:211], v[176:179], v[68:71]
	v_mfma_f32_16x16x32_bf16 v[60:63], v[200:203], v[184:187], v[60:63]
	v_mfma_f32_16x16x32_bf16 v[56:59], v[208:211], v[184:187], v[56:59]
	v_mfma_f32_16x16x32_bf16 v[52:55], v[200:203], v[192:195], v[52:55]
	v_mfma_f32_16x16x32_bf16 v[48:51], v[208:211], v[192:195], v[48:51]
	v_mfma_f32_16x16x32_bf16 v[92:95], v[204:207], v[172:175], v[92:95]
	s_waitcnt lgkmcnt(0)
	v_mfma_f32_16x16x32_bf16 v[88:91], v[212:215], v[172:175], v[88:91]
	v_mfma_f32_16x16x32_bf16 v[80:83], v[204:207], v[180:183], v[80:83]
	v_mfma_f32_16x16x32_bf16 v[68:71], v[212:215], v[180:183], v[68:71]
	v_mfma_f32_16x16x32_bf16 v[60:63], v[204:207], v[188:191], v[60:63]
	v_mfma_f32_16x16x32_bf16 v[56:59], v[212:215], v[188:191], v[56:59]
	v_mfma_f32_16x16x32_bf16 v[52:55], v[204:207], v[196:199], v[52:55]
	v_mfma_f32_16x16x32_bf16 v[48:51], v[212:215], v[196:199], v[48:51]
	s_addk_i32 s7, 0x180
	s_mov_b32 m0, s43
	s_barrier
	ds_read_b128 v[168:171], v129 offset:49152
	ds_read_b128 v[172:175], v129 offset:50176
	ds_read_b128 v[176:179], v132 offset:49152
	ds_read_b128 v[180:183], v132 offset:50176
	ds_read_b128 v[184:187], v131 offset:49152
	ds_read_b128 v[188:191], v131 offset:50176
	ds_read_b128 v[192:195], v130 offset:49152
	ds_read_b128 v[196:199], v130 offset:50176
	buffer_load_dwordx4 v141, s[8:11], s7 offen lds
	s_mov_b32 m0, s59
	s_nop 0
	buffer_load_dwordx4 v142, s[8:11], s7 offen lds
	s_barrier
; #define STAGE(P, RS, SOFF, OFF, kt) do { const int _so = (SOFF) + (kt) * (BK * 2); \
;     _Pragma("unroll") for (int _i = 0; _i < 2; ++_i) { \
;       __builtin_amdgcn_raw_ptr_buffer_load_lds(RS, (__attribute__((address_space(3))) void*)((P) + wave * 1024 + _i * 8192), 16, OFF[_i], _so, 0, 0); } } while (0)
; #define LDA(dst, b, h) _Pragma("unroll") for (int m = 0; m < 4; ++m) _Pragma("unroll") for (int k = 0; k < 2; ++k) \
;     dst[m][k] = *reinterpret_cast<const bf16x8*>(SA(b, h) + lds_byte(wr * 64 + m * 16 + fr, k * 32 + fq * 8))
; #define LDB(dst, b, h) _Pragma("unroll") for (int n = 0; n < 2; ++n) _Pragma("unroll") for (int k = 0; k < 2; ++k) \
;     dst[n][k] = *reinterpret_cast<const bf16x8*>(SB(b, h) + lds_byte(wc * 32 + n * 16 + fr, k * 32 + fq * 8))
; #define WAIT_V(n) asm volatile("s_waitcnt vmcnt(" #n ")" ::: "memory")
; #define WAIT_L(n) asm volatile("s_waitcnt lgkmcnt(" #n ")" ::: "memory")
; #define BAR __builtin_amdgcn_s_barrier()
; #define SCHED __builtin_amdgcn_sched_barrier(0)
;     ...
;       BAR; WAIT_L(0); MMA(1, 0, At, B0); BAR; SCHED;
;       STAGE(SB(1, 1), rsB, sB1, offB, t + 3);
;       WAIT_V(6); BAR; MMA(1, 1, At, B1); BAR;
;     }
;     { LDB(B0, 0, 0); LDA(At, 0, 0); STAGE(SA(1, 1), rsA, sA1, offA, nt - 1);
;       BAR; WAIT_L(0); MMA(0, 0, At, B0); BAR;
;       LDB(B1, 0, 1); BAR; WAIT_L(0); MMA(0, 1, At, B1); BAR;
	s_waitcnt lgkmcnt(0)
	s_waitcnt lgkmcnt(7)
	v_mfma_f32_16x16x32_bf16 v[44:47], v[152:155], v[168:171], v[44:47]
	v_mfma_f32_16x16x32_bf16 v[40:43], v[160:163], v[168:171], v[40:43]
	s_waitcnt lgkmcnt(5)
	v_mfma_f32_16x16x32_bf16 v[36:39], v[152:155], v[176:179], v[36:39]
	v_mfma_f32_16x16x32_bf16 v[32:35], v[160:163], v[176:179], v[32:35]
	s_waitcnt lgkmcnt(3)
	v_mfma_f32_16x16x32_bf16 v[28:31], v[152:155], v[184:187], v[28:31]
	v_mfma_f32_16x16x32_bf16 v[24:27], v[160:163], v[184:187], v[24:27]
	s_waitcnt lgkmcnt(1)
	v_mfma_f32_16x16x32_bf16 v[20:23], v[152:155], v[192:195], v[20:23]
	v_mfma_f32_16x16x32_bf16 v[16:19], v[160:163], v[192:195], v[16:19]
	v_mfma_f32_16x16x32_bf16 v[44:47], v[156:159], v[172:175], v[44:47]
	v_mfma_f32_16x16x32_bf16 v[40:43], v[164:167], v[172:175], v[40:43]
	v_mfma_f32_16x16x32_bf16 v[36:39], v[156:159], v[180:183], v[36:39]
	v_mfma_f32_16x16x32_bf16 v[32:35], v[164:167], v[180:183], v[32:35]
	v_mfma_f32_16x16x32_bf16 v[28:31], v[156:159], v[188:191], v[28:31]
	v_mfma_f32_16x16x32_bf16 v[24:27], v[164:167], v[188:191], v[24:27]
	s_waitcnt lgkmcnt(0)
	v_mfma_f32_16x16x32_bf16 v[20:23], v[156:159], v[196:199], v[20:23]
	v_mfma_f32_16x16x32_bf16 v[16:19], v[164:167], v[196:199], v[16:19]
	s_barrier
	s_addk_i32 s22, 0x180
	s_mov_b32 m0, s44
	s_nop 0
	buffer_load_dwordx4 v141, s[12:15], s22 offen lds
	s_mov_b32 m0, s60
	s_nop 0
	buffer_load_dwordx4 v142, s[12:15], s22 offen lds
	s_waitcnt vmcnt(6)
	s_barrier
	v_mfma_f32_16x16x32_bf16 v[12:15], v[200:203], v[168:171], v[12:15]
	v_mfma_f32_16x16x32_bf16 v[8:11], v[208:211], v[168:171], v[8:11]
	v_mfma_f32_16x16x32_bf16 v[4:7], v[200:203], v[176:179], v[4:7]
	v_mfma_f32_16x16x32_bf16 v[0:3], v[208:211], v[176:179], v[0:3]
	v_mfma_f32_16x16x32_bf16 v[64:67], v[200:203], v[184:187], v[64:67]
	v_mfma_f32_16x16x32_bf16 v[72:75], v[208:211], v[184:187], v[72:75]
	v_mfma_f32_16x16x32_bf16 v[76:79], v[200:203], v[192:195], v[76:79]
	v_mfma_f32_16x16x32_bf16 v[84:87], v[208:211], v[192:195], v[84:87]
	v_mfma_f32_16x16x32_bf16 v[12:15], v[204:207], v[172:175], v[12:15]
	v_mfma_f32_16x16x32_bf16 v[8:11], v[212:215], v[172:175], v[8:11]
	v_mfma_f32_16x16x32_bf16 v[4:7], v[204:207], v[180:183], v[4:7]
	v_mfma_f32_16x16x32_bf16 v[0:3], v[212:215], v[180:183], v[0:3]
	v_mfma_f32_16x16x32_bf16 v[64:67], v[204:207], v[188:191], v[64:67]
	v_mfma_f32_16x16x32_bf16 v[72:75], v[212:215], v[188:191], v[72:75]
	v_mfma_f32_16x16x32_bf16 v[76:79], v[204:207], v[196:199], v[76:79]
	v_mfma_f32_16x16x32_bf16 v[84:87], v[212:215], v[196:199], v[84:87]
	s_add_i32 s1, s1, 2
	s_addk_i32 s3, 0x100
	s_cmp_gt_u32 s1, 11
	s_barrier
	s_cbranch_scc0 .LBB0_291
	s_add_i32 s1, s94, 0x780
	s_mov_b32 m0, s36
	ds_read_b128 v[152:155], v147
	ds_read_b128 v[156:159], v148
	ds_read_b128 v[160:163], v149
	ds_read_b128 v[148:151], v150
	ds_read_b128 v[164:167], v129
	ds_read_b128 v[168:171], v129 offset:1024
	ds_read_b128 v[172:175], v132
	ds_read_b128 v[176:179], v132 offset:1024
	ds_read_b128 v[180:183], v131
	ds_read_b128 v[184:187], v131 offset:1024
	ds_read_b128 v[188:191], v130
	ds_read_b128 v[192:195], v130 offset:1024
	buffer_load_dwordx4 v141, s[8:11], s1 offen lds
	s_mov_b32 m0, s61
	s_nop 0
	buffer_load_dwordx4 v142, s[8:11], s1 offen lds
	s_barrier
	s_waitcnt lgkmcnt(0)
	s_waitcnt lgkmcnt(7)
	v_mfma_f32_16x16x32_bf16 v[124:127], v[152:155], v[164:167], v[124:127]
	v_mfma_f32_16x16x32_bf16 v[120:123], v[160:163], v[164:167], v[120:123]
	s_waitcnt lgkmcnt(5)
	v_mfma_f32_16x16x32_bf16 v[116:119], v[152:155], v[172:175], v[116:119]
	v_mfma_f32_16x16x32_bf16 v[112:115], v[160:163], v[172:175], v[112:115]
	s_waitcnt lgkmcnt(3)
	v_mfma_f32_16x16x32_bf16 v[108:111], v[152:155], v[180:183], v[108:111]
	v_mfma_f32_16x16x32_bf16 v[104:107], v[160:163], v[180:183], v[104:107]
	s_waitcnt lgkmcnt(1)
	v_mfma_f32_16x16x32_bf16 v[100:103], v[152:155], v[188:191], v[100:103]
	v_mfma_f32_16x16x32_bf16 v[96:99], v[160:163], v[188:191], v[96:99]
	v_mfma_f32_16x16x32_bf16 v[124:127], v[156:159], v[168:171], v[124:127]
	v_mfma_f32_16x16x32_bf16 v[120:123], v[148:151], v[168:171], v[120:123]
	v_mfma_f32_16x16x32_bf16 v[116:119], v[156:159], v[176:179], v[116:119]
	v_mfma_f32_16x16x32_bf16 v[112:115], v[148:151], v[176:179], v[112:115]
	v_mfma_f32_16x16x32_bf16 v[108:111], v[156:159], v[184:187], v[108:111]
	v_mfma_f32_16x16x32_bf16 v[104:107], v[148:151], v[184:187], v[104:107]
	s_waitcnt lgkmcnt(0)
	v_mfma_f32_16x16x32_bf16 v[100:103], v[156:159], v[192:195], v[100:103]
	v_mfma_f32_16x16x32_bf16 v[96:99], v[148:151], v[192:195], v[96:99]
	s_barrier
	ds_read_b128 v[196:199], v143
	ds_read_b128 v[200:203], v144
	ds_read_b128 v[142:145], v145
	ds_read_b128 v[204:207], v146
	s_barrier
	s_waitcnt lgkmcnt(0)
	s_waitcnt lgkmcnt(1)
	v_mfma_f32_16x16x32_bf16 v[88:91], v[142:145], v[164:167], v[88:91]
	v_mfma_f32_16x16x32_bf16 v[80:83], v[196:199], v[172:175], v[80:83]
	v_mfma_f32_16x16x32_bf16 v[60:63], v[196:199], v[180:183], v[60:63]
	v_mfma_f32_16x16x32_bf16 v[56:59], v[142:145], v[180:183], v[56:59]
	v_mfma_f32_16x16x32_bf16 v[52:55], v[196:199], v[188:191], v[52:55]
	v_mfma_f32_16x16x32_bf16 v[48:51], v[142:145], v[188:191], v[48:51]
	v_mfma_f32_16x16x32_bf16 v[92:95], v[196:199], v[164:167], v[92:95]
	v_mfma_f32_16x16x32_bf16 v[68:71], v[142:145], v[172:175], v[68:71]
	s_waitcnt lgkmcnt(0)
	v_mfma_f32_16x16x32_bf16 v[88:91], v[204:207], v[168:171], v[88:91]
	v_mfma_f32_16x16x32_bf16 v[80:83], v[200:203], v[176:179], v[80:83]
	v_mfma_f32_16x16x32_bf16 v[60:63], v[200:203], v[184:187], v[60:63]
	v_mfma_f32_16x16x32_bf16 v[56:59], v[204:207], v[184:187], v[56:59]
	v_mfma_f32_16x16x32_bf16 v[52:55], v[200:203], v[192:195], v[52:55]
	v_mfma_f32_16x16x32_bf16 v[48:51], v[204:207], v[192:195], v[48:51]
	v_mfma_f32_16x16x32_bf16 v[164:167], v[200:203], v[168:171], v[92:95]
	v_mfma_f32_16x16x32_bf16 v[168:171], v[204:207], v[176:179], v[68:71]
	s_barrier
; #define LDA(dst, b, h) _Pragma("unroll") for (int m = 0; m < 4; ++m) _Pragma("unroll") for (int k = 0; k < 2; ++k) \
;     dst[m][k] = *reinterpret_cast<const bf16x8*>(SA(b, h) + lds_byte(wr * 64 + m * 16 + fr, k * 32 + fq * 8))
; #define LDB(dst, b, h) _Pragma("unroll") for (int n = 0; n < 2; ++n) _Pragma("unroll") for (int k = 0; k < 2; ++k) \
;     dst[n][k] = *reinterpret_cast<const bf16x8*>(SB(b, h) + lds_byte(wc * 32 + n * 16 + fr, k * 32 + fq * 8))
; #define WAIT_V(n) asm volatile("s_waitcnt vmcnt(" #n ")" ::: "memory")
; #define WAIT_L(n) asm volatile("s_waitcnt lgkmcnt(" #n ")" ::: "memory")
; #define BAR __builtin_amdgcn_s_barrier()
;     ...
;       LDB(B1, 0, 1); BAR; WAIT_L(0); MMA(0, 1, At, B1); BAR;
;       LDA(At, 0, 1); WAIT_V(4); BAR; WAIT_L(0); MMA(1, 0, At, B0); MMA(1, 1, At, B1); BAR; }
;     { LDB(B0, 1, 0); LDA(At, 1, 0); WAIT_V(2); BAR; WAIT_L(0); MMA(0, 0, At, B0); BAR;
;       LDB(B1, 1, 1); WAIT_V(0); BAR; WAIT_L(0); MMA(0, 1, At, B1); BAR;
	s_nop 0
	ds_read_b128 v[68:71], v129 offset:16384
	ds_read_b128 v[92:95], v129 offset:17408
	ds_read_b128 v[172:175], v132 offset:16384
	ds_read_b128 v[176:179], v132 offset:17408
	ds_read_b128 v[180:183], v131 offset:16384
	ds_read_b128 v[184:187], v131 offset:17408
	ds_read_b128 v[188:191], v130 offset:16384
	ds_read_b128 v[192:195], v130 offset:17408
	s_waitcnt vmcnt(4)
	s_barrier
	s_waitcnt lgkmcnt(0)
	s_waitcnt lgkmcnt(7)
	v_mfma_f32_16x16x32_bf16 v[44:47], v[152:155], v[68:71], v[44:47]
	v_mfma_f32_16x16x32_bf16 v[40:43], v[160:163], v[68:71], v[40:43]
	s_waitcnt lgkmcnt(5)
	v_mfma_f32_16x16x32_bf16 v[36:39], v[152:155], v[172:175], v[36:39]
	v_mfma_f32_16x16x32_bf16 v[32:35], v[160:163], v[172:175], v[32:35]
	s_waitcnt lgkmcnt(3)
	v_mfma_f32_16x16x32_bf16 v[28:31], v[152:155], v[180:183], v[28:31]
	v_mfma_f32_16x16x32_bf16 v[24:27], v[160:163], v[180:183], v[24:27]
	s_waitcnt lgkmcnt(1)
	v_mfma_f32_16x16x32_bf16 v[20:23], v[152:155], v[188:191], v[20:23]
	v_mfma_f32_16x16x32_bf16 v[16:19], v[160:163], v[188:191], v[16:19]
	v_mfma_f32_16x16x32_bf16 v[44:47], v[156:159], v[92:95], v[44:47]
	v_mfma_f32_16x16x32_bf16 v[40:43], v[148:151], v[92:95], v[40:43]
	v_mfma_f32_16x16x32_bf16 v[36:39], v[156:159], v[176:179], v[36:39]
	v_mfma_f32_16x16x32_bf16 v[32:35], v[148:151], v[176:179], v[32:35]
	v_mfma_f32_16x16x32_bf16 v[28:31], v[156:159], v[184:187], v[28:31]
	v_mfma_f32_16x16x32_bf16 v[24:27], v[148:151], v[184:187], v[24:27]
	s_waitcnt lgkmcnt(0)
	v_mfma_f32_16x16x32_bf16 v[20:23], v[156:159], v[192:195], v[20:23]
	v_mfma_f32_16x16x32_bf16 v[16:19], v[148:151], v[192:195], v[16:19]
	v_mfma_f32_16x16x32_bf16 v[4:7], v[196:199], v[172:175], v[4:7]
	v_mfma_f32_16x16x32_bf16 v[0:3], v[142:145], v[172:175], v[0:3]
	v_mfma_f32_16x16x32_bf16 v[12:15], v[196:199], v[68:71], v[12:15]
	v_mfma_f32_16x16x32_bf16 v[8:11], v[142:145], v[68:71], v[8:11]
	v_mfma_f32_16x16x32_bf16 v[64:67], v[196:199], v[180:183], v[64:67]
	v_mfma_f32_16x16x32_bf16 v[68:71], v[142:145], v[180:183], v[72:75]
	v_mfma_f32_16x16x32_bf16 v[72:75], v[196:199], v[188:191], v[76:79]
	v_mfma_f32_16x16x32_bf16 v[76:79], v[142:145], v[188:191], v[84:87]
	v_mfma_f32_16x16x32_bf16 v[4:7], v[200:203], v[176:179], v[4:7]
	v_mfma_f32_16x16x32_bf16 v[0:3], v[204:207], v[176:179], v[0:3]
	v_mfma_f32_16x16x32_bf16 v[142:145], v[200:203], v[92:95], v[12:15]
	v_mfma_f32_16x16x32_bf16 v[146:149], v[204:207], v[92:95], v[8:11]
	v_mfma_f32_16x16x32_bf16 v[150:153], v[200:203], v[184:187], v[64:67]
	v_mfma_f32_16x16x32_bf16 v[154:157], v[204:207], v[184:187], v[68:71]
	v_mfma_f32_16x16x32_bf16 v[158:161], v[200:203], v[192:195], v[72:75]
	v_mfma_f32_16x16x32_bf16 v[172:175], v[204:207], v[192:195], v[76:79]
	s_barrier
	ds_read_b128 v[8:11], v137
	ds_read_b128 v[12:15], v138
	ds_read_b128 v[176:179], v139
	ds_read_b128 v[138:141], v140
	ds_read_b128 v[64:67], v129 offset:32768
	ds_read_b128 v[72:75], v129 offset:33792
	ds_read_b128 v[180:183], v132 offset:32768
	ds_read_b128 v[184:187], v132 offset:33792
	ds_read_b128 v[188:191], v131 offset:32768
	ds_read_b128 v[192:195], v131 offset:33792
	ds_read_b128 v[196:199], v130 offset:32768
	ds_read_b128 v[200:203], v130 offset:33792
	s_waitcnt vmcnt(2)
	s_barrier
	s_waitcnt lgkmcnt(0)
	s_waitcnt lgkmcnt(7)
	v_mfma_f32_16x16x32_bf16 v[68:71], v[8:11], v[64:67], v[124:127]
	v_mfma_f32_16x16x32_bf16 v[76:79], v[176:179], v[64:67], v[120:123]
	s_waitcnt lgkmcnt(5)
	v_mfma_f32_16x16x32_bf16 v[84:87], v[8:11], v[180:183], v[116:119]
	v_mfma_f32_16x16x32_bf16 v[92:95], v[176:179], v[180:183], v[112:115]
	s_waitcnt lgkmcnt(3)
	v_mfma_f32_16x16x32_bf16 v[112:115], v[8:11], v[188:191], v[108:111]
	v_mfma_f32_16x16x32_bf16 v[104:107], v[176:179], v[188:191], v[104:107]
	s_waitcnt lgkmcnt(1)
	v_mfma_f32_16x16x32_bf16 v[120:123], v[8:11], v[196:199], v[100:103]
	v_mfma_f32_16x16x32_bf16 v[96:99], v[176:179], v[196:199], v[96:99]
	v_mfma_f32_16x16x32_bf16 v[124:127], v[12:15], v[72:75], v[68:71]
	v_mfma_f32_16x16x32_bf16 v[116:119], v[138:141], v[72:75], v[76:79]
	v_mfma_f32_16x16x32_bf16 v[108:111], v[12:15], v[184:187], v[84:87]
	v_mfma_f32_16x16x32_bf16 v[100:103], v[138:141], v[184:187], v[92:95]
	v_mfma_f32_16x16x32_bf16 v[92:95], v[12:15], v[192:195], v[112:115]
	v_mfma_f32_16x16x32_bf16 v[84:87], v[138:141], v[192:195], v[104:107]
	s_waitcnt lgkmcnt(0)
	v_mfma_f32_16x16x32_bf16 v[76:79], v[12:15], v[200:203], v[120:123]
	v_mfma_f32_16x16x32_bf16 v[68:71], v[138:141], v[200:203], v[96:99]
	s_barrier
; #define LDA(dst, b, h) _Pragma("unroll") for (int m = 0; m < 4; ++m) _Pragma("unroll") for (int k = 0; k < 2; ++k) \
;     dst[m][k] = *reinterpret_cast<const bf16x8*>(SA(b, h) + lds_byte(wr * 64 + m * 16 + fr, k * 32 + fq * 8))
; #define LDB(dst, b, h) _Pragma("unroll") for (int n = 0; n < 2; ++n) _Pragma("unroll") for (int k = 0; k < 2; ++k) \
;     dst[n][k] = *reinterpret_cast<const bf16x8*>(SB(b, h) + lds_byte(wc * 32 + n * 16 + fr, k * 32 + fq * 8))
; #define WAIT_V(n) asm volatile("s_waitcnt vmcnt(" #n ")" ::: "memory")
; #define WAIT_L(n) asm volatile("s_waitcnt lgkmcnt(" #n ")" ::: "memory")
; #define BAR __builtin_amdgcn_s_barrier()
;     ...
;     { LDB(B0, 1, 0); LDA(At, 1, 0); WAIT_V(2); BAR; WAIT_L(0); MMA(0, 0, At, B0); BAR;
;       LDB(B1, 1, 1); WAIT_V(0); BAR; WAIT_L(0); MMA(0, 1, At, B1); BAR;
;       LDA(At, 1, 1); BAR; WAIT_L(0); MMA(1, 0, At, B0); MMA(1, 1, At, B1); BAR; }
;     if (wr == 0) BAR;
	ds_read_b128 v[204:207], v133
	ds_read_b128 v[208:211], v134
	ds_read_b128 v[212:215], v135
	ds_read_b128 v[134:137], v136
	s_waitcnt vmcnt(0)
	s_barrier
	s_waitcnt lgkmcnt(0)
	s_waitcnt lgkmcnt(3)
	v_mfma_f32_16x16x32_bf16 v[96:99], v[204:207], v[64:67], v[164:167]
	s_waitcnt lgkmcnt(1)
	v_mfma_f32_16x16x32_bf16 v[64:67], v[212:215], v[64:67], v[88:91]
	v_mfma_f32_16x16x32_bf16 v[80:83], v[204:207], v[180:183], v[80:83]
	v_mfma_f32_16x16x32_bf16 v[88:91], v[212:215], v[180:183], v[168:171]
	v_mfma_f32_16x16x32_bf16 v[60:63], v[204:207], v[188:191], v[60:63]
	v_mfma_f32_16x16x32_bf16 v[56:59], v[212:215], v[188:191], v[56:59]
	v_mfma_f32_16x16x32_bf16 v[52:55], v[204:207], v[196:199], v[52:55]
	v_mfma_f32_16x16x32_bf16 v[48:51], v[212:215], v[196:199], v[48:51]
	v_mfma_f32_16x16x32_bf16 v[120:123], v[208:211], v[72:75], v[96:99]
	s_waitcnt lgkmcnt(0)
	v_mfma_f32_16x16x32_bf16 v[112:115], v[134:137], v[72:75], v[64:67]
	v_mfma_f32_16x16x32_bf16 v[104:107], v[208:211], v[184:187], v[80:83]
	v_mfma_f32_16x16x32_bf16 v[96:99], v[134:137], v[184:187], v[88:91]
	v_mfma_f32_16x16x32_bf16 v[88:91], v[208:211], v[192:195], v[60:63]
	v_mfma_f32_16x16x32_bf16 v[80:83], v[134:137], v[192:195], v[56:59]
	v_mfma_f32_16x16x32_bf16 v[72:75], v[208:211], v[200:203], v[52:55]
	v_mfma_f32_16x16x32_bf16 v[64:67], v[134:137], v[200:203], v[48:51]
	s_barrier
	s_nop 0
	ds_read_b128 v[48:51], v129 offset:49152
	ds_read_b128 v[162:165], v129 offset:50176
	ds_read_b128 v[52:55], v132 offset:49152
	ds_read_b128 v[166:169], v132 offset:50176
	ds_read_b128 v[180:183], v131 offset:49152
	ds_read_b128 v[184:187], v131 offset:50176
	ds_read_b128 v[188:191], v130 offset:49152
	ds_read_b128 v[130:133], v130 offset:50176
	s_barrier
	s_waitcnt lgkmcnt(0)
	s_waitcnt lgkmcnt(7)
	v_mfma_f32_16x16x32_bf16 v[44:47], v[8:11], v[48:51], v[44:47]
	v_mfma_f32_16x16x32_bf16 v[40:43], v[176:179], v[48:51], v[40:43]
	s_waitcnt lgkmcnt(5)
	v_mfma_f32_16x16x32_bf16 v[36:39], v[8:11], v[52:55], v[36:39]
	v_mfma_f32_16x16x32_bf16 v[32:35], v[176:179], v[52:55], v[32:35]
	s_waitcnt lgkmcnt(3)
	v_mfma_f32_16x16x32_bf16 v[28:31], v[8:11], v[180:183], v[28:31]
	v_mfma_f32_16x16x32_bf16 v[24:27], v[176:179], v[180:183], v[24:27]
	s_waitcnt lgkmcnt(1)
	v_mfma_f32_16x16x32_bf16 v[8:11], v[8:11], v[188:191], v[20:23]
	v_mfma_f32_16x16x32_bf16 v[16:19], v[176:179], v[188:191], v[16:19]
	v_mfma_f32_16x16x32_bf16 v[60:63], v[12:15], v[162:165], v[44:47]
	v_mfma_f32_16x16x32_bf16 v[56:59], v[138:141], v[162:165], v[40:43]
	v_mfma_f32_16x16x32_bf16 v[44:47], v[12:15], v[166:169], v[36:39]
	v_mfma_f32_16x16x32_bf16 v[40:43], v[138:141], v[166:169], v[32:35]
	v_mfma_f32_16x16x32_bf16 v[28:31], v[12:15], v[184:187], v[28:31]
	v_mfma_f32_16x16x32_bf16 v[24:27], v[138:141], v[184:187], v[24:27]
	s_waitcnt lgkmcnt(0)
	v_mfma_f32_16x16x32_bf16 v[12:15], v[12:15], v[130:133], v[8:11]
	v_mfma_f32_16x16x32_bf16 v[8:11], v[138:141], v[130:133], v[16:19]
	v_mfma_f32_16x16x32_bf16 v[16:19], v[204:207], v[48:51], v[142:145]
	v_mfma_f32_16x16x32_bf16 v[20:23], v[212:215], v[48:51], v[146:149]
	v_mfma_f32_16x16x32_bf16 v[4:7], v[204:207], v[52:55], v[4:7]
	v_mfma_f32_16x16x32_bf16 v[0:3], v[212:215], v[52:55], v[0:3]
	v_mfma_f32_16x16x32_bf16 v[138:141], v[204:207], v[180:183], v[150:153]
	v_mfma_f32_16x16x32_bf16 v[142:145], v[212:215], v[180:183], v[154:157]
	v_mfma_f32_16x16x32_bf16 v[146:149], v[204:207], v[188:191], v[158:161]
	v_mfma_f32_16x16x32_bf16 v[150:153], v[212:215], v[188:191], v[172:175]
	v_mfma_f32_16x16x32_bf16 v[52:55], v[208:211], v[162:165], v[16:19]
	v_mfma_f32_16x16x32_bf16 v[48:51], v[134:137], v[162:165], v[20:23]
	v_mfma_f32_16x16x32_bf16 v[36:39], v[208:211], v[166:169], v[4:7]
	v_mfma_f32_16x16x32_bf16 v[32:35], v[134:137], v[166:169], v[0:3]
	v_mfma_f32_16x16x32_bf16 v[20:23], v[208:211], v[184:187], v[138:141]
	v_mfma_f32_16x16x32_bf16 v[16:19], v[134:137], v[184:187], v[142:145]
	v_mfma_f32_16x16x32_bf16 v[4:7], v[208:211], v[130:133], v[146:149]
	v_mfma_f32_16x16x32_bf16 v[0:3], v[134:137], v[130:133], v[150:153]
	v_cmp_gt_u32_e32 vcc, s46, v128
	s_barrier
	s_and_saveexec_b64 s[6:7], vcc
	s_cbranch_execz .LBB0_294
	s_barrier

; #define STAGE(P, RS, SOFF, OFF, kt) do { const int _so = (SOFF) + (kt) * (BK * 2); \
;     _Pragma("unroll") for (int _i = 0; _i < 2; ++_i) { \
;       __builtin_amdgcn_raw_ptr_buffer_load_lds(RS, (__attribute__((address_space(3))) void*)((P) + wave * 1024 + _i * 8192), 16, OFF[_i], _so, 0, 0); } } while (0)
; #define LDA(dst, b, h) _Pragma("unroll") for (int m = 0; m < 4; ++m) _Pragma("unroll") for (int k = 0; k < 2; ++k) \
;     dst[m][k] = *reinterpret_cast<const bf16x8*>(SA(b, h) + lds_byte(wr * 64 + m * 16 + fr, k * 32 + fq * 8))
; #define LDB(dst, b, h) _Pragma("unroll") for (int n = 0; n < 2; ++n) _Pragma("unroll") for (int k = 0; k < 2; ++k) \
;     dst[n][k] = *reinterpret_cast<const bf16x8*>(SB(b, h) + lds_byte(wc * 32 + n * 16 + fr, k * 32 + fq * 8))
; #define WAIT_V(n) asm volatile("s_waitcnt vmcnt(" #n ")" ::: "memory")
; #define WAIT_L(n) asm volatile("s_waitcnt lgkmcnt(" #n ")" ::: "memory")
; #define BAR __builtin_amdgcn_s_barrier()
; #define SCHED __builtin_amdgcn_sched_barrier(0)
;     ...
;       LDB(B0, 0, 0); SCHED; LDA(At, 0, 0); STAGE(SA(1, 1), rsA, sA1, offA, t + 1);
;       WAIT_L(8); BAR; WAIT_L(0); MMA(0, 0, At, B0); BAR; SCHED;
;       LDB(B1, 0, 1); STAGE(SB(0, 0), rsB, sB0, offB, t + 2);
;       BAR; WAIT_L(0); MMA(0, 1, At, B1); BAR;
;       LDA(At, 0, 1); STAGE(SA(0, 0), rsA, sA0, offA, t + 2);
;       BAR; WAIT_L(0); MMA(1, 0, At, B0); BAR; SCHED;
;       STAGE(SB(0, 1), rsB, sB1, offB, t + 2);
;       WAIT_V(6); BAR; MMA(1, 1, At, B1); BAR;
.LBB0_354:
	ds_read_b128 v[154:157], v149
	ds_read_b128 v[158:161], v150
	ds_read_b128 v[162:165], v151
	ds_read_b128 v[166:169], v152
	s_add_i32 s43, s37, s17
	s_add_i32 s10, s43, 0x80
	s_mov_b32 m0, s30
	ds_read_b128 v[170:173], v131
	ds_read_b128 v[174:177], v131 offset:1024
	ds_read_b128 v[178:181], v134
	ds_read_b128 v[182:185], v134 offset:1024
	ds_read_b128 v[186:189], v133
	ds_read_b128 v[190:193], v133 offset:1024
	ds_read_b128 v[194:197], v132
	ds_read_b128 v[198:201], v132 offset:1024
	buffer_load_dwordx4 v143, s[4:7], s10 offen lds
	s_mov_b32 m0, s31
	s_nop 0
	buffer_load_dwordx4 v144, s[4:7], s10 offen lds
	s_waitcnt lgkmcnt(8)
	s_barrier
	s_waitcnt lgkmcnt(0)
	s_waitcnt lgkmcnt(7)
	v_mfma_f32_16x16x32_bf16 v[124:127], v[154:157], v[170:173], v[124:127]
	v_mfma_f32_16x16x32_bf16 v[120:123], v[162:165], v[170:173], v[120:123]
	s_waitcnt lgkmcnt(5)
	v_mfma_f32_16x16x32_bf16 v[116:119], v[154:157], v[178:181], v[116:119]
	v_mfma_f32_16x16x32_bf16 v[112:115], v[162:165], v[178:181], v[112:115]
	s_waitcnt lgkmcnt(3)
	v_mfma_f32_16x16x32_bf16 v[108:111], v[154:157], v[186:189], v[108:111]
	v_mfma_f32_16x16x32_bf16 v[104:107], v[162:165], v[186:189], v[104:107]
	s_waitcnt lgkmcnt(1)
	v_mfma_f32_16x16x32_bf16 v[100:103], v[154:157], v[194:197], v[100:103]
	v_mfma_f32_16x16x32_bf16 v[96:99], v[162:165], v[194:197], v[96:99]
	v_mfma_f32_16x16x32_bf16 v[124:127], v[158:161], v[174:177], v[124:127]
	v_mfma_f32_16x16x32_bf16 v[120:123], v[166:169], v[174:177], v[120:123]
	v_mfma_f32_16x16x32_bf16 v[116:119], v[158:161], v[182:185], v[116:119]
	v_mfma_f32_16x16x32_bf16 v[112:115], v[166:169], v[182:185], v[112:115]
	v_mfma_f32_16x16x32_bf16 v[108:111], v[158:161], v[190:193], v[108:111]
	v_mfma_f32_16x16x32_bf16 v[104:107], v[166:169], v[190:193], v[104:107]
	s_waitcnt lgkmcnt(0)
	v_mfma_f32_16x16x32_bf16 v[100:103], v[158:161], v[198:201], v[100:103]
	v_mfma_f32_16x16x32_bf16 v[96:99], v[166:169], v[198:201], v[96:99]
	s_barrier
	s_add_i32 s44, s39, s17
	s_add_i32 s45, s44, 0x100
	s_mov_b32 s10, s6
	s_mov_b32 s11, s7
	s_mov_b32 m0, s1
	ds_read_b128 v[202:205], v145
	ds_read_b128 v[206:209], v146
	ds_read_b128 v[210:213], v147
	ds_read_b128 v[214:217], v148
	buffer_load_dwordx4 v143, s[8:11], s45 offen lds
	s_mov_b32 m0, s3
	s_nop 0
	buffer_load_dwordx4 v144, s[8:11], s45 offen lds
	s_barrier
	s_waitcnt lgkmcnt(0)
	s_waitcnt lgkmcnt(3)
	v_mfma_f32_16x16x32_bf16 v[92:95], v[202:205], v[170:173], v[92:95]
	s_waitcnt lgkmcnt(1)
	v_mfma_f32_16x16x32_bf16 v[88:91], v[210:213], v[170:173], v[88:91]
	v_mfma_f32_16x16x32_bf16 v[84:87], v[202:205], v[178:181], v[84:87]
	v_mfma_f32_16x16x32_bf16 v[80:83], v[210:213], v[178:181], v[80:83]
	v_mfma_f32_16x16x32_bf16 v[76:79], v[202:205], v[186:189], v[76:79]
	v_mfma_f32_16x16x32_bf16 v[72:75], v[210:213], v[186:189], v[72:75]
	v_mfma_f32_16x16x32_bf16 v[68:71], v[202:205], v[194:197], v[68:71]
	v_mfma_f32_16x16x32_bf16 v[64:67], v[210:213], v[194:197], v[64:67]
	v_mfma_f32_16x16x32_bf16 v[92:95], v[206:209], v[174:177], v[92:95]
	s_waitcnt lgkmcnt(0)
	v_mfma_f32_16x16x32_bf16 v[88:91], v[214:217], v[174:177], v[88:91]
	v_mfma_f32_16x16x32_bf16 v[84:87], v[206:209], v[182:185], v[84:87]
	v_mfma_f32_16x16x32_bf16 v[80:83], v[214:217], v[182:185], v[80:83]
	v_mfma_f32_16x16x32_bf16 v[76:79], v[206:209], v[190:193], v[76:79]
	v_mfma_f32_16x16x32_bf16 v[72:75], v[214:217], v[190:193], v[72:75]
	v_mfma_f32_16x16x32_bf16 v[68:71], v[206:209], v[198:201], v[68:71]
	v_mfma_f32_16x16x32_bf16 v[64:67], v[214:217], v[198:201], v[64:67]
	s_add_i32 s45, s38, s17
	s_add_i32 s46, s45, 0x100
	s_mov_b32 m0, s0
	s_barrier
	ds_read_b128 v[170:173], v131 offset:16384
	ds_read_b128 v[174:177], v131 offset:17408
	ds_read_b128 v[178:181], v134 offset:16384
	ds_read_b128 v[182:185], v134 offset:17408
	ds_read_b128 v[186:189], v133 offset:16384
	ds_read_b128 v[190:193], v133 offset:17408
	ds_read_b128 v[194:197], v132 offset:16384
	ds_read_b128 v[198:201], v132 offset:17408
	buffer_load_dwordx4 v143, s[4:7], s46 offen lds
	s_mov_b32 m0, s18
	s_nop 0
	buffer_load_dwordx4 v144, s[4:7], s46 offen lds
	s_barrier
	s_waitcnt lgkmcnt(0)
	s_waitcnt lgkmcnt(7)
	v_mfma_f32_16x16x32_bf16 v[60:63], v[154:157], v[170:173], v[60:63]
	v_mfma_f32_16x16x32_bf16 v[56:59], v[162:165], v[170:173], v[56:59]
	s_waitcnt lgkmcnt(5)
	v_mfma_f32_16x16x32_bf16 v[52:55], v[154:157], v[178:181], v[52:55]
	v_mfma_f32_16x16x32_bf16 v[48:51], v[162:165], v[178:181], v[48:51]
	s_waitcnt lgkmcnt(3)
	v_mfma_f32_16x16x32_bf16 v[44:47], v[154:157], v[186:189], v[44:47]
	v_mfma_f32_16x16x32_bf16 v[40:43], v[162:165], v[186:189], v[40:43]
	s_waitcnt lgkmcnt(1)
	v_mfma_f32_16x16x32_bf16 v[36:39], v[154:157], v[194:197], v[36:39]
	v_mfma_f32_16x16x32_bf16 v[32:35], v[162:165], v[194:197], v[32:35]
	v_mfma_f32_16x16x32_bf16 v[60:63], v[158:161], v[174:177], v[60:63]
	v_mfma_f32_16x16x32_bf16 v[56:59], v[166:169], v[174:177], v[56:59]
	v_mfma_f32_16x16x32_bf16 v[52:55], v[158:161], v[182:185], v[52:55]
	v_mfma_f32_16x16x32_bf16 v[48:51], v[166:169], v[182:185], v[48:51]
	v_mfma_f32_16x16x32_bf16 v[44:47], v[158:161], v[190:193], v[44:47]
	v_mfma_f32_16x16x32_bf16 v[40:43], v[166:169], v[190:193], v[40:43]
	s_waitcnt lgkmcnt(0)
	v_mfma_f32_16x16x32_bf16 v[36:39], v[158:161], v[198:201], v[36:39]
	v_mfma_f32_16x16x32_bf16 v[32:35], v[166:169], v[198:201], v[32:35]
	s_barrier
	s_add_i32 s46, s40, s17
	s_add_i32 s47, s46, 0x100
	s_mov_b32 m0, s19
	s_nop 0
	buffer_load_dwordx4 v143, s[8:11], s47 offen lds
	s_mov_b32 m0, s20
	s_nop 0
	buffer_load_dwordx4 v144, s[8:11], s47 offen lds
	s_waitcnt vmcnt(6)
	s_barrier
; #define STAGE(P, RS, SOFF, OFF, kt) do { const int _so = (SOFF) + (kt) * (BK * 2); \
;     _Pragma("unroll") for (int _i = 0; _i < 2; ++_i) { \
;       __builtin_amdgcn_raw_ptr_buffer_load_lds(RS, (__attribute__((address_space(3))) void*)((P) + wave * 1024 + _i * 8192), 16, OFF[_i], _so, 0, 0); } } while (0)
; #define LDA(dst, b, h) _Pragma("unroll") for (int m = 0; m < 4; ++m) _Pragma("unroll") for (int k = 0; k < 2; ++k) \
;     dst[m][k] = *reinterpret_cast<const bf16x8*>(SA(b, h) + lds_byte(wr * 64 + m * 16 + fr, k * 32 + fq * 8))
; #define LDB(dst, b, h) _Pragma("unroll") for (int n = 0; n < 2; ++n) _Pragma("unroll") for (int k = 0; k < 2; ++k) \
;     dst[n][k] = *reinterpret_cast<const bf16x8*>(SB(b, h) + lds_byte(wc * 32 + n * 16 + fr, k * 32 + fq * 8))
; #define WAIT_V(n) asm volatile("s_waitcnt vmcnt(" #n ")" ::: "memory")
; #define WAIT_L(n) asm volatile("s_waitcnt lgkmcnt(" #n ")" ::: "memory")
; #define BAR __builtin_amdgcn_s_barrier()
; #define SCHED __builtin_amdgcn_sched_barrier(0)
;     ...
;       WAIT_V(6); BAR; MMA(1, 1, At, B1); BAR;
;       LDB(B0, 1, 0); SCHED; LDA(At, 1, 0); STAGE(SA(0, 1), rsA, sA1, offA, t + 2);
;       WAIT_L(8); BAR; WAIT_L(0); MMA(0, 0, At, B0); BAR; SCHED;
;       LDB(B1, 1, 1); STAGE(SB(1, 0), rsB, sB0, offB, t + 3);
;       BAR; WAIT_L(0); MMA(0, 1, At, B1); BAR;
;       LDA(At, 1, 1); STAGE(SA(1, 0), rsA, sA0, offA, t + 3);
;       BAR; WAIT_L(0); MMA(1, 0, At, B0); BAR; SCHED;
;       STAGE(SB(1, 1), rsB, sB1, offB, t + 3);
	v_mfma_f32_16x16x32_bf16 v[28:31], v[202:205], v[170:173], v[28:31]
	v_mfma_f32_16x16x32_bf16 v[24:27], v[210:213], v[170:173], v[24:27]
	v_mfma_f32_16x16x32_bf16 v[20:23], v[202:205], v[178:181], v[20:23]
	v_mfma_f32_16x16x32_bf16 v[16:19], v[210:213], v[178:181], v[16:19]
	v_mfma_f32_16x16x32_bf16 v[12:15], v[202:205], v[186:189], v[12:15]
	v_mfma_f32_16x16x32_bf16 v[8:11], v[210:213], v[186:189], v[8:11]
	v_mfma_f32_16x16x32_bf16 v[4:7], v[202:205], v[194:197], v[4:7]
	v_mfma_f32_16x16x32_bf16 v[0:3], v[210:213], v[194:197], v[0:3]
	v_mfma_f32_16x16x32_bf16 v[28:31], v[206:209], v[174:177], v[28:31]
	v_mfma_f32_16x16x32_bf16 v[24:27], v[214:217], v[174:177], v[24:27]
	v_mfma_f32_16x16x32_bf16 v[20:23], v[206:209], v[182:185], v[20:23]
	v_mfma_f32_16x16x32_bf16 v[16:19], v[214:217], v[182:185], v[16:19]
	v_mfma_f32_16x16x32_bf16 v[12:15], v[206:209], v[190:193], v[12:15]
	v_mfma_f32_16x16x32_bf16 v[8:11], v[214:217], v[190:193], v[8:11]
	v_mfma_f32_16x16x32_bf16 v[4:7], v[206:209], v[198:201], v[4:7]
	v_mfma_f32_16x16x32_bf16 v[0:3], v[214:217], v[198:201], v[0:3]
	s_barrier
	ds_read_b128 v[154:157], v139
	ds_read_b128 v[158:161], v140
	ds_read_b128 v[162:165], v141
	ds_read_b128 v[166:169], v142
	s_addk_i32 s43, 0x100
	s_mov_b32 m0, s21
	ds_read_b128 v[170:173], v131 offset:32768
	ds_read_b128 v[174:177], v131 offset:33792
	ds_read_b128 v[178:181], v134 offset:32768
	ds_read_b128 v[182:185], v134 offset:33792
	ds_read_b128 v[186:189], v133 offset:32768
	ds_read_b128 v[190:193], v133 offset:33792
	ds_read_b128 v[194:197], v132 offset:32768
	ds_read_b128 v[198:201], v132 offset:33792
	buffer_load_dwordx4 v143, s[4:7], s43 offen lds
	s_mov_b32 m0, s22
	s_nop 0
	buffer_load_dwordx4 v144, s[4:7], s43 offen lds
	s_waitcnt lgkmcnt(8)
	s_barrier
	s_waitcnt lgkmcnt(0)
	s_waitcnt lgkmcnt(7)
	v_mfma_f32_16x16x32_bf16 v[124:127], v[154:157], v[170:173], v[124:127]
	v_mfma_f32_16x16x32_bf16 v[120:123], v[162:165], v[170:173], v[120:123]
	s_waitcnt lgkmcnt(5)
	v_mfma_f32_16x16x32_bf16 v[116:119], v[154:157], v[178:181], v[116:119]
	v_mfma_f32_16x16x32_bf16 v[112:115], v[162:165], v[178:181], v[112:115]
	s_waitcnt lgkmcnt(3)
	v_mfma_f32_16x16x32_bf16 v[108:111], v[154:157], v[186:189], v[108:111]
	v_mfma_f32_16x16x32_bf16 v[104:107], v[162:165], v[186:189], v[104:107]
	s_waitcnt lgkmcnt(1)
	v_mfma_f32_16x16x32_bf16 v[100:103], v[154:157], v[194:197], v[100:103]
	v_mfma_f32_16x16x32_bf16 v[96:99], v[162:165], v[194:197], v[96:99]
	v_mfma_f32_16x16x32_bf16 v[124:127], v[158:161], v[174:177], v[124:127]
	v_mfma_f32_16x16x32_bf16 v[120:123], v[166:169], v[174:177], v[120:123]
	v_mfma_f32_16x16x32_bf16 v[116:119], v[158:161], v[182:185], v[116:119]
	v_mfma_f32_16x16x32_bf16 v[112:115], v[166:169], v[182:185], v[112:115]
	v_mfma_f32_16x16x32_bf16 v[108:111], v[158:161], v[190:193], v[108:111]
	v_mfma_f32_16x16x32_bf16 v[104:107], v[166:169], v[190:193], v[104:107]
	s_waitcnt lgkmcnt(0)
	v_mfma_f32_16x16x32_bf16 v[100:103], v[158:161], v[198:201], v[100:103]
	v_mfma_f32_16x16x32_bf16 v[96:99], v[166:169], v[198:201], v[96:99]
	s_barrier
	s_addk_i32 s44, 0x180
	s_mov_b32 m0, s23
	ds_read_b128 v[202:205], v135
	ds_read_b128 v[206:209], v136
	ds_read_b128 v[210:213], v137
	ds_read_b128 v[214:217], v138
	buffer_load_dwordx4 v143, s[8:11], s44 offen lds
	s_mov_b32 m0, s24
	s_nop 0
	buffer_load_dwordx4 v144, s[8:11], s44 offen lds
	s_barrier
	s_waitcnt lgkmcnt(0)
	s_waitcnt lgkmcnt(3)
	v_mfma_f32_16x16x32_bf16 v[92:95], v[202:205], v[170:173], v[92:95]
	s_waitcnt lgkmcnt(1)
	v_mfma_f32_16x16x32_bf16 v[88:91], v[210:213], v[170:173], v[88:91]
	v_mfma_f32_16x16x32_bf16 v[84:87], v[202:205], v[178:181], v[84:87]
	v_mfma_f32_16x16x32_bf16 v[80:83], v[210:213], v[178:181], v[80:83]
	v_mfma_f32_16x16x32_bf16 v[76:79], v[202:205], v[186:189], v[76:79]
	v_mfma_f32_16x16x32_bf16 v[72:75], v[210:213], v[186:189], v[72:75]
	v_mfma_f32_16x16x32_bf16 v[68:71], v[202:205], v[194:197], v[68:71]
	v_mfma_f32_16x16x32_bf16 v[64:67], v[210:213], v[194:197], v[64:67]
	v_mfma_f32_16x16x32_bf16 v[92:95], v[206:209], v[174:177], v[92:95]
	s_waitcnt lgkmcnt(0)
	v_mfma_f32_16x16x32_bf16 v[88:91], v[214:217], v[174:177], v[88:91]
	v_mfma_f32_16x16x32_bf16 v[84:87], v[206:209], v[182:185], v[84:87]
	v_mfma_f32_16x16x32_bf16 v[80:83], v[214:217], v[182:185], v[80:83]
	v_mfma_f32_16x16x32_bf16 v[76:79], v[206:209], v[190:193], v[76:79]
	v_mfma_f32_16x16x32_bf16 v[72:75], v[214:217], v[190:193], v[72:75]
	v_mfma_f32_16x16x32_bf16 v[68:71], v[206:209], v[198:201], v[68:71]
	v_mfma_f32_16x16x32_bf16 v[64:67], v[214:217], v[198:201], v[64:67]
	s_addk_i32 s45, 0x180
	s_mov_b32 m0, s25
	s_barrier
	ds_read_b128 v[170:173], v131 offset:49152
	ds_read_b128 v[174:177], v131 offset:50176
	ds_read_b128 v[178:181], v134 offset:49152
	ds_read_b128 v[182:185], v134 offset:50176
	ds_read_b128 v[186:189], v133 offset:49152
	ds_read_b128 v[190:193], v133 offset:50176
	ds_read_b128 v[194:197], v132 offset:49152
	ds_read_b128 v[198:201], v132 offset:50176
	buffer_load_dwordx4 v143, s[4:7], s45 offen lds
	s_mov_b32 m0, s26
	s_nop 0
	buffer_load_dwordx4 v144, s[4:7], s45 offen lds
	s_barrier
; #define STAGE(P, RS, SOFF, OFF, kt) do { const int _so = (SOFF) + (kt) * (BK * 2); \
;     _Pragma("unroll") for (int _i = 0; _i < 2; ++_i) { \
;       __builtin_amdgcn_raw_ptr_buffer_load_lds(RS, (__attribute__((address_space(3))) void*)((P) + wave * 1024 + _i * 8192), 16, OFF[_i], _so, 0, 0); } } while (0)
; #define LDA(dst, b, h) _Pragma("unroll") for (int m = 0; m < 4; ++m) _Pragma("unroll") for (int k = 0; k < 2; ++k) \
;     dst[m][k] = *reinterpret_cast<const bf16x8*>(SA(b, h) + lds_byte(wr * 64 + m * 16 + fr, k * 32 + fq * 8))
; #define LDB(dst, b, h) _Pragma("unroll") for (int n = 0; n < 2; ++n) _Pragma("unroll") for (int k = 0; k < 2; ++k) \
;     dst[n][k] = *reinterpret_cast<const bf16x8*>(SB(b, h) + lds_byte(wc * 32 + n * 16 + fr, k * 32 + fq * 8))
; #define WAIT_V(n) asm volatile("s_waitcnt vmcnt(" #n ")" ::: "memory")
; #define WAIT_L(n) asm volatile("s_waitcnt lgkmcnt(" #n ")" ::: "memory")
; #define BAR __builtin_amdgcn_s_barrier()
; #define SCHED __builtin_amdgcn_sched_barrier(0)
;     ...
;       BAR; WAIT_L(0); MMA(1, 0, At, B0); BAR; SCHED;
;       STAGE(SB(1, 1), rsB, sB1, offB, t + 3);
;       WAIT_V(6); BAR; MMA(1, 1, At, B1); BAR;
;     }
;     { LDB(B0, 0, 0); LDA(At, 0, 0); STAGE(SA(1, 1), rsA, sA1, offA, nt - 1);
;       BAR; WAIT_L(0); MMA(0, 0, At, B0); BAR;
;       LDB(B1, 0, 1); BAR; WAIT_L(0); MMA(0, 1, At, B1); BAR;
	s_waitcnt lgkmcnt(0)
	s_waitcnt lgkmcnt(7)
	v_mfma_f32_16x16x32_bf16 v[60:63], v[154:157], v[170:173], v[60:63]
	v_mfma_f32_16x16x32_bf16 v[56:59], v[162:165], v[170:173], v[56:59]
	s_waitcnt lgkmcnt(5)
	v_mfma_f32_16x16x32_bf16 v[52:55], v[154:157], v[178:181], v[52:55]
	v_mfma_f32_16x16x32_bf16 v[48:51], v[162:165], v[178:181], v[48:51]
	s_waitcnt lgkmcnt(3)
	v_mfma_f32_16x16x32_bf16 v[44:47], v[154:157], v[186:189], v[44:47]
	v_mfma_f32_16x16x32_bf16 v[40:43], v[162:165], v[186:189], v[40:43]
	s_waitcnt lgkmcnt(1)
	v_mfma_f32_16x16x32_bf16 v[36:39], v[154:157], v[194:197], v[36:39]
	v_mfma_f32_16x16x32_bf16 v[32:35], v[162:165], v[194:197], v[32:35]
	v_mfma_f32_16x16x32_bf16 v[60:63], v[158:161], v[174:177], v[60:63]
	v_mfma_f32_16x16x32_bf16 v[56:59], v[166:169], v[174:177], v[56:59]
	v_mfma_f32_16x16x32_bf16 v[52:55], v[158:161], v[182:185], v[52:55]
	v_mfma_f32_16x16x32_bf16 v[48:51], v[166:169], v[182:185], v[48:51]
	v_mfma_f32_16x16x32_bf16 v[44:47], v[158:161], v[190:193], v[44:47]
	v_mfma_f32_16x16x32_bf16 v[40:43], v[166:169], v[190:193], v[40:43]
	s_waitcnt lgkmcnt(0)
	v_mfma_f32_16x16x32_bf16 v[36:39], v[158:161], v[198:201], v[36:39]
	v_mfma_f32_16x16x32_bf16 v[32:35], v[166:169], v[198:201], v[32:35]
	s_barrier
	s_addk_i32 s46, 0x180
	s_mov_b32 m0, s27
	s_nop 0
	buffer_load_dwordx4 v143, s[8:11], s46 offen lds
	s_mov_b32 m0, s28
	s_nop 0
	buffer_load_dwordx4 v144, s[8:11], s46 offen lds
	s_waitcnt vmcnt(6)
	s_barrier
	v_mfma_f32_16x16x32_bf16 v[28:31], v[202:205], v[170:173], v[28:31]
	v_mfma_f32_16x16x32_bf16 v[24:27], v[210:213], v[170:173], v[24:27]
	v_mfma_f32_16x16x32_bf16 v[20:23], v[202:205], v[178:181], v[20:23]
	v_mfma_f32_16x16x32_bf16 v[16:19], v[210:213], v[178:181], v[16:19]
	v_mfma_f32_16x16x32_bf16 v[12:15], v[202:205], v[186:189], v[12:15]
	v_mfma_f32_16x16x32_bf16 v[8:11], v[210:213], v[186:189], v[8:11]
	v_mfma_f32_16x16x32_bf16 v[4:7], v[202:205], v[194:197], v[4:7]
	v_mfma_f32_16x16x32_bf16 v[0:3], v[210:213], v[194:197], v[0:3]
	v_mfma_f32_16x16x32_bf16 v[28:31], v[206:209], v[174:177], v[28:31]
	v_mfma_f32_16x16x32_bf16 v[24:27], v[214:217], v[174:177], v[24:27]
	v_mfma_f32_16x16x32_bf16 v[20:23], v[206:209], v[182:185], v[20:23]
	v_mfma_f32_16x16x32_bf16 v[16:19], v[214:217], v[182:185], v[16:19]
	v_mfma_f32_16x16x32_bf16 v[12:15], v[206:209], v[190:193], v[12:15]
	v_mfma_f32_16x16x32_bf16 v[8:11], v[214:217], v[190:193], v[8:11]
	v_mfma_f32_16x16x32_bf16 v[4:7], v[206:209], v[198:201], v[4:7]
	v_mfma_f32_16x16x32_bf16 v[0:3], v[214:217], v[198:201], v[0:3]
	s_add_i32 s16, s16, 2
	s_addk_i32 s17, 0x100
	s_cmp_gt_u32 s16, 27
	s_barrier
	s_cbranch_scc0 .LBB0_354
	s_add_i32 s10, s37, 0xf80
	s_mov_b32 m0, s30
	ds_read_b128 v[154:157], v149
	ds_read_b128 v[158:161], v150
	ds_read_b128 v[162:165], v151
	ds_read_b128 v[150:153], v152
	ds_read_b128 v[166:169], v131
	ds_read_b128 v[170:173], v131 offset:1024
	ds_read_b128 v[174:177], v134
	ds_read_b128 v[178:181], v134 offset:1024
	ds_read_b128 v[182:185], v133
	ds_read_b128 v[186:189], v133 offset:1024
	ds_read_b128 v[190:193], v132
	ds_read_b128 v[194:197], v132 offset:1024
	buffer_load_dwordx4 v143, s[4:7], s10 offen lds
	s_mov_b32 m0, s31
	s_nop 0
	buffer_load_dwordx4 v144, s[4:7], s10 offen lds
	s_barrier
	s_waitcnt lgkmcnt(0)
	s_waitcnt lgkmcnt(7)
	v_mfma_f32_16x16x32_bf16 v[124:127], v[154:157], v[166:169], v[124:127]
	v_mfma_f32_16x16x32_bf16 v[120:123], v[162:165], v[166:169], v[120:123]
	s_waitcnt lgkmcnt(5)
	v_mfma_f32_16x16x32_bf16 v[116:119], v[154:157], v[174:177], v[116:119]
	v_mfma_f32_16x16x32_bf16 v[112:115], v[162:165], v[174:177], v[112:115]
	s_waitcnt lgkmcnt(3)
	v_mfma_f32_16x16x32_bf16 v[108:111], v[154:157], v[182:185], v[108:111]
	v_mfma_f32_16x16x32_bf16 v[104:107], v[162:165], v[182:185], v[104:107]
	s_waitcnt lgkmcnt(1)
	v_mfma_f32_16x16x32_bf16 v[100:103], v[154:157], v[190:193], v[100:103]
	v_mfma_f32_16x16x32_bf16 v[96:99], v[162:165], v[190:193], v[96:99]
	v_mfma_f32_16x16x32_bf16 v[124:127], v[158:161], v[170:173], v[124:127]
	v_mfma_f32_16x16x32_bf16 v[120:123], v[150:153], v[170:173], v[120:123]
	v_mfma_f32_16x16x32_bf16 v[116:119], v[158:161], v[178:181], v[116:119]
	v_mfma_f32_16x16x32_bf16 v[112:115], v[150:153], v[178:181], v[112:115]
	v_mfma_f32_16x16x32_bf16 v[108:111], v[158:161], v[186:189], v[108:111]
	v_mfma_f32_16x16x32_bf16 v[104:107], v[150:153], v[186:189], v[104:107]
	s_waitcnt lgkmcnt(0)
	v_mfma_f32_16x16x32_bf16 v[100:103], v[158:161], v[194:197], v[100:103]
	v_mfma_f32_16x16x32_bf16 v[96:99], v[150:153], v[194:197], v[96:99]
	s_barrier
	ds_read_b128 v[198:201], v145
	ds_read_b128 v[202:205], v146
	ds_read_b128 v[144:147], v147
	ds_read_b128 v[206:209], v148
	s_barrier
	s_waitcnt lgkmcnt(0)
	s_waitcnt lgkmcnt(3)
	v_mfma_f32_16x16x32_bf16 v[92:95], v[198:201], v[166:169], v[92:95]
	v_mfma_f32_16x16x32_bf16 v[84:87], v[198:201], v[174:177], v[84:87]
	v_mfma_f32_16x16x32_bf16 v[76:79], v[198:201], v[182:185], v[76:79]
	v_mfma_f32_16x16x32_bf16 v[68:71], v[198:201], v[190:193], v[68:71]
	s_waitcnt lgkmcnt(1)
	v_mfma_f32_16x16x32_bf16 v[88:91], v[144:147], v[166:169], v[88:91]
	v_mfma_f32_16x16x32_bf16 v[80:83], v[144:147], v[174:177], v[80:83]
	v_mfma_f32_16x16x32_bf16 v[72:75], v[144:147], v[182:185], v[72:75]
	v_mfma_f32_16x16x32_bf16 v[64:67], v[144:147], v[190:193], v[64:67]
	v_mfma_f32_16x16x32_bf16 v[92:95], v[202:205], v[170:173], v[92:95]
	v_mfma_f32_16x16x32_bf16 v[84:87], v[202:205], v[178:181], v[84:87]
	v_mfma_f32_16x16x32_bf16 v[76:79], v[202:205], v[186:189], v[76:79]
	v_mfma_f32_16x16x32_bf16 v[68:71], v[202:205], v[194:197], v[68:71]
	s_waitcnt lgkmcnt(0)
	v_mfma_f32_16x16x32_bf16 v[166:169], v[206:209], v[170:173], v[88:91]
	v_mfma_f32_16x16x32_bf16 v[170:173], v[206:209], v[178:181], v[80:83]
	v_mfma_f32_16x16x32_bf16 v[174:177], v[206:209], v[186:189], v[72:75]
	v_mfma_f32_16x16x32_bf16 v[178:181], v[206:209], v[194:197], v[64:67]
	s_barrier
; #define LDA(dst, b, h) _Pragma("unroll") for (int m = 0; m < 4; ++m) _Pragma("unroll") for (int k = 0; k < 2; ++k) \
;     dst[m][k] = *reinterpret_cast<const bf16x8*>(SA(b, h) + lds_byte(wr * 64 + m * 16 + fr, k * 32 + fq * 8))
; #define LDB(dst, b, h) _Pragma("unroll") for (int n = 0; n < 2; ++n) _Pragma("unroll") for (int k = 0; k < 2; ++k) \
;     dst[n][k] = *reinterpret_cast<const bf16x8*>(SB(b, h) + lds_byte(wc * 32 + n * 16 + fr, k * 32 + fq * 8))
; #define WAIT_V(n) asm volatile("s_waitcnt vmcnt(" #n ")" ::: "memory")
; #define WAIT_L(n) asm volatile("s_waitcnt lgkmcnt(" #n ")" ::: "memory")
; #define BAR __builtin_amdgcn_s_barrier()
;     ...
;       LDB(B1, 0, 1); BAR; WAIT_L(0); MMA(0, 1, At, B1); BAR;
;       LDA(At, 0, 1); WAIT_V(4); BAR; WAIT_L(0); MMA(1, 0, At, B0); MMA(1, 1, At, B1); BAR; }
;     { LDB(B0, 1, 0); LDA(At, 1, 0); WAIT_V(2); BAR; WAIT_L(0); MMA(0, 0, At, B0); BAR;
;       LDB(B1, 1, 1); WAIT_V(0); BAR; WAIT_L(0); MMA(0, 1, At, B1); BAR;
	s_nop 0
	ds_read_b128 v[64:67], v131 offset:16384
	ds_read_b128 v[72:75], v131 offset:17408
	ds_read_b128 v[80:83], v134 offset:16384
	ds_read_b128 v[88:91], v134 offset:17408
	ds_read_b128 v[182:185], v133 offset:16384
	ds_read_b128 v[186:189], v133 offset:17408
	ds_read_b128 v[190:193], v132 offset:16384
	ds_read_b128 v[194:197], v132 offset:17408
	s_waitcnt vmcnt(4)
	s_barrier
	s_waitcnt lgkmcnt(0)
	s_waitcnt lgkmcnt(7)
	v_mfma_f32_16x16x32_bf16 v[60:63], v[154:157], v[64:67], v[60:63]
	v_mfma_f32_16x16x32_bf16 v[56:59], v[162:165], v[64:67], v[56:59]
	s_waitcnt lgkmcnt(5)
	v_mfma_f32_16x16x32_bf16 v[52:55], v[154:157], v[80:83], v[52:55]
	v_mfma_f32_16x16x32_bf16 v[48:51], v[162:165], v[80:83], v[48:51]
	s_waitcnt lgkmcnt(3)
	v_mfma_f32_16x16x32_bf16 v[44:47], v[154:157], v[182:185], v[44:47]
	v_mfma_f32_16x16x32_bf16 v[40:43], v[162:165], v[182:185], v[40:43]
	s_waitcnt lgkmcnt(1)
	v_mfma_f32_16x16x32_bf16 v[36:39], v[154:157], v[190:193], v[36:39]
	v_mfma_f32_16x16x32_bf16 v[32:35], v[162:165], v[190:193], v[32:35]
	v_mfma_f32_16x16x32_bf16 v[60:63], v[158:161], v[72:75], v[60:63]
	v_mfma_f32_16x16x32_bf16 v[56:59], v[150:153], v[72:75], v[56:59]
	v_mfma_f32_16x16x32_bf16 v[52:55], v[158:161], v[88:91], v[52:55]
	v_mfma_f32_16x16x32_bf16 v[48:51], v[150:153], v[88:91], v[48:51]
	v_mfma_f32_16x16x32_bf16 v[44:47], v[158:161], v[186:189], v[44:47]
	v_mfma_f32_16x16x32_bf16 v[40:43], v[150:153], v[186:189], v[40:43]
	s_waitcnt lgkmcnt(0)
	v_mfma_f32_16x16x32_bf16 v[36:39], v[158:161], v[194:197], v[36:39]
	v_mfma_f32_16x16x32_bf16 v[32:35], v[150:153], v[194:197], v[32:35]
	v_mfma_f32_16x16x32_bf16 v[28:31], v[198:201], v[64:67], v[28:31]
	v_mfma_f32_16x16x32_bf16 v[20:23], v[198:201], v[80:83], v[20:23]
	v_mfma_f32_16x16x32_bf16 v[12:15], v[198:201], v[182:185], v[12:15]
	v_mfma_f32_16x16x32_bf16 v[4:7], v[198:201], v[190:193], v[4:7]
	v_mfma_f32_16x16x32_bf16 v[24:27], v[144:147], v[64:67], v[24:27]
	v_mfma_f32_16x16x32_bf16 v[16:19], v[144:147], v[80:83], v[16:19]
	v_mfma_f32_16x16x32_bf16 v[8:11], v[144:147], v[182:185], v[8:11]
	v_mfma_f32_16x16x32_bf16 v[0:3], v[144:147], v[190:193], v[0:3]
	v_mfma_f32_16x16x32_bf16 v[28:31], v[202:205], v[72:75], v[28:31]
	v_mfma_f32_16x16x32_bf16 v[20:23], v[202:205], v[88:91], v[20:23]
	v_mfma_f32_16x16x32_bf16 v[12:15], v[202:205], v[186:189], v[12:15]
	v_mfma_f32_16x16x32_bf16 v[4:7], v[202:205], v[194:197], v[4:7]
	v_mfma_f32_16x16x32_bf16 v[144:147], v[206:209], v[72:75], v[24:27]
	v_mfma_f32_16x16x32_bf16 v[148:151], v[206:209], v[88:91], v[16:19]
	v_mfma_f32_16x16x32_bf16 v[152:155], v[206:209], v[186:189], v[8:11]
	v_mfma_f32_16x16x32_bf16 v[156:159], v[206:209], v[194:197], v[0:3]
	s_barrier
	s_nop 0
	ds_read_b128 v[0:3], v139
	ds_read_b128 v[8:11], v140
	ds_read_b128 v[16:19], v141
	ds_read_b128 v[140:143], v142
	ds_read_b128 v[24:27], v131 offset:32768
	ds_read_b128 v[160:163], v131 offset:33792
	ds_read_b128 v[182:185], v134 offset:32768
	ds_read_b128 v[186:189], v134 offset:33792
	ds_read_b128 v[190:193], v133 offset:32768
	ds_read_b128 v[194:197], v133 offset:33792
	ds_read_b128 v[198:201], v132 offset:32768
	ds_read_b128 v[202:205], v132 offset:33792
	s_waitcnt vmcnt(2)
	s_barrier
	s_waitcnt lgkmcnt(0)
	s_waitcnt lgkmcnt(7)
	v_mfma_f32_16x16x32_bf16 v[64:67], v[0:3], v[24:27], v[124:127]
	v_mfma_f32_16x16x32_bf16 v[72:75], v[16:19], v[24:27], v[120:123]
	s_waitcnt lgkmcnt(5)
	v_mfma_f32_16x16x32_bf16 v[80:83], v[0:3], v[182:185], v[116:119]
	v_mfma_f32_16x16x32_bf16 v[88:91], v[16:19], v[182:185], v[112:115]
	s_waitcnt lgkmcnt(3)
	v_mfma_f32_16x16x32_bf16 v[108:111], v[0:3], v[190:193], v[108:111]
	v_mfma_f32_16x16x32_bf16 v[116:119], v[16:19], v[190:193], v[104:107]
	s_waitcnt lgkmcnt(1)
	v_mfma_f32_16x16x32_bf16 v[100:103], v[0:3], v[198:201], v[100:103]
	v_mfma_f32_16x16x32_bf16 v[124:127], v[16:19], v[198:201], v[96:99]
	v_mfma_f32_16x16x32_bf16 v[120:123], v[8:11], v[160:163], v[64:67]
	v_mfma_f32_16x16x32_bf16 v[112:115], v[140:143], v[160:163], v[72:75]
	v_mfma_f32_16x16x32_bf16 v[104:107], v[8:11], v[186:189], v[80:83]
	v_mfma_f32_16x16x32_bf16 v[96:99], v[140:143], v[186:189], v[88:91]
	v_mfma_f32_16x16x32_bf16 v[88:91], v[8:11], v[194:197], v[108:111]
	v_mfma_f32_16x16x32_bf16 v[80:83], v[140:143], v[194:197], v[116:119]
	s_waitcnt lgkmcnt(0)
	v_mfma_f32_16x16x32_bf16 v[72:75], v[8:11], v[202:205], v[100:103]
	v_mfma_f32_16x16x32_bf16 v[64:67], v[140:143], v[202:205], v[124:127]
	s_barrier
; #define LDA(dst, b, h) _Pragma("unroll") for (int m = 0; m < 4; ++m) _Pragma("unroll") for (int k = 0; k < 2; ++k) \
;     dst[m][k] = *reinterpret_cast<const bf16x8*>(SA(b, h) + lds_byte(wr * 64 + m * 16 + fr, k * 32 + fq * 8))
; #define LDB(dst, b, h) _Pragma("unroll") for (int n = 0; n < 2; ++n) _Pragma("unroll") for (int k = 0; k < 2; ++k) \
;     dst[n][k] = *reinterpret_cast<const bf16x8*>(SB(b, h) + lds_byte(wc * 32 + n * 16 + fr, k * 32 + fq * 8))
; #define WAIT_V(n) asm volatile("s_waitcnt vmcnt(" #n ")" ::: "memory")
; #define WAIT_L(n) asm volatile("s_waitcnt lgkmcnt(" #n ")" ::: "memory")
; #define BAR __builtin_amdgcn_s_barrier()
;     ...
;     { LDB(B0, 1, 0); LDA(At, 1, 0); WAIT_V(2); BAR; WAIT_L(0); MMA(0, 0, At, B0); BAR;
;       LDB(B1, 1, 1); WAIT_V(0); BAR; WAIT_L(0); MMA(0, 1, At, B1); BAR;
;       LDA(At, 1, 1); BAR; WAIT_L(0); MMA(1, 0, At, B0); MMA(1, 1, At, B1); BAR; }
;     if (wr == 0) BAR;
	ds_read_b128 v[206:209], v135
	ds_read_b128 v[210:213], v136
	ds_read_b128 v[214:217], v137
	ds_read_b128 v[136:139], v138
	s_waitcnt vmcnt(0)
	s_barrier
	s_waitcnt lgkmcnt(0)
	s_waitcnt lgkmcnt(3)
	v_mfma_f32_16x16x32_bf16 v[92:95], v[206:209], v[24:27], v[92:95]
	s_waitcnt lgkmcnt(1)
	v_mfma_f32_16x16x32_bf16 v[24:27], v[214:217], v[24:27], v[166:169]
	v_mfma_f32_16x16x32_bf16 v[84:87], v[206:209], v[182:185], v[84:87]
	v_mfma_f32_16x16x32_bf16 v[100:103], v[214:217], v[182:185], v[170:173]
	v_mfma_f32_16x16x32_bf16 v[76:79], v[206:209], v[190:193], v[76:79]
	v_mfma_f32_16x16x32_bf16 v[164:167], v[214:217], v[190:193], v[174:177]
	v_mfma_f32_16x16x32_bf16 v[68:71], v[206:209], v[198:201], v[68:71]
	v_mfma_f32_16x16x32_bf16 v[168:171], v[214:217], v[198:201], v[178:181]
	v_mfma_f32_16x16x32_bf16 v[124:127], v[210:213], v[160:163], v[92:95]
	s_waitcnt lgkmcnt(0)
	v_mfma_f32_16x16x32_bf16 v[116:119], v[136:139], v[160:163], v[24:27]
	v_mfma_f32_16x16x32_bf16 v[108:111], v[210:213], v[186:189], v[84:87]
	v_mfma_f32_16x16x32_bf16 v[100:103], v[136:139], v[186:189], v[100:103]
	v_mfma_f32_16x16x32_bf16 v[92:95], v[210:213], v[194:197], v[76:79]
	v_mfma_f32_16x16x32_bf16 v[84:87], v[136:139], v[194:197], v[164:167]
	v_mfma_f32_16x16x32_bf16 v[76:79], v[210:213], v[202:205], v[68:71]
	v_mfma_f32_16x16x32_bf16 v[68:71], v[136:139], v[202:205], v[168:171]
	s_barrier
	ds_read_b128 v[160:163], v131 offset:49152
	ds_read_b128 v[164:167], v131 offset:50176
	ds_read_b128 v[168:171], v134 offset:49152
	ds_read_b128 v[172:175], v134 offset:50176
	ds_read_b128 v[176:179], v133 offset:49152
	ds_read_b128 v[180:183], v133 offset:50176
	ds_read_b128 v[184:187], v132 offset:49152
	ds_read_b128 v[132:135], v132 offset:50176
	s_barrier
	s_waitcnt lgkmcnt(0)
	s_waitcnt lgkmcnt(7)
	v_mfma_f32_16x16x32_bf16 v[24:27], v[0:3], v[160:163], v[60:63]
	v_mfma_f32_16x16x32_bf16 v[60:63], v[16:19], v[160:163], v[56:59]
	s_waitcnt lgkmcnt(5)
	v_mfma_f32_16x16x32_bf16 v[52:55], v[0:3], v[168:171], v[52:55]
	v_mfma_f32_16x16x32_bf16 v[188:191], v[16:19], v[168:171], v[48:51]
	s_waitcnt lgkmcnt(3)
	v_mfma_f32_16x16x32_bf16 v[44:47], v[0:3], v[176:179], v[44:47]
	v_mfma_f32_16x16x32_bf16 v[192:195], v[16:19], v[176:179], v[40:43]
	s_waitcnt lgkmcnt(1)
	v_mfma_f32_16x16x32_bf16 v[0:3], v[0:3], v[184:187], v[36:39]
	v_mfma_f32_16x16x32_bf16 v[36:39], v[16:19], v[184:187], v[32:35]
	v_mfma_f32_16x16x32_bf16 v[56:59], v[8:11], v[164:167], v[24:27]
	v_mfma_f32_16x16x32_bf16 v[48:51], v[140:143], v[164:167], v[60:63]
	v_mfma_f32_16x16x32_bf16 v[40:43], v[8:11], v[172:175], v[52:55]
	v_mfma_f32_16x16x32_bf16 v[32:35], v[140:143], v[172:175], v[188:191]
	v_mfma_f32_16x16x32_bf16 v[24:27], v[8:11], v[180:183], v[44:47]
	v_mfma_f32_16x16x32_bf16 v[16:19], v[140:143], v[180:183], v[192:195]
	s_waitcnt lgkmcnt(0)
	v_mfma_f32_16x16x32_bf16 v[8:11], v[8:11], v[132:135], v[0:3]
	v_mfma_f32_16x16x32_bf16 v[0:3], v[140:143], v[132:135], v[36:39]
	v_mfma_f32_16x16x32_bf16 v[28:31], v[206:209], v[160:163], v[28:31]
	v_mfma_f32_16x16x32_bf16 v[36:39], v[214:217], v[160:163], v[144:147]
	v_mfma_f32_16x16x32_bf16 v[20:23], v[206:209], v[168:171], v[20:23]
	v_mfma_f32_16x16x32_bf16 v[140:143], v[214:217], v[168:171], v[148:151]
	v_mfma_f32_16x16x32_bf16 v[12:15], v[206:209], v[176:179], v[12:15]
	v_mfma_f32_16x16x32_bf16 v[144:147], v[214:217], v[176:179], v[152:155]
	v_mfma_f32_16x16x32_bf16 v[4:7], v[206:209], v[184:187], v[4:7]
	v_mfma_f32_16x16x32_bf16 v[148:151], v[214:217], v[184:187], v[156:159]
	v_mfma_f32_16x16x32_bf16 v[60:63], v[210:213], v[164:167], v[28:31]
	v_mfma_f32_16x16x32_bf16 v[52:55], v[136:139], v[164:167], v[36:39]
	v_mfma_f32_16x16x32_bf16 v[44:47], v[210:213], v[172:175], v[20:23]
	v_mfma_f32_16x16x32_bf16 v[36:39], v[136:139], v[172:175], v[140:143]
	v_mfma_f32_16x16x32_bf16 v[28:31], v[210:213], v[180:183], v[12:15]
	v_mfma_f32_16x16x32_bf16 v[20:23], v[136:139], v[180:183], v[144:147]
	v_mfma_f32_16x16x32_bf16 v[12:15], v[210:213], v[132:135], v[4:7]
	v_mfma_f32_16x16x32_bf16 v[4:7], v[136:139], v[132:135], v[148:151]
	v_cmp_gt_u32_e32 vcc, s35, v130
	s_barrier
	s_and_saveexec_b64 s[10:11], vcc
	s_cbranch_execz .LBB0_357
	s_barrier

; #define STAGE(P, RS, SOFF, OFF, kt) do { const int _so = (SOFF) + (kt) * (BK * 2); \
;     _Pragma("unroll") for (int _i = 0; _i < 2; ++_i) { \
;       __builtin_amdgcn_raw_ptr_buffer_load_lds(RS, (__attribute__((address_space(3))) void*)((P) + wave * 1024 + _i * 8192), 16, OFF[_i], _so, 0, 0); } } while (0)
; #define LDA(dst, b, h) _Pragma("unroll") for (int m = 0; m < 4; ++m) _Pragma("unroll") for (int k = 0; k < 2; ++k) \
;     dst[m][k] = *reinterpret_cast<const bf16x8*>(SA(b, h) + lds_byte(wr * 64 + m * 16 + fr, k * 32 + fq * 8))
; #define LDB(dst, b, h) _Pragma("unroll") for (int n = 0; n < 2; ++n) _Pragma("unroll") for (int k = 0; k < 2; ++k) \
;     dst[n][k] = *reinterpret_cast<const bf16x8*>(SB(b, h) + lds_byte(wc * 32 + n * 16 + fr, k * 32 + fq * 8))
; #define WAIT_V(n) asm volatile("s_waitcnt vmcnt(" #n ")" ::: "memory")
; #define WAIT_L(n) asm volatile("s_waitcnt lgkmcnt(" #n ")" ::: "memory")
; #define BAR __builtin_amdgcn_s_barrier()
; #define SCHED __builtin_amdgcn_sched_barrier(0)
;     ...
;       LDB(B0, 0, 0); SCHED; LDA(At, 0, 0); STAGE(SA(1, 1), rsA, sA1, offA, t + 1);
;       WAIT_L(8); BAR; WAIT_L(0); MMA(0, 0, At, B0); BAR; SCHED;
;       LDB(B1, 0, 1); STAGE(SB(0, 0), rsB, sB0, offB, t + 2);
;       BAR; WAIT_L(0); MMA(0, 1, At, B1); BAR;
;       LDA(At, 0, 1); STAGE(SA(0, 0), rsA, sA0, offA, t + 2);
;       BAR; WAIT_L(0); MMA(1, 0, At, B0); BAR; SCHED;
;       STAGE(SB(0, 1), rsB, sB1, offB, t + 2);
;       WAIT_V(6); BAR; MMA(1, 1, At, B1); BAR;
.LBB0_392:
	ds_read_b128 v[152:155], v147
	ds_read_b128 v[156:159], v148
	ds_read_b128 v[160:163], v149
	ds_read_b128 v[164:167], v150
	s_add_i32 s5, s86, s3
	s_add_i32 s6, s5, 0x80
	s_mov_b32 m0, s36
	ds_read_b128 v[168:171], v129
	ds_read_b128 v[172:175], v129 offset:1024
	ds_read_b128 v[176:179], v132
	ds_read_b128 v[180:183], v132 offset:1024
	ds_read_b128 v[184:187], v131
	ds_read_b128 v[188:191], v131 offset:1024
	ds_read_b128 v[192:195], v130
	ds_read_b128 v[196:199], v130 offset:1024
	buffer_load_dwordx4 v141, s[8:11], s6 offen lds
	s_mov_b32 m0, s59
	s_nop 0
	buffer_load_dwordx4 v142, s[8:11], s6 offen lds
	s_waitcnt lgkmcnt(8)
	s_barrier
	s_waitcnt lgkmcnt(0)
	s_waitcnt lgkmcnt(7)
	v_mfma_f32_16x16x32_bf16 v[124:127], v[152:155], v[168:171], v[124:127]
	v_mfma_f32_16x16x32_bf16 v[120:123], v[160:163], v[168:171], v[120:123]
	s_waitcnt lgkmcnt(5)
	v_mfma_f32_16x16x32_bf16 v[116:119], v[152:155], v[176:179], v[116:119]
	v_mfma_f32_16x16x32_bf16 v[112:115], v[160:163], v[176:179], v[112:115]
	s_waitcnt lgkmcnt(3)
	v_mfma_f32_16x16x32_bf16 v[108:111], v[152:155], v[184:187], v[108:111]
	v_mfma_f32_16x16x32_bf16 v[104:107], v[160:163], v[184:187], v[104:107]
	s_waitcnt lgkmcnt(1)
	v_mfma_f32_16x16x32_bf16 v[100:103], v[152:155], v[192:195], v[100:103]
	v_mfma_f32_16x16x32_bf16 v[96:99], v[160:163], v[192:195], v[96:99]
	v_mfma_f32_16x16x32_bf16 v[124:127], v[156:159], v[172:175], v[124:127]
	v_mfma_f32_16x16x32_bf16 v[120:123], v[164:167], v[172:175], v[120:123]
	v_mfma_f32_16x16x32_bf16 v[116:119], v[156:159], v[180:183], v[116:119]
	v_mfma_f32_16x16x32_bf16 v[112:115], v[164:167], v[180:183], v[112:115]
	v_mfma_f32_16x16x32_bf16 v[108:111], v[156:159], v[188:191], v[108:111]
	v_mfma_f32_16x16x32_bf16 v[104:107], v[164:167], v[188:191], v[104:107]
	s_waitcnt lgkmcnt(0)
	v_mfma_f32_16x16x32_bf16 v[100:103], v[156:159], v[196:199], v[100:103]
	v_mfma_f32_16x16x32_bf16 v[96:99], v[164:167], v[196:199], v[96:99]
	s_barrier
	s_add_i32 s6, s92, s3
	s_add_i32 s7, s6, 0x100
	s_mov_b32 s14, s10
	s_mov_b32 s15, s11
	s_mov_b32 m0, s37
	ds_read_b128 v[200:203], v143
	ds_read_b128 v[204:207], v144
	ds_read_b128 v[208:211], v145
	ds_read_b128 v[212:215], v146
	buffer_load_dwordx4 v141, s[12:15], s7 offen lds
	s_mov_b32 m0, s48
	s_nop 0
	buffer_load_dwordx4 v142, s[12:15], s7 offen lds
	s_barrier
	s_waitcnt lgkmcnt(0)
	s_waitcnt lgkmcnt(3)
	v_mfma_f32_16x16x32_bf16 v[92:95], v[200:203], v[168:171], v[92:95]
	s_waitcnt lgkmcnt(1)
	v_mfma_f32_16x16x32_bf16 v[88:91], v[208:211], v[168:171], v[88:91]
	v_mfma_f32_16x16x32_bf16 v[80:83], v[200:203], v[176:179], v[80:83]
	v_mfma_f32_16x16x32_bf16 v[68:71], v[208:211], v[176:179], v[68:71]
	v_mfma_f32_16x16x32_bf16 v[60:63], v[200:203], v[184:187], v[60:63]
	v_mfma_f32_16x16x32_bf16 v[56:59], v[208:211], v[184:187], v[56:59]
	v_mfma_f32_16x16x32_bf16 v[52:55], v[200:203], v[192:195], v[52:55]
	v_mfma_f32_16x16x32_bf16 v[48:51], v[208:211], v[192:195], v[48:51]
	v_mfma_f32_16x16x32_bf16 v[92:95], v[204:207], v[172:175], v[92:95]
	s_waitcnt lgkmcnt(0)
	v_mfma_f32_16x16x32_bf16 v[88:91], v[212:215], v[172:175], v[88:91]
	v_mfma_f32_16x16x32_bf16 v[80:83], v[204:207], v[180:183], v[80:83]
	v_mfma_f32_16x16x32_bf16 v[68:71], v[212:215], v[180:183], v[68:71]
	v_mfma_f32_16x16x32_bf16 v[60:63], v[204:207], v[188:191], v[60:63]
	v_mfma_f32_16x16x32_bf16 v[56:59], v[212:215], v[188:191], v[56:59]
	v_mfma_f32_16x16x32_bf16 v[52:55], v[204:207], v[196:199], v[52:55]
	v_mfma_f32_16x16x32_bf16 v[48:51], v[212:215], v[196:199], v[48:51]
	s_add_i32 s7, s87, s3
	s_add_i32 s22, s7, 0x100
	s_mov_b32 m0, s35
	s_barrier
	ds_read_b128 v[168:171], v129 offset:16384
	ds_read_b128 v[172:175], v129 offset:17408
	ds_read_b128 v[176:179], v132 offset:16384
	ds_read_b128 v[180:183], v132 offset:17408
	ds_read_b128 v[184:187], v131 offset:16384
	ds_read_b128 v[188:191], v131 offset:17408
	ds_read_b128 v[192:195], v130 offset:16384
	ds_read_b128 v[196:199], v130 offset:17408
	buffer_load_dwordx4 v141, s[8:11], s22 offen lds
	s_mov_b32 m0, s49
	s_nop 0
	buffer_load_dwordx4 v142, s[8:11], s22 offen lds
	s_barrier
	s_waitcnt lgkmcnt(0)
	s_waitcnt lgkmcnt(7)
	v_mfma_f32_16x16x32_bf16 v[44:47], v[152:155], v[168:171], v[44:47]
	v_mfma_f32_16x16x32_bf16 v[40:43], v[160:163], v[168:171], v[40:43]
	s_waitcnt lgkmcnt(5)
	v_mfma_f32_16x16x32_bf16 v[36:39], v[152:155], v[176:179], v[36:39]
	v_mfma_f32_16x16x32_bf16 v[32:35], v[160:163], v[176:179], v[32:35]
	s_waitcnt lgkmcnt(3)
	v_mfma_f32_16x16x32_bf16 v[28:31], v[152:155], v[184:187], v[28:31]
	v_mfma_f32_16x16x32_bf16 v[24:27], v[160:163], v[184:187], v[24:27]
	s_waitcnt lgkmcnt(1)
	v_mfma_f32_16x16x32_bf16 v[20:23], v[152:155], v[192:195], v[20:23]
	v_mfma_f32_16x16x32_bf16 v[16:19], v[160:163], v[192:195], v[16:19]
	v_mfma_f32_16x16x32_bf16 v[44:47], v[156:159], v[172:175], v[44:47]
	v_mfma_f32_16x16x32_bf16 v[40:43], v[164:167], v[172:175], v[40:43]
	v_mfma_f32_16x16x32_bf16 v[36:39], v[156:159], v[180:183], v[36:39]
	v_mfma_f32_16x16x32_bf16 v[32:35], v[164:167], v[180:183], v[32:35]
	v_mfma_f32_16x16x32_bf16 v[28:31], v[156:159], v[188:191], v[28:31]
	v_mfma_f32_16x16x32_bf16 v[24:27], v[164:167], v[188:191], v[24:27]
	s_waitcnt lgkmcnt(0)
	v_mfma_f32_16x16x32_bf16 v[20:23], v[156:159], v[196:199], v[20:23]
	v_mfma_f32_16x16x32_bf16 v[16:19], v[164:167], v[196:199], v[16:19]
	s_barrier
	s_add_i32 s22, s93, s3
	s_add_i32 s23, s22, 0x100
	s_mov_b32 m0, s38
	s_nop 0
	buffer_load_dwordx4 v141, s[12:15], s23 offen lds
	s_mov_b32 m0, s54
	s_nop 0
	buffer_load_dwordx4 v142, s[12:15], s23 offen lds
	s_waitcnt vmcnt(6)
	s_barrier
; #define STAGE(P, RS, SOFF, OFF, kt) do { const int _so = (SOFF) + (kt) * (BK * 2); \
;     _Pragma("unroll") for (int _i = 0; _i < 2; ++_i) { \
;       __builtin_amdgcn_raw_ptr_buffer_load_lds(RS, (__attribute__((address_space(3))) void*)((P) + wave * 1024 + _i * 8192), 16, OFF[_i], _so, 0, 0); } } while (0)
; #define LDA(dst, b, h) _Pragma("unroll") for (int m = 0; m < 4; ++m) _Pragma("unroll") for (int k = 0; k < 2; ++k) \
;     dst[m][k] = *reinterpret_cast<const bf16x8*>(SA(b, h) + lds_byte(wr * 64 + m * 16 + fr, k * 32 + fq * 8))
; #define LDB(dst, b, h) _Pragma("unroll") for (int n = 0; n < 2; ++n) _Pragma("unroll") for (int k = 0; k < 2; ++k) \
;     dst[n][k] = *reinterpret_cast<const bf16x8*>(SB(b, h) + lds_byte(wc * 32 + n * 16 + fr, k * 32 + fq * 8))
; #define WAIT_V(n) asm volatile("s_waitcnt vmcnt(" #n ")" ::: "memory")
; #define WAIT_L(n) asm volatile("s_waitcnt lgkmcnt(" #n ")" ::: "memory")
; #define BAR __builtin_amdgcn_s_barrier()
; #define SCHED __builtin_amdgcn_sched_barrier(0)
;     ...
;       WAIT_V(6); BAR; MMA(1, 1, At, B1); BAR;
;       LDB(B0, 1, 0); SCHED; LDA(At, 1, 0); STAGE(SA(0, 1), rsA, sA1, offA, t + 2);
;       WAIT_L(8); BAR; WAIT_L(0); MMA(0, 0, At, B0); BAR; SCHED;
;       LDB(B1, 1, 1); STAGE(SB(1, 0), rsB, sB0, offB, t + 3);
;       BAR; WAIT_L(0); MMA(0, 1, At, B1); BAR;
;       LDA(At, 1, 1); STAGE(SA(1, 0), rsA, sA0, offA, t + 3);
;       BAR; WAIT_L(0); MMA(1, 0, At, B0); BAR; SCHED;
;       STAGE(SB(1, 1), rsB, sB1, offB, t + 3);
	v_mfma_f32_16x16x32_bf16 v[12:15], v[200:203], v[168:171], v[12:15]
	v_mfma_f32_16x16x32_bf16 v[8:11], v[208:211], v[168:171], v[8:11]
	v_mfma_f32_16x16x32_bf16 v[4:7], v[200:203], v[176:179], v[4:7]
	v_mfma_f32_16x16x32_bf16 v[0:3], v[208:211], v[176:179], v[0:3]
	v_mfma_f32_16x16x32_bf16 v[64:67], v[200:203], v[184:187], v[64:67]
	v_mfma_f32_16x16x32_bf16 v[72:75], v[208:211], v[184:187], v[72:75]
	v_mfma_f32_16x16x32_bf16 v[76:79], v[200:203], v[192:195], v[76:79]
	v_mfma_f32_16x16x32_bf16 v[84:87], v[208:211], v[192:195], v[84:87]
	v_mfma_f32_16x16x32_bf16 v[12:15], v[204:207], v[172:175], v[12:15]
	v_mfma_f32_16x16x32_bf16 v[8:11], v[212:215], v[172:175], v[8:11]
	v_mfma_f32_16x16x32_bf16 v[4:7], v[204:207], v[180:183], v[4:7]
	v_mfma_f32_16x16x32_bf16 v[0:3], v[212:215], v[180:183], v[0:3]
	v_mfma_f32_16x16x32_bf16 v[64:67], v[204:207], v[188:191], v[64:67]
	v_mfma_f32_16x16x32_bf16 v[72:75], v[212:215], v[188:191], v[72:75]
	v_mfma_f32_16x16x32_bf16 v[76:79], v[204:207], v[196:199], v[76:79]
	v_mfma_f32_16x16x32_bf16 v[84:87], v[212:215], v[196:199], v[84:87]
	s_barrier
	ds_read_b128 v[152:155], v137
	ds_read_b128 v[156:159], v138
	ds_read_b128 v[160:163], v139
	ds_read_b128 v[164:167], v140
	s_addk_i32 s5, 0x100
	s_mov_b32 m0, s39
	ds_read_b128 v[168:171], v129 offset:32768
	ds_read_b128 v[172:175], v129 offset:33792
	ds_read_b128 v[176:179], v132 offset:32768
	ds_read_b128 v[180:183], v132 offset:33792
	ds_read_b128 v[184:187], v131 offset:32768
	ds_read_b128 v[188:191], v131 offset:33792
	ds_read_b128 v[192:195], v130 offset:32768
	ds_read_b128 v[196:199], v130 offset:33792
	buffer_load_dwordx4 v141, s[8:11], s5 offen lds
	s_mov_b32 m0, s55
	s_nop 0
	buffer_load_dwordx4 v142, s[8:11], s5 offen lds
	s_waitcnt lgkmcnt(8)
	s_barrier
	s_waitcnt lgkmcnt(0)
	s_waitcnt lgkmcnt(7)
	v_mfma_f32_16x16x32_bf16 v[124:127], v[152:155], v[168:171], v[124:127]
	v_mfma_f32_16x16x32_bf16 v[120:123], v[160:163], v[168:171], v[120:123]
	s_waitcnt lgkmcnt(5)
	v_mfma_f32_16x16x32_bf16 v[116:119], v[152:155], v[176:179], v[116:119]
	v_mfma_f32_16x16x32_bf16 v[112:115], v[160:163], v[176:179], v[112:115]
	s_waitcnt lgkmcnt(3)
	v_mfma_f32_16x16x32_bf16 v[108:111], v[152:155], v[184:187], v[108:111]
	v_mfma_f32_16x16x32_bf16 v[104:107], v[160:163], v[184:187], v[104:107]
	s_waitcnt lgkmcnt(1)
	v_mfma_f32_16x16x32_bf16 v[100:103], v[152:155], v[192:195], v[100:103]
	v_mfma_f32_16x16x32_bf16 v[96:99], v[160:163], v[192:195], v[96:99]
	v_mfma_f32_16x16x32_bf16 v[124:127], v[156:159], v[172:175], v[124:127]
	v_mfma_f32_16x16x32_bf16 v[120:123], v[164:167], v[172:175], v[120:123]
	v_mfma_f32_16x16x32_bf16 v[116:119], v[156:159], v[180:183], v[116:119]
	v_mfma_f32_16x16x32_bf16 v[112:115], v[164:167], v[180:183], v[112:115]
	v_mfma_f32_16x16x32_bf16 v[108:111], v[156:159], v[188:191], v[108:111]
	v_mfma_f32_16x16x32_bf16 v[104:107], v[164:167], v[188:191], v[104:107]
	s_waitcnt lgkmcnt(0)
	v_mfma_f32_16x16x32_bf16 v[100:103], v[156:159], v[196:199], v[100:103]
	v_mfma_f32_16x16x32_bf16 v[96:99], v[164:167], v[196:199], v[96:99]
	s_barrier
	s_addk_i32 s6, 0x180
	s_mov_b32 m0, s42
	ds_read_b128 v[200:203], v133
	ds_read_b128 v[204:207], v134
	ds_read_b128 v[208:211], v135
	ds_read_b128 v[212:215], v136
	buffer_load_dwordx4 v141, s[12:15], s6 offen lds
	s_mov_b32 m0, s56
	s_nop 0
	buffer_load_dwordx4 v142, s[12:15], s6 offen lds
	s_barrier
	s_waitcnt lgkmcnt(0)
	s_waitcnt lgkmcnt(3)
	v_mfma_f32_16x16x32_bf16 v[92:95], v[200:203], v[168:171], v[92:95]
	s_waitcnt lgkmcnt(1)
	v_mfma_f32_16x16x32_bf16 v[88:91], v[208:211], v[168:171], v[88:91]
	v_mfma_f32_16x16x32_bf16 v[80:83], v[200:203], v[176:179], v[80:83]
	v_mfma_f32_16x16x32_bf16 v[68:71], v[208:211], v[176:179], v[68:71]
	v_mfma_f32_16x16x32_bf16 v[60:63], v[200:203], v[184:187], v[60:63]
	v_mfma_f32_16x16x32_bf16 v[56:59], v[208:211], v[184:187], v[56:59]
	v_mfma_f32_16x16x32_bf16 v[52:55], v[200:203], v[192:195], v[52:55]
	v_mfma_f32_16x16x32_bf16 v[48:51], v[208:211], v[192:195], v[48:51]
	v_mfma_f32_16x16x32_bf16 v[92:95], v[204:207], v[172:175], v[92:95]
	s_waitcnt lgkmcnt(0)
	v_mfma_f32_16x16x32_bf16 v[88:91], v[212:215], v[172:175], v[88:91]
	v_mfma_f32_16x16x32_bf16 v[80:83], v[204:207], v[180:183], v[80:83]
	v_mfma_f32_16x16x32_bf16 v[68:71], v[212:215], v[180:183], v[68:71]
	v_mfma_f32_16x16x32_bf16 v[60:63], v[204:207], v[188:191], v[60:63]
	v_mfma_f32_16x16x32_bf16 v[56:59], v[212:215], v[188:191], v[56:59]
	v_mfma_f32_16x16x32_bf16 v[52:55], v[204:207], v[196:199], v[52:55]
	v_mfma_f32_16x16x32_bf16 v[48:51], v[212:215], v[196:199], v[48:51]
	s_addk_i32 s7, 0x180
	s_mov_b32 m0, s43
	s_barrier
	ds_read_b128 v[168:171], v129 offset:49152
	ds_read_b128 v[172:175], v129 offset:50176
	ds_read_b128 v[176:179], v132 offset:49152
	ds_read_b128 v[180:183], v132 offset:50176
	ds_read_b128 v[184:187], v131 offset:49152
	ds_read_b128 v[188:191], v131 offset:50176
	ds_read_b128 v[192:195], v130 offset:49152
	ds_read_b128 v[196:199], v130 offset:50176
	buffer_load_dwordx4 v141, s[8:11], s7 offen lds
	s_mov_b32 m0, s57
	s_nop 0
	buffer_load_dwordx4 v142, s[8:11], s7 offen lds
	s_barrier
; #define STAGE(P, RS, SOFF, OFF, kt) do { const int _so = (SOFF) + (kt) * (BK * 2); \
;     _Pragma("unroll") for (int _i = 0; _i < 2; ++_i) { \
;       __builtin_amdgcn_raw_ptr_buffer_load_lds(RS, (__attribute__((address_space(3))) void*)((P) + wave * 1024 + _i * 8192), 16, OFF[_i], _so, 0, 0); } } while (0)
; #define LDA(dst, b, h) _Pragma("unroll") for (int m = 0; m < 4; ++m) _Pragma("unroll") for (int k = 0; k < 2; ++k) \
;     dst[m][k] = *reinterpret_cast<const bf16x8*>(SA(b, h) + lds_byte(wr * 64 + m * 16 + fr, k * 32 + fq * 8))
; #define LDB(dst, b, h) _Pragma("unroll") for (int n = 0; n < 2; ++n) _Pragma("unroll") for (int k = 0; k < 2; ++k) \
;     dst[n][k] = *reinterpret_cast<const bf16x8*>(SB(b, h) + lds_byte(wc * 32 + n * 16 + fr, k * 32 + fq * 8))
; #define WAIT_V(n) asm volatile("s_waitcnt vmcnt(" #n ")" ::: "memory")
; #define WAIT_L(n) asm volatile("s_waitcnt lgkmcnt(" #n ")" ::: "memory")
; #define BAR __builtin_amdgcn_s_barrier()
; #define SCHED __builtin_amdgcn_sched_barrier(0)
;     ...
;       BAR; WAIT_L(0); MMA(1, 0, At, B0); BAR; SCHED;
;       STAGE(SB(1, 1), rsB, sB1, offB, t + 3);
;       WAIT_V(6); BAR; MMA(1, 1, At, B1); BAR;
;     }
;     { LDB(B0, 0, 0); LDA(At, 0, 0); STAGE(SA(1, 1), rsA, sA1, offA, nt - 1);
;       BAR; WAIT_L(0); MMA(0, 0, At, B0); BAR;
;       LDB(B1, 0, 1); BAR; WAIT_L(0); MMA(0, 1, At, B1); BAR;
	s_waitcnt lgkmcnt(0)
	s_waitcnt lgkmcnt(7)
	v_mfma_f32_16x16x32_bf16 v[44:47], v[152:155], v[168:171], v[44:47]
	v_mfma_f32_16x16x32_bf16 v[40:43], v[160:163], v[168:171], v[40:43]
	s_waitcnt lgkmcnt(5)
	v_mfma_f32_16x16x32_bf16 v[36:39], v[152:155], v[176:179], v[36:39]
	v_mfma_f32_16x16x32_bf16 v[32:35], v[160:163], v[176:179], v[32:35]
	s_waitcnt lgkmcnt(3)
	v_mfma_f32_16x16x32_bf16 v[28:31], v[152:155], v[184:187], v[28:31]
	v_mfma_f32_16x16x32_bf16 v[24:27], v[160:163], v[184:187], v[24:27]
	s_waitcnt lgkmcnt(1)
	v_mfma_f32_16x16x32_bf16 v[20:23], v[152:155], v[192:195], v[20:23]
	v_mfma_f32_16x16x32_bf16 v[16:19], v[160:163], v[192:195], v[16:19]
	v_mfma_f32_16x16x32_bf16 v[44:47], v[156:159], v[172:175], v[44:47]
	v_mfma_f32_16x16x32_bf16 v[40:43], v[164:167], v[172:175], v[40:43]
	v_mfma_f32_16x16x32_bf16 v[36:39], v[156:159], v[180:183], v[36:39]
	v_mfma_f32_16x16x32_bf16 v[32:35], v[164:167], v[180:183], v[32:35]
	v_mfma_f32_16x16x32_bf16 v[28:31], v[156:159], v[188:191], v[28:31]
	v_mfma_f32_16x16x32_bf16 v[24:27], v[164:167], v[188:191], v[24:27]
	s_waitcnt lgkmcnt(0)
	v_mfma_f32_16x16x32_bf16 v[20:23], v[156:159], v[196:199], v[20:23]
	v_mfma_f32_16x16x32_bf16 v[16:19], v[164:167], v[196:199], v[16:19]
	s_barrier
	s_addk_i32 s22, 0x180
	s_mov_b32 m0, s44
	s_nop 0
	buffer_load_dwordx4 v141, s[12:15], s22 offen lds
	s_mov_b32 m0, s58
	s_nop 0
	buffer_load_dwordx4 v142, s[12:15], s22 offen lds
	s_waitcnt vmcnt(6)
	s_barrier
	v_mfma_f32_16x16x32_bf16 v[12:15], v[200:203], v[168:171], v[12:15]
	v_mfma_f32_16x16x32_bf16 v[8:11], v[208:211], v[168:171], v[8:11]
	v_mfma_f32_16x16x32_bf16 v[4:7], v[200:203], v[176:179], v[4:7]
	v_mfma_f32_16x16x32_bf16 v[0:3], v[208:211], v[176:179], v[0:3]
	v_mfma_f32_16x16x32_bf16 v[64:67], v[200:203], v[184:187], v[64:67]
	v_mfma_f32_16x16x32_bf16 v[72:75], v[208:211], v[184:187], v[72:75]
	v_mfma_f32_16x16x32_bf16 v[76:79], v[200:203], v[192:195], v[76:79]
	v_mfma_f32_16x16x32_bf16 v[84:87], v[208:211], v[192:195], v[84:87]
	v_mfma_f32_16x16x32_bf16 v[12:15], v[204:207], v[172:175], v[12:15]
	v_mfma_f32_16x16x32_bf16 v[8:11], v[212:215], v[172:175], v[8:11]
	v_mfma_f32_16x16x32_bf16 v[4:7], v[204:207], v[180:183], v[4:7]
	v_mfma_f32_16x16x32_bf16 v[0:3], v[212:215], v[180:183], v[0:3]
	v_mfma_f32_16x16x32_bf16 v[64:67], v[204:207], v[188:191], v[64:67]
	v_mfma_f32_16x16x32_bf16 v[72:75], v[212:215], v[188:191], v[72:75]
	v_mfma_f32_16x16x32_bf16 v[76:79], v[204:207], v[196:199], v[76:79]
	v_mfma_f32_16x16x32_bf16 v[84:87], v[212:215], v[196:199], v[84:87]
	s_add_i32 s1, s1, 2
	s_addk_i32 s3, 0x100
	s_cmp_gt_u32 s1, 59
	s_barrier
	s_cbranch_scc0 .LBB0_392
	s_add_i32 s1, s86, 0x1f80
	s_mov_b32 m0, s36
	ds_read_b128 v[152:155], v147
	ds_read_b128 v[156:159], v148
	ds_read_b128 v[160:163], v149
	ds_read_b128 v[148:151], v150
	ds_read_b128 v[164:167], v129
	ds_read_b128 v[168:171], v129 offset:1024
	ds_read_b128 v[172:175], v132
	ds_read_b128 v[176:179], v132 offset:1024
	ds_read_b128 v[180:183], v131
	ds_read_b128 v[184:187], v131 offset:1024
	ds_read_b128 v[188:191], v130
	ds_read_b128 v[192:195], v130 offset:1024
	buffer_load_dwordx4 v141, s[8:11], s1 offen lds
	s_mov_b32 m0, s59
	s_nop 0
	buffer_load_dwordx4 v142, s[8:11], s1 offen lds
	s_barrier
	s_waitcnt lgkmcnt(0)
	s_waitcnt lgkmcnt(7)
	v_mfma_f32_16x16x32_bf16 v[124:127], v[152:155], v[164:167], v[124:127]
	v_mfma_f32_16x16x32_bf16 v[120:123], v[160:163], v[164:167], v[120:123]
	s_waitcnt lgkmcnt(5)
	v_mfma_f32_16x16x32_bf16 v[116:119], v[152:155], v[172:175], v[116:119]
	v_mfma_f32_16x16x32_bf16 v[112:115], v[160:163], v[172:175], v[112:115]
	s_waitcnt lgkmcnt(3)
	v_mfma_f32_16x16x32_bf16 v[108:111], v[152:155], v[180:183], v[108:111]
	v_mfma_f32_16x16x32_bf16 v[104:107], v[160:163], v[180:183], v[104:107]
	s_waitcnt lgkmcnt(1)
	v_mfma_f32_16x16x32_bf16 v[100:103], v[152:155], v[188:191], v[100:103]
	v_mfma_f32_16x16x32_bf16 v[96:99], v[160:163], v[188:191], v[96:99]
	v_mfma_f32_16x16x32_bf16 v[124:127], v[156:159], v[168:171], v[124:127]
	v_mfma_f32_16x16x32_bf16 v[120:123], v[148:151], v[168:171], v[120:123]
	v_mfma_f32_16x16x32_bf16 v[116:119], v[156:159], v[176:179], v[116:119]
	v_mfma_f32_16x16x32_bf16 v[112:115], v[148:151], v[176:179], v[112:115]
	v_mfma_f32_16x16x32_bf16 v[108:111], v[156:159], v[184:187], v[108:111]
	v_mfma_f32_16x16x32_bf16 v[104:107], v[148:151], v[184:187], v[104:107]
	s_waitcnt lgkmcnt(0)
	v_mfma_f32_16x16x32_bf16 v[100:103], v[156:159], v[192:195], v[100:103]
	v_mfma_f32_16x16x32_bf16 v[96:99], v[148:151], v[192:195], v[96:99]
	s_barrier
	ds_read_b128 v[196:199], v143
	ds_read_b128 v[200:203], v144
	ds_read_b128 v[142:145], v145
	ds_read_b128 v[204:207], v146
	s_barrier
	s_waitcnt lgkmcnt(0)
	s_waitcnt lgkmcnt(3)
	v_mfma_f32_16x16x32_bf16 v[80:83], v[196:199], v[172:175], v[80:83]
	s_waitcnt lgkmcnt(1)
	v_mfma_f32_16x16x32_bf16 v[68:71], v[142:145], v[172:175], v[68:71]
	v_mfma_f32_16x16x32_bf16 v[60:63], v[196:199], v[180:183], v[60:63]
	v_mfma_f32_16x16x32_bf16 v[56:59], v[142:145], v[180:183], v[56:59]
	v_mfma_f32_16x16x32_bf16 v[52:55], v[196:199], v[188:191], v[52:55]
	v_mfma_f32_16x16x32_bf16 v[48:51], v[142:145], v[188:191], v[48:51]
	v_mfma_f32_16x16x32_bf16 v[92:95], v[196:199], v[164:167], v[92:95]
	v_mfma_f32_16x16x32_bf16 v[88:91], v[142:145], v[164:167], v[88:91]
	v_mfma_f32_16x16x32_bf16 v[80:83], v[200:203], v[176:179], v[80:83]
	s_waitcnt lgkmcnt(0)
	v_mfma_f32_16x16x32_bf16 v[68:71], v[204:207], v[176:179], v[68:71]
	v_mfma_f32_16x16x32_bf16 v[60:63], v[200:203], v[184:187], v[60:63]
	v_mfma_f32_16x16x32_bf16 v[56:59], v[204:207], v[184:187], v[56:59]
	v_mfma_f32_16x16x32_bf16 v[52:55], v[200:203], v[192:195], v[52:55]
	v_mfma_f32_16x16x32_bf16 v[48:51], v[204:207], v[192:195], v[48:51]
	v_mfma_f32_16x16x32_bf16 v[164:167], v[200:203], v[168:171], v[92:95]
	v_mfma_f32_16x16x32_bf16 v[168:171], v[204:207], v[168:171], v[88:91]
	s_barrier
; #define LDA(dst, b, h) _Pragma("unroll") for (int m = 0; m < 4; ++m) _Pragma("unroll") for (int k = 0; k < 2; ++k) \
;     dst[m][k] = *reinterpret_cast<const bf16x8*>(SA(b, h) + lds_byte(wr * 64 + m * 16 + fr, k * 32 + fq * 8))
; #define LDB(dst, b, h) _Pragma("unroll") for (int n = 0; n < 2; ++n) _Pragma("unroll") for (int k = 0; k < 2; ++k) \
;     dst[n][k] = *reinterpret_cast<const bf16x8*>(SB(b, h) + lds_byte(wc * 32 + n * 16 + fr, k * 32 + fq * 8))
; #define WAIT_V(n) asm volatile("s_waitcnt vmcnt(" #n ")" ::: "memory")
; #define WAIT_L(n) asm volatile("s_waitcnt lgkmcnt(" #n ")" ::: "memory")
; #define BAR __builtin_amdgcn_s_barrier()
;     ...
;       LDB(B1, 0, 1); BAR; WAIT_L(0); MMA(0, 1, At, B1); BAR;
;       LDA(At, 0, 1); WAIT_V(4); BAR; WAIT_L(0); MMA(1, 0, At, B0); MMA(1, 1, At, B1); BAR; }
;     { LDB(B0, 1, 0); LDA(At, 1, 0); WAIT_V(2); BAR; WAIT_L(0); MMA(0, 0, At, B0); BAR;
;       LDB(B1, 1, 1); WAIT_V(0); BAR; WAIT_L(0); MMA(0, 1, At, B1); BAR;
	s_nop 0
	ds_read_b128 v[88:91], v129 offset:16384
	ds_read_b128 v[92:95], v129 offset:17408
	ds_read_b128 v[172:175], v132 offset:16384
	ds_read_b128 v[176:179], v132 offset:17408
	ds_read_b128 v[180:183], v131 offset:16384
	ds_read_b128 v[184:187], v131 offset:17408
	ds_read_b128 v[188:191], v130 offset:16384
	ds_read_b128 v[192:195], v130 offset:17408
	s_waitcnt vmcnt(4)
	s_barrier
	s_waitcnt lgkmcnt(0)
	s_waitcnt lgkmcnt(7)
	v_mfma_f32_16x16x32_bf16 v[44:47], v[152:155], v[88:91], v[44:47]
	v_mfma_f32_16x16x32_bf16 v[40:43], v[160:163], v[88:91], v[40:43]
	s_waitcnt lgkmcnt(5)
	v_mfma_f32_16x16x32_bf16 v[36:39], v[152:155], v[172:175], v[36:39]
	v_mfma_f32_16x16x32_bf16 v[32:35], v[160:163], v[172:175], v[32:35]
	s_waitcnt lgkmcnt(3)
	v_mfma_f32_16x16x32_bf16 v[28:31], v[152:155], v[180:183], v[28:31]
	v_mfma_f32_16x16x32_bf16 v[24:27], v[160:163], v[180:183], v[24:27]
	s_waitcnt lgkmcnt(1)
	v_mfma_f32_16x16x32_bf16 v[20:23], v[152:155], v[188:191], v[20:23]
	v_mfma_f32_16x16x32_bf16 v[16:19], v[160:163], v[188:191], v[16:19]
	v_mfma_f32_16x16x32_bf16 v[44:47], v[156:159], v[92:95], v[44:47]
	v_mfma_f32_16x16x32_bf16 v[40:43], v[148:151], v[92:95], v[40:43]
	v_mfma_f32_16x16x32_bf16 v[36:39], v[156:159], v[176:179], v[36:39]
	v_mfma_f32_16x16x32_bf16 v[32:35], v[148:151], v[176:179], v[32:35]
	v_mfma_f32_16x16x32_bf16 v[28:31], v[156:159], v[184:187], v[28:31]
	v_mfma_f32_16x16x32_bf16 v[24:27], v[148:151], v[184:187], v[24:27]
	s_waitcnt lgkmcnt(0)
	v_mfma_f32_16x16x32_bf16 v[20:23], v[156:159], v[192:195], v[20:23]
	v_mfma_f32_16x16x32_bf16 v[16:19], v[148:151], v[192:195], v[16:19]
	v_mfma_f32_16x16x32_bf16 v[4:7], v[196:199], v[172:175], v[4:7]
	v_mfma_f32_16x16x32_bf16 v[0:3], v[142:145], v[172:175], v[0:3]
	v_mfma_f32_16x16x32_bf16 v[12:15], v[196:199], v[88:91], v[12:15]
	v_mfma_f32_16x16x32_bf16 v[8:11], v[142:145], v[88:91], v[8:11]
	v_mfma_f32_16x16x32_bf16 v[64:67], v[196:199], v[180:183], v[64:67]
	v_mfma_f32_16x16x32_bf16 v[72:75], v[142:145], v[180:183], v[72:75]
	v_mfma_f32_16x16x32_bf16 v[76:79], v[196:199], v[188:191], v[76:79]
	v_mfma_f32_16x16x32_bf16 v[84:87], v[142:145], v[188:191], v[84:87]
	v_mfma_f32_16x16x32_bf16 v[4:7], v[200:203], v[176:179], v[4:7]
	v_mfma_f32_16x16x32_bf16 v[0:3], v[204:207], v[176:179], v[0:3]
	v_mfma_f32_16x16x32_bf16 v[142:145], v[200:203], v[92:95], v[12:15]
	v_mfma_f32_16x16x32_bf16 v[146:149], v[204:207], v[92:95], v[8:11]
	v_mfma_f32_16x16x32_bf16 v[150:153], v[200:203], v[184:187], v[64:67]
	v_mfma_f32_16x16x32_bf16 v[154:157], v[204:207], v[184:187], v[72:75]
	v_mfma_f32_16x16x32_bf16 v[158:161], v[200:203], v[192:195], v[76:79]
	v_mfma_f32_16x16x32_bf16 v[172:175], v[204:207], v[192:195], v[84:87]
	s_barrier
	ds_read_b128 v[8:11], v137
	ds_read_b128 v[12:15], v138
	ds_read_b128 v[176:179], v139
	ds_read_b128 v[138:141], v140
	ds_read_b128 v[64:67], v129 offset:32768
	ds_read_b128 v[84:87], v129 offset:33792
	ds_read_b128 v[180:183], v132 offset:32768
	ds_read_b128 v[184:187], v132 offset:33792
	ds_read_b128 v[188:191], v131 offset:32768
	ds_read_b128 v[192:195], v131 offset:33792
	ds_read_b128 v[196:199], v130 offset:32768
	ds_read_b128 v[200:203], v130 offset:33792
	s_waitcnt vmcnt(2)
	s_barrier
	s_waitcnt lgkmcnt(0)
	s_waitcnt lgkmcnt(7)
	v_mfma_f32_16x16x32_bf16 v[72:75], v[8:11], v[64:67], v[124:127]
	v_mfma_f32_16x16x32_bf16 v[76:79], v[176:179], v[64:67], v[120:123]
	s_waitcnt lgkmcnt(5)
	v_mfma_f32_16x16x32_bf16 v[88:91], v[8:11], v[180:183], v[116:119]
	v_mfma_f32_16x16x32_bf16 v[92:95], v[176:179], v[180:183], v[112:115]
	s_waitcnt lgkmcnt(3)
	v_mfma_f32_16x16x32_bf16 v[112:115], v[8:11], v[188:191], v[108:111]
	v_mfma_f32_16x16x32_bf16 v[120:123], v[176:179], v[188:191], v[104:107]
	s_waitcnt lgkmcnt(1)
	v_mfma_f32_16x16x32_bf16 v[100:103], v[8:11], v[196:199], v[100:103]
	v_mfma_f32_16x16x32_bf16 v[96:99], v[176:179], v[196:199], v[96:99]
	v_mfma_f32_16x16x32_bf16 v[124:127], v[12:15], v[84:87], v[72:75]
	v_mfma_f32_16x16x32_bf16 v[116:119], v[138:141], v[84:87], v[76:79]
	v_mfma_f32_16x16x32_bf16 v[108:111], v[12:15], v[184:187], v[88:91]
	v_mfma_f32_16x16x32_bf16 v[104:107], v[138:141], v[184:187], v[92:95]
	v_mfma_f32_16x16x32_bf16 v[92:95], v[12:15], v[192:195], v[112:115]
	v_mfma_f32_16x16x32_bf16 v[88:91], v[138:141], v[192:195], v[120:123]
	s_waitcnt lgkmcnt(0)
	v_mfma_f32_16x16x32_bf16 v[76:79], v[12:15], v[200:203], v[100:103]
	v_mfma_f32_16x16x32_bf16 v[72:75], v[138:141], v[200:203], v[96:99]
	s_barrier
; #define LDA(dst, b, h) _Pragma("unroll") for (int m = 0; m < 4; ++m) _Pragma("unroll") for (int k = 0; k < 2; ++k) \
;     dst[m][k] = *reinterpret_cast<const bf16x8*>(SA(b, h) + lds_byte(wr * 64 + m * 16 + fr, k * 32 + fq * 8))
; #define LDB(dst, b, h) _Pragma("unroll") for (int n = 0; n < 2; ++n) _Pragma("unroll") for (int k = 0; k < 2; ++k) \
;     dst[n][k] = *reinterpret_cast<const bf16x8*>(SB(b, h) + lds_byte(wc * 32 + n * 16 + fr, k * 32 + fq * 8))
; #define WAIT_V(n) asm volatile("s_waitcnt vmcnt(" #n ")" ::: "memory")
; #define WAIT_L(n) asm volatile("s_waitcnt lgkmcnt(" #n ")" ::: "memory")
; #define BAR __builtin_amdgcn_s_barrier()
;     ...
;     { LDB(B0, 1, 0); LDA(At, 1, 0); WAIT_V(2); BAR; WAIT_L(0); MMA(0, 0, At, B0); BAR;
;       LDB(B1, 1, 1); WAIT_V(0); BAR; WAIT_L(0); MMA(0, 1, At, B1); BAR;
;       LDA(At, 1, 1); BAR; WAIT_L(0); MMA(1, 0, At, B0); MMA(1, 1, At, B1); BAR; }
;     if (wr == 0) BAR;
	ds_read_b128 v[204:207], v133
	ds_read_b128 v[208:211], v134
	ds_read_b128 v[212:215], v135
	ds_read_b128 v[134:137], v136
	s_waitcnt vmcnt(0)
	s_barrier
	s_waitcnt lgkmcnt(0)
	s_waitcnt lgkmcnt(3)
	v_mfma_f32_16x16x32_bf16 v[96:99], v[204:207], v[64:67], v[164:167]
	s_waitcnt lgkmcnt(1)
	v_mfma_f32_16x16x32_bf16 v[64:67], v[212:215], v[64:67], v[168:171]
	v_mfma_f32_16x16x32_bf16 v[80:83], v[204:207], v[180:183], v[80:83]
	v_mfma_f32_16x16x32_bf16 v[68:71], v[212:215], v[180:183], v[68:71]
	v_mfma_f32_16x16x32_bf16 v[60:63], v[204:207], v[188:191], v[60:63]
	v_mfma_f32_16x16x32_bf16 v[56:59], v[212:215], v[188:191], v[56:59]
	v_mfma_f32_16x16x32_bf16 v[52:55], v[204:207], v[196:199], v[52:55]
	v_mfma_f32_16x16x32_bf16 v[48:51], v[212:215], v[196:199], v[48:51]
	v_mfma_f32_16x16x32_bf16 v[120:123], v[208:211], v[84:87], v[96:99]
	s_waitcnt lgkmcnt(0)
	v_mfma_f32_16x16x32_bf16 v[112:115], v[134:137], v[84:87], v[64:67]
	v_mfma_f32_16x16x32_bf16 v[100:103], v[208:211], v[184:187], v[80:83]
	v_mfma_f32_16x16x32_bf16 v[96:99], v[134:137], v[184:187], v[68:71]
	v_mfma_f32_16x16x32_bf16 v[84:87], v[208:211], v[192:195], v[60:63]
	v_mfma_f32_16x16x32_bf16 v[80:83], v[134:137], v[192:195], v[56:59]
	v_mfma_f32_16x16x32_bf16 v[68:71], v[208:211], v[200:203], v[52:55]
	v_mfma_f32_16x16x32_bf16 v[64:67], v[134:137], v[200:203], v[48:51]
	s_barrier
	s_nop 0
	ds_read_b128 v[48:51], v129 offset:49152
	ds_read_b128 v[162:165], v129 offset:50176
	ds_read_b128 v[52:55], v132 offset:49152
	ds_read_b128 v[166:169], v132 offset:50176
	ds_read_b128 v[180:183], v131 offset:49152
	ds_read_b128 v[184:187], v131 offset:50176
	ds_read_b128 v[188:191], v130 offset:49152
	ds_read_b128 v[130:133], v130 offset:50176
	s_barrier
	s_waitcnt lgkmcnt(0)
	s_waitcnt lgkmcnt(7)
	v_mfma_f32_16x16x32_bf16 v[44:47], v[8:11], v[48:51], v[44:47]
	v_mfma_f32_16x16x32_bf16 v[40:43], v[176:179], v[48:51], v[40:43]
	s_waitcnt lgkmcnt(5)
	v_mfma_f32_16x16x32_bf16 v[36:39], v[8:11], v[52:55], v[36:39]
	v_mfma_f32_16x16x32_bf16 v[32:35], v[176:179], v[52:55], v[32:35]
	s_waitcnt lgkmcnt(3)
	v_mfma_f32_16x16x32_bf16 v[28:31], v[8:11], v[180:183], v[28:31]
	v_mfma_f32_16x16x32_bf16 v[24:27], v[176:179], v[180:183], v[24:27]
	s_waitcnt lgkmcnt(1)
	v_mfma_f32_16x16x32_bf16 v[8:11], v[8:11], v[188:191], v[20:23]
	v_mfma_f32_16x16x32_bf16 v[16:19], v[176:179], v[188:191], v[16:19]
	v_mfma_f32_16x16x32_bf16 v[60:63], v[12:15], v[162:165], v[44:47]
	v_mfma_f32_16x16x32_bf16 v[56:59], v[138:141], v[162:165], v[40:43]
	v_mfma_f32_16x16x32_bf16 v[44:47], v[12:15], v[166:169], v[36:39]
	v_mfma_f32_16x16x32_bf16 v[40:43], v[138:141], v[166:169], v[32:35]
	v_mfma_f32_16x16x32_bf16 v[28:31], v[12:15], v[184:187], v[28:31]
	v_mfma_f32_16x16x32_bf16 v[24:27], v[138:141], v[184:187], v[24:27]
	s_waitcnt lgkmcnt(0)
	v_mfma_f32_16x16x32_bf16 v[12:15], v[12:15], v[130:133], v[8:11]
	v_mfma_f32_16x16x32_bf16 v[8:11], v[138:141], v[130:133], v[16:19]
	v_mfma_f32_16x16x32_bf16 v[16:19], v[204:207], v[48:51], v[142:145]
	v_mfma_f32_16x16x32_bf16 v[20:23], v[212:215], v[48:51], v[146:149]
	v_mfma_f32_16x16x32_bf16 v[4:7], v[204:207], v[52:55], v[4:7]
	v_mfma_f32_16x16x32_bf16 v[0:3], v[212:215], v[52:55], v[0:3]
	v_mfma_f32_16x16x32_bf16 v[138:141], v[204:207], v[180:183], v[150:153]
	v_mfma_f32_16x16x32_bf16 v[142:145], v[212:215], v[180:183], v[154:157]
	v_mfma_f32_16x16x32_bf16 v[146:149], v[204:207], v[188:191], v[158:161]
	v_mfma_f32_16x16x32_bf16 v[150:153], v[212:215], v[188:191], v[172:175]
	v_mfma_f32_16x16x32_bf16 v[52:55], v[208:211], v[162:165], v[16:19]
	v_mfma_f32_16x16x32_bf16 v[48:51], v[134:137], v[162:165], v[20:23]
	v_mfma_f32_16x16x32_bf16 v[36:39], v[208:211], v[166:169], v[4:7]
	v_mfma_f32_16x16x32_bf16 v[32:35], v[134:137], v[166:169], v[0:3]
	v_mfma_f32_16x16x32_bf16 v[20:23], v[208:211], v[184:187], v[138:141]
	v_mfma_f32_16x16x32_bf16 v[16:19], v[134:137], v[184:187], v[142:145]
	v_mfma_f32_16x16x32_bf16 v[4:7], v[208:211], v[130:133], v[146:149]
	v_mfma_f32_16x16x32_bf16 v[0:3], v[134:137], v[130:133], v[150:153]
	v_cmp_gt_u32_e32 vcc, s40, v128
	s_barrier
	s_and_saveexec_b64 s[6:7], vcc
	s_cbranch_execz .LBB0_395
	s_barrier

; #define STAGE(P, RS, SOFF, OFF, kt) do { const int _so = (SOFF) + (kt) * (BK * 2); \
;     _Pragma("unroll") for (int _i = 0; _i < 2; ++_i) { \
;       __builtin_amdgcn_raw_ptr_buffer_load_lds(RS, (__attribute__((address_space(3))) void*)((P) + wave * 1024 + _i * 8192), 16, OFF[_i], _so, 0, 0); } } while (0)
; #define LDA(dst, b, h) _Pragma("unroll") for (int m = 0; m < 4; ++m) _Pragma("unroll") for (int k = 0; k < 2; ++k) \
;     dst[m][k] = *reinterpret_cast<const bf16x8*>(SA(b, h) + lds_byte(wr * 64 + m * 16 + fr, k * 32 + fq * 8))
; #define LDB(dst, b, h) _Pragma("unroll") for (int n = 0; n < 2; ++n) _Pragma("unroll") for (int k = 0; k < 2; ++k) \
;     dst[n][k] = *reinterpret_cast<const bf16x8*>(SB(b, h) + lds_byte(wc * 32 + n * 16 + fr, k * 32 + fq * 8))
; #define WAIT_V(n) asm volatile("s_waitcnt vmcnt(" #n ")" ::: "memory")
; #define WAIT_L(n) asm volatile("s_waitcnt lgkmcnt(" #n ")" ::: "memory")
; #define BAR __builtin_amdgcn_s_barrier()
; #define SCHED __builtin_amdgcn_sched_barrier(0)
;     ...
;       LDB(B0, 0, 0); SCHED; LDA(At, 0, 0); STAGE(SA(1, 1), rsA, sA1, offA, t + 1);
;       WAIT_L(8); BAR; WAIT_L(0); MMA(0, 0, At, B0); BAR; SCHED;
;       LDB(B1, 0, 1); STAGE(SB(0, 0), rsB, sB0, offB, t + 2);
;       BAR; WAIT_L(0); MMA(0, 1, At, B1); BAR;
;       LDA(At, 0, 1); STAGE(SA(0, 0), rsA, sA0, offA, t + 2);
;       BAR; WAIT_L(0); MMA(1, 0, At, B0); BAR; SCHED;
;       STAGE(SB(0, 1), rsB, sB1, offB, t + 2);
;       WAIT_V(6); BAR; MMA(1, 1, At, B1); BAR;
.LBB0_494:
	ds_read_b128 v[152:155], v147
	ds_read_b128 v[156:159], v148
	ds_read_b128 v[160:163], v149
	ds_read_b128 v[164:167], v150
	s_add_i32 s5, s82, s3
	s_add_i32 s6, s5, 0x80
	s_mov_b32 m0, s36
	ds_read_b128 v[168:171], v129
	ds_read_b128 v[172:175], v129 offset:1024
	ds_read_b128 v[176:179], v132
	ds_read_b128 v[180:183], v132 offset:1024
	ds_read_b128 v[184:187], v131
	ds_read_b128 v[188:191], v131 offset:1024
	ds_read_b128 v[192:195], v130
	ds_read_b128 v[196:199], v130 offset:1024
	buffer_load_dwordx4 v141, s[8:11], s6 offen lds
	s_mov_b32 m0, s59
	s_nop 0
	buffer_load_dwordx4 v142, s[8:11], s6 offen lds
	s_waitcnt lgkmcnt(8)
	s_barrier
	s_waitcnt lgkmcnt(0)
	s_waitcnt lgkmcnt(7)
	v_mfma_f32_16x16x32_bf16 v[124:127], v[152:155], v[168:171], v[124:127]
	v_mfma_f32_16x16x32_bf16 v[120:123], v[160:163], v[168:171], v[120:123]
	s_waitcnt lgkmcnt(5)
	v_mfma_f32_16x16x32_bf16 v[116:119], v[152:155], v[176:179], v[116:119]
	v_mfma_f32_16x16x32_bf16 v[112:115], v[160:163], v[176:179], v[112:115]
	s_waitcnt lgkmcnt(3)
	v_mfma_f32_16x16x32_bf16 v[108:111], v[152:155], v[184:187], v[108:111]
	v_mfma_f32_16x16x32_bf16 v[104:107], v[160:163], v[184:187], v[104:107]
	s_waitcnt lgkmcnt(1)
	v_mfma_f32_16x16x32_bf16 v[100:103], v[152:155], v[192:195], v[100:103]
	v_mfma_f32_16x16x32_bf16 v[96:99], v[160:163], v[192:195], v[96:99]
	v_mfma_f32_16x16x32_bf16 v[124:127], v[156:159], v[172:175], v[124:127]
	v_mfma_f32_16x16x32_bf16 v[120:123], v[164:167], v[172:175], v[120:123]
	v_mfma_f32_16x16x32_bf16 v[116:119], v[156:159], v[180:183], v[116:119]
	v_mfma_f32_16x16x32_bf16 v[112:115], v[164:167], v[180:183], v[112:115]
	v_mfma_f32_16x16x32_bf16 v[108:111], v[156:159], v[188:191], v[108:111]
	v_mfma_f32_16x16x32_bf16 v[104:107], v[164:167], v[188:191], v[104:107]
	s_waitcnt lgkmcnt(0)
	v_mfma_f32_16x16x32_bf16 v[100:103], v[156:159], v[196:199], v[100:103]
	v_mfma_f32_16x16x32_bf16 v[96:99], v[164:167], v[196:199], v[96:99]
	s_barrier
	s_add_i32 s6, s84, s3
	s_add_i32 s7, s6, 0x100
	s_mov_b32 s14, s10
	s_mov_b32 s15, s11
	s_mov_b32 m0, s37
	ds_read_b128 v[200:203], v143
	ds_read_b128 v[204:207], v144
	ds_read_b128 v[208:211], v145
	ds_read_b128 v[212:215], v146
	buffer_load_dwordx4 v141, s[12:15], s7 offen lds
	s_mov_b32 m0, s70
	s_nop 0
	buffer_load_dwordx4 v142, s[12:15], s7 offen lds
	s_barrier
	s_waitcnt lgkmcnt(0)
	s_waitcnt lgkmcnt(3)
	v_mfma_f32_16x16x32_bf16 v[92:95], v[200:203], v[168:171], v[92:95]
	s_waitcnt lgkmcnt(1)
	v_mfma_f32_16x16x32_bf16 v[88:91], v[208:211], v[168:171], v[88:91]
	v_mfma_f32_16x16x32_bf16 v[80:83], v[200:203], v[176:179], v[80:83]
	v_mfma_f32_16x16x32_bf16 v[68:71], v[208:211], v[176:179], v[68:71]
	v_mfma_f32_16x16x32_bf16 v[60:63], v[200:203], v[184:187], v[60:63]
	v_mfma_f32_16x16x32_bf16 v[56:59], v[208:211], v[184:187], v[56:59]
	v_mfma_f32_16x16x32_bf16 v[52:55], v[200:203], v[192:195], v[52:55]
	v_mfma_f32_16x16x32_bf16 v[48:51], v[208:211], v[192:195], v[48:51]
	v_mfma_f32_16x16x32_bf16 v[92:95], v[204:207], v[172:175], v[92:95]
	s_waitcnt lgkmcnt(0)
	v_mfma_f32_16x16x32_bf16 v[88:91], v[212:215], v[172:175], v[88:91]
	v_mfma_f32_16x16x32_bf16 v[80:83], v[204:207], v[180:183], v[80:83]
	v_mfma_f32_16x16x32_bf16 v[68:71], v[212:215], v[180:183], v[68:71]
	v_mfma_f32_16x16x32_bf16 v[60:63], v[204:207], v[188:191], v[60:63]
	v_mfma_f32_16x16x32_bf16 v[56:59], v[212:215], v[188:191], v[56:59]
	v_mfma_f32_16x16x32_bf16 v[52:55], v[204:207], v[196:199], v[52:55]
	v_mfma_f32_16x16x32_bf16 v[48:51], v[212:215], v[196:199], v[48:51]
	s_add_i32 s7, s83, s3
	s_add_i32 s22, s7, 0x100
	s_mov_b32 m0, s35
	s_barrier
	ds_read_b128 v[168:171], v129 offset:16384
	ds_read_b128 v[172:175], v129 offset:17408
	ds_read_b128 v[176:179], v132 offset:16384
	ds_read_b128 v[180:183], v132 offset:17408
	ds_read_b128 v[184:187], v131 offset:16384
	ds_read_b128 v[188:191], v131 offset:17408
	ds_read_b128 v[192:195], v130 offset:16384
	ds_read_b128 v[196:199], v130 offset:17408
	buffer_load_dwordx4 v141, s[8:11], s22 offen lds
	s_mov_b32 m0, s95
	s_nop 0
	buffer_load_dwordx4 v142, s[8:11], s22 offen lds
	s_barrier
	s_waitcnt lgkmcnt(0)
	s_waitcnt lgkmcnt(7)
	v_mfma_f32_16x16x32_bf16 v[44:47], v[152:155], v[168:171], v[44:47]
	v_mfma_f32_16x16x32_bf16 v[40:43], v[160:163], v[168:171], v[40:43]
	s_waitcnt lgkmcnt(5)
	v_mfma_f32_16x16x32_bf16 v[36:39], v[152:155], v[176:179], v[36:39]
	v_mfma_f32_16x16x32_bf16 v[32:35], v[160:163], v[176:179], v[32:35]
	s_waitcnt lgkmcnt(3)
	v_mfma_f32_16x16x32_bf16 v[28:31], v[152:155], v[184:187], v[28:31]
	v_mfma_f32_16x16x32_bf16 v[24:27], v[160:163], v[184:187], v[24:27]
	s_waitcnt lgkmcnt(1)
	v_mfma_f32_16x16x32_bf16 v[20:23], v[152:155], v[192:195], v[20:23]
	v_mfma_f32_16x16x32_bf16 v[16:19], v[160:163], v[192:195], v[16:19]
	v_mfma_f32_16x16x32_bf16 v[44:47], v[156:159], v[172:175], v[44:47]
	v_mfma_f32_16x16x32_bf16 v[40:43], v[164:167], v[172:175], v[40:43]
	v_mfma_f32_16x16x32_bf16 v[36:39], v[156:159], v[180:183], v[36:39]
	v_mfma_f32_16x16x32_bf16 v[32:35], v[164:167], v[180:183], v[32:35]
	v_mfma_f32_16x16x32_bf16 v[28:31], v[156:159], v[188:191], v[28:31]
	v_mfma_f32_16x16x32_bf16 v[24:27], v[164:167], v[188:191], v[24:27]
	s_waitcnt lgkmcnt(0)
	v_mfma_f32_16x16x32_bf16 v[20:23], v[156:159], v[196:199], v[20:23]
	v_mfma_f32_16x16x32_bf16 v[16:19], v[164:167], v[196:199], v[16:19]
	s_barrier
	s_add_i32 s22, s85, s3
	s_add_i32 s23, s22, 0x100
	s_mov_b32 m0, s38
	s_nop 0
	buffer_load_dwordx4 v141, s[12:15], s23 offen lds
	s_mov_b32 m0, s71
	s_nop 0
	buffer_load_dwordx4 v142, s[12:15], s23 offen lds
	s_waitcnt vmcnt(6)
	s_barrier
; #define STAGE(P, RS, SOFF, OFF, kt) do { const int _so = (SOFF) + (kt) * (BK * 2); \
;     _Pragma("unroll") for (int _i = 0; _i < 2; ++_i) { \
;       __builtin_amdgcn_raw_ptr_buffer_load_lds(RS, (__attribute__((address_space(3))) void*)((P) + wave * 1024 + _i * 8192), 16, OFF[_i], _so, 0, 0); } } while (0)
; #define LDA(dst, b, h) _Pragma("unroll") for (int m = 0; m < 4; ++m) _Pragma("unroll") for (int k = 0; k < 2; ++k) \
;     dst[m][k] = *reinterpret_cast<const bf16x8*>(SA(b, h) + lds_byte(wr * 64 + m * 16 + fr, k * 32 + fq * 8))
; #define LDB(dst, b, h) _Pragma("unroll") for (int n = 0; n < 2; ++n) _Pragma("unroll") for (int k = 0; k < 2; ++k) \
;     dst[n][k] = *reinterpret_cast<const bf16x8*>(SB(b, h) + lds_byte(wc * 32 + n * 16 + fr, k * 32 + fq * 8))
; #define WAIT_V(n) asm volatile("s_waitcnt vmcnt(" #n ")" ::: "memory")
; #define WAIT_L(n) asm volatile("s_waitcnt lgkmcnt(" #n ")" ::: "memory")
; #define BAR __builtin_amdgcn_s_barrier()
; #define SCHED __builtin_amdgcn_sched_barrier(0)
;     ...
;       WAIT_V(6); BAR; MMA(1, 1, At, B1); BAR;
;       LDB(B0, 1, 0); SCHED; LDA(At, 1, 0); STAGE(SA(0, 1), rsA, sA1, offA, t + 2);
;       WAIT_L(8); BAR; WAIT_L(0); MMA(0, 0, At, B0); BAR; SCHED;
;       LDB(B1, 1, 1); STAGE(SB(1, 0), rsB, sB0, offB, t + 3);
;       BAR; WAIT_L(0); MMA(0, 1, At, B1); BAR;
;       LDA(At, 1, 1); STAGE(SA(1, 0), rsA, sA0, offA, t + 3);
;       BAR; WAIT_L(0); MMA(1, 0, At, B0); BAR; SCHED;
;       STAGE(SB(1, 1), rsB, sB1, offB, t + 3);
	v_mfma_f32_16x16x32_bf16 v[12:15], v[200:203], v[168:171], v[12:15]
	v_mfma_f32_16x16x32_bf16 v[8:11], v[208:211], v[168:171], v[8:11]
	v_mfma_f32_16x16x32_bf16 v[4:7], v[200:203], v[176:179], v[4:7]
	v_mfma_f32_16x16x32_bf16 v[0:3], v[208:211], v[176:179], v[0:3]
	v_mfma_f32_16x16x32_bf16 v[64:67], v[200:203], v[184:187], v[64:67]
	v_mfma_f32_16x16x32_bf16 v[72:75], v[208:211], v[184:187], v[72:75]
	v_mfma_f32_16x16x32_bf16 v[76:79], v[200:203], v[192:195], v[76:79]
	v_mfma_f32_16x16x32_bf16 v[84:87], v[208:211], v[192:195], v[84:87]
	v_mfma_f32_16x16x32_bf16 v[12:15], v[204:207], v[172:175], v[12:15]
	v_mfma_f32_16x16x32_bf16 v[8:11], v[212:215], v[172:175], v[8:11]
	v_mfma_f32_16x16x32_bf16 v[4:7], v[204:207], v[180:183], v[4:7]
	v_mfma_f32_16x16x32_bf16 v[0:3], v[212:215], v[180:183], v[0:3]
	v_mfma_f32_16x16x32_bf16 v[64:67], v[204:207], v[188:191], v[64:67]
	v_mfma_f32_16x16x32_bf16 v[72:75], v[212:215], v[188:191], v[72:75]
	v_mfma_f32_16x16x32_bf16 v[76:79], v[204:207], v[196:199], v[76:79]
	v_mfma_f32_16x16x32_bf16 v[84:87], v[212:215], v[196:199], v[84:87]
	s_barrier
	ds_read_b128 v[152:155], v137
	ds_read_b128 v[156:159], v138
	ds_read_b128 v[160:163], v139
	ds_read_b128 v[164:167], v140
	s_addk_i32 s5, 0x100
	s_mov_b32 m0, s39
	ds_read_b128 v[168:171], v129 offset:32768
	ds_read_b128 v[172:175], v129 offset:33792
	ds_read_b128 v[176:179], v132 offset:32768
	ds_read_b128 v[180:183], v132 offset:33792
	ds_read_b128 v[184:187], v131 offset:32768
	ds_read_b128 v[188:191], v131 offset:33792
	ds_read_b128 v[192:195], v130 offset:32768
	ds_read_b128 v[196:199], v130 offset:33792
	buffer_load_dwordx4 v141, s[8:11], s5 offen lds
	s_mov_b32 m0, s97
	s_nop 0
	buffer_load_dwordx4 v142, s[8:11], s5 offen lds
	s_waitcnt lgkmcnt(8)
	s_barrier
	s_waitcnt lgkmcnt(0)
	s_waitcnt lgkmcnt(7)
	v_mfma_f32_16x16x32_bf16 v[124:127], v[152:155], v[168:171], v[124:127]
	v_mfma_f32_16x16x32_bf16 v[120:123], v[160:163], v[168:171], v[120:123]
	s_waitcnt lgkmcnt(5)
	v_mfma_f32_16x16x32_bf16 v[116:119], v[152:155], v[176:179], v[116:119]
	v_mfma_f32_16x16x32_bf16 v[112:115], v[160:163], v[176:179], v[112:115]
	s_waitcnt lgkmcnt(3)
	v_mfma_f32_16x16x32_bf16 v[108:111], v[152:155], v[184:187], v[108:111]
	v_mfma_f32_16x16x32_bf16 v[104:107], v[160:163], v[184:187], v[104:107]
	s_waitcnt lgkmcnt(1)
	v_mfma_f32_16x16x32_bf16 v[100:103], v[152:155], v[192:195], v[100:103]
	v_mfma_f32_16x16x32_bf16 v[96:99], v[160:163], v[192:195], v[96:99]
	v_mfma_f32_16x16x32_bf16 v[124:127], v[156:159], v[172:175], v[124:127]
	v_mfma_f32_16x16x32_bf16 v[120:123], v[164:167], v[172:175], v[120:123]
	v_mfma_f32_16x16x32_bf16 v[116:119], v[156:159], v[180:183], v[116:119]
	v_mfma_f32_16x16x32_bf16 v[112:115], v[164:167], v[180:183], v[112:115]
	v_mfma_f32_16x16x32_bf16 v[108:111], v[156:159], v[188:191], v[108:111]
	v_mfma_f32_16x16x32_bf16 v[104:107], v[164:167], v[188:191], v[104:107]
	s_waitcnt lgkmcnt(0)
	v_mfma_f32_16x16x32_bf16 v[100:103], v[156:159], v[196:199], v[100:103]
	v_mfma_f32_16x16x32_bf16 v[96:99], v[164:167], v[196:199], v[96:99]
	s_barrier
	s_addk_i32 s6, 0x180
	s_mov_b32 m0, s92
	ds_read_b128 v[200:203], v133
	ds_read_b128 v[204:207], v134
	ds_read_b128 v[208:211], v135
	ds_read_b128 v[212:215], v136
	buffer_load_dwordx4 v141, s[12:15], s6 offen lds
	s_mov_b32 m0, s56
	s_nop 0
	buffer_load_dwordx4 v142, s[12:15], s6 offen lds
	s_barrier
	s_waitcnt lgkmcnt(0)
	s_waitcnt lgkmcnt(3)
	v_mfma_f32_16x16x32_bf16 v[92:95], v[200:203], v[168:171], v[92:95]
	s_waitcnt lgkmcnt(1)
	v_mfma_f32_16x16x32_bf16 v[88:91], v[208:211], v[168:171], v[88:91]
	v_mfma_f32_16x16x32_bf16 v[80:83], v[200:203], v[176:179], v[80:83]
	v_mfma_f32_16x16x32_bf16 v[68:71], v[208:211], v[176:179], v[68:71]
	v_mfma_f32_16x16x32_bf16 v[60:63], v[200:203], v[184:187], v[60:63]
	v_mfma_f32_16x16x32_bf16 v[56:59], v[208:211], v[184:187], v[56:59]
	v_mfma_f32_16x16x32_bf16 v[52:55], v[200:203], v[192:195], v[52:55]
	v_mfma_f32_16x16x32_bf16 v[48:51], v[208:211], v[192:195], v[48:51]
	v_mfma_f32_16x16x32_bf16 v[92:95], v[204:207], v[172:175], v[92:95]
	s_waitcnt lgkmcnt(0)
	v_mfma_f32_16x16x32_bf16 v[88:91], v[212:215], v[172:175], v[88:91]
	v_mfma_f32_16x16x32_bf16 v[80:83], v[204:207], v[180:183], v[80:83]
	v_mfma_f32_16x16x32_bf16 v[68:71], v[212:215], v[180:183], v[68:71]
	v_mfma_f32_16x16x32_bf16 v[60:63], v[204:207], v[188:191], v[60:63]
	v_mfma_f32_16x16x32_bf16 v[56:59], v[212:215], v[188:191], v[56:59]
	v_mfma_f32_16x16x32_bf16 v[52:55], v[204:207], v[196:199], v[52:55]
	v_mfma_f32_16x16x32_bf16 v[48:51], v[212:215], v[196:199], v[48:51]
	s_addk_i32 s7, 0x180
	s_mov_b32 m0, s93
	s_barrier
	ds_read_b128 v[168:171], v129 offset:49152
	ds_read_b128 v[172:175], v129 offset:50176
	ds_read_b128 v[176:179], v132 offset:49152
	ds_read_b128 v[180:183], v132 offset:50176
	ds_read_b128 v[184:187], v131 offset:49152
	ds_read_b128 v[188:191], v131 offset:50176
	ds_read_b128 v[192:195], v130 offset:49152
	ds_read_b128 v[196:199], v130 offset:50176
	buffer_load_dwordx4 v141, s[8:11], s7 offen lds
	s_mov_b32 m0, s57
	s_nop 0
	buffer_load_dwordx4 v142, s[8:11], s7 offen lds
	s_barrier
; #define STAGE(P, RS, SOFF, OFF, kt) do { const int _so = (SOFF) + (kt) * (BK * 2); \
;     _Pragma("unroll") for (int _i = 0; _i < 2; ++_i) { \
;       __builtin_amdgcn_raw_ptr_buffer_load_lds(RS, (__attribute__((address_space(3))) void*)((P) + wave * 1024 + _i * 8192), 16, OFF[_i], _so, 0, 0); } } while (0)
; #define LDA(dst, b, h) _Pragma("unroll") for (int m = 0; m < 4; ++m) _Pragma("unroll") for (int k = 0; k < 2; ++k) \
;     dst[m][k] = *reinterpret_cast<const bf16x8*>(SA(b, h) + lds_byte(wr * 64 + m * 16 + fr, k * 32 + fq * 8))
; #define LDB(dst, b, h) _Pragma("unroll") for (int n = 0; n < 2; ++n) _Pragma("unroll") for (int k = 0; k < 2; ++k) \
;     dst[n][k] = *reinterpret_cast<const bf16x8*>(SB(b, h) + lds_byte(wc * 32 + n * 16 + fr, k * 32 + fq * 8))
; #define WAIT_V(n) asm volatile("s_waitcnt vmcnt(" #n ")" ::: "memory")
; #define WAIT_L(n) asm volatile("s_waitcnt lgkmcnt(" #n ")" ::: "memory")
; #define BAR __builtin_amdgcn_s_barrier()
; #define SCHED __builtin_amdgcn_sched_barrier(0)
;     ...
;       BAR; WAIT_L(0); MMA(1, 0, At, B0); BAR; SCHED;
;       STAGE(SB(1, 1), rsB, sB1, offB, t + 3);
;       WAIT_V(6); BAR; MMA(1, 1, At, B1); BAR;
;     }
;     { LDB(B0, 0, 0); LDA(At, 0, 0); STAGE(SA(1, 1), rsA, sA1, offA, nt - 1);
;       BAR; WAIT_L(0); MMA(0, 0, At, B0); BAR;
;       LDB(B1, 0, 1); BAR; WAIT_L(0); MMA(0, 1, At, B1); BAR;
	s_waitcnt lgkmcnt(0)
	s_waitcnt lgkmcnt(7)
	v_mfma_f32_16x16x32_bf16 v[44:47], v[152:155], v[168:171], v[44:47]
	v_mfma_f32_16x16x32_bf16 v[40:43], v[160:163], v[168:171], v[40:43]
	s_waitcnt lgkmcnt(5)
	v_mfma_f32_16x16x32_bf16 v[36:39], v[152:155], v[176:179], v[36:39]
	v_mfma_f32_16x16x32_bf16 v[32:35], v[160:163], v[176:179], v[32:35]
	s_waitcnt lgkmcnt(3)
	v_mfma_f32_16x16x32_bf16 v[28:31], v[152:155], v[184:187], v[28:31]
	v_mfma_f32_16x16x32_bf16 v[24:27], v[160:163], v[184:187], v[24:27]
	s_waitcnt lgkmcnt(1)
	v_mfma_f32_16x16x32_bf16 v[20:23], v[152:155], v[192:195], v[20:23]
	v_mfma_f32_16x16x32_bf16 v[16:19], v[160:163], v[192:195], v[16:19]
	v_mfma_f32_16x16x32_bf16 v[44:47], v[156:159], v[172:175], v[44:47]
	v_mfma_f32_16x16x32_bf16 v[40:43], v[164:167], v[172:175], v[40:43]
	v_mfma_f32_16x16x32_bf16 v[36:39], v[156:159], v[180:183], v[36:39]
	v_mfma_f32_16x16x32_bf16 v[32:35], v[164:167], v[180:183], v[32:35]
	v_mfma_f32_16x16x32_bf16 v[28:31], v[156:159], v[188:191], v[28:31]
	v_mfma_f32_16x16x32_bf16 v[24:27], v[164:167], v[188:191], v[24:27]
	s_waitcnt lgkmcnt(0)
	v_mfma_f32_16x16x32_bf16 v[20:23], v[156:159], v[196:199], v[20:23]
	v_mfma_f32_16x16x32_bf16 v[16:19], v[164:167], v[196:199], v[16:19]
	s_barrier
	s_addk_i32 s22, 0x180
	s_mov_b32 m0, s94
	s_nop 0
	buffer_load_dwordx4 v141, s[12:15], s22 offen lds
	s_mov_b32 m0, s58
	s_nop 0
	buffer_load_dwordx4 v142, s[12:15], s22 offen lds
	s_waitcnt vmcnt(6)
	s_barrier
	v_mfma_f32_16x16x32_bf16 v[12:15], v[200:203], v[168:171], v[12:15]
	v_mfma_f32_16x16x32_bf16 v[8:11], v[208:211], v[168:171], v[8:11]
	v_mfma_f32_16x16x32_bf16 v[4:7], v[200:203], v[176:179], v[4:7]
	v_mfma_f32_16x16x32_bf16 v[0:3], v[208:211], v[176:179], v[0:3]
	v_mfma_f32_16x16x32_bf16 v[64:67], v[200:203], v[184:187], v[64:67]
	v_mfma_f32_16x16x32_bf16 v[72:75], v[208:211], v[184:187], v[72:75]
	v_mfma_f32_16x16x32_bf16 v[76:79], v[200:203], v[192:195], v[76:79]
	v_mfma_f32_16x16x32_bf16 v[84:87], v[208:211], v[192:195], v[84:87]
	v_mfma_f32_16x16x32_bf16 v[12:15], v[204:207], v[172:175], v[12:15]
	v_mfma_f32_16x16x32_bf16 v[8:11], v[212:215], v[172:175], v[8:11]
	v_mfma_f32_16x16x32_bf16 v[4:7], v[204:207], v[180:183], v[4:7]
	v_mfma_f32_16x16x32_bf16 v[0:3], v[212:215], v[180:183], v[0:3]
	v_mfma_f32_16x16x32_bf16 v[64:67], v[204:207], v[188:191], v[64:67]
	v_mfma_f32_16x16x32_bf16 v[72:75], v[212:215], v[188:191], v[72:75]
	v_mfma_f32_16x16x32_bf16 v[76:79], v[204:207], v[196:199], v[76:79]
	v_mfma_f32_16x16x32_bf16 v[84:87], v[212:215], v[196:199], v[84:87]
	s_add_i32 s1, s1, 2
	s_addk_i32 s3, 0x100
	s_cmp_gt_u32 s1, 59
	s_barrier
	s_cbranch_scc0 .LBB0_494
	s_add_i32 s1, s82, 0x1f80
	s_mov_b32 m0, s36
	ds_read_b128 v[152:155], v147
	ds_read_b128 v[156:159], v148
	ds_read_b128 v[160:163], v149
	ds_read_b128 v[148:151], v150
	ds_read_b128 v[164:167], v129
	ds_read_b128 v[168:171], v129 offset:1024
	ds_read_b128 v[172:175], v132
	ds_read_b128 v[176:179], v132 offset:1024
	ds_read_b128 v[180:183], v131
	ds_read_b128 v[184:187], v131 offset:1024
	ds_read_b128 v[188:191], v130
	ds_read_b128 v[192:195], v130 offset:1024
	buffer_load_dwordx4 v141, s[8:11], s1 offen lds
	s_mov_b32 m0, s59
	s_nop 0
	buffer_load_dwordx4 v142, s[8:11], s1 offen lds
	s_barrier
	s_waitcnt lgkmcnt(0)
	s_waitcnt lgkmcnt(7)
	v_mfma_f32_16x16x32_bf16 v[124:127], v[152:155], v[164:167], v[124:127]
	v_mfma_f32_16x16x32_bf16 v[120:123], v[160:163], v[164:167], v[120:123]
	s_waitcnt lgkmcnt(5)
	v_mfma_f32_16x16x32_bf16 v[116:119], v[152:155], v[172:175], v[116:119]
	v_mfma_f32_16x16x32_bf16 v[112:115], v[160:163], v[172:175], v[112:115]
	s_waitcnt lgkmcnt(3)
	v_mfma_f32_16x16x32_bf16 v[108:111], v[152:155], v[180:183], v[108:111]
	v_mfma_f32_16x16x32_bf16 v[104:107], v[160:163], v[180:183], v[104:107]
	s_waitcnt lgkmcnt(1)
	v_mfma_f32_16x16x32_bf16 v[100:103], v[152:155], v[188:191], v[100:103]
	v_mfma_f32_16x16x32_bf16 v[96:99], v[160:163], v[188:191], v[96:99]
	v_mfma_f32_16x16x32_bf16 v[124:127], v[156:159], v[168:171], v[124:127]
	v_mfma_f32_16x16x32_bf16 v[120:123], v[148:151], v[168:171], v[120:123]
	v_mfma_f32_16x16x32_bf16 v[116:119], v[156:159], v[176:179], v[116:119]
	v_mfma_f32_16x16x32_bf16 v[112:115], v[148:151], v[176:179], v[112:115]
	v_mfma_f32_16x16x32_bf16 v[108:111], v[156:159], v[184:187], v[108:111]
	v_mfma_f32_16x16x32_bf16 v[104:107], v[148:151], v[184:187], v[104:107]
	s_waitcnt lgkmcnt(0)
	v_mfma_f32_16x16x32_bf16 v[100:103], v[156:159], v[192:195], v[100:103]
	v_mfma_f32_16x16x32_bf16 v[96:99], v[148:151], v[192:195], v[96:99]
	s_barrier
	ds_read_b128 v[196:199], v143
	ds_read_b128 v[200:203], v144
	ds_read_b128 v[142:145], v145
	ds_read_b128 v[204:207], v146
	s_barrier
	s_waitcnt lgkmcnt(0)
	s_waitcnt lgkmcnt(3)
	v_mfma_f32_16x16x32_bf16 v[80:83], v[196:199], v[172:175], v[80:83]
	s_waitcnt lgkmcnt(1)
	v_mfma_f32_16x16x32_bf16 v[68:71], v[142:145], v[172:175], v[68:71]
	v_mfma_f32_16x16x32_bf16 v[60:63], v[196:199], v[180:183], v[60:63]
	v_mfma_f32_16x16x32_bf16 v[56:59], v[142:145], v[180:183], v[56:59]
	v_mfma_f32_16x16x32_bf16 v[52:55], v[196:199], v[188:191], v[52:55]
	v_mfma_f32_16x16x32_bf16 v[48:51], v[142:145], v[188:191], v[48:51]
	v_mfma_f32_16x16x32_bf16 v[92:95], v[196:199], v[164:167], v[92:95]
	v_mfma_f32_16x16x32_bf16 v[88:91], v[142:145], v[164:167], v[88:91]
	v_mfma_f32_16x16x32_bf16 v[80:83], v[200:203], v[176:179], v[80:83]
	s_waitcnt lgkmcnt(0)
	v_mfma_f32_16x16x32_bf16 v[68:71], v[204:207], v[176:179], v[68:71]
	v_mfma_f32_16x16x32_bf16 v[60:63], v[200:203], v[184:187], v[60:63]
	v_mfma_f32_16x16x32_bf16 v[56:59], v[204:207], v[184:187], v[56:59]
	v_mfma_f32_16x16x32_bf16 v[52:55], v[200:203], v[192:195], v[52:55]
	v_mfma_f32_16x16x32_bf16 v[48:51], v[204:207], v[192:195], v[48:51]
	v_mfma_f32_16x16x32_bf16 v[164:167], v[200:203], v[168:171], v[92:95]
	v_mfma_f32_16x16x32_bf16 v[168:171], v[204:207], v[168:171], v[88:91]
	s_barrier
; #define LDA(dst, b, h) _Pragma("unroll") for (int m = 0; m < 4; ++m) _Pragma("unroll") for (int k = 0; k < 2; ++k) \
;     dst[m][k] = *reinterpret_cast<const bf16x8*>(SA(b, h) + lds_byte(wr * 64 + m * 16 + fr, k * 32 + fq * 8))
; #define LDB(dst, b, h) _Pragma("unroll") for (int n = 0; n < 2; ++n) _Pragma("unroll") for (int k = 0; k < 2; ++k) \
;     dst[n][k] = *reinterpret_cast<const bf16x8*>(SB(b, h) + lds_byte(wc * 32 + n * 16 + fr, k * 32 + fq * 8))
; #define WAIT_V(n) asm volatile("s_waitcnt vmcnt(" #n ")" ::: "memory")
; #define WAIT_L(n) asm volatile("s_waitcnt lgkmcnt(" #n ")" ::: "memory")
; #define BAR __builtin_amdgcn_s_barrier()
;     ...
;       LDB(B1, 0, 1); BAR; WAIT_L(0); MMA(0, 1, At, B1); BAR;
;       LDA(At, 0, 1); WAIT_V(4); BAR; WAIT_L(0); MMA(1, 0, At, B0); MMA(1, 1, At, B1); BAR; }
;     { LDB(B0, 1, 0); LDA(At, 1, 0); WAIT_V(2); BAR; WAIT_L(0); MMA(0, 0, At, B0); BAR;
;       LDB(B1, 1, 1); WAIT_V(0); BAR; WAIT_L(0); MMA(0, 1, At, B1); BAR;
	s_nop 0
	ds_read_b128 v[88:91], v129 offset:16384
	ds_read_b128 v[92:95], v129 offset:17408
	ds_read_b128 v[172:175], v132 offset:16384
	ds_read_b128 v[176:179], v132 offset:17408
	ds_read_b128 v[180:183], v131 offset:16384
	ds_read_b128 v[184:187], v131 offset:17408
	ds_read_b128 v[188:191], v130 offset:16384
	ds_read_b128 v[192:195], v130 offset:17408
	s_waitcnt vmcnt(4)
	s_barrier
	s_waitcnt lgkmcnt(0)
	s_waitcnt lgkmcnt(7)
	v_mfma_f32_16x16x32_bf16 v[44:47], v[152:155], v[88:91], v[44:47]
	v_mfma_f32_16x16x32_bf16 v[40:43], v[160:163], v[88:91], v[40:43]
	s_waitcnt lgkmcnt(5)
	v_mfma_f32_16x16x32_bf16 v[36:39], v[152:155], v[172:175], v[36:39]
	v_mfma_f32_16x16x32_bf16 v[32:35], v[160:163], v[172:175], v[32:35]
	s_waitcnt lgkmcnt(3)
	v_mfma_f32_16x16x32_bf16 v[28:31], v[152:155], v[180:183], v[28:31]
	v_mfma_f32_16x16x32_bf16 v[24:27], v[160:163], v[180:183], v[24:27]
	s_waitcnt lgkmcnt(1)
	v_mfma_f32_16x16x32_bf16 v[20:23], v[152:155], v[188:191], v[20:23]
	v_mfma_f32_16x16x32_bf16 v[16:19], v[160:163], v[188:191], v[16:19]
	v_mfma_f32_16x16x32_bf16 v[44:47], v[156:159], v[92:95], v[44:47]
	v_mfma_f32_16x16x32_bf16 v[40:43], v[148:151], v[92:95], v[40:43]
	v_mfma_f32_16x16x32_bf16 v[36:39], v[156:159], v[176:179], v[36:39]
	v_mfma_f32_16x16x32_bf16 v[32:35], v[148:151], v[176:179], v[32:35]
	v_mfma_f32_16x16x32_bf16 v[28:31], v[156:159], v[184:187], v[28:31]
	v_mfma_f32_16x16x32_bf16 v[24:27], v[148:151], v[184:187], v[24:27]
	s_waitcnt lgkmcnt(0)
	v_mfma_f32_16x16x32_bf16 v[20:23], v[156:159], v[192:195], v[20:23]
	v_mfma_f32_16x16x32_bf16 v[16:19], v[148:151], v[192:195], v[16:19]
	v_mfma_f32_16x16x32_bf16 v[4:7], v[196:199], v[172:175], v[4:7]
	v_mfma_f32_16x16x32_bf16 v[0:3], v[142:145], v[172:175], v[0:3]
	v_mfma_f32_16x16x32_bf16 v[12:15], v[196:199], v[88:91], v[12:15]
	v_mfma_f32_16x16x32_bf16 v[8:11], v[142:145], v[88:91], v[8:11]
	v_mfma_f32_16x16x32_bf16 v[64:67], v[196:199], v[180:183], v[64:67]
	v_mfma_f32_16x16x32_bf16 v[72:75], v[142:145], v[180:183], v[72:75]
	v_mfma_f32_16x16x32_bf16 v[76:79], v[196:199], v[188:191], v[76:79]
	v_mfma_f32_16x16x32_bf16 v[84:87], v[142:145], v[188:191], v[84:87]
	v_mfma_f32_16x16x32_bf16 v[4:7], v[200:203], v[176:179], v[4:7]
	v_mfma_f32_16x16x32_bf16 v[0:3], v[204:207], v[176:179], v[0:3]
	v_mfma_f32_16x16x32_bf16 v[142:145], v[200:203], v[92:95], v[12:15]
	v_mfma_f32_16x16x32_bf16 v[146:149], v[204:207], v[92:95], v[8:11]
	v_mfma_f32_16x16x32_bf16 v[150:153], v[200:203], v[184:187], v[64:67]
	v_mfma_f32_16x16x32_bf16 v[154:157], v[204:207], v[184:187], v[72:75]
	v_mfma_f32_16x16x32_bf16 v[158:161], v[200:203], v[192:195], v[76:79]
	v_mfma_f32_16x16x32_bf16 v[172:175], v[204:207], v[192:195], v[84:87]
	s_barrier
	ds_read_b128 v[8:11], v137
	ds_read_b128 v[12:15], v138
	ds_read_b128 v[176:179], v139
	ds_read_b128 v[138:141], v140
	ds_read_b128 v[64:67], v129 offset:32768
	ds_read_b128 v[84:87], v129 offset:33792
	ds_read_b128 v[180:183], v132 offset:32768
	ds_read_b128 v[184:187], v132 offset:33792
	ds_read_b128 v[188:191], v131 offset:32768
	ds_read_b128 v[192:195], v131 offset:33792
	ds_read_b128 v[196:199], v130 offset:32768
	ds_read_b128 v[200:203], v130 offset:33792
	s_waitcnt vmcnt(2)
	s_barrier
	s_waitcnt lgkmcnt(0)
	s_waitcnt lgkmcnt(7)
	v_mfma_f32_16x16x32_bf16 v[72:75], v[8:11], v[64:67], v[124:127]
	v_mfma_f32_16x16x32_bf16 v[76:79], v[176:179], v[64:67], v[120:123]
	s_waitcnt lgkmcnt(5)
	v_mfma_f32_16x16x32_bf16 v[88:91], v[8:11], v[180:183], v[116:119]
	v_mfma_f32_16x16x32_bf16 v[92:95], v[176:179], v[180:183], v[112:115]
	s_waitcnt lgkmcnt(3)
	v_mfma_f32_16x16x32_bf16 v[112:115], v[8:11], v[188:191], v[108:111]
	v_mfma_f32_16x16x32_bf16 v[120:123], v[176:179], v[188:191], v[104:107]
	s_waitcnt lgkmcnt(1)
	v_mfma_f32_16x16x32_bf16 v[100:103], v[8:11], v[196:199], v[100:103]
	v_mfma_f32_16x16x32_bf16 v[96:99], v[176:179], v[196:199], v[96:99]
	v_mfma_f32_16x16x32_bf16 v[124:127], v[12:15], v[84:87], v[72:75]
	v_mfma_f32_16x16x32_bf16 v[116:119], v[138:141], v[84:87], v[76:79]
	v_mfma_f32_16x16x32_bf16 v[108:111], v[12:15], v[184:187], v[88:91]
	v_mfma_f32_16x16x32_bf16 v[104:107], v[138:141], v[184:187], v[92:95]
	v_mfma_f32_16x16x32_bf16 v[92:95], v[12:15], v[192:195], v[112:115]
	v_mfma_f32_16x16x32_bf16 v[88:91], v[138:141], v[192:195], v[120:123]
	s_waitcnt lgkmcnt(0)
	v_mfma_f32_16x16x32_bf16 v[76:79], v[12:15], v[200:203], v[100:103]
	v_mfma_f32_16x16x32_bf16 v[72:75], v[138:141], v[200:203], v[96:99]
	s_barrier
; #define LDA(dst, b, h) _Pragma("unroll") for (int m = 0; m < 4; ++m) _Pragma("unroll") for (int k = 0; k < 2; ++k) \
;     dst[m][k] = *reinterpret_cast<const bf16x8*>(SA(b, h) + lds_byte(wr * 64 + m * 16 + fr, k * 32 + fq * 8))
; #define LDB(dst, b, h) _Pragma("unroll") for (int n = 0; n < 2; ++n) _Pragma("unroll") for (int k = 0; k < 2; ++k) \
;     dst[n][k] = *reinterpret_cast<const bf16x8*>(SB(b, h) + lds_byte(wc * 32 + n * 16 + fr, k * 32 + fq * 8))
; #define WAIT_V(n) asm volatile("s_waitcnt vmcnt(" #n ")" ::: "memory")
; #define WAIT_L(n) asm volatile("s_waitcnt lgkmcnt(" #n ")" ::: "memory")
; #define BAR __builtin_amdgcn_s_barrier()
;     ...
;     { LDB(B0, 1, 0); LDA(At, 1, 0); WAIT_V(2); BAR; WAIT_L(0); MMA(0, 0, At, B0); BAR;
;       LDB(B1, 1, 1); WAIT_V(0); BAR; WAIT_L(0); MMA(0, 1, At, B1); BAR;
;       LDA(At, 1, 1); BAR; WAIT_L(0); MMA(1, 0, At, B0); MMA(1, 1, At, B1); BAR; }
;     if (wr == 0) BAR;
	ds_read_b128 v[204:207], v133
	ds_read_b128 v[208:211], v134
	ds_read_b128 v[212:215], v135
	ds_read_b128 v[134:137], v136
	s_waitcnt vmcnt(0)
	s_barrier
	s_waitcnt lgkmcnt(0)
	s_waitcnt lgkmcnt(3)
	v_mfma_f32_16x16x32_bf16 v[96:99], v[204:207], v[64:67], v[164:167]
	s_waitcnt lgkmcnt(1)
	v_mfma_f32_16x16x32_bf16 v[64:67], v[212:215], v[64:67], v[168:171]
	v_mfma_f32_16x16x32_bf16 v[80:83], v[204:207], v[180:183], v[80:83]
	v_mfma_f32_16x16x32_bf16 v[68:71], v[212:215], v[180:183], v[68:71]
	v_mfma_f32_16x16x32_bf16 v[60:63], v[204:207], v[188:191], v[60:63]
	v_mfma_f32_16x16x32_bf16 v[56:59], v[212:215], v[188:191], v[56:59]
	v_mfma_f32_16x16x32_bf16 v[52:55], v[204:207], v[196:199], v[52:55]
	v_mfma_f32_16x16x32_bf16 v[48:51], v[212:215], v[196:199], v[48:51]
	v_mfma_f32_16x16x32_bf16 v[120:123], v[208:211], v[84:87], v[96:99]
	s_waitcnt lgkmcnt(0)
	v_mfma_f32_16x16x32_bf16 v[112:115], v[134:137], v[84:87], v[64:67]
	v_mfma_f32_16x16x32_bf16 v[100:103], v[208:211], v[184:187], v[80:83]
	v_mfma_f32_16x16x32_bf16 v[96:99], v[134:137], v[184:187], v[68:71]
	v_mfma_f32_16x16x32_bf16 v[84:87], v[208:211], v[192:195], v[60:63]
	v_mfma_f32_16x16x32_bf16 v[80:83], v[134:137], v[192:195], v[56:59]
	v_mfma_f32_16x16x32_bf16 v[68:71], v[208:211], v[200:203], v[52:55]
	v_mfma_f32_16x16x32_bf16 v[64:67], v[134:137], v[200:203], v[48:51]
	s_barrier
	s_nop 0
	ds_read_b128 v[48:51], v129 offset:49152
	ds_read_b128 v[162:165], v129 offset:50176
	ds_read_b128 v[52:55], v132 offset:49152
	ds_read_b128 v[166:169], v132 offset:50176
	ds_read_b128 v[180:183], v131 offset:49152
	ds_read_b128 v[184:187], v131 offset:50176
	ds_read_b128 v[188:191], v130 offset:49152
	ds_read_b128 v[130:133], v130 offset:50176
	s_barrier
	s_waitcnt lgkmcnt(0)
	s_waitcnt lgkmcnt(7)
	v_mfma_f32_16x16x32_bf16 v[44:47], v[8:11], v[48:51], v[44:47]
	v_mfma_f32_16x16x32_bf16 v[40:43], v[176:179], v[48:51], v[40:43]
	s_waitcnt lgkmcnt(5)
	v_mfma_f32_16x16x32_bf16 v[36:39], v[8:11], v[52:55], v[36:39]
	v_mfma_f32_16x16x32_bf16 v[32:35], v[176:179], v[52:55], v[32:35]
	s_waitcnt lgkmcnt(3)
	v_mfma_f32_16x16x32_bf16 v[28:31], v[8:11], v[180:183], v[28:31]
	v_mfma_f32_16x16x32_bf16 v[24:27], v[176:179], v[180:183], v[24:27]
	s_waitcnt lgkmcnt(1)
	v_mfma_f32_16x16x32_bf16 v[8:11], v[8:11], v[188:191], v[20:23]
	v_mfma_f32_16x16x32_bf16 v[16:19], v[176:179], v[188:191], v[16:19]
	v_mfma_f32_16x16x32_bf16 v[60:63], v[12:15], v[162:165], v[44:47]
	v_mfma_f32_16x16x32_bf16 v[56:59], v[138:141], v[162:165], v[40:43]
	v_mfma_f32_16x16x32_bf16 v[44:47], v[12:15], v[166:169], v[36:39]
	v_mfma_f32_16x16x32_bf16 v[40:43], v[138:141], v[166:169], v[32:35]
	v_mfma_f32_16x16x32_bf16 v[28:31], v[12:15], v[184:187], v[28:31]
	v_mfma_f32_16x16x32_bf16 v[24:27], v[138:141], v[184:187], v[24:27]
	s_waitcnt lgkmcnt(0)
	v_mfma_f32_16x16x32_bf16 v[12:15], v[12:15], v[130:133], v[8:11]
	v_mfma_f32_16x16x32_bf16 v[8:11], v[138:141], v[130:133], v[16:19]
	v_mfma_f32_16x16x32_bf16 v[16:19], v[204:207], v[48:51], v[142:145]
	v_mfma_f32_16x16x32_bf16 v[20:23], v[212:215], v[48:51], v[146:149]
	v_mfma_f32_16x16x32_bf16 v[4:7], v[204:207], v[52:55], v[4:7]
	v_mfma_f32_16x16x32_bf16 v[0:3], v[212:215], v[52:55], v[0:3]
	v_mfma_f32_16x16x32_bf16 v[138:141], v[204:207], v[180:183], v[150:153]
	v_mfma_f32_16x16x32_bf16 v[142:145], v[212:215], v[180:183], v[154:157]
	v_mfma_f32_16x16x32_bf16 v[146:149], v[204:207], v[188:191], v[158:161]
	v_mfma_f32_16x16x32_bf16 v[150:153], v[212:215], v[188:191], v[172:175]
	v_mfma_f32_16x16x32_bf16 v[52:55], v[208:211], v[162:165], v[16:19]
	v_mfma_f32_16x16x32_bf16 v[48:51], v[134:137], v[162:165], v[20:23]
	v_mfma_f32_16x16x32_bf16 v[36:39], v[208:211], v[166:169], v[4:7]
	v_mfma_f32_16x16x32_bf16 v[32:35], v[134:137], v[166:169], v[0:3]
	v_mfma_f32_16x16x32_bf16 v[20:23], v[208:211], v[184:187], v[138:141]
	v_mfma_f32_16x16x32_bf16 v[16:19], v[134:137], v[184:187], v[142:145]
	v_mfma_f32_16x16x32_bf16 v[4:7], v[208:211], v[130:133], v[146:149]
	v_mfma_f32_16x16x32_bf16 v[0:3], v[134:137], v[130:133], v[150:153]
	v_cmp_gt_u32_e32 vcc, s76, v128
	s_barrier
	s_and_saveexec_b64 s[6:7], vcc
	s_cbranch_execz .LBB0_497
	s_barrier

; #define STAGE(P, RS, SOFF, OFF, kt) do { const int _so = (SOFF) + (kt) * (BK * 2); \
;     _Pragma("unroll") for (int _i = 0; _i < 2; ++_i) { \
;       __builtin_amdgcn_raw_ptr_buffer_load_lds(RS, (__attribute__((address_space(3))) void*)((P) + wave * 1024 + _i * 8192), 16, OFF[_i], _so, 0, 0); } } while (0)
; #define LDA(dst, b, h) _Pragma("unroll") for (int m = 0; m < 4; ++m) _Pragma("unroll") for (int k = 0; k < 2; ++k) \
;     dst[m][k] = *reinterpret_cast<const bf16x8*>(SA(b, h) + lds_byte(wr * 64 + m * 16 + fr, k * 32 + fq * 8))
; #define LDB(dst, b, h) _Pragma("unroll") for (int n = 0; n < 2; ++n) _Pragma("unroll") for (int k = 0; k < 2; ++k) \
;     dst[n][k] = *reinterpret_cast<const bf16x8*>(SB(b, h) + lds_byte(wc * 32 + n * 16 + fr, k * 32 + fq * 8))
; #define WAIT_V(n) asm volatile("s_waitcnt vmcnt(" #n ")" ::: "memory")
; #define WAIT_L(n) asm volatile("s_waitcnt lgkmcnt(" #n ")" ::: "memory")
; #define BAR __builtin_amdgcn_s_barrier()
; #define SCHED __builtin_amdgcn_sched_barrier(0)
;     ...
;       LDB(B0, 0, 0); SCHED; LDA(At, 0, 0); STAGE(SA(1, 1), rsA, sA1, offA, t + 1);
;       WAIT_L(8); BAR; WAIT_L(0); MMA(0, 0, At, B0); BAR; SCHED;
;       LDB(B1, 0, 1); STAGE(SB(0, 0), rsB, sB0, offB, t + 2);
;       BAR; WAIT_L(0); MMA(0, 1, At, B1); BAR;
;       LDA(At, 0, 1); STAGE(SA(0, 0), rsA, sA0, offA, t + 2);
;       BAR; WAIT_L(0); MMA(1, 0, At, B0); BAR; SCHED;
;       STAGE(SB(0, 1), rsB, sB1, offB, t + 2);
;       WAIT_V(6); BAR; MMA(1, 1, At, B1); BAR;
.LBB0_556:
	ds_read_b128 v[154:157], v149
	ds_read_b128 v[158:161], v150
	ds_read_b128 v[162:165], v151
	ds_read_b128 v[166:169], v152
	s_add_i32 s43, s37, s17
	s_add_i32 s10, s43, 0x80
	s_mov_b32 m0, s30
	ds_read_b128 v[170:173], v131
	ds_read_b128 v[174:177], v131 offset:1024
	ds_read_b128 v[178:181], v134
	ds_read_b128 v[182:185], v134 offset:1024
	ds_read_b128 v[186:189], v133
	ds_read_b128 v[190:193], v133 offset:1024
	ds_read_b128 v[194:197], v132
	ds_read_b128 v[198:201], v132 offset:1024
	buffer_load_dwordx4 v143, s[4:7], s10 offen lds
	s_mov_b32 m0, s31
	s_nop 0
	buffer_load_dwordx4 v144, s[4:7], s10 offen lds
	s_waitcnt lgkmcnt(8)
	s_barrier
	s_waitcnt lgkmcnt(0)
	s_waitcnt lgkmcnt(7)
	v_mfma_f32_16x16x32_bf16 v[124:127], v[154:157], v[170:173], v[124:127]
	v_mfma_f32_16x16x32_bf16 v[120:123], v[162:165], v[170:173], v[120:123]
	s_waitcnt lgkmcnt(5)
	v_mfma_f32_16x16x32_bf16 v[116:119], v[154:157], v[178:181], v[116:119]
	v_mfma_f32_16x16x32_bf16 v[112:115], v[162:165], v[178:181], v[112:115]
	s_waitcnt lgkmcnt(3)
	v_mfma_f32_16x16x32_bf16 v[108:111], v[154:157], v[186:189], v[108:111]
	v_mfma_f32_16x16x32_bf16 v[104:107], v[162:165], v[186:189], v[104:107]
	s_waitcnt lgkmcnt(1)
	v_mfma_f32_16x16x32_bf16 v[100:103], v[154:157], v[194:197], v[100:103]
	v_mfma_f32_16x16x32_bf16 v[96:99], v[162:165], v[194:197], v[96:99]
	v_mfma_f32_16x16x32_bf16 v[124:127], v[158:161], v[174:177], v[124:127]
	v_mfma_f32_16x16x32_bf16 v[120:123], v[166:169], v[174:177], v[120:123]
	v_mfma_f32_16x16x32_bf16 v[116:119], v[158:161], v[182:185], v[116:119]
	v_mfma_f32_16x16x32_bf16 v[112:115], v[166:169], v[182:185], v[112:115]
	v_mfma_f32_16x16x32_bf16 v[108:111], v[158:161], v[190:193], v[108:111]
	v_mfma_f32_16x16x32_bf16 v[104:107], v[166:169], v[190:193], v[104:107]
	s_waitcnt lgkmcnt(0)
	v_mfma_f32_16x16x32_bf16 v[100:103], v[158:161], v[198:201], v[100:103]
	v_mfma_f32_16x16x32_bf16 v[96:99], v[166:169], v[198:201], v[96:99]
	s_barrier
	s_add_i32 s44, s39, s17
	s_add_i32 s45, s44, 0x100
	s_mov_b32 s10, s6
	s_mov_b32 s11, s7
	s_mov_b32 m0, s1
	ds_read_b128 v[202:205], v145
	ds_read_b128 v[206:209], v146
	ds_read_b128 v[210:213], v147
	ds_read_b128 v[214:217], v148
	buffer_load_dwordx4 v143, s[8:11], s45 offen lds
	s_mov_b32 m0, s3
	s_nop 0
	buffer_load_dwordx4 v144, s[8:11], s45 offen lds
	s_barrier
	s_waitcnt lgkmcnt(0)
	s_waitcnt lgkmcnt(3)
	v_mfma_f32_16x16x32_bf16 v[92:95], v[202:205], v[170:173], v[92:95]
	s_waitcnt lgkmcnt(1)
	v_mfma_f32_16x16x32_bf16 v[88:91], v[210:213], v[170:173], v[88:91]
	v_mfma_f32_16x16x32_bf16 v[84:87], v[202:205], v[178:181], v[84:87]
	v_mfma_f32_16x16x32_bf16 v[80:83], v[210:213], v[178:181], v[80:83]
	v_mfma_f32_16x16x32_bf16 v[76:79], v[202:205], v[186:189], v[76:79]
	v_mfma_f32_16x16x32_bf16 v[72:75], v[210:213], v[186:189], v[72:75]
	v_mfma_f32_16x16x32_bf16 v[68:71], v[202:205], v[194:197], v[68:71]
	v_mfma_f32_16x16x32_bf16 v[64:67], v[210:213], v[194:197], v[64:67]
	v_mfma_f32_16x16x32_bf16 v[92:95], v[206:209], v[174:177], v[92:95]
	s_waitcnt lgkmcnt(0)
	v_mfma_f32_16x16x32_bf16 v[88:91], v[214:217], v[174:177], v[88:91]
	v_mfma_f32_16x16x32_bf16 v[84:87], v[206:209], v[182:185], v[84:87]
	v_mfma_f32_16x16x32_bf16 v[80:83], v[214:217], v[182:185], v[80:83]
	v_mfma_f32_16x16x32_bf16 v[76:79], v[206:209], v[190:193], v[76:79]
	v_mfma_f32_16x16x32_bf16 v[72:75], v[214:217], v[190:193], v[72:75]
	v_mfma_f32_16x16x32_bf16 v[68:71], v[206:209], v[198:201], v[68:71]
	v_mfma_f32_16x16x32_bf16 v[64:67], v[214:217], v[198:201], v[64:67]
	s_add_i32 s45, s38, s17
	s_add_i32 s46, s45, 0x100
	s_mov_b32 m0, s0
	s_barrier
	ds_read_b128 v[170:173], v131 offset:16384
	ds_read_b128 v[174:177], v131 offset:17408
	ds_read_b128 v[178:181], v134 offset:16384
	ds_read_b128 v[182:185], v134 offset:17408
	ds_read_b128 v[186:189], v133 offset:16384
	ds_read_b128 v[190:193], v133 offset:17408
	ds_read_b128 v[194:197], v132 offset:16384
	ds_read_b128 v[198:201], v132 offset:17408
	buffer_load_dwordx4 v143, s[4:7], s46 offen lds
	s_mov_b32 m0, s18
	s_nop 0
	buffer_load_dwordx4 v144, s[4:7], s46 offen lds
	s_barrier
	s_waitcnt lgkmcnt(0)
	s_waitcnt lgkmcnt(7)
	v_mfma_f32_16x16x32_bf16 v[60:63], v[154:157], v[170:173], v[60:63]
	v_mfma_f32_16x16x32_bf16 v[56:59], v[162:165], v[170:173], v[56:59]
	s_waitcnt lgkmcnt(5)
	v_mfma_f32_16x16x32_bf16 v[52:55], v[154:157], v[178:181], v[52:55]
	v_mfma_f32_16x16x32_bf16 v[48:51], v[162:165], v[178:181], v[48:51]
	s_waitcnt lgkmcnt(3)
	v_mfma_f32_16x16x32_bf16 v[44:47], v[154:157], v[186:189], v[44:47]
	v_mfma_f32_16x16x32_bf16 v[40:43], v[162:165], v[186:189], v[40:43]
	s_waitcnt lgkmcnt(1)
	v_mfma_f32_16x16x32_bf16 v[36:39], v[154:157], v[194:197], v[36:39]
	v_mfma_f32_16x16x32_bf16 v[32:35], v[162:165], v[194:197], v[32:35]
	v_mfma_f32_16x16x32_bf16 v[60:63], v[158:161], v[174:177], v[60:63]
	v_mfma_f32_16x16x32_bf16 v[56:59], v[166:169], v[174:177], v[56:59]
	v_mfma_f32_16x16x32_bf16 v[52:55], v[158:161], v[182:185], v[52:55]
	v_mfma_f32_16x16x32_bf16 v[48:51], v[166:169], v[182:185], v[48:51]
	v_mfma_f32_16x16x32_bf16 v[44:47], v[158:161], v[190:193], v[44:47]
	v_mfma_f32_16x16x32_bf16 v[40:43], v[166:169], v[190:193], v[40:43]
	s_waitcnt lgkmcnt(0)
	v_mfma_f32_16x16x32_bf16 v[36:39], v[158:161], v[198:201], v[36:39]
	v_mfma_f32_16x16x32_bf16 v[32:35], v[166:169], v[198:201], v[32:35]
	s_barrier
	s_add_i32 s46, s40, s17
	s_add_i32 s47, s46, 0x100
	s_mov_b32 m0, s19
	s_nop 0
	buffer_load_dwordx4 v143, s[8:11], s47 offen lds
	s_mov_b32 m0, s20
	s_nop 0
	buffer_load_dwordx4 v144, s[8:11], s47 offen lds
	s_waitcnt vmcnt(6)
	s_barrier
; #define STAGE(P, RS, SOFF, OFF, kt) do { const int _so = (SOFF) + (kt) * (BK * 2); \
;     _Pragma("unroll") for (int _i = 0; _i < 2; ++_i) { \
;       __builtin_amdgcn_raw_ptr_buffer_load_lds(RS, (__attribute__((address_space(3))) void*)((P) + wave * 1024 + _i * 8192), 16, OFF[_i], _so, 0, 0); } } while (0)
; #define LDA(dst, b, h) _Pragma("unroll") for (int m = 0; m < 4; ++m) _Pragma("unroll") for (int k = 0; k < 2; ++k) \
;     dst[m][k] = *reinterpret_cast<const bf16x8*>(SA(b, h) + lds_byte(wr * 64 + m * 16 + fr, k * 32 + fq * 8))
; #define LDB(dst, b, h) _Pragma("unroll") for (int n = 0; n < 2; ++n) _Pragma("unroll") for (int k = 0; k < 2; ++k) \
;     dst[n][k] = *reinterpret_cast<const bf16x8*>(SB(b, h) + lds_byte(wc * 32 + n * 16 + fr, k * 32 + fq * 8))
; #define WAIT_V(n) asm volatile("s_waitcnt vmcnt(" #n ")" ::: "memory")
; #define WAIT_L(n) asm volatile("s_waitcnt lgkmcnt(" #n ")" ::: "memory")
; #define BAR __builtin_amdgcn_s_barrier()
; #define SCHED __builtin_amdgcn_sched_barrier(0)
;     ...
;       WAIT_V(6); BAR; MMA(1, 1, At, B1); BAR;
;       LDB(B0, 1, 0); SCHED; LDA(At, 1, 0); STAGE(SA(0, 1), rsA, sA1, offA, t + 2);
;       WAIT_L(8); BAR; WAIT_L(0); MMA(0, 0, At, B0); BAR; SCHED;
;       LDB(B1, 1, 1); STAGE(SB(1, 0), rsB, sB0, offB, t + 3);
;       BAR; WAIT_L(0); MMA(0, 1, At, B1); BAR;
;       LDA(At, 1, 1); STAGE(SA(1, 0), rsA, sA0, offA, t + 3);
;       BAR; WAIT_L(0); MMA(1, 0, At, B0); BAR; SCHED;
;       STAGE(SB(1, 1), rsB, sB1, offB, t + 3);
	v_mfma_f32_16x16x32_bf16 v[28:31], v[202:205], v[170:173], v[28:31]
	v_mfma_f32_16x16x32_bf16 v[24:27], v[210:213], v[170:173], v[24:27]
	v_mfma_f32_16x16x32_bf16 v[20:23], v[202:205], v[178:181], v[20:23]
	v_mfma_f32_16x16x32_bf16 v[16:19], v[210:213], v[178:181], v[16:19]
	v_mfma_f32_16x16x32_bf16 v[12:15], v[202:205], v[186:189], v[12:15]
	v_mfma_f32_16x16x32_bf16 v[8:11], v[210:213], v[186:189], v[8:11]
	v_mfma_f32_16x16x32_bf16 v[4:7], v[202:205], v[194:197], v[4:7]
	v_mfma_f32_16x16x32_bf16 v[0:3], v[210:213], v[194:197], v[0:3]
	v_mfma_f32_16x16x32_bf16 v[28:31], v[206:209], v[174:177], v[28:31]
	v_mfma_f32_16x16x32_bf16 v[24:27], v[214:217], v[174:177], v[24:27]
	v_mfma_f32_16x16x32_bf16 v[20:23], v[206:209], v[182:185], v[20:23]
	v_mfma_f32_16x16x32_bf16 v[16:19], v[214:217], v[182:185], v[16:19]
	v_mfma_f32_16x16x32_bf16 v[12:15], v[206:209], v[190:193], v[12:15]
	v_mfma_f32_16x16x32_bf16 v[8:11], v[214:217], v[190:193], v[8:11]
	v_mfma_f32_16x16x32_bf16 v[4:7], v[206:209], v[198:201], v[4:7]
	v_mfma_f32_16x16x32_bf16 v[0:3], v[214:217], v[198:201], v[0:3]
	s_barrier
	ds_read_b128 v[154:157], v139
	ds_read_b128 v[158:161], v140
	ds_read_b128 v[162:165], v141
	ds_read_b128 v[166:169], v142
	s_addk_i32 s43, 0x100
	s_mov_b32 m0, s21
	ds_read_b128 v[170:173], v131 offset:32768
	ds_read_b128 v[174:177], v131 offset:33792
	ds_read_b128 v[178:181], v134 offset:32768
	ds_read_b128 v[182:185], v134 offset:33792
	ds_read_b128 v[186:189], v133 offset:32768
	ds_read_b128 v[190:193], v133 offset:33792
	ds_read_b128 v[194:197], v132 offset:32768
	ds_read_b128 v[198:201], v132 offset:33792
	buffer_load_dwordx4 v143, s[4:7], s43 offen lds
	s_mov_b32 m0, s22
	s_nop 0
	buffer_load_dwordx4 v144, s[4:7], s43 offen lds
	s_waitcnt lgkmcnt(8)
	s_barrier
	s_waitcnt lgkmcnt(0)
	s_waitcnt lgkmcnt(7)
	v_mfma_f32_16x16x32_bf16 v[124:127], v[154:157], v[170:173], v[124:127]
	v_mfma_f32_16x16x32_bf16 v[120:123], v[162:165], v[170:173], v[120:123]
	s_waitcnt lgkmcnt(5)
	v_mfma_f32_16x16x32_bf16 v[116:119], v[154:157], v[178:181], v[116:119]
	v_mfma_f32_16x16x32_bf16 v[112:115], v[162:165], v[178:181], v[112:115]
	s_waitcnt lgkmcnt(3)
	v_mfma_f32_16x16x32_bf16 v[108:111], v[154:157], v[186:189], v[108:111]
	v_mfma_f32_16x16x32_bf16 v[104:107], v[162:165], v[186:189], v[104:107]
	s_waitcnt lgkmcnt(1)
	v_mfma_f32_16x16x32_bf16 v[100:103], v[154:157], v[194:197], v[100:103]
	v_mfma_f32_16x16x32_bf16 v[96:99], v[162:165], v[194:197], v[96:99]
	v_mfma_f32_16x16x32_bf16 v[124:127], v[158:161], v[174:177], v[124:127]
	v_mfma_f32_16x16x32_bf16 v[120:123], v[166:169], v[174:177], v[120:123]
	v_mfma_f32_16x16x32_bf16 v[116:119], v[158:161], v[182:185], v[116:119]
	v_mfma_f32_16x16x32_bf16 v[112:115], v[166:169], v[182:185], v[112:115]
	v_mfma_f32_16x16x32_bf16 v[108:111], v[158:161], v[190:193], v[108:111]
	v_mfma_f32_16x16x32_bf16 v[104:107], v[166:169], v[190:193], v[104:107]
	s_waitcnt lgkmcnt(0)
	v_mfma_f32_16x16x32_bf16 v[100:103], v[158:161], v[198:201], v[100:103]
	v_mfma_f32_16x16x32_bf16 v[96:99], v[166:169], v[198:201], v[96:99]
	s_barrier
	s_addk_i32 s44, 0x180
	s_mov_b32 m0, s23
	ds_read_b128 v[202:205], v135
	ds_read_b128 v[206:209], v136
	ds_read_b128 v[210:213], v137
	ds_read_b128 v[214:217], v138
	buffer_load_dwordx4 v143, s[8:11], s44 offen lds
	s_mov_b32 m0, s24
	s_nop 0
	buffer_load_dwordx4 v144, s[8:11], s44 offen lds
	s_barrier
	s_waitcnt lgkmcnt(0)
	s_waitcnt lgkmcnt(3)
	v_mfma_f32_16x16x32_bf16 v[92:95], v[202:205], v[170:173], v[92:95]
	s_waitcnt lgkmcnt(1)
	v_mfma_f32_16x16x32_bf16 v[88:91], v[210:213], v[170:173], v[88:91]
	v_mfma_f32_16x16x32_bf16 v[84:87], v[202:205], v[178:181], v[84:87]
	v_mfma_f32_16x16x32_bf16 v[80:83], v[210:213], v[178:181], v[80:83]
	v_mfma_f32_16x16x32_bf16 v[76:79], v[202:205], v[186:189], v[76:79]
	v_mfma_f32_16x16x32_bf16 v[72:75], v[210:213], v[186:189], v[72:75]
	v_mfma_f32_16x16x32_bf16 v[68:71], v[202:205], v[194:197], v[68:71]
	v_mfma_f32_16x16x32_bf16 v[64:67], v[210:213], v[194:197], v[64:67]
	v_mfma_f32_16x16x32_bf16 v[92:95], v[206:209], v[174:177], v[92:95]
	s_waitcnt lgkmcnt(0)
	v_mfma_f32_16x16x32_bf16 v[88:91], v[214:217], v[174:177], v[88:91]
	v_mfma_f32_16x16x32_bf16 v[84:87], v[206:209], v[182:185], v[84:87]
	v_mfma_f32_16x16x32_bf16 v[80:83], v[214:217], v[182:185], v[80:83]
	v_mfma_f32_16x16x32_bf16 v[76:79], v[206:209], v[190:193], v[76:79]
	v_mfma_f32_16x16x32_bf16 v[72:75], v[214:217], v[190:193], v[72:75]
	v_mfma_f32_16x16x32_bf16 v[68:71], v[206:209], v[198:201], v[68:71]
	v_mfma_f32_16x16x32_bf16 v[64:67], v[214:217], v[198:201], v[64:67]
	s_addk_i32 s45, 0x180
	s_mov_b32 m0, s25
	s_barrier
	ds_read_b128 v[170:173], v131 offset:49152
	ds_read_b128 v[174:177], v131 offset:50176
	ds_read_b128 v[178:181], v134 offset:49152
	ds_read_b128 v[182:185], v134 offset:50176
	ds_read_b128 v[186:189], v133 offset:49152
	ds_read_b128 v[190:193], v133 offset:50176
	ds_read_b128 v[194:197], v132 offset:49152
	ds_read_b128 v[198:201], v132 offset:50176
	buffer_load_dwordx4 v143, s[4:7], s45 offen lds
	s_mov_b32 m0, s26
	s_nop 0
	buffer_load_dwordx4 v144, s[4:7], s45 offen lds
	s_barrier
; #define STAGE(P, RS, SOFF, OFF, kt) do { const int _so = (SOFF) + (kt) * (BK * 2); \
;     _Pragma("unroll") for (int _i = 0; _i < 2; ++_i) { \
;       __builtin_amdgcn_raw_ptr_buffer_load_lds(RS, (__attribute__((address_space(3))) void*)((P) + wave * 1024 + _i * 8192), 16, OFF[_i], _so, 0, 0); } } while (0)
; #define LDA(dst, b, h) _Pragma("unroll") for (int m = 0; m < 4; ++m) _Pragma("unroll") for (int k = 0; k < 2; ++k) \
;     dst[m][k] = *reinterpret_cast<const bf16x8*>(SA(b, h) + lds_byte(wr * 64 + m * 16 + fr, k * 32 + fq * 8))
; #define LDB(dst, b, h) _Pragma("unroll") for (int n = 0; n < 2; ++n) _Pragma("unroll") for (int k = 0; k < 2; ++k) \
;     dst[n][k] = *reinterpret_cast<const bf16x8*>(SB(b, h) + lds_byte(wc * 32 + n * 16 + fr, k * 32 + fq * 8))
; #define WAIT_V(n) asm volatile("s_waitcnt vmcnt(" #n ")" ::: "memory")
; #define WAIT_L(n) asm volatile("s_waitcnt lgkmcnt(" #n ")" ::: "memory")
; #define BAR __builtin_amdgcn_s_barrier()
; #define SCHED __builtin_amdgcn_sched_barrier(0)
;     ...
;       BAR; WAIT_L(0); MMA(1, 0, At, B0); BAR; SCHED;
;       STAGE(SB(1, 1), rsB, sB1, offB, t + 3);
;       WAIT_V(6); BAR; MMA(1, 1, At, B1); BAR;
;     }
;     { LDB(B0, 0, 0); LDA(At, 0, 0); STAGE(SA(1, 1), rsA, sA1, offA, nt - 1);
;       BAR; WAIT_L(0); MMA(0, 0, At, B0); BAR;
;       LDB(B1, 0, 1); BAR; WAIT_L(0); MMA(0, 1, At, B1); BAR;
	s_waitcnt lgkmcnt(0)
	s_waitcnt lgkmcnt(7)
	v_mfma_f32_16x16x32_bf16 v[60:63], v[154:157], v[170:173], v[60:63]
	v_mfma_f32_16x16x32_bf16 v[56:59], v[162:165], v[170:173], v[56:59]
	s_waitcnt lgkmcnt(5)
	v_mfma_f32_16x16x32_bf16 v[52:55], v[154:157], v[178:181], v[52:55]
	v_mfma_f32_16x16x32_bf16 v[48:51], v[162:165], v[178:181], v[48:51]
	s_waitcnt lgkmcnt(3)
	v_mfma_f32_16x16x32_bf16 v[44:47], v[154:157], v[186:189], v[44:47]
	v_mfma_f32_16x16x32_bf16 v[40:43], v[162:165], v[186:189], v[40:43]
	s_waitcnt lgkmcnt(1)
	v_mfma_f32_16x16x32_bf16 v[36:39], v[154:157], v[194:197], v[36:39]
	v_mfma_f32_16x16x32_bf16 v[32:35], v[162:165], v[194:197], v[32:35]
	v_mfma_f32_16x16x32_bf16 v[60:63], v[158:161], v[174:177], v[60:63]
	v_mfma_f32_16x16x32_bf16 v[56:59], v[166:169], v[174:177], v[56:59]
	v_mfma_f32_16x16x32_bf16 v[52:55], v[158:161], v[182:185], v[52:55]
	v_mfma_f32_16x16x32_bf16 v[48:51], v[166:169], v[182:185], v[48:51]
	v_mfma_f32_16x16x32_bf16 v[44:47], v[158:161], v[190:193], v[44:47]
	v_mfma_f32_16x16x32_bf16 v[40:43], v[166:169], v[190:193], v[40:43]
	s_waitcnt lgkmcnt(0)
	v_mfma_f32_16x16x32_bf16 v[36:39], v[158:161], v[198:201], v[36:39]
	v_mfma_f32_16x16x32_bf16 v[32:35], v[166:169], v[198:201], v[32:35]
	s_barrier
	s_addk_i32 s46, 0x180
	s_mov_b32 m0, s27
	s_nop 0
	buffer_load_dwordx4 v143, s[8:11], s46 offen lds
	s_mov_b32 m0, s28
	s_nop 0
	buffer_load_dwordx4 v144, s[8:11], s46 offen lds
	s_waitcnt vmcnt(6)
	s_barrier
	v_mfma_f32_16x16x32_bf16 v[28:31], v[202:205], v[170:173], v[28:31]
	v_mfma_f32_16x16x32_bf16 v[24:27], v[210:213], v[170:173], v[24:27]
	v_mfma_f32_16x16x32_bf16 v[20:23], v[202:205], v[178:181], v[20:23]
	v_mfma_f32_16x16x32_bf16 v[16:19], v[210:213], v[178:181], v[16:19]
	v_mfma_f32_16x16x32_bf16 v[12:15], v[202:205], v[186:189], v[12:15]
	v_mfma_f32_16x16x32_bf16 v[8:11], v[210:213], v[186:189], v[8:11]
	v_mfma_f32_16x16x32_bf16 v[4:7], v[202:205], v[194:197], v[4:7]
	v_mfma_f32_16x16x32_bf16 v[0:3], v[210:213], v[194:197], v[0:3]
	v_mfma_f32_16x16x32_bf16 v[28:31], v[206:209], v[174:177], v[28:31]
	v_mfma_f32_16x16x32_bf16 v[24:27], v[214:217], v[174:177], v[24:27]
	v_mfma_f32_16x16x32_bf16 v[20:23], v[206:209], v[182:185], v[20:23]
	v_mfma_f32_16x16x32_bf16 v[16:19], v[214:217], v[182:185], v[16:19]
	v_mfma_f32_16x16x32_bf16 v[12:15], v[206:209], v[190:193], v[12:15]
	v_mfma_f32_16x16x32_bf16 v[8:11], v[214:217], v[190:193], v[8:11]
	v_mfma_f32_16x16x32_bf16 v[4:7], v[206:209], v[198:201], v[4:7]
	v_mfma_f32_16x16x32_bf16 v[0:3], v[214:217], v[198:201], v[0:3]
	s_add_i32 s16, s16, 2
	s_addk_i32 s17, 0x100
	s_cmp_gt_u32 s16, 27
	s_barrier
	s_cbranch_scc0 .LBB0_556
	s_add_i32 s10, s37, 0xf80
	s_mov_b32 m0, s30
	ds_read_b128 v[154:157], v149
	ds_read_b128 v[158:161], v150
	ds_read_b128 v[162:165], v151
	ds_read_b128 v[150:153], v152
	ds_read_b128 v[166:169], v131
	ds_read_b128 v[170:173], v131 offset:1024
	ds_read_b128 v[174:177], v134
	ds_read_b128 v[178:181], v134 offset:1024
	ds_read_b128 v[182:185], v133
	ds_read_b128 v[186:189], v133 offset:1024
	ds_read_b128 v[190:193], v132
	ds_read_b128 v[194:197], v132 offset:1024
	buffer_load_dwordx4 v143, s[4:7], s10 offen lds
	s_mov_b32 m0, s31
	s_nop 0
	buffer_load_dwordx4 v144, s[4:7], s10 offen lds
	s_barrier
	s_waitcnt lgkmcnt(0)
	s_waitcnt lgkmcnt(7)
	v_mfma_f32_16x16x32_bf16 v[124:127], v[154:157], v[166:169], v[124:127]
	v_mfma_f32_16x16x32_bf16 v[120:123], v[162:165], v[166:169], v[120:123]
	s_waitcnt lgkmcnt(5)
	v_mfma_f32_16x16x32_bf16 v[116:119], v[154:157], v[174:177], v[116:119]
	v_mfma_f32_16x16x32_bf16 v[112:115], v[162:165], v[174:177], v[112:115]
	s_waitcnt lgkmcnt(3)
	v_mfma_f32_16x16x32_bf16 v[108:111], v[154:157], v[182:185], v[108:111]
	v_mfma_f32_16x16x32_bf16 v[104:107], v[162:165], v[182:185], v[104:107]
	s_waitcnt lgkmcnt(1)
	v_mfma_f32_16x16x32_bf16 v[100:103], v[154:157], v[190:193], v[100:103]
	v_mfma_f32_16x16x32_bf16 v[96:99], v[162:165], v[190:193], v[96:99]
	v_mfma_f32_16x16x32_bf16 v[124:127], v[158:161], v[170:173], v[124:127]
	v_mfma_f32_16x16x32_bf16 v[120:123], v[150:153], v[170:173], v[120:123]
	v_mfma_f32_16x16x32_bf16 v[116:119], v[158:161], v[178:181], v[116:119]
	v_mfma_f32_16x16x32_bf16 v[112:115], v[150:153], v[178:181], v[112:115]
	v_mfma_f32_16x16x32_bf16 v[108:111], v[158:161], v[186:189], v[108:111]
	v_mfma_f32_16x16x32_bf16 v[104:107], v[150:153], v[186:189], v[104:107]
	s_waitcnt lgkmcnt(0)
	v_mfma_f32_16x16x32_bf16 v[100:103], v[158:161], v[194:197], v[100:103]
	v_mfma_f32_16x16x32_bf16 v[96:99], v[150:153], v[194:197], v[96:99]
	s_barrier
	ds_read_b128 v[198:201], v145
	ds_read_b128 v[202:205], v146
	ds_read_b128 v[144:147], v147
	ds_read_b128 v[206:209], v148
	s_barrier
	s_waitcnt lgkmcnt(0)
	s_waitcnt lgkmcnt(3)
	v_mfma_f32_16x16x32_bf16 v[92:95], v[198:201], v[166:169], v[92:95]
	s_waitcnt lgkmcnt(1)
	v_mfma_f32_16x16x32_bf16 v[88:91], v[144:147], v[166:169], v[88:91]
	v_mfma_f32_16x16x32_bf16 v[84:87], v[198:201], v[174:177], v[84:87]
	v_mfma_f32_16x16x32_bf16 v[80:83], v[144:147], v[174:177], v[80:83]
	v_mfma_f32_16x16x32_bf16 v[76:79], v[198:201], v[182:185], v[76:79]
	v_mfma_f32_16x16x32_bf16 v[72:75], v[144:147], v[182:185], v[72:75]
	v_mfma_f32_16x16x32_bf16 v[68:71], v[198:201], v[190:193], v[68:71]
	v_mfma_f32_16x16x32_bf16 v[64:67], v[144:147], v[190:193], v[64:67]
	v_mfma_f32_16x16x32_bf16 v[92:95], v[202:205], v[170:173], v[92:95]
	s_waitcnt lgkmcnt(0)
	v_mfma_f32_16x16x32_bf16 v[88:91], v[206:209], v[170:173], v[88:91]
	v_mfma_f32_16x16x32_bf16 v[84:87], v[202:205], v[178:181], v[84:87]
	v_mfma_f32_16x16x32_bf16 v[80:83], v[206:209], v[178:181], v[80:83]
	v_mfma_f32_16x16x32_bf16 v[76:79], v[202:205], v[186:189], v[76:79]
	v_mfma_f32_16x16x32_bf16 v[72:75], v[206:209], v[186:189], v[72:75]
	v_mfma_f32_16x16x32_bf16 v[68:71], v[202:205], v[194:197], v[68:71]
	v_mfma_f32_16x16x32_bf16 v[64:67], v[206:209], v[194:197], v[64:67]
	s_barrier
; #define LDA(dst, b, h) _Pragma("unroll") for (int m = 0; m < 4; ++m) _Pragma("unroll") for (int k = 0; k < 2; ++k) \
;     dst[m][k] = *reinterpret_cast<const bf16x8*>(SA(b, h) + lds_byte(wr * 64 + m * 16 + fr, k * 32 + fq * 8))
; #define LDB(dst, b, h) _Pragma("unroll") for (int n = 0; n < 2; ++n) _Pragma("unroll") for (int k = 0; k < 2; ++k) \
;     dst[n][k] = *reinterpret_cast<const bf16x8*>(SB(b, h) + lds_byte(wc * 32 + n * 16 + fr, k * 32 + fq * 8))
; #define WAIT_V(n) asm volatile("s_waitcnt vmcnt(" #n ")" ::: "memory")
; #define WAIT_L(n) asm volatile("s_waitcnt lgkmcnt(" #n ")" ::: "memory")
; #define BAR __builtin_amdgcn_s_barrier()
;     ...
;       LDB(B1, 0, 1); BAR; WAIT_L(0); MMA(0, 1, At, B1); BAR;
;       LDA(At, 0, 1); WAIT_V(4); BAR; WAIT_L(0); MMA(1, 0, At, B0); MMA(1, 1, At, B1); BAR; }
;     { LDB(B0, 1, 0); LDA(At, 1, 0); WAIT_V(2); BAR; WAIT_L(0); MMA(0, 0, At, B0); BAR;
;       LDB(B1, 1, 1); WAIT_V(0); BAR; WAIT_L(0); MMA(0, 1, At, B1); BAR;
	ds_read_b128 v[166:169], v131 offset:16384
	ds_read_b128 v[170:173], v131 offset:17408
	ds_read_b128 v[174:177], v134 offset:16384
	ds_read_b128 v[178:181], v134 offset:17408
	ds_read_b128 v[182:185], v133 offset:16384
	ds_read_b128 v[186:189], v133 offset:17408
	ds_read_b128 v[190:193], v132 offset:16384
	ds_read_b128 v[194:197], v132 offset:17408
	s_waitcnt vmcnt(4)
	s_barrier
	s_waitcnt lgkmcnt(0)
	s_waitcnt lgkmcnt(7)
	v_mfma_f32_16x16x32_bf16 v[60:63], v[154:157], v[166:169], v[60:63]
	v_mfma_f32_16x16x32_bf16 v[56:59], v[162:165], v[166:169], v[56:59]
	s_waitcnt lgkmcnt(5)
	v_mfma_f32_16x16x32_bf16 v[52:55], v[154:157], v[174:177], v[52:55]
	v_mfma_f32_16x16x32_bf16 v[48:51], v[162:165], v[174:177], v[48:51]
	s_waitcnt lgkmcnt(3)
	v_mfma_f32_16x16x32_bf16 v[44:47], v[154:157], v[182:185], v[44:47]
	v_mfma_f32_16x16x32_bf16 v[40:43], v[162:165], v[182:185], v[40:43]
	s_waitcnt lgkmcnt(1)
	v_mfma_f32_16x16x32_bf16 v[36:39], v[154:157], v[190:193], v[36:39]
	v_mfma_f32_16x16x32_bf16 v[32:35], v[162:165], v[190:193], v[32:35]
	v_mfma_f32_16x16x32_bf16 v[60:63], v[158:161], v[170:173], v[60:63]
	v_mfma_f32_16x16x32_bf16 v[56:59], v[150:153], v[170:173], v[56:59]
	v_mfma_f32_16x16x32_bf16 v[52:55], v[158:161], v[178:181], v[52:55]
	v_mfma_f32_16x16x32_bf16 v[48:51], v[150:153], v[178:181], v[48:51]
	v_mfma_f32_16x16x32_bf16 v[44:47], v[158:161], v[186:189], v[44:47]
	v_mfma_f32_16x16x32_bf16 v[40:43], v[150:153], v[186:189], v[40:43]
	s_waitcnt lgkmcnt(0)
	v_mfma_f32_16x16x32_bf16 v[36:39], v[158:161], v[194:197], v[36:39]
	v_mfma_f32_16x16x32_bf16 v[32:35], v[150:153], v[194:197], v[32:35]
	v_mfma_f32_16x16x32_bf16 v[28:31], v[198:201], v[166:169], v[28:31]
	v_mfma_f32_16x16x32_bf16 v[24:27], v[144:147], v[166:169], v[24:27]
	v_mfma_f32_16x16x32_bf16 v[20:23], v[198:201], v[174:177], v[20:23]
	v_mfma_f32_16x16x32_bf16 v[16:19], v[144:147], v[174:177], v[16:19]
	v_mfma_f32_16x16x32_bf16 v[12:15], v[198:201], v[182:185], v[12:15]
	v_mfma_f32_16x16x32_bf16 v[8:11], v[144:147], v[182:185], v[8:11]
	v_mfma_f32_16x16x32_bf16 v[4:7], v[198:201], v[190:193], v[4:7]
	v_mfma_f32_16x16x32_bf16 v[0:3], v[144:147], v[190:193], v[0:3]
	v_mfma_f32_16x16x32_bf16 v[28:31], v[202:205], v[170:173], v[28:31]
	v_mfma_f32_16x16x32_bf16 v[24:27], v[206:209], v[170:173], v[24:27]
	v_mfma_f32_16x16x32_bf16 v[20:23], v[202:205], v[178:181], v[20:23]
	v_mfma_f32_16x16x32_bf16 v[16:19], v[206:209], v[178:181], v[16:19]
	v_mfma_f32_16x16x32_bf16 v[12:15], v[202:205], v[186:189], v[12:15]
	v_mfma_f32_16x16x32_bf16 v[8:11], v[206:209], v[186:189], v[8:11]
	v_mfma_f32_16x16x32_bf16 v[4:7], v[202:205], v[194:197], v[4:7]
	v_mfma_f32_16x16x32_bf16 v[0:3], v[206:209], v[194:197], v[0:3]
	s_barrier
	ds_read_b128 v[144:147], v139
	ds_read_b128 v[148:151], v140
	ds_read_b128 v[152:155], v141
	ds_read_b128 v[140:143], v142
	ds_read_b128 v[156:159], v131 offset:32768
	ds_read_b128 v[160:163], v131 offset:33792
	ds_read_b128 v[164:167], v134 offset:32768
	ds_read_b128 v[168:171], v134 offset:33792
	ds_read_b128 v[172:175], v133 offset:32768
	ds_read_b128 v[176:179], v133 offset:33792
	ds_read_b128 v[180:183], v132 offset:32768
	ds_read_b128 v[184:187], v132 offset:33792
	s_waitcnt vmcnt(2)
	s_barrier
	s_waitcnt lgkmcnt(0)
	s_waitcnt lgkmcnt(7)
	v_mfma_f32_16x16x32_bf16 v[124:127], v[144:147], v[156:159], v[124:127]
	v_mfma_f32_16x16x32_bf16 v[120:123], v[152:155], v[156:159], v[120:123]
	s_waitcnt lgkmcnt(5)
	v_mfma_f32_16x16x32_bf16 v[116:119], v[144:147], v[164:167], v[116:119]
	v_mfma_f32_16x16x32_bf16 v[112:115], v[152:155], v[164:167], v[112:115]
	s_waitcnt lgkmcnt(3)
	v_mfma_f32_16x16x32_bf16 v[108:111], v[144:147], v[172:175], v[108:111]
	v_mfma_f32_16x16x32_bf16 v[104:107], v[152:155], v[172:175], v[104:107]
	s_waitcnt lgkmcnt(1)
	v_mfma_f32_16x16x32_bf16 v[100:103], v[144:147], v[180:183], v[100:103]
	v_mfma_f32_16x16x32_bf16 v[96:99], v[152:155], v[180:183], v[96:99]
	v_mfma_f32_16x16x32_bf16 v[124:127], v[148:151], v[160:163], v[124:127]
	v_mfma_f32_16x16x32_bf16 v[120:123], v[140:143], v[160:163], v[120:123]
	v_mfma_f32_16x16x32_bf16 v[116:119], v[148:151], v[168:171], v[116:119]
	v_mfma_f32_16x16x32_bf16 v[112:115], v[140:143], v[168:171], v[112:115]
	v_mfma_f32_16x16x32_bf16 v[108:111], v[148:151], v[176:179], v[108:111]
	v_mfma_f32_16x16x32_bf16 v[104:107], v[140:143], v[176:179], v[104:107]
	s_waitcnt lgkmcnt(0)
	v_mfma_f32_16x16x32_bf16 v[100:103], v[148:151], v[184:187], v[100:103]
	v_mfma_f32_16x16x32_bf16 v[96:99], v[140:143], v[184:187], v[96:99]
	s_barrier
; #define LDA(dst, b, h) _Pragma("unroll") for (int m = 0; m < 4; ++m) _Pragma("unroll") for (int k = 0; k < 2; ++k) \
;     dst[m][k] = *reinterpret_cast<const bf16x8*>(SA(b, h) + lds_byte(wr * 64 + m * 16 + fr, k * 32 + fq * 8))
; #define LDB(dst, b, h) _Pragma("unroll") for (int n = 0; n < 2; ++n) _Pragma("unroll") for (int k = 0; k < 2; ++k) \
;     dst[n][k] = *reinterpret_cast<const bf16x8*>(SB(b, h) + lds_byte(wc * 32 + n * 16 + fr, k * 32 + fq * 8))
; #define WAIT_V(n) asm volatile("s_waitcnt vmcnt(" #n ")" ::: "memory")
; #define WAIT_L(n) asm volatile("s_waitcnt lgkmcnt(" #n ")" ::: "memory")
; #define BAR __builtin_amdgcn_s_barrier()
;     ...
;     { LDB(B0, 1, 0); LDA(At, 1, 0); WAIT_V(2); BAR; WAIT_L(0); MMA(0, 0, At, B0); BAR;
;       LDB(B1, 1, 1); WAIT_V(0); BAR; WAIT_L(0); MMA(0, 1, At, B1); BAR;
;       LDA(At, 1, 1); BAR; WAIT_L(0); MMA(1, 0, At, B0); MMA(1, 1, At, B1); BAR; }
;     if (wr == 0) BAR;
	ds_read_b128 v[188:191], v135
	ds_read_b128 v[192:195], v136
	ds_read_b128 v[196:199], v137
	ds_read_b128 v[136:139], v138
	s_waitcnt vmcnt(0)
	s_barrier
	s_waitcnt lgkmcnt(0)
	s_waitcnt lgkmcnt(3)
	v_mfma_f32_16x16x32_bf16 v[92:95], v[188:191], v[156:159], v[92:95]
	s_waitcnt lgkmcnt(1)
	v_mfma_f32_16x16x32_bf16 v[88:91], v[196:199], v[156:159], v[88:91]
	v_mfma_f32_16x16x32_bf16 v[84:87], v[188:191], v[164:167], v[84:87]
	v_mfma_f32_16x16x32_bf16 v[80:83], v[196:199], v[164:167], v[80:83]
	v_mfma_f32_16x16x32_bf16 v[76:79], v[188:191], v[172:175], v[76:79]
	v_mfma_f32_16x16x32_bf16 v[72:75], v[196:199], v[172:175], v[72:75]
	v_mfma_f32_16x16x32_bf16 v[68:71], v[188:191], v[180:183], v[68:71]
	v_mfma_f32_16x16x32_bf16 v[64:67], v[196:199], v[180:183], v[64:67]
	v_mfma_f32_16x16x32_bf16 v[92:95], v[192:195], v[160:163], v[92:95]
	s_waitcnt lgkmcnt(0)
	v_mfma_f32_16x16x32_bf16 v[88:91], v[136:139], v[160:163], v[88:91]
	v_mfma_f32_16x16x32_bf16 v[84:87], v[192:195], v[168:171], v[84:87]
	v_mfma_f32_16x16x32_bf16 v[80:83], v[136:139], v[168:171], v[80:83]
	v_mfma_f32_16x16x32_bf16 v[76:79], v[192:195], v[176:179], v[76:79]
	v_mfma_f32_16x16x32_bf16 v[72:75], v[136:139], v[176:179], v[72:75]
	v_mfma_f32_16x16x32_bf16 v[68:71], v[192:195], v[184:187], v[68:71]
	v_mfma_f32_16x16x32_bf16 v[64:67], v[136:139], v[184:187], v[64:67]
	s_barrier
	ds_read_b128 v[156:159], v131 offset:49152
	ds_read_b128 v[160:163], v131 offset:50176
	ds_read_b128 v[164:167], v134 offset:49152
	ds_read_b128 v[168:171], v134 offset:50176
	ds_read_b128 v[172:175], v133 offset:49152
	ds_read_b128 v[176:179], v133 offset:50176
	ds_read_b128 v[180:183], v132 offset:49152
	ds_read_b128 v[132:135], v132 offset:50176
	s_barrier
	s_waitcnt lgkmcnt(0)
	s_waitcnt lgkmcnt(7)
	v_mfma_f32_16x16x32_bf16 v[60:63], v[144:147], v[156:159], v[60:63]
	v_mfma_f32_16x16x32_bf16 v[56:59], v[152:155], v[156:159], v[56:59]
	s_waitcnt lgkmcnt(5)
	v_mfma_f32_16x16x32_bf16 v[52:55], v[144:147], v[164:167], v[52:55]
	v_mfma_f32_16x16x32_bf16 v[48:51], v[152:155], v[164:167], v[48:51]
	s_waitcnt lgkmcnt(3)
	v_mfma_f32_16x16x32_bf16 v[44:47], v[144:147], v[172:175], v[44:47]
	v_mfma_f32_16x16x32_bf16 v[40:43], v[152:155], v[172:175], v[40:43]
	s_waitcnt lgkmcnt(1)
	v_mfma_f32_16x16x32_bf16 v[36:39], v[144:147], v[180:183], v[36:39]
	v_mfma_f32_16x16x32_bf16 v[32:35], v[152:155], v[180:183], v[32:35]
	v_mfma_f32_16x16x32_bf16 v[60:63], v[148:151], v[160:163], v[60:63]
	v_mfma_f32_16x16x32_bf16 v[56:59], v[140:143], v[160:163], v[56:59]
	v_mfma_f32_16x16x32_bf16 v[52:55], v[148:151], v[168:171], v[52:55]
	v_mfma_f32_16x16x32_bf16 v[48:51], v[140:143], v[168:171], v[48:51]
	v_mfma_f32_16x16x32_bf16 v[44:47], v[148:151], v[176:179], v[44:47]
	v_mfma_f32_16x16x32_bf16 v[40:43], v[140:143], v[176:179], v[40:43]
	s_waitcnt lgkmcnt(0)
	v_mfma_f32_16x16x32_bf16 v[36:39], v[148:151], v[132:135], v[36:39]
	v_mfma_f32_16x16x32_bf16 v[32:35], v[140:143], v[132:135], v[32:35]
	v_mfma_f32_16x16x32_bf16 v[28:31], v[188:191], v[156:159], v[28:31]
	v_mfma_f32_16x16x32_bf16 v[24:27], v[196:199], v[156:159], v[24:27]
	v_mfma_f32_16x16x32_bf16 v[20:23], v[188:191], v[164:167], v[20:23]
	v_mfma_f32_16x16x32_bf16 v[16:19], v[196:199], v[164:167], v[16:19]
	v_mfma_f32_16x16x32_bf16 v[12:15], v[188:191], v[172:175], v[12:15]
	v_mfma_f32_16x16x32_bf16 v[8:11], v[196:199], v[172:175], v[8:11]
	v_mfma_f32_16x16x32_bf16 v[4:7], v[188:191], v[180:183], v[4:7]
	v_mfma_f32_16x16x32_bf16 v[0:3], v[196:199], v[180:183], v[0:3]
	v_mfma_f32_16x16x32_bf16 v[28:31], v[192:195], v[160:163], v[28:31]
	v_mfma_f32_16x16x32_bf16 v[24:27], v[136:139], v[160:163], v[24:27]
	v_mfma_f32_16x16x32_bf16 v[20:23], v[192:195], v[168:171], v[20:23]
	v_mfma_f32_16x16x32_bf16 v[16:19], v[136:139], v[168:171], v[16:19]
	v_mfma_f32_16x16x32_bf16 v[12:15], v[192:195], v[176:179], v[12:15]
	v_mfma_f32_16x16x32_bf16 v[8:11], v[136:139], v[176:179], v[8:11]
	v_mfma_f32_16x16x32_bf16 v[4:7], v[192:195], v[132:135], v[4:7]
	v_mfma_f32_16x16x32_bf16 v[0:3], v[136:139], v[132:135], v[0:3]
	v_cmp_gt_u32_e32 vcc, s35, v130
	s_barrier
	s_and_saveexec_b64 s[10:11], vcc
	s_cbranch_execz .LBB0_559
	s_barrier

; #define STAGE(P, RS, SOFF, OFF, kt) do { const int _so = (SOFF) + (kt) * (BK * 2); \
;     _Pragma("unroll") for (int _i = 0; _i < 2; ++_i) { \
;       __builtin_amdgcn_raw_ptr_buffer_load_lds(RS, (__attribute__((address_space(3))) void*)((P) + wave * 1024 + _i * 8192), 16, OFF[_i], _so, 0, 0); } } while (0)
; #define LDA(dst, b, h) _Pragma("unroll") for (int m = 0; m < 4; ++m) _Pragma("unroll") for (int k = 0; k < 2; ++k) \
;     dst[m][k] = *reinterpret_cast<const bf16x8*>(SA(b, h) + lds_byte(wr * 64 + m * 16 + fr, k * 32 + fq * 8))
; #define LDB(dst, b, h) _Pragma("unroll") for (int n = 0; n < 2; ++n) _Pragma("unroll") for (int k = 0; k < 2; ++k) \
;     dst[n][k] = *reinterpret_cast<const bf16x8*>(SB(b, h) + lds_byte(wc * 32 + n * 16 + fr, k * 32 + fq * 8))
; #define WAIT_V(n) asm volatile("s_waitcnt vmcnt(" #n ")" ::: "memory")
; #define WAIT_L(n) asm volatile("s_waitcnt lgkmcnt(" #n ")" ::: "memory")
; #define BAR __builtin_amdgcn_s_barrier()
; #define SCHED __builtin_amdgcn_sched_barrier(0)
;     ...
;       LDB(B0, 0, 0); SCHED; LDA(At, 0, 0); STAGE(SA(1, 1), rsA, sA1, offA, t + 1);
;       WAIT_L(8); BAR; WAIT_L(0); MMA(0, 0, At, B0); BAR; SCHED;
;       LDB(B1, 0, 1); STAGE(SB(0, 0), rsB, sB0, offB, t + 2);
;       BAR; WAIT_L(0); MMA(0, 1, At, B1); BAR;
;       LDA(At, 0, 1); STAGE(SA(0, 0), rsA, sA0, offA, t + 2);
;       BAR; WAIT_L(0); MMA(1, 0, At, B0); BAR; SCHED;
;       STAGE(SB(0, 1), rsB, sB1, offB, t + 2);
;       WAIT_V(6); BAR; MMA(1, 1, At, B1); BAR;
.LBB0_657:
	ds_read_b128 v[152:155], v147
	ds_read_b128 v[156:159], v148
	ds_read_b128 v[160:163], v149
	ds_read_b128 v[164:167], v150
	s_add_i32 s5, s81, s3
	s_add_i32 s6, s5, 0x80
	s_mov_b32 m0, s39
	ds_read_b128 v[168:171], v129
	ds_read_b128 v[172:175], v129 offset:1024
	ds_read_b128 v[176:179], v132
	ds_read_b128 v[180:183], v132 offset:1024
	ds_read_b128 v[184:187], v131
	ds_read_b128 v[188:191], v131 offset:1024
	ds_read_b128 v[192:195], v130
	ds_read_b128 v[196:199], v130 offset:1024
	buffer_load_dwordx4 v141, s[8:11], s6 offen lds
	s_mov_b32 m0, s58
	s_nop 0
	buffer_load_dwordx4 v142, s[8:11], s6 offen lds
	s_waitcnt lgkmcnt(8)
	s_barrier
	s_waitcnt lgkmcnt(0)
	s_waitcnt lgkmcnt(7)
	v_mfma_f32_16x16x32_bf16 v[124:127], v[152:155], v[168:171], v[124:127]
	v_mfma_f32_16x16x32_bf16 v[120:123], v[160:163], v[168:171], v[120:123]
	s_waitcnt lgkmcnt(5)
	v_mfma_f32_16x16x32_bf16 v[116:119], v[152:155], v[176:179], v[116:119]
	v_mfma_f32_16x16x32_bf16 v[112:115], v[160:163], v[176:179], v[112:115]
	s_waitcnt lgkmcnt(3)
	v_mfma_f32_16x16x32_bf16 v[108:111], v[152:155], v[184:187], v[108:111]
	v_mfma_f32_16x16x32_bf16 v[104:107], v[160:163], v[184:187], v[104:107]
	s_waitcnt lgkmcnt(1)
	v_mfma_f32_16x16x32_bf16 v[100:103], v[152:155], v[192:195], v[100:103]
	v_mfma_f32_16x16x32_bf16 v[96:99], v[160:163], v[192:195], v[96:99]
	v_mfma_f32_16x16x32_bf16 v[124:127], v[156:159], v[172:175], v[124:127]
	v_mfma_f32_16x16x32_bf16 v[120:123], v[164:167], v[172:175], v[120:123]
	v_mfma_f32_16x16x32_bf16 v[116:119], v[156:159], v[180:183], v[116:119]
	v_mfma_f32_16x16x32_bf16 v[112:115], v[164:167], v[180:183], v[112:115]
	v_mfma_f32_16x16x32_bf16 v[108:111], v[156:159], v[188:191], v[108:111]
	v_mfma_f32_16x16x32_bf16 v[104:107], v[164:167], v[188:191], v[104:107]
	s_waitcnt lgkmcnt(0)
	v_mfma_f32_16x16x32_bf16 v[100:103], v[156:159], v[196:199], v[100:103]
	v_mfma_f32_16x16x32_bf16 v[96:99], v[164:167], v[196:199], v[96:99]
	s_barrier
	s_add_i32 s6, s83, s3
	s_add_i32 s7, s6, 0x100
	s_mov_b32 s14, s10
	s_mov_b32 s15, s11
	s_mov_b32 m0, s85
	ds_read_b128 v[200:203], v143
	ds_read_b128 v[204:207], v144
	ds_read_b128 v[208:211], v145
	ds_read_b128 v[212:215], v146
	buffer_load_dwordx4 v141, s[12:15], s7 offen lds
	s_mov_b32 m0, s75
	s_nop 0
	buffer_load_dwordx4 v142, s[12:15], s7 offen lds
	s_barrier
	s_waitcnt lgkmcnt(0)
	s_waitcnt lgkmcnt(3)
	v_mfma_f32_16x16x32_bf16 v[92:95], v[200:203], v[168:171], v[92:95]
	s_waitcnt lgkmcnt(1)
	v_mfma_f32_16x16x32_bf16 v[88:91], v[208:211], v[168:171], v[88:91]
	v_mfma_f32_16x16x32_bf16 v[80:83], v[200:203], v[176:179], v[80:83]
	v_mfma_f32_16x16x32_bf16 v[68:71], v[208:211], v[176:179], v[68:71]
	v_mfma_f32_16x16x32_bf16 v[60:63], v[200:203], v[184:187], v[60:63]
	v_mfma_f32_16x16x32_bf16 v[56:59], v[208:211], v[184:187], v[56:59]
	v_mfma_f32_16x16x32_bf16 v[52:55], v[200:203], v[192:195], v[52:55]
	v_mfma_f32_16x16x32_bf16 v[48:51], v[208:211], v[192:195], v[48:51]
	v_mfma_f32_16x16x32_bf16 v[92:95], v[204:207], v[172:175], v[92:95]
	s_waitcnt lgkmcnt(0)
	v_mfma_f32_16x16x32_bf16 v[88:91], v[212:215], v[172:175], v[88:91]
	v_mfma_f32_16x16x32_bf16 v[80:83], v[204:207], v[180:183], v[80:83]
	v_mfma_f32_16x16x32_bf16 v[68:71], v[212:215], v[180:183], v[68:71]
	v_mfma_f32_16x16x32_bf16 v[60:63], v[204:207], v[188:191], v[60:63]
	v_mfma_f32_16x16x32_bf16 v[56:59], v[212:215], v[188:191], v[56:59]
	v_mfma_f32_16x16x32_bf16 v[52:55], v[204:207], v[196:199], v[52:55]
	v_mfma_f32_16x16x32_bf16 v[48:51], v[212:215], v[196:199], v[48:51]
	s_add_i32 s7, s82, s3
	s_add_i32 s22, s7, 0x100
	s_mov_b32 m0, s38
	s_barrier
	ds_read_b128 v[168:171], v129 offset:16384
	ds_read_b128 v[172:175], v129 offset:17408
	ds_read_b128 v[176:179], v132 offset:16384
	ds_read_b128 v[180:183], v132 offset:17408
	ds_read_b128 v[184:187], v131 offset:16384
	ds_read_b128 v[188:191], v131 offset:17408
	ds_read_b128 v[192:195], v130 offset:16384
	ds_read_b128 v[196:199], v130 offset:17408
	buffer_load_dwordx4 v141, s[8:11], s22 offen lds
	s_mov_b32 m0, s95
	s_nop 0
	buffer_load_dwordx4 v142, s[8:11], s22 offen lds
	s_barrier
	s_waitcnt lgkmcnt(0)
	s_waitcnt lgkmcnt(7)
	v_mfma_f32_16x16x32_bf16 v[44:47], v[152:155], v[168:171], v[44:47]
	v_mfma_f32_16x16x32_bf16 v[40:43], v[160:163], v[168:171], v[40:43]
	s_waitcnt lgkmcnt(5)
	v_mfma_f32_16x16x32_bf16 v[36:39], v[152:155], v[176:179], v[36:39]
	v_mfma_f32_16x16x32_bf16 v[32:35], v[160:163], v[176:179], v[32:35]
	s_waitcnt lgkmcnt(3)
	v_mfma_f32_16x16x32_bf16 v[28:31], v[152:155], v[184:187], v[28:31]
	v_mfma_f32_16x16x32_bf16 v[24:27], v[160:163], v[184:187], v[24:27]
	s_waitcnt lgkmcnt(1)
	v_mfma_f32_16x16x32_bf16 v[20:23], v[152:155], v[192:195], v[20:23]
	v_mfma_f32_16x16x32_bf16 v[16:19], v[160:163], v[192:195], v[16:19]
	v_mfma_f32_16x16x32_bf16 v[44:47], v[156:159], v[172:175], v[44:47]
	v_mfma_f32_16x16x32_bf16 v[40:43], v[164:167], v[172:175], v[40:43]
	v_mfma_f32_16x16x32_bf16 v[36:39], v[156:159], v[180:183], v[36:39]
	v_mfma_f32_16x16x32_bf16 v[32:35], v[164:167], v[180:183], v[32:35]
	v_mfma_f32_16x16x32_bf16 v[28:31], v[156:159], v[188:191], v[28:31]
	v_mfma_f32_16x16x32_bf16 v[24:27], v[164:167], v[188:191], v[24:27]
	s_waitcnt lgkmcnt(0)
	v_mfma_f32_16x16x32_bf16 v[20:23], v[156:159], v[196:199], v[20:23]
	v_mfma_f32_16x16x32_bf16 v[16:19], v[164:167], v[196:199], v[16:19]
	s_barrier
	s_add_i32 s22, s84, s3
	s_add_i32 s23, s22, 0x100
	s_mov_b32 m0, s86
	s_nop 0
	buffer_load_dwordx4 v141, s[12:15], s23 offen lds
	s_mov_b32 m0, s28
	s_nop 0
	buffer_load_dwordx4 v142, s[12:15], s23 offen lds
	s_waitcnt vmcnt(6)
	s_barrier
; #define STAGE(P, RS, SOFF, OFF, kt) do { const int _so = (SOFF) + (kt) * (BK * 2); \
;     _Pragma("unroll") for (int _i = 0; _i < 2; ++_i) { \
;       __builtin_amdgcn_raw_ptr_buffer_load_lds(RS, (__attribute__((address_space(3))) void*)((P) + wave * 1024 + _i * 8192), 16, OFF[_i], _so, 0, 0); } } while (0)
; #define LDA(dst, b, h) _Pragma("unroll") for (int m = 0; m < 4; ++m) _Pragma("unroll") for (int k = 0; k < 2; ++k) \
;     dst[m][k] = *reinterpret_cast<const bf16x8*>(SA(b, h) + lds_byte(wr * 64 + m * 16 + fr, k * 32 + fq * 8))
; #define LDB(dst, b, h) _Pragma("unroll") for (int n = 0; n < 2; ++n) _Pragma("unroll") for (int k = 0; k < 2; ++k) \
;     dst[n][k] = *reinterpret_cast<const bf16x8*>(SB(b, h) + lds_byte(wc * 32 + n * 16 + fr, k * 32 + fq * 8))
; #define WAIT_V(n) asm volatile("s_waitcnt vmcnt(" #n ")" ::: "memory")
; #define WAIT_L(n) asm volatile("s_waitcnt lgkmcnt(" #n ")" ::: "memory")
; #define BAR __builtin_amdgcn_s_barrier()
; #define SCHED __builtin_amdgcn_sched_barrier(0)
;     ...
;       WAIT_V(6); BAR; MMA(1, 1, At, B1); BAR;
;       LDB(B0, 1, 0); SCHED; LDA(At, 1, 0); STAGE(SA(0, 1), rsA, sA1, offA, t + 2);
;       WAIT_L(8); BAR; WAIT_L(0); MMA(0, 0, At, B0); BAR; SCHED;
;       LDB(B1, 1, 1); STAGE(SB(1, 0), rsB, sB0, offB, t + 3);
;       BAR; WAIT_L(0); MMA(0, 1, At, B1); BAR;
;       LDA(At, 1, 1); STAGE(SA(1, 0), rsA, sA0, offA, t + 3);
	v_mfma_f32_16x16x32_bf16 v[12:15], v[200:203], v[168:171], v[12:15]
	v_mfma_f32_16x16x32_bf16 v[8:11], v[208:211], v[168:171], v[8:11]
	v_mfma_f32_16x16x32_bf16 v[4:7], v[200:203], v[176:179], v[4:7]
	v_mfma_f32_16x16x32_bf16 v[0:3], v[208:211], v[176:179], v[0:3]
	v_mfma_f32_16x16x32_bf16 v[64:67], v[200:203], v[184:187], v[64:67]
	v_mfma_f32_16x16x32_bf16 v[72:75], v[208:211], v[184:187], v[72:75]
	v_mfma_f32_16x16x32_bf16 v[76:79], v[200:203], v[192:195], v[76:79]
	v_mfma_f32_16x16x32_bf16 v[84:87], v[208:211], v[192:195], v[84:87]
	v_mfma_f32_16x16x32_bf16 v[12:15], v[204:207], v[172:175], v[12:15]
	v_mfma_f32_16x16x32_bf16 v[8:11], v[212:215], v[172:175], v[8:11]
	v_mfma_f32_16x16x32_bf16 v[4:7], v[204:207], v[180:183], v[4:7]
	v_mfma_f32_16x16x32_bf16 v[0:3], v[212:215], v[180:183], v[0:3]
	v_mfma_f32_16x16x32_bf16 v[64:67], v[204:207], v[188:191], v[64:67]
	v_mfma_f32_16x16x32_bf16 v[72:75], v[212:215], v[188:191], v[72:75]
	v_mfma_f32_16x16x32_bf16 v[76:79], v[204:207], v[196:199], v[76:79]
	v_mfma_f32_16x16x32_bf16 v[84:87], v[212:215], v[196:199], v[84:87]
	s_barrier
	ds_read_b128 v[152:155], v137
	ds_read_b128 v[156:159], v138
	ds_read_b128 v[160:163], v139
	ds_read_b128 v[164:167], v140
	s_addk_i32 s5, 0x100
	s_mov_b32 m0, s87
	ds_read_b128 v[168:171], v129 offset:32768
	ds_read_b128 v[172:175], v129 offset:33792
	ds_read_b128 v[176:179], v132 offset:32768
	ds_read_b128 v[180:183], v132 offset:33792
	ds_read_b128 v[184:187], v131 offset:32768
	ds_read_b128 v[188:191], v131 offset:33792
	ds_read_b128 v[192:195], v130 offset:32768
	ds_read_b128 v[196:199], v130 offset:33792
	buffer_load_dwordx4 v141, s[8:11], s5 offen lds
	s_mov_b32 m0, s97
	s_nop 0
	buffer_load_dwordx4 v142, s[8:11], s5 offen lds
	s_waitcnt lgkmcnt(8)
	s_barrier
	s_waitcnt lgkmcnt(0)
	s_waitcnt lgkmcnt(7)
	v_mfma_f32_16x16x32_bf16 v[124:127], v[152:155], v[168:171], v[124:127]
	v_mfma_f32_16x16x32_bf16 v[120:123], v[160:163], v[168:171], v[120:123]
	s_waitcnt lgkmcnt(5)
	v_mfma_f32_16x16x32_bf16 v[116:119], v[152:155], v[176:179], v[116:119]
	v_mfma_f32_16x16x32_bf16 v[112:115], v[160:163], v[176:179], v[112:115]
	s_waitcnt lgkmcnt(3)
	v_mfma_f32_16x16x32_bf16 v[108:111], v[152:155], v[184:187], v[108:111]
	v_mfma_f32_16x16x32_bf16 v[104:107], v[160:163], v[184:187], v[104:107]
	s_waitcnt lgkmcnt(1)
	v_mfma_f32_16x16x32_bf16 v[100:103], v[152:155], v[192:195], v[100:103]
	v_mfma_f32_16x16x32_bf16 v[96:99], v[160:163], v[192:195], v[96:99]
	v_mfma_f32_16x16x32_bf16 v[124:127], v[156:159], v[172:175], v[124:127]
	v_mfma_f32_16x16x32_bf16 v[120:123], v[164:167], v[172:175], v[120:123]
	v_mfma_f32_16x16x32_bf16 v[116:119], v[156:159], v[180:183], v[116:119]
	v_mfma_f32_16x16x32_bf16 v[112:115], v[164:167], v[180:183], v[112:115]
	v_mfma_f32_16x16x32_bf16 v[108:111], v[156:159], v[188:191], v[108:111]
	v_mfma_f32_16x16x32_bf16 v[104:107], v[164:167], v[188:191], v[104:107]
	s_waitcnt lgkmcnt(0)
	v_mfma_f32_16x16x32_bf16 v[100:103], v[156:159], v[196:199], v[100:103]
	v_mfma_f32_16x16x32_bf16 v[96:99], v[164:167], v[196:199], v[96:99]
	s_barrier
	s_addk_i32 s6, 0x180
	s_mov_b32 m0, s92
	ds_read_b128 v[200:203], v133
	ds_read_b128 v[204:207], v134
	ds_read_b128 v[208:211], v135
	ds_read_b128 v[212:215], v136
	buffer_load_dwordx4 v141, s[12:15], s6 offen lds
	s_mov_b32 m0, s29
	s_nop 0
	buffer_load_dwordx4 v142, s[12:15], s6 offen lds
	s_barrier
	s_waitcnt lgkmcnt(0)
	s_waitcnt lgkmcnt(3)
	v_mfma_f32_16x16x32_bf16 v[92:95], v[200:203], v[168:171], v[92:95]
	s_waitcnt lgkmcnt(1)
	v_mfma_f32_16x16x32_bf16 v[88:91], v[208:211], v[168:171], v[88:91]
	v_mfma_f32_16x16x32_bf16 v[80:83], v[200:203], v[176:179], v[80:83]
	v_mfma_f32_16x16x32_bf16 v[68:71], v[208:211], v[176:179], v[68:71]
	v_mfma_f32_16x16x32_bf16 v[60:63], v[200:203], v[184:187], v[60:63]
	v_mfma_f32_16x16x32_bf16 v[56:59], v[208:211], v[184:187], v[56:59]
	v_mfma_f32_16x16x32_bf16 v[52:55], v[200:203], v[192:195], v[52:55]
	v_mfma_f32_16x16x32_bf16 v[48:51], v[208:211], v[192:195], v[48:51]
	v_mfma_f32_16x16x32_bf16 v[92:95], v[204:207], v[172:175], v[92:95]
	s_waitcnt lgkmcnt(0)
	v_mfma_f32_16x16x32_bf16 v[88:91], v[212:215], v[172:175], v[88:91]
	v_mfma_f32_16x16x32_bf16 v[80:83], v[204:207], v[180:183], v[80:83]
	v_mfma_f32_16x16x32_bf16 v[68:71], v[212:215], v[180:183], v[68:71]
	v_mfma_f32_16x16x32_bf16 v[60:63], v[204:207], v[188:191], v[60:63]
	v_mfma_f32_16x16x32_bf16 v[56:59], v[212:215], v[188:191], v[56:59]
	v_mfma_f32_16x16x32_bf16 v[52:55], v[204:207], v[196:199], v[52:55]
	v_mfma_f32_16x16x32_bf16 v[48:51], v[212:215], v[196:199], v[48:51]
	s_addk_i32 s7, 0x180
	s_mov_b32 m0, s93
	s_barrier
	ds_read_b128 v[168:171], v129 offset:49152
	ds_read_b128 v[172:175], v129 offset:50176
	ds_read_b128 v[176:179], v132 offset:49152
	ds_read_b128 v[180:183], v132 offset:50176
	ds_read_b128 v[184:187], v131 offset:49152
	ds_read_b128 v[188:191], v131 offset:50176
	ds_read_b128 v[192:195], v130 offset:49152
	ds_read_b128 v[196:199], v130 offset:50176
	buffer_load_dwordx4 v141, s[8:11], s7 offen lds
	s_mov_b32 m0, s56
	s_nop 0
	buffer_load_dwordx4 v142, s[8:11], s7 offen lds
	s_barrier
; #define STAGE(P, RS, SOFF, OFF, kt) do { const int _so = (SOFF) + (kt) * (BK * 2); \
;     _Pragma("unroll") for (int _i = 0; _i < 2; ++_i) { \
;       __builtin_amdgcn_raw_ptr_buffer_load_lds(RS, (__attribute__((address_space(3))) void*)((P) + wave * 1024 + _i * 8192), 16, OFF[_i], _so, 0, 0); } } while (0)
; #define LDA(dst, b, h) _Pragma("unroll") for (int m = 0; m < 4; ++m) _Pragma("unroll") for (int k = 0; k < 2; ++k) \
;     dst[m][k] = *reinterpret_cast<const bf16x8*>(SA(b, h) + lds_byte(wr * 64 + m * 16 + fr, k * 32 + fq * 8))
; #define LDB(dst, b, h) _Pragma("unroll") for (int n = 0; n < 2; ++n) _Pragma("unroll") for (int k = 0; k < 2; ++k) \
;     dst[n][k] = *reinterpret_cast<const bf16x8*>(SB(b, h) + lds_byte(wc * 32 + n * 16 + fr, k * 32 + fq * 8))
; #define WAIT_V(n) asm volatile("s_waitcnt vmcnt(" #n ")" ::: "memory")
; #define WAIT_L(n) asm volatile("s_waitcnt lgkmcnt(" #n ")" ::: "memory")
; #define BAR __builtin_amdgcn_s_barrier()
; #define SCHED __builtin_amdgcn_sched_barrier(0)
;     ...
;       BAR; WAIT_L(0); MMA(1, 0, At, B0); BAR; SCHED;
;       STAGE(SB(1, 1), rsB, sB1, offB, t + 3);
;       WAIT_V(6); BAR; MMA(1, 1, At, B1); BAR;
;     }
;     { LDB(B0, 0, 0); LDA(At, 0, 0); STAGE(SA(1, 1), rsA, sA1, offA, nt - 1);
;       BAR; WAIT_L(0); MMA(0, 0, At, B0); BAR;
;       LDB(B1, 0, 1); BAR; WAIT_L(0); MMA(0, 1, At, B1); BAR;
	s_waitcnt lgkmcnt(0)
	s_waitcnt lgkmcnt(7)
	v_mfma_f32_16x16x32_bf16 v[44:47], v[152:155], v[168:171], v[44:47]
	v_mfma_f32_16x16x32_bf16 v[40:43], v[160:163], v[168:171], v[40:43]
	s_waitcnt lgkmcnt(5)
	v_mfma_f32_16x16x32_bf16 v[36:39], v[152:155], v[176:179], v[36:39]
	v_mfma_f32_16x16x32_bf16 v[32:35], v[160:163], v[176:179], v[32:35]
	s_waitcnt lgkmcnt(3)
	v_mfma_f32_16x16x32_bf16 v[28:31], v[152:155], v[184:187], v[28:31]
	v_mfma_f32_16x16x32_bf16 v[24:27], v[160:163], v[184:187], v[24:27]
	s_waitcnt lgkmcnt(1)
	v_mfma_f32_16x16x32_bf16 v[20:23], v[152:155], v[192:195], v[20:23]
	v_mfma_f32_16x16x32_bf16 v[16:19], v[160:163], v[192:195], v[16:19]
	v_mfma_f32_16x16x32_bf16 v[44:47], v[156:159], v[172:175], v[44:47]
	v_mfma_f32_16x16x32_bf16 v[40:43], v[164:167], v[172:175], v[40:43]
	v_mfma_f32_16x16x32_bf16 v[36:39], v[156:159], v[180:183], v[36:39]
	v_mfma_f32_16x16x32_bf16 v[32:35], v[164:167], v[180:183], v[32:35]
	v_mfma_f32_16x16x32_bf16 v[28:31], v[156:159], v[188:191], v[28:31]
	v_mfma_f32_16x16x32_bf16 v[24:27], v[164:167], v[188:191], v[24:27]
	s_waitcnt lgkmcnt(0)
	v_mfma_f32_16x16x32_bf16 v[20:23], v[156:159], v[196:199], v[20:23]
	v_mfma_f32_16x16x32_bf16 v[16:19], v[164:167], v[196:199], v[16:19]
	s_barrier
	s_addk_i32 s22, 0x180
	s_mov_b32 m0, s94
	s_nop 0
	buffer_load_dwordx4 v141, s[12:15], s22 offen lds
	s_mov_b32 m0, s57
	s_nop 0
	buffer_load_dwordx4 v142, s[12:15], s22 offen lds
	s_waitcnt vmcnt(6)
	s_barrier
	v_mfma_f32_16x16x32_bf16 v[12:15], v[200:203], v[168:171], v[12:15]
	v_mfma_f32_16x16x32_bf16 v[8:11], v[208:211], v[168:171], v[8:11]
	v_mfma_f32_16x16x32_bf16 v[4:7], v[200:203], v[176:179], v[4:7]
	v_mfma_f32_16x16x32_bf16 v[0:3], v[208:211], v[176:179], v[0:3]
	v_mfma_f32_16x16x32_bf16 v[64:67], v[200:203], v[184:187], v[64:67]
	v_mfma_f32_16x16x32_bf16 v[72:75], v[208:211], v[184:187], v[72:75]
	v_mfma_f32_16x16x32_bf16 v[76:79], v[200:203], v[192:195], v[76:79]
	v_mfma_f32_16x16x32_bf16 v[84:87], v[208:211], v[192:195], v[84:87]
	v_mfma_f32_16x16x32_bf16 v[12:15], v[204:207], v[172:175], v[12:15]
	v_mfma_f32_16x16x32_bf16 v[8:11], v[212:215], v[172:175], v[8:11]
	v_mfma_f32_16x16x32_bf16 v[4:7], v[204:207], v[180:183], v[4:7]
	v_mfma_f32_16x16x32_bf16 v[0:3], v[212:215], v[180:183], v[0:3]
	v_mfma_f32_16x16x32_bf16 v[64:67], v[204:207], v[188:191], v[64:67]
	v_mfma_f32_16x16x32_bf16 v[72:75], v[212:215], v[188:191], v[72:75]
	v_mfma_f32_16x16x32_bf16 v[76:79], v[204:207], v[196:199], v[76:79]
	v_mfma_f32_16x16x32_bf16 v[84:87], v[212:215], v[196:199], v[84:87]
	s_add_i32 s1, s1, 2
	s_addk_i32 s3, 0x100
	s_cmp_gt_u32 s1, 27
	s_barrier
	s_cbranch_scc0 .LBB0_657
	s_add_i32 s1, s81, 0xf80
	s_mov_b32 m0, s39
	ds_read_b128 v[152:155], v147
	ds_read_b128 v[156:159], v148
	ds_read_b128 v[160:163], v149
	ds_read_b128 v[148:151], v150
	ds_read_b128 v[164:167], v129
	ds_read_b128 v[168:171], v129 offset:1024
	ds_read_b128 v[172:175], v132
	ds_read_b128 v[176:179], v132 offset:1024
	ds_read_b128 v[180:183], v131
	ds_read_b128 v[184:187], v131 offset:1024
	ds_read_b128 v[188:191], v130
	ds_read_b128 v[192:195], v130 offset:1024
	buffer_load_dwordx4 v141, s[8:11], s1 offen lds
	s_mov_b32 m0, s58
	s_nop 0
	buffer_load_dwordx4 v142, s[8:11], s1 offen lds
	s_barrier
	s_waitcnt lgkmcnt(0)
	s_waitcnt lgkmcnt(7)
	v_mfma_f32_16x16x32_bf16 v[124:127], v[152:155], v[164:167], v[124:127]
	v_mfma_f32_16x16x32_bf16 v[120:123], v[160:163], v[164:167], v[120:123]
	s_waitcnt lgkmcnt(5)
	v_mfma_f32_16x16x32_bf16 v[116:119], v[152:155], v[172:175], v[116:119]
	v_mfma_f32_16x16x32_bf16 v[112:115], v[160:163], v[172:175], v[112:115]
	s_waitcnt lgkmcnt(3)
	v_mfma_f32_16x16x32_bf16 v[108:111], v[152:155], v[180:183], v[108:111]
	v_mfma_f32_16x16x32_bf16 v[104:107], v[160:163], v[180:183], v[104:107]
	s_waitcnt lgkmcnt(1)
	v_mfma_f32_16x16x32_bf16 v[100:103], v[152:155], v[188:191], v[100:103]
	v_mfma_f32_16x16x32_bf16 v[96:99], v[160:163], v[188:191], v[96:99]
	v_mfma_f32_16x16x32_bf16 v[124:127], v[156:159], v[168:171], v[124:127]
	v_mfma_f32_16x16x32_bf16 v[120:123], v[148:151], v[168:171], v[120:123]
	v_mfma_f32_16x16x32_bf16 v[116:119], v[156:159], v[176:179], v[116:119]
	v_mfma_f32_16x16x32_bf16 v[112:115], v[148:151], v[176:179], v[112:115]
	v_mfma_f32_16x16x32_bf16 v[108:111], v[156:159], v[184:187], v[108:111]
	v_mfma_f32_16x16x32_bf16 v[104:107], v[148:151], v[184:187], v[104:107]
	s_waitcnt lgkmcnt(0)
	v_mfma_f32_16x16x32_bf16 v[100:103], v[156:159], v[192:195], v[100:103]
	v_mfma_f32_16x16x32_bf16 v[96:99], v[148:151], v[192:195], v[96:99]
	s_barrier
	ds_read_b128 v[196:199], v143
	ds_read_b128 v[200:203], v144
	ds_read_b128 v[142:145], v145
	ds_read_b128 v[204:207], v146
	s_barrier
	s_waitcnt lgkmcnt(0)
	s_waitcnt lgkmcnt(1)
	v_mfma_f32_16x16x32_bf16 v[88:91], v[142:145], v[164:167], v[88:91]
	v_mfma_f32_16x16x32_bf16 v[80:83], v[196:199], v[172:175], v[80:83]
	v_mfma_f32_16x16x32_bf16 v[60:63], v[196:199], v[180:183], v[60:63]
	v_mfma_f32_16x16x32_bf16 v[56:59], v[142:145], v[180:183], v[56:59]
	v_mfma_f32_16x16x32_bf16 v[52:55], v[196:199], v[188:191], v[52:55]
	v_mfma_f32_16x16x32_bf16 v[48:51], v[142:145], v[188:191], v[48:51]
	v_mfma_f32_16x16x32_bf16 v[92:95], v[196:199], v[164:167], v[92:95]
	v_mfma_f32_16x16x32_bf16 v[68:71], v[142:145], v[172:175], v[68:71]
	s_waitcnt lgkmcnt(0)
	v_mfma_f32_16x16x32_bf16 v[88:91], v[204:207], v[168:171], v[88:91]
	v_mfma_f32_16x16x32_bf16 v[80:83], v[200:203], v[176:179], v[80:83]
	v_mfma_f32_16x16x32_bf16 v[60:63], v[200:203], v[184:187], v[60:63]
	v_mfma_f32_16x16x32_bf16 v[56:59], v[204:207], v[184:187], v[56:59]
	v_mfma_f32_16x16x32_bf16 v[52:55], v[200:203], v[192:195], v[52:55]
	v_mfma_f32_16x16x32_bf16 v[48:51], v[204:207], v[192:195], v[48:51]
	v_mfma_f32_16x16x32_bf16 v[164:167], v[200:203], v[168:171], v[92:95]
	v_mfma_f32_16x16x32_bf16 v[168:171], v[204:207], v[176:179], v[68:71]
	s_barrier
; #define LDA(dst, b, h) _Pragma("unroll") for (int m = 0; m < 4; ++m) _Pragma("unroll") for (int k = 0; k < 2; ++k) \
;     dst[m][k] = *reinterpret_cast<const bf16x8*>(SA(b, h) + lds_byte(wr * 64 + m * 16 + fr, k * 32 + fq * 8))
; #define LDB(dst, b, h) _Pragma("unroll") for (int n = 0; n < 2; ++n) _Pragma("unroll") for (int k = 0; k < 2; ++k) \
;     dst[n][k] = *reinterpret_cast<const bf16x8*>(SB(b, h) + lds_byte(wc * 32 + n * 16 + fr, k * 32 + fq * 8))
; #define WAIT_V(n) asm volatile("s_waitcnt vmcnt(" #n ")" ::: "memory")
; #define WAIT_L(n) asm volatile("s_waitcnt lgkmcnt(" #n ")" ::: "memory")
; #define BAR __builtin_amdgcn_s_barrier()
;     ...
;       LDA(At, 0, 1); WAIT_V(4); BAR; WAIT_L(0); MMA(1, 0, At, B0); MMA(1, 1, At, B1); BAR; }
;     { LDB(B0, 1, 0); LDA(At, 1, 0); WAIT_V(2); BAR; WAIT_L(0); MMA(0, 0, At, B0); BAR;
	s_nop 0
	ds_read_b128 v[68:71], v129 offset:16384
	ds_read_b128 v[92:95], v129 offset:17408
	ds_read_b128 v[172:175], v132 offset:16384
	ds_read_b128 v[176:179], v132 offset:17408
	ds_read_b128 v[180:183], v131 offset:16384
	ds_read_b128 v[184:187], v131 offset:17408
	ds_read_b128 v[188:191], v130 offset:16384
	ds_read_b128 v[192:195], v130 offset:17408
	s_waitcnt vmcnt(4)
	s_barrier
	s_waitcnt lgkmcnt(0)
	s_waitcnt lgkmcnt(7)
	v_mfma_f32_16x16x32_bf16 v[44:47], v[152:155], v[68:71], v[44:47]
	v_mfma_f32_16x16x32_bf16 v[40:43], v[160:163], v[68:71], v[40:43]
	s_waitcnt lgkmcnt(5)
	v_mfma_f32_16x16x32_bf16 v[36:39], v[152:155], v[172:175], v[36:39]
	v_mfma_f32_16x16x32_bf16 v[32:35], v[160:163], v[172:175], v[32:35]
	s_waitcnt lgkmcnt(3)
	v_mfma_f32_16x16x32_bf16 v[28:31], v[152:155], v[180:183], v[28:31]
	v_mfma_f32_16x16x32_bf16 v[24:27], v[160:163], v[180:183], v[24:27]
	s_waitcnt lgkmcnt(1)
	v_mfma_f32_16x16x32_bf16 v[20:23], v[152:155], v[188:191], v[20:23]
	v_mfma_f32_16x16x32_bf16 v[16:19], v[160:163], v[188:191], v[16:19]
	v_mfma_f32_16x16x32_bf16 v[44:47], v[156:159], v[92:95], v[44:47]
	v_mfma_f32_16x16x32_bf16 v[40:43], v[148:151], v[92:95], v[40:43]
	v_mfma_f32_16x16x32_bf16 v[36:39], v[156:159], v[176:179], v[36:39]
	v_mfma_f32_16x16x32_bf16 v[32:35], v[148:151], v[176:179], v[32:35]
	v_mfma_f32_16x16x32_bf16 v[28:31], v[156:159], v[184:187], v[28:31]
	v_mfma_f32_16x16x32_bf16 v[24:27], v[148:151], v[184:187], v[24:27]
	s_waitcnt lgkmcnt(0)
	v_mfma_f32_16x16x32_bf16 v[20:23], v[156:159], v[192:195], v[20:23]
	v_mfma_f32_16x16x32_bf16 v[16:19], v[148:151], v[192:195], v[16:19]
	v_mfma_f32_16x16x32_bf16 v[4:7], v[196:199], v[172:175], v[4:7]
	v_mfma_f32_16x16x32_bf16 v[0:3], v[142:145], v[172:175], v[0:3]
	v_mfma_f32_16x16x32_bf16 v[12:15], v[196:199], v[68:71], v[12:15]
	v_mfma_f32_16x16x32_bf16 v[8:11], v[142:145], v[68:71], v[8:11]
	v_mfma_f32_16x16x32_bf16 v[64:67], v[196:199], v[180:183], v[64:67]
	v_mfma_f32_16x16x32_bf16 v[68:71], v[142:145], v[180:183], v[72:75]
	v_mfma_f32_16x16x32_bf16 v[72:75], v[196:199], v[188:191], v[76:79]
	v_mfma_f32_16x16x32_bf16 v[76:79], v[142:145], v[188:191], v[84:87]
	v_mfma_f32_16x16x32_bf16 v[4:7], v[200:203], v[176:179], v[4:7]
	v_mfma_f32_16x16x32_bf16 v[0:3], v[204:207], v[176:179], v[0:3]
	v_mfma_f32_16x16x32_bf16 v[142:145], v[200:203], v[92:95], v[12:15]
	v_mfma_f32_16x16x32_bf16 v[146:149], v[204:207], v[92:95], v[8:11]
	v_mfma_f32_16x16x32_bf16 v[150:153], v[200:203], v[184:187], v[64:67]
	v_mfma_f32_16x16x32_bf16 v[154:157], v[204:207], v[184:187], v[68:71]
	v_mfma_f32_16x16x32_bf16 v[158:161], v[200:203], v[192:195], v[72:75]
	v_mfma_f32_16x16x32_bf16 v[172:175], v[204:207], v[192:195], v[76:79]
	s_barrier
	ds_read_b128 v[8:11], v137
	ds_read_b128 v[12:15], v138
	ds_read_b128 v[176:179], v139
	ds_read_b128 v[138:141], v140
	ds_read_b128 v[64:67], v129 offset:32768
	ds_read_b128 v[72:75], v129 offset:33792
	ds_read_b128 v[180:183], v132 offset:32768
	ds_read_b128 v[184:187], v132 offset:33792
	ds_read_b128 v[188:191], v131 offset:32768
	ds_read_b128 v[192:195], v131 offset:33792
	ds_read_b128 v[196:199], v130 offset:32768
	ds_read_b128 v[200:203], v130 offset:33792
	s_waitcnt vmcnt(2)
	s_barrier
	s_waitcnt lgkmcnt(0)
	s_waitcnt lgkmcnt(7)
	v_mfma_f32_16x16x32_bf16 v[68:71], v[8:11], v[64:67], v[124:127]
	v_mfma_f32_16x16x32_bf16 v[76:79], v[176:179], v[64:67], v[120:123]
	s_waitcnt lgkmcnt(5)
	v_mfma_f32_16x16x32_bf16 v[84:87], v[8:11], v[180:183], v[116:119]
	v_mfma_f32_16x16x32_bf16 v[92:95], v[176:179], v[180:183], v[112:115]
	s_waitcnt lgkmcnt(3)
	v_mfma_f32_16x16x32_bf16 v[112:115], v[8:11], v[188:191], v[108:111]
	v_mfma_f32_16x16x32_bf16 v[104:107], v[176:179], v[188:191], v[104:107]
	s_waitcnt lgkmcnt(1)
	v_mfma_f32_16x16x32_bf16 v[120:123], v[8:11], v[196:199], v[100:103]
	v_mfma_f32_16x16x32_bf16 v[96:99], v[176:179], v[196:199], v[96:99]
	v_mfma_f32_16x16x32_bf16 v[124:127], v[12:15], v[72:75], v[68:71]
	v_mfma_f32_16x16x32_bf16 v[116:119], v[138:141], v[72:75], v[76:79]
	v_mfma_f32_16x16x32_bf16 v[108:111], v[12:15], v[184:187], v[84:87]
	v_mfma_f32_16x16x32_bf16 v[100:103], v[138:141], v[184:187], v[92:95]
	v_mfma_f32_16x16x32_bf16 v[92:95], v[12:15], v[192:195], v[112:115]
	v_mfma_f32_16x16x32_bf16 v[84:87], v[138:141], v[192:195], v[104:107]
	s_waitcnt lgkmcnt(0)
	v_mfma_f32_16x16x32_bf16 v[76:79], v[12:15], v[200:203], v[120:123]
	v_mfma_f32_16x16x32_bf16 v[68:71], v[138:141], v[200:203], v[96:99]
	s_barrier
; #define LDA(dst, b, h) _Pragma("unroll") for (int m = 0; m < 4; ++m) _Pragma("unroll") for (int k = 0; k < 2; ++k) \
;     dst[m][k] = *reinterpret_cast<const bf16x8*>(SA(b, h) + lds_byte(wr * 64 + m * 16 + fr, k * 32 + fq * 8))
; #define LDB(dst, b, h) _Pragma("unroll") for (int n = 0; n < 2; ++n) _Pragma("unroll") for (int k = 0; k < 2; ++k) \
;     dst[n][k] = *reinterpret_cast<const bf16x8*>(SB(b, h) + lds_byte(wc * 32 + n * 16 + fr, k * 32 + fq * 8))
; #define WAIT_V(n) asm volatile("s_waitcnt vmcnt(" #n ")" ::: "memory")
; #define WAIT_L(n) asm volatile("s_waitcnt lgkmcnt(" #n ")" ::: "memory")
; #define BAR __builtin_amdgcn_s_barrier()
;     ...
;       LDB(B1, 1, 1); WAIT_V(0); BAR; WAIT_L(0); MMA(0, 1, At, B1); BAR;
;       LDA(At, 1, 1); BAR; WAIT_L(0); MMA(1, 0, At, B0); MMA(1, 1, At, B1); BAR; }
;     if (wr == 0) BAR;
	ds_read_b128 v[204:207], v133
	ds_read_b128 v[208:211], v134
	ds_read_b128 v[212:215], v135
	ds_read_b128 v[134:137], v136
	s_waitcnt vmcnt(0)
	s_barrier
	s_waitcnt lgkmcnt(0)
	s_waitcnt lgkmcnt(3)
	v_mfma_f32_16x16x32_bf16 v[96:99], v[204:207], v[64:67], v[164:167]
	s_waitcnt lgkmcnt(1)
	v_mfma_f32_16x16x32_bf16 v[64:67], v[212:215], v[64:67], v[88:91]
	v_mfma_f32_16x16x32_bf16 v[80:83], v[204:207], v[180:183], v[80:83]
	v_mfma_f32_16x16x32_bf16 v[88:91], v[212:215], v[180:183], v[168:171]
	v_mfma_f32_16x16x32_bf16 v[60:63], v[204:207], v[188:191], v[60:63]
	v_mfma_f32_16x16x32_bf16 v[56:59], v[212:215], v[188:191], v[56:59]
	v_mfma_f32_16x16x32_bf16 v[52:55], v[204:207], v[196:199], v[52:55]
	v_mfma_f32_16x16x32_bf16 v[48:51], v[212:215], v[196:199], v[48:51]
	v_mfma_f32_16x16x32_bf16 v[120:123], v[208:211], v[72:75], v[96:99]
	s_waitcnt lgkmcnt(0)
	v_mfma_f32_16x16x32_bf16 v[112:115], v[134:137], v[72:75], v[64:67]
	v_mfma_f32_16x16x32_bf16 v[104:107], v[208:211], v[184:187], v[80:83]
	v_mfma_f32_16x16x32_bf16 v[96:99], v[134:137], v[184:187], v[88:91]
	v_mfma_f32_16x16x32_bf16 v[88:91], v[208:211], v[192:195], v[60:63]
	v_mfma_f32_16x16x32_bf16 v[80:83], v[134:137], v[192:195], v[56:59]
	v_mfma_f32_16x16x32_bf16 v[72:75], v[208:211], v[200:203], v[52:55]
	v_mfma_f32_16x16x32_bf16 v[64:67], v[134:137], v[200:203], v[48:51]
	s_barrier
	s_nop 0
	ds_read_b128 v[48:51], v129 offset:49152
	ds_read_b128 v[162:165], v129 offset:50176
	ds_read_b128 v[52:55], v132 offset:49152
	ds_read_b128 v[166:169], v132 offset:50176
	ds_read_b128 v[180:183], v131 offset:49152
	ds_read_b128 v[184:187], v131 offset:50176
	ds_read_b128 v[188:191], v130 offset:49152
	ds_read_b128 v[130:133], v130 offset:50176
	s_barrier
	s_waitcnt lgkmcnt(0)
	s_waitcnt lgkmcnt(7)
	v_mfma_f32_16x16x32_bf16 v[44:47], v[8:11], v[48:51], v[44:47]
	v_mfma_f32_16x16x32_bf16 v[40:43], v[176:179], v[48:51], v[40:43]
	s_waitcnt lgkmcnt(5)
	v_mfma_f32_16x16x32_bf16 v[36:39], v[8:11], v[52:55], v[36:39]
	v_mfma_f32_16x16x32_bf16 v[32:35], v[176:179], v[52:55], v[32:35]
	s_waitcnt lgkmcnt(3)
	v_mfma_f32_16x16x32_bf16 v[28:31], v[8:11], v[180:183], v[28:31]
	v_mfma_f32_16x16x32_bf16 v[24:27], v[176:179], v[180:183], v[24:27]
	s_waitcnt lgkmcnt(1)
	v_mfma_f32_16x16x32_bf16 v[8:11], v[8:11], v[188:191], v[20:23]
	v_mfma_f32_16x16x32_bf16 v[16:19], v[176:179], v[188:191], v[16:19]
	v_mfma_f32_16x16x32_bf16 v[60:63], v[12:15], v[162:165], v[44:47]
	v_mfma_f32_16x16x32_bf16 v[56:59], v[138:141], v[162:165], v[40:43]
	v_mfma_f32_16x16x32_bf16 v[44:47], v[12:15], v[166:169], v[36:39]
	v_mfma_f32_16x16x32_bf16 v[40:43], v[138:141], v[166:169], v[32:35]
	v_mfma_f32_16x16x32_bf16 v[28:31], v[12:15], v[184:187], v[28:31]
	v_mfma_f32_16x16x32_bf16 v[24:27], v[138:141], v[184:187], v[24:27]
	s_waitcnt lgkmcnt(0)
	v_mfma_f32_16x16x32_bf16 v[12:15], v[12:15], v[130:133], v[8:11]
	v_mfma_f32_16x16x32_bf16 v[8:11], v[138:141], v[130:133], v[16:19]
	v_mfma_f32_16x16x32_bf16 v[16:19], v[204:207], v[48:51], v[142:145]
	v_mfma_f32_16x16x32_bf16 v[20:23], v[212:215], v[48:51], v[146:149]
	v_mfma_f32_16x16x32_bf16 v[4:7], v[204:207], v[52:55], v[4:7]
	v_mfma_f32_16x16x32_bf16 v[0:3], v[212:215], v[52:55], v[0:3]
	v_mfma_f32_16x16x32_bf16 v[138:141], v[204:207], v[180:183], v[150:153]
	v_mfma_f32_16x16x32_bf16 v[142:145], v[212:215], v[180:183], v[154:157]
	v_mfma_f32_16x16x32_bf16 v[146:149], v[204:207], v[188:191], v[158:161]
	v_mfma_f32_16x16x32_bf16 v[150:153], v[212:215], v[188:191], v[172:175]
	v_mfma_f32_16x16x32_bf16 v[52:55], v[208:211], v[162:165], v[16:19]
	v_mfma_f32_16x16x32_bf16 v[48:51], v[134:137], v[162:165], v[20:23]
	v_mfma_f32_16x16x32_bf16 v[36:39], v[208:211], v[166:169], v[4:7]
	v_mfma_f32_16x16x32_bf16 v[32:35], v[134:137], v[166:169], v[0:3]
	v_mfma_f32_16x16x32_bf16 v[20:23], v[208:211], v[184:187], v[138:141]
	v_mfma_f32_16x16x32_bf16 v[16:19], v[134:137], v[184:187], v[142:145]
	v_mfma_f32_16x16x32_bf16 v[4:7], v[208:211], v[130:133], v[146:149]
	v_mfma_f32_16x16x32_bf16 v[0:3], v[134:137], v[130:133], v[150:153]
	v_cmp_gt_u32_e32 vcc, s73, v128
	s_barrier
	s_and_saveexec_b64 s[6:7], vcc
	s_cbranch_execz .LBB0_660
	s_barrier

; #define STAGE(P, RS, SOFF, OFF, kt) do { const int _so = (SOFF) + (kt) * (BK * 2); \
;     _Pragma("unroll") for (int _i = 0; _i < 2; ++_i) { \
;       __builtin_amdgcn_raw_ptr_buffer_load_lds(RS, (__attribute__((address_space(3))) void*)((P) + wave * 1024 + _i * 8192), 16, OFF[_i], _so, 0, 0); } } while (0)
; #define LDA(dst, b, h) _Pragma("unroll") for (int m = 0; m < 4; ++m) _Pragma("unroll") for (int k = 0; k < 2; ++k) \
;     dst[m][k] = *reinterpret_cast<const bf16x8*>(SA(b, h) + lds_byte(wr * 64 + m * 16 + fr, k * 32 + fq * 8))
; #define LDB(dst, b, h) _Pragma("unroll") for (int n = 0; n < 2; ++n) _Pragma("unroll") for (int k = 0; k < 2; ++k) \
;     dst[n][k] = *reinterpret_cast<const bf16x8*>(SB(b, h) + lds_byte(wc * 32 + n * 16 + fr, k * 32 + fq * 8))
; #define WAIT_V(n) asm volatile("s_waitcnt vmcnt(" #n ")" ::: "memory")
; #define WAIT_L(n) asm volatile("s_waitcnt lgkmcnt(" #n ")" ::: "memory")
; #define BAR __builtin_amdgcn_s_barrier()
; #define SCHED __builtin_amdgcn_sched_barrier(0)
;     ...
;       LDB(B0, 0, 0); SCHED; LDA(At, 0, 0); STAGE(SA(1, 1), rsA, sA1, offA, t + 1);
;       WAIT_L(8); BAR; WAIT_L(0); MMA(0, 0, At, B0); BAR; SCHED;
;       LDB(B1, 0, 1); STAGE(SB(0, 0), rsB, sB0, offB, t + 2);
;       BAR; WAIT_L(0); MMA(0, 1, At, B1); BAR;
;       LDA(At, 0, 1); STAGE(SA(0, 0), rsA, sA0, offA, t + 2);
;       BAR; WAIT_L(0); MMA(1, 0, At, B0); BAR; SCHED;
;       STAGE(SB(0, 1), rsB, sB1, offB, t + 2);
;       WAIT_V(6); BAR; MMA(1, 1, At, B1); BAR;
.LBB0_757:
	ds_read_b128 v[152:155], v147
	ds_read_b128 v[156:159], v148
	ds_read_b128 v[160:163], v149
	ds_read_b128 v[164:167], v150
	s_add_i32 s6, s85, s5
	s_add_i32 s7, s6, 0x80
	s_mov_b32 m0, s39
	ds_read_b128 v[168:171], v129
	ds_read_b128 v[172:175], v129 offset:1024
	ds_read_b128 v[176:179], v132
	ds_read_b128 v[180:183], v132 offset:1024
	ds_read_b128 v[184:187], v131
	ds_read_b128 v[188:191], v131 offset:1024
	ds_read_b128 v[192:195], v130
	ds_read_b128 v[196:199], v130 offset:1024
	buffer_load_dwordx4 v141, s[8:11], s7 offen lds
	s_mov_b32 m0, s56
	s_nop 0
	buffer_load_dwordx4 v142, s[8:11], s7 offen lds
	s_waitcnt lgkmcnt(8)
	s_barrier
	s_waitcnt lgkmcnt(0)
	s_waitcnt lgkmcnt(7)
	v_mfma_f32_16x16x32_bf16 v[124:127], v[152:155], v[168:171], v[124:127]
	v_mfma_f32_16x16x32_bf16 v[120:123], v[160:163], v[168:171], v[120:123]
	s_waitcnt lgkmcnt(5)
	v_mfma_f32_16x16x32_bf16 v[116:119], v[152:155], v[176:179], v[116:119]
	v_mfma_f32_16x16x32_bf16 v[112:115], v[160:163], v[176:179], v[112:115]
	s_waitcnt lgkmcnt(3)
	v_mfma_f32_16x16x32_bf16 v[108:111], v[152:155], v[184:187], v[108:111]
	v_mfma_f32_16x16x32_bf16 v[104:107], v[160:163], v[184:187], v[104:107]
	s_waitcnt lgkmcnt(1)
	v_mfma_f32_16x16x32_bf16 v[100:103], v[152:155], v[192:195], v[100:103]
	v_mfma_f32_16x16x32_bf16 v[96:99], v[160:163], v[192:195], v[96:99]
	v_mfma_f32_16x16x32_bf16 v[124:127], v[156:159], v[172:175], v[124:127]
	v_mfma_f32_16x16x32_bf16 v[120:123], v[164:167], v[172:175], v[120:123]
	v_mfma_f32_16x16x32_bf16 v[116:119], v[156:159], v[180:183], v[116:119]
	v_mfma_f32_16x16x32_bf16 v[112:115], v[164:167], v[180:183], v[112:115]
	v_mfma_f32_16x16x32_bf16 v[108:111], v[156:159], v[188:191], v[108:111]
	v_mfma_f32_16x16x32_bf16 v[104:107], v[164:167], v[188:191], v[104:107]
	s_waitcnt lgkmcnt(0)
	v_mfma_f32_16x16x32_bf16 v[100:103], v[156:159], v[196:199], v[100:103]
	v_mfma_f32_16x16x32_bf16 v[96:99], v[164:167], v[196:199], v[96:99]
	s_barrier
	s_add_i32 s7, s87, s5
	s_add_i32 s23, s7, 0x100
	s_mov_b32 s14, s10
	s_mov_b32 s15, s11
	s_mov_b32 m0, s42
	ds_read_b128 v[200:203], v143
	ds_read_b128 v[204:207], v144
	ds_read_b128 v[208:211], v145
	ds_read_b128 v[212:215], v146
	buffer_load_dwordx4 v141, s[12:15], s23 offen lds
	s_mov_b32 m0, s49
	s_nop 0
	buffer_load_dwordx4 v142, s[12:15], s23 offen lds
	s_barrier
	s_waitcnt lgkmcnt(0)
	s_waitcnt lgkmcnt(3)
	v_mfma_f32_16x16x32_bf16 v[92:95], v[200:203], v[168:171], v[92:95]
	s_waitcnt lgkmcnt(1)
	v_mfma_f32_16x16x32_bf16 v[88:91], v[208:211], v[168:171], v[88:91]
	v_mfma_f32_16x16x32_bf16 v[80:83], v[200:203], v[176:179], v[80:83]
	v_mfma_f32_16x16x32_bf16 v[68:71], v[208:211], v[176:179], v[68:71]
	v_mfma_f32_16x16x32_bf16 v[60:63], v[200:203], v[184:187], v[60:63]
	v_mfma_f32_16x16x32_bf16 v[56:59], v[208:211], v[184:187], v[56:59]
	v_mfma_f32_16x16x32_bf16 v[52:55], v[200:203], v[192:195], v[52:55]
	v_mfma_f32_16x16x32_bf16 v[48:51], v[208:211], v[192:195], v[48:51]
	v_mfma_f32_16x16x32_bf16 v[92:95], v[204:207], v[172:175], v[92:95]
	s_waitcnt lgkmcnt(0)
	v_mfma_f32_16x16x32_bf16 v[88:91], v[212:215], v[172:175], v[88:91]
	v_mfma_f32_16x16x32_bf16 v[80:83], v[204:207], v[180:183], v[80:83]
	v_mfma_f32_16x16x32_bf16 v[68:71], v[212:215], v[180:183], v[68:71]
	v_mfma_f32_16x16x32_bf16 v[60:63], v[204:207], v[188:191], v[60:63]
	v_mfma_f32_16x16x32_bf16 v[56:59], v[212:215], v[188:191], v[56:59]
	v_mfma_f32_16x16x32_bf16 v[52:55], v[204:207], v[196:199], v[52:55]
	v_mfma_f32_16x16x32_bf16 v[48:51], v[212:215], v[196:199], v[48:51]
	s_add_i32 s23, s86, s5
	s_add_i32 s26, s23, 0x100
	s_mov_b32 m0, s33
	s_barrier
	ds_read_b128 v[168:171], v129 offset:16384
	ds_read_b128 v[172:175], v129 offset:17408
	ds_read_b128 v[176:179], v132 offset:16384
	ds_read_b128 v[180:183], v132 offset:17408
	ds_read_b128 v[184:187], v131 offset:16384
	ds_read_b128 v[188:191], v131 offset:17408
	ds_read_b128 v[192:195], v130 offset:16384
	ds_read_b128 v[196:199], v130 offset:17408
	buffer_load_dwordx4 v141, s[8:11], s26 offen lds
	s_mov_b32 m0, s50
	s_nop 0
	buffer_load_dwordx4 v142, s[8:11], s26 offen lds
	s_barrier
	s_waitcnt lgkmcnt(0)
	s_waitcnt lgkmcnt(7)
	v_mfma_f32_16x16x32_bf16 v[44:47], v[152:155], v[168:171], v[44:47]
	v_mfma_f32_16x16x32_bf16 v[40:43], v[160:163], v[168:171], v[40:43]
	s_waitcnt lgkmcnt(5)
	v_mfma_f32_16x16x32_bf16 v[36:39], v[152:155], v[176:179], v[36:39]
	v_mfma_f32_16x16x32_bf16 v[32:35], v[160:163], v[176:179], v[32:35]
	s_waitcnt lgkmcnt(3)
	v_mfma_f32_16x16x32_bf16 v[28:31], v[152:155], v[184:187], v[28:31]
	v_mfma_f32_16x16x32_bf16 v[24:27], v[160:163], v[184:187], v[24:27]
	s_waitcnt lgkmcnt(1)
	v_mfma_f32_16x16x32_bf16 v[20:23], v[152:155], v[192:195], v[20:23]
	v_mfma_f32_16x16x32_bf16 v[16:19], v[160:163], v[192:195], v[16:19]
	v_mfma_f32_16x16x32_bf16 v[44:47], v[156:159], v[172:175], v[44:47]
	v_mfma_f32_16x16x32_bf16 v[40:43], v[164:167], v[172:175], v[40:43]
	v_mfma_f32_16x16x32_bf16 v[36:39], v[156:159], v[180:183], v[36:39]
	v_mfma_f32_16x16x32_bf16 v[32:35], v[164:167], v[180:183], v[32:35]
	v_mfma_f32_16x16x32_bf16 v[28:31], v[156:159], v[188:191], v[28:31]
	v_mfma_f32_16x16x32_bf16 v[24:27], v[164:167], v[188:191], v[24:27]
	s_waitcnt lgkmcnt(0)
	v_mfma_f32_16x16x32_bf16 v[20:23], v[156:159], v[196:199], v[20:23]
	v_mfma_f32_16x16x32_bf16 v[16:19], v[164:167], v[196:199], v[16:19]
	s_barrier
	s_add_i32 s26, s90, s5
	s_add_i32 s27, s26, 0x100
	s_mov_b32 m0, s43
	s_nop 0
	buffer_load_dwordx4 v141, s[12:15], s27 offen lds
	s_mov_b32 m0, s51
	s_nop 0
	buffer_load_dwordx4 v142, s[12:15], s27 offen lds
	s_waitcnt vmcnt(6)
	s_barrier
; #define STAGE(P, RS, SOFF, OFF, kt) do { const int _so = (SOFF) + (kt) * (BK * 2); \
;     _Pragma("unroll") for (int _i = 0; _i < 2; ++_i) { \
;       __builtin_amdgcn_raw_ptr_buffer_load_lds(RS, (__attribute__((address_space(3))) void*)((P) + wave * 1024 + _i * 8192), 16, OFF[_i], _so, 0, 0); } } while (0)
; #define LDA(dst, b, h) _Pragma("unroll") for (int m = 0; m < 4; ++m) _Pragma("unroll") for (int k = 0; k < 2; ++k) \
;     dst[m][k] = *reinterpret_cast<const bf16x8*>(SA(b, h) + lds_byte(wr * 64 + m * 16 + fr, k * 32 + fq * 8))
; #define LDB(dst, b, h) _Pragma("unroll") for (int n = 0; n < 2; ++n) _Pragma("unroll") for (int k = 0; k < 2; ++k) \
;     dst[n][k] = *reinterpret_cast<const bf16x8*>(SB(b, h) + lds_byte(wc * 32 + n * 16 + fr, k * 32 + fq * 8))
; #define WAIT_V(n) asm volatile("s_waitcnt vmcnt(" #n ")" ::: "memory")
; #define WAIT_L(n) asm volatile("s_waitcnt lgkmcnt(" #n ")" ::: "memory")
; #define BAR __builtin_amdgcn_s_barrier()
; #define SCHED __builtin_amdgcn_sched_barrier(0)
;     ...
;       WAIT_V(6); BAR; MMA(1, 1, At, B1); BAR;
;       LDB(B0, 1, 0); SCHED; LDA(At, 1, 0); STAGE(SA(0, 1), rsA, sA1, offA, t + 2);
;       WAIT_L(8); BAR; WAIT_L(0); MMA(0, 0, At, B0); BAR; SCHED;
;       LDB(B1, 1, 1); STAGE(SB(1, 0), rsB, sB0, offB, t + 3);
;       BAR; WAIT_L(0); MMA(0, 1, At, B1); BAR;
;       LDA(At, 1, 1); STAGE(SA(1, 0), rsA, sA0, offA, t + 3);
	v_mfma_f32_16x16x32_bf16 v[12:15], v[200:203], v[168:171], v[12:15]
	v_mfma_f32_16x16x32_bf16 v[8:11], v[208:211], v[168:171], v[8:11]
	v_mfma_f32_16x16x32_bf16 v[4:7], v[200:203], v[176:179], v[4:7]
	v_mfma_f32_16x16x32_bf16 v[0:3], v[208:211], v[176:179], v[0:3]
	v_mfma_f32_16x16x32_bf16 v[64:67], v[200:203], v[184:187], v[64:67]
	v_mfma_f32_16x16x32_bf16 v[72:75], v[208:211], v[184:187], v[72:75]
	v_mfma_f32_16x16x32_bf16 v[76:79], v[200:203], v[192:195], v[76:79]
	v_mfma_f32_16x16x32_bf16 v[84:87], v[208:211], v[192:195], v[84:87]
	v_mfma_f32_16x16x32_bf16 v[12:15], v[204:207], v[172:175], v[12:15]
	v_mfma_f32_16x16x32_bf16 v[8:11], v[212:215], v[172:175], v[8:11]
	v_mfma_f32_16x16x32_bf16 v[4:7], v[204:207], v[180:183], v[4:7]
	v_mfma_f32_16x16x32_bf16 v[0:3], v[212:215], v[180:183], v[0:3]
	v_mfma_f32_16x16x32_bf16 v[64:67], v[204:207], v[188:191], v[64:67]
	v_mfma_f32_16x16x32_bf16 v[72:75], v[212:215], v[188:191], v[72:75]
	v_mfma_f32_16x16x32_bf16 v[76:79], v[204:207], v[196:199], v[76:79]
	v_mfma_f32_16x16x32_bf16 v[84:87], v[212:215], v[196:199], v[84:87]
	s_barrier
	ds_read_b128 v[152:155], v137
	ds_read_b128 v[156:159], v138
	ds_read_b128 v[160:163], v139
	ds_read_b128 v[164:167], v140
	s_addk_i32 s6, 0x100
	s_mov_b32 m0, s44
	ds_read_b128 v[168:171], v129 offset:32768
	ds_read_b128 v[172:175], v129 offset:33792
	ds_read_b128 v[176:179], v132 offset:32768
	ds_read_b128 v[180:183], v132 offset:33792
	ds_read_b128 v[184:187], v131 offset:32768
	ds_read_b128 v[188:191], v131 offset:33792
	ds_read_b128 v[192:195], v130 offset:32768
	ds_read_b128 v[196:199], v130 offset:33792
	buffer_load_dwordx4 v141, s[8:11], s6 offen lds
	s_mov_b32 m0, s52
	s_nop 0
	buffer_load_dwordx4 v142, s[8:11], s6 offen lds
	s_waitcnt lgkmcnt(8)
	s_barrier
	s_waitcnt lgkmcnt(0)
	s_waitcnt lgkmcnt(7)
	v_mfma_f32_16x16x32_bf16 v[124:127], v[152:155], v[168:171], v[124:127]
	v_mfma_f32_16x16x32_bf16 v[120:123], v[160:163], v[168:171], v[120:123]
	s_waitcnt lgkmcnt(5)
	v_mfma_f32_16x16x32_bf16 v[116:119], v[152:155], v[176:179], v[116:119]
	v_mfma_f32_16x16x32_bf16 v[112:115], v[160:163], v[176:179], v[112:115]
	s_waitcnt lgkmcnt(3)
	v_mfma_f32_16x16x32_bf16 v[108:111], v[152:155], v[184:187], v[108:111]
	v_mfma_f32_16x16x32_bf16 v[104:107], v[160:163], v[184:187], v[104:107]
	s_waitcnt lgkmcnt(1)
	v_mfma_f32_16x16x32_bf16 v[100:103], v[152:155], v[192:195], v[100:103]
	v_mfma_f32_16x16x32_bf16 v[96:99], v[160:163], v[192:195], v[96:99]
	v_mfma_f32_16x16x32_bf16 v[124:127], v[156:159], v[172:175], v[124:127]
	v_mfma_f32_16x16x32_bf16 v[120:123], v[164:167], v[172:175], v[120:123]
	v_mfma_f32_16x16x32_bf16 v[116:119], v[156:159], v[180:183], v[116:119]
	v_mfma_f32_16x16x32_bf16 v[112:115], v[164:167], v[180:183], v[112:115]
	v_mfma_f32_16x16x32_bf16 v[108:111], v[156:159], v[188:191], v[108:111]
	v_mfma_f32_16x16x32_bf16 v[104:107], v[164:167], v[188:191], v[104:107]
	s_waitcnt lgkmcnt(0)
	v_mfma_f32_16x16x32_bf16 v[100:103], v[156:159], v[196:199], v[100:103]
	v_mfma_f32_16x16x32_bf16 v[96:99], v[164:167], v[196:199], v[96:99]
	s_barrier
	s_addk_i32 s7, 0x180
	s_mov_b32 m0, s45
	ds_read_b128 v[200:203], v133
	ds_read_b128 v[204:207], v134
	ds_read_b128 v[208:211], v135
	ds_read_b128 v[212:215], v136
	buffer_load_dwordx4 v141, s[12:15], s7 offen lds
	s_mov_b32 m0, s53
	s_nop 0
	buffer_load_dwordx4 v142, s[12:15], s7 offen lds
	s_barrier
	s_waitcnt lgkmcnt(0)
	s_waitcnt lgkmcnt(3)
	v_mfma_f32_16x16x32_bf16 v[92:95], v[200:203], v[168:171], v[92:95]
	s_waitcnt lgkmcnt(1)
	v_mfma_f32_16x16x32_bf16 v[88:91], v[208:211], v[168:171], v[88:91]
	v_mfma_f32_16x16x32_bf16 v[80:83], v[200:203], v[176:179], v[80:83]
	v_mfma_f32_16x16x32_bf16 v[68:71], v[208:211], v[176:179], v[68:71]
	v_mfma_f32_16x16x32_bf16 v[60:63], v[200:203], v[184:187], v[60:63]
	v_mfma_f32_16x16x32_bf16 v[56:59], v[208:211], v[184:187], v[56:59]
	v_mfma_f32_16x16x32_bf16 v[52:55], v[200:203], v[192:195], v[52:55]
	v_mfma_f32_16x16x32_bf16 v[48:51], v[208:211], v[192:195], v[48:51]
	v_mfma_f32_16x16x32_bf16 v[92:95], v[204:207], v[172:175], v[92:95]
	s_waitcnt lgkmcnt(0)
	v_mfma_f32_16x16x32_bf16 v[88:91], v[212:215], v[172:175], v[88:91]
	v_mfma_f32_16x16x32_bf16 v[80:83], v[204:207], v[180:183], v[80:83]
	v_mfma_f32_16x16x32_bf16 v[68:71], v[212:215], v[180:183], v[68:71]
	v_mfma_f32_16x16x32_bf16 v[60:63], v[204:207], v[188:191], v[60:63]
	v_mfma_f32_16x16x32_bf16 v[56:59], v[212:215], v[188:191], v[56:59]
	v_mfma_f32_16x16x32_bf16 v[52:55], v[204:207], v[196:199], v[52:55]
	v_mfma_f32_16x16x32_bf16 v[48:51], v[212:215], v[196:199], v[48:51]
	s_addk_i32 s23, 0x180
	s_mov_b32 m0, s46
	s_barrier
	ds_read_b128 v[168:171], v129 offset:49152
	ds_read_b128 v[172:175], v129 offset:50176
	ds_read_b128 v[176:179], v132 offset:49152
	ds_read_b128 v[180:183], v132 offset:50176
	ds_read_b128 v[184:187], v131 offset:49152
	ds_read_b128 v[188:191], v131 offset:50176
	ds_read_b128 v[192:195], v130 offset:49152
	ds_read_b128 v[196:199], v130 offset:50176
	buffer_load_dwordx4 v141, s[8:11], s23 offen lds
	s_mov_b32 m0, s54
	s_nop 0
	buffer_load_dwordx4 v142, s[8:11], s23 offen lds
	s_barrier
; #define STAGE(P, RS, SOFF, OFF, kt) do { const int _so = (SOFF) + (kt) * (BK * 2); \
;     _Pragma("unroll") for (int _i = 0; _i < 2; ++_i) { \
;       __builtin_amdgcn_raw_ptr_buffer_load_lds(RS, (__attribute__((address_space(3))) void*)((P) + wave * 1024 + _i * 8192), 16, OFF[_i], _so, 0, 0); } } while (0)
; #define LDA(dst, b, h) _Pragma("unroll") for (int m = 0; m < 4; ++m) _Pragma("unroll") for (int k = 0; k < 2; ++k) \
;     dst[m][k] = *reinterpret_cast<const bf16x8*>(SA(b, h) + lds_byte(wr * 64 + m * 16 + fr, k * 32 + fq * 8))
; #define LDB(dst, b, h) _Pragma("unroll") for (int n = 0; n < 2; ++n) _Pragma("unroll") for (int k = 0; k < 2; ++k) \
;     dst[n][k] = *reinterpret_cast<const bf16x8*>(SB(b, h) + lds_byte(wc * 32 + n * 16 + fr, k * 32 + fq * 8))
; #define WAIT_V(n) asm volatile("s_waitcnt vmcnt(" #n ")" ::: "memory")
; #define WAIT_L(n) asm volatile("s_waitcnt lgkmcnt(" #n ")" ::: "memory")
; #define BAR __builtin_amdgcn_s_barrier()
; #define SCHED __builtin_amdgcn_sched_barrier(0)
;     ...
;       BAR; WAIT_L(0); MMA(1, 0, At, B0); BAR; SCHED;
;       STAGE(SB(1, 1), rsB, sB1, offB, t + 3);
;       WAIT_V(6); BAR; MMA(1, 1, At, B1); BAR;
;     }
;     { LDB(B0, 0, 0); LDA(At, 0, 0); STAGE(SA(1, 1), rsA, sA1, offA, nt - 1);
;       BAR; WAIT_L(0); MMA(0, 0, At, B0); BAR;
;       LDB(B1, 0, 1); BAR; WAIT_L(0); MMA(0, 1, At, B1); BAR;
	s_waitcnt lgkmcnt(0)
	s_waitcnt lgkmcnt(7)
	v_mfma_f32_16x16x32_bf16 v[44:47], v[152:155], v[168:171], v[44:47]
	v_mfma_f32_16x16x32_bf16 v[40:43], v[160:163], v[168:171], v[40:43]
	s_waitcnt lgkmcnt(5)
	v_mfma_f32_16x16x32_bf16 v[36:39], v[152:155], v[176:179], v[36:39]
	v_mfma_f32_16x16x32_bf16 v[32:35], v[160:163], v[176:179], v[32:35]
	s_waitcnt lgkmcnt(3)
	v_mfma_f32_16x16x32_bf16 v[28:31], v[152:155], v[184:187], v[28:31]
	v_mfma_f32_16x16x32_bf16 v[24:27], v[160:163], v[184:187], v[24:27]
	s_waitcnt lgkmcnt(1)
	v_mfma_f32_16x16x32_bf16 v[20:23], v[152:155], v[192:195], v[20:23]
	v_mfma_f32_16x16x32_bf16 v[16:19], v[160:163], v[192:195], v[16:19]
	v_mfma_f32_16x16x32_bf16 v[44:47], v[156:159], v[172:175], v[44:47]
	v_mfma_f32_16x16x32_bf16 v[40:43], v[164:167], v[172:175], v[40:43]
	v_mfma_f32_16x16x32_bf16 v[36:39], v[156:159], v[180:183], v[36:39]
	v_mfma_f32_16x16x32_bf16 v[32:35], v[164:167], v[180:183], v[32:35]
	v_mfma_f32_16x16x32_bf16 v[28:31], v[156:159], v[188:191], v[28:31]
	v_mfma_f32_16x16x32_bf16 v[24:27], v[164:167], v[188:191], v[24:27]
	s_waitcnt lgkmcnt(0)
	v_mfma_f32_16x16x32_bf16 v[20:23], v[156:159], v[196:199], v[20:23]
	v_mfma_f32_16x16x32_bf16 v[16:19], v[164:167], v[196:199], v[16:19]
	s_barrier
	s_addk_i32 s26, 0x180
	s_mov_b32 m0, s47
	s_nop 0
	buffer_load_dwordx4 v141, s[12:15], s26 offen lds
	s_mov_b32 m0, s55
	s_nop 0
	buffer_load_dwordx4 v142, s[12:15], s26 offen lds
	s_waitcnt vmcnt(6)
	s_barrier
	v_mfma_f32_16x16x32_bf16 v[12:15], v[200:203], v[168:171], v[12:15]
	v_mfma_f32_16x16x32_bf16 v[8:11], v[208:211], v[168:171], v[8:11]
	v_mfma_f32_16x16x32_bf16 v[4:7], v[200:203], v[176:179], v[4:7]
	v_mfma_f32_16x16x32_bf16 v[0:3], v[208:211], v[176:179], v[0:3]
	v_mfma_f32_16x16x32_bf16 v[64:67], v[200:203], v[184:187], v[64:67]
	v_mfma_f32_16x16x32_bf16 v[72:75], v[208:211], v[184:187], v[72:75]
	v_mfma_f32_16x16x32_bf16 v[76:79], v[200:203], v[192:195], v[76:79]
	v_mfma_f32_16x16x32_bf16 v[84:87], v[208:211], v[192:195], v[84:87]
	v_mfma_f32_16x16x32_bf16 v[12:15], v[204:207], v[172:175], v[12:15]
	v_mfma_f32_16x16x32_bf16 v[8:11], v[212:215], v[172:175], v[8:11]
	v_mfma_f32_16x16x32_bf16 v[4:7], v[204:207], v[180:183], v[4:7]
	v_mfma_f32_16x16x32_bf16 v[0:3], v[212:215], v[180:183], v[0:3]
	v_mfma_f32_16x16x32_bf16 v[64:67], v[204:207], v[188:191], v[64:67]
	v_mfma_f32_16x16x32_bf16 v[72:75], v[212:215], v[188:191], v[72:75]
	v_mfma_f32_16x16x32_bf16 v[76:79], v[204:207], v[196:199], v[76:79]
	v_mfma_f32_16x16x32_bf16 v[84:87], v[212:215], v[196:199], v[84:87]
	s_add_i32 s4, s4, 2
	s_addk_i32 s5, 0x100
	s_cmp_gt_u32 s4, 59
	s_barrier
	s_cbranch_scc0 .LBB0_757
	s_add_i32 s4, s85, 0x1f80
	s_mov_b32 m0, s39
	ds_read_b128 v[152:155], v147
	ds_read_b128 v[156:159], v148
	ds_read_b128 v[160:163], v149
	ds_read_b128 v[148:151], v150
	ds_read_b128 v[164:167], v129
	ds_read_b128 v[168:171], v129 offset:1024
	ds_read_b128 v[172:175], v132
	ds_read_b128 v[176:179], v132 offset:1024
	ds_read_b128 v[180:183], v131
	ds_read_b128 v[184:187], v131 offset:1024
	ds_read_b128 v[188:191], v130
	ds_read_b128 v[192:195], v130 offset:1024
	buffer_load_dwordx4 v141, s[8:11], s4 offen lds
	s_mov_b32 m0, s56
	s_nop 0
	buffer_load_dwordx4 v142, s[8:11], s4 offen lds
	s_barrier
	s_waitcnt lgkmcnt(0)
	s_waitcnt lgkmcnt(7)
	v_mfma_f32_16x16x32_bf16 v[124:127], v[152:155], v[164:167], v[124:127]
	v_mfma_f32_16x16x32_bf16 v[120:123], v[160:163], v[164:167], v[120:123]
	s_waitcnt lgkmcnt(5)
	v_mfma_f32_16x16x32_bf16 v[116:119], v[152:155], v[172:175], v[116:119]
	v_mfma_f32_16x16x32_bf16 v[112:115], v[160:163], v[172:175], v[112:115]
	s_waitcnt lgkmcnt(3)
	v_mfma_f32_16x16x32_bf16 v[108:111], v[152:155], v[180:183], v[108:111]
	v_mfma_f32_16x16x32_bf16 v[104:107], v[160:163], v[180:183], v[104:107]
	s_waitcnt lgkmcnt(1)
	v_mfma_f32_16x16x32_bf16 v[100:103], v[152:155], v[188:191], v[100:103]
	v_mfma_f32_16x16x32_bf16 v[96:99], v[160:163], v[188:191], v[96:99]
	v_mfma_f32_16x16x32_bf16 v[124:127], v[156:159], v[168:171], v[124:127]
	v_mfma_f32_16x16x32_bf16 v[120:123], v[148:151], v[168:171], v[120:123]
	v_mfma_f32_16x16x32_bf16 v[116:119], v[156:159], v[176:179], v[116:119]
	v_mfma_f32_16x16x32_bf16 v[112:115], v[148:151], v[176:179], v[112:115]
	v_mfma_f32_16x16x32_bf16 v[108:111], v[156:159], v[184:187], v[108:111]
	v_mfma_f32_16x16x32_bf16 v[104:107], v[148:151], v[184:187], v[104:107]
	s_waitcnt lgkmcnt(0)
	v_mfma_f32_16x16x32_bf16 v[100:103], v[156:159], v[192:195], v[100:103]
	v_mfma_f32_16x16x32_bf16 v[96:99], v[148:151], v[192:195], v[96:99]
	s_barrier
	ds_read_b128 v[196:199], v143
	ds_read_b128 v[200:203], v144
	ds_read_b128 v[142:145], v145
	ds_read_b128 v[204:207], v146
	s_barrier
	s_waitcnt lgkmcnt(0)
	s_waitcnt lgkmcnt(1)
	v_mfma_f32_16x16x32_bf16 v[88:91], v[142:145], v[164:167], v[88:91]
	v_mfma_f32_16x16x32_bf16 v[80:83], v[196:199], v[172:175], v[80:83]
	v_mfma_f32_16x16x32_bf16 v[60:63], v[196:199], v[180:183], v[60:63]
	v_mfma_f32_16x16x32_bf16 v[56:59], v[142:145], v[180:183], v[56:59]
	v_mfma_f32_16x16x32_bf16 v[52:55], v[196:199], v[188:191], v[52:55]
	v_mfma_f32_16x16x32_bf16 v[48:51], v[142:145], v[188:191], v[48:51]
	v_mfma_f32_16x16x32_bf16 v[92:95], v[196:199], v[164:167], v[92:95]
	v_mfma_f32_16x16x32_bf16 v[68:71], v[142:145], v[172:175], v[68:71]
	s_waitcnt lgkmcnt(0)
	v_mfma_f32_16x16x32_bf16 v[88:91], v[204:207], v[168:171], v[88:91]
	v_mfma_f32_16x16x32_bf16 v[80:83], v[200:203], v[176:179], v[80:83]
	v_mfma_f32_16x16x32_bf16 v[60:63], v[200:203], v[184:187], v[60:63]
	v_mfma_f32_16x16x32_bf16 v[56:59], v[204:207], v[184:187], v[56:59]
	v_mfma_f32_16x16x32_bf16 v[52:55], v[200:203], v[192:195], v[52:55]
	v_mfma_f32_16x16x32_bf16 v[48:51], v[204:207], v[192:195], v[48:51]
	v_mfma_f32_16x16x32_bf16 v[164:167], v[200:203], v[168:171], v[92:95]
	v_mfma_f32_16x16x32_bf16 v[168:171], v[204:207], v[176:179], v[68:71]
	s_barrier
; #define LDA(dst, b, h) _Pragma("unroll") for (int m = 0; m < 4; ++m) _Pragma("unroll") for (int k = 0; k < 2; ++k) \
;     dst[m][k] = *reinterpret_cast<const bf16x8*>(SA(b, h) + lds_byte(wr * 64 + m * 16 + fr, k * 32 + fq * 8))
; #define LDB(dst, b, h) _Pragma("unroll") for (int n = 0; n < 2; ++n) _Pragma("unroll") for (int k = 0; k < 2; ++k) \
;     dst[n][k] = *reinterpret_cast<const bf16x8*>(SB(b, h) + lds_byte(wc * 32 + n * 16 + fr, k * 32 + fq * 8))
; #define WAIT_V(n) asm volatile("s_waitcnt vmcnt(" #n ")" ::: "memory")
; #define WAIT_L(n) asm volatile("s_waitcnt lgkmcnt(" #n ")" ::: "memory")
; #define BAR __builtin_amdgcn_s_barrier()
;     ...
;       LDA(At, 0, 1); WAIT_V(4); BAR; WAIT_L(0); MMA(1, 0, At, B0); MMA(1, 1, At, B1); BAR; }
;     { LDB(B0, 1, 0); LDA(At, 1, 0); WAIT_V(2); BAR; WAIT_L(0); MMA(0, 0, At, B0); BAR;
	s_nop 0
	ds_read_b128 v[68:71], v129 offset:16384
	ds_read_b128 v[92:95], v129 offset:17408
	ds_read_b128 v[172:175], v132 offset:16384
	ds_read_b128 v[176:179], v132 offset:17408
	ds_read_b128 v[180:183], v131 offset:16384
	ds_read_b128 v[184:187], v131 offset:17408
	ds_read_b128 v[188:191], v130 offset:16384
	ds_read_b128 v[192:195], v130 offset:17408
	s_waitcnt vmcnt(4)
	s_barrier
	s_waitcnt lgkmcnt(0)
	s_waitcnt lgkmcnt(7)
	v_mfma_f32_16x16x32_bf16 v[44:47], v[152:155], v[68:71], v[44:47]
	v_mfma_f32_16x16x32_bf16 v[40:43], v[160:163], v[68:71], v[40:43]
	s_waitcnt lgkmcnt(5)
	v_mfma_f32_16x16x32_bf16 v[36:39], v[152:155], v[172:175], v[36:39]
	v_mfma_f32_16x16x32_bf16 v[32:35], v[160:163], v[172:175], v[32:35]
	s_waitcnt lgkmcnt(3)
	v_mfma_f32_16x16x32_bf16 v[28:31], v[152:155], v[180:183], v[28:31]
	v_mfma_f32_16x16x32_bf16 v[24:27], v[160:163], v[180:183], v[24:27]
	s_waitcnt lgkmcnt(1)
	v_mfma_f32_16x16x32_bf16 v[20:23], v[152:155], v[188:191], v[20:23]
	v_mfma_f32_16x16x32_bf16 v[16:19], v[160:163], v[188:191], v[16:19]
	v_mfma_f32_16x16x32_bf16 v[44:47], v[156:159], v[92:95], v[44:47]
	v_mfma_f32_16x16x32_bf16 v[40:43], v[148:151], v[92:95], v[40:43]
	v_mfma_f32_16x16x32_bf16 v[36:39], v[156:159], v[176:179], v[36:39]
	v_mfma_f32_16x16x32_bf16 v[32:35], v[148:151], v[176:179], v[32:35]
	v_mfma_f32_16x16x32_bf16 v[28:31], v[156:159], v[184:187], v[28:31]
	v_mfma_f32_16x16x32_bf16 v[24:27], v[148:151], v[184:187], v[24:27]
	s_waitcnt lgkmcnt(0)
	v_mfma_f32_16x16x32_bf16 v[20:23], v[156:159], v[192:195], v[20:23]
	v_mfma_f32_16x16x32_bf16 v[16:19], v[148:151], v[192:195], v[16:19]
	v_mfma_f32_16x16x32_bf16 v[4:7], v[196:199], v[172:175], v[4:7]
	v_mfma_f32_16x16x32_bf16 v[0:3], v[142:145], v[172:175], v[0:3]
	v_mfma_f32_16x16x32_bf16 v[12:15], v[196:199], v[68:71], v[12:15]
	v_mfma_f32_16x16x32_bf16 v[8:11], v[142:145], v[68:71], v[8:11]
	v_mfma_f32_16x16x32_bf16 v[64:67], v[196:199], v[180:183], v[64:67]
	v_mfma_f32_16x16x32_bf16 v[68:71], v[142:145], v[180:183], v[72:75]
	v_mfma_f32_16x16x32_bf16 v[72:75], v[196:199], v[188:191], v[76:79]
	v_mfma_f32_16x16x32_bf16 v[76:79], v[142:145], v[188:191], v[84:87]
	v_mfma_f32_16x16x32_bf16 v[4:7], v[200:203], v[176:179], v[4:7]
	v_mfma_f32_16x16x32_bf16 v[0:3], v[204:207], v[176:179], v[0:3]
	v_mfma_f32_16x16x32_bf16 v[142:145], v[200:203], v[92:95], v[12:15]
	v_mfma_f32_16x16x32_bf16 v[146:149], v[204:207], v[92:95], v[8:11]
	v_mfma_f32_16x16x32_bf16 v[150:153], v[200:203], v[184:187], v[64:67]
	v_mfma_f32_16x16x32_bf16 v[154:157], v[204:207], v[184:187], v[68:71]
	v_mfma_f32_16x16x32_bf16 v[158:161], v[200:203], v[192:195], v[72:75]
	v_mfma_f32_16x16x32_bf16 v[172:175], v[204:207], v[192:195], v[76:79]
	s_barrier
	ds_read_b128 v[8:11], v137
	ds_read_b128 v[12:15], v138
	ds_read_b128 v[176:179], v139
	ds_read_b128 v[138:141], v140
	ds_read_b128 v[64:67], v129 offset:32768
	ds_read_b128 v[72:75], v129 offset:33792
	ds_read_b128 v[180:183], v132 offset:32768
	ds_read_b128 v[184:187], v132 offset:33792
	ds_read_b128 v[188:191], v131 offset:32768
	ds_read_b128 v[192:195], v131 offset:33792
	ds_read_b128 v[196:199], v130 offset:32768
	ds_read_b128 v[200:203], v130 offset:33792
	s_waitcnt vmcnt(2)
	s_barrier
	s_waitcnt lgkmcnt(0)
	s_waitcnt lgkmcnt(7)
	v_mfma_f32_16x16x32_bf16 v[68:71], v[8:11], v[64:67], v[124:127]
	v_mfma_f32_16x16x32_bf16 v[76:79], v[176:179], v[64:67], v[120:123]
	s_waitcnt lgkmcnt(5)
	v_mfma_f32_16x16x32_bf16 v[84:87], v[8:11], v[180:183], v[116:119]
	v_mfma_f32_16x16x32_bf16 v[92:95], v[176:179], v[180:183], v[112:115]
	s_waitcnt lgkmcnt(3)
	v_mfma_f32_16x16x32_bf16 v[112:115], v[8:11], v[188:191], v[108:111]
	v_mfma_f32_16x16x32_bf16 v[104:107], v[176:179], v[188:191], v[104:107]
	s_waitcnt lgkmcnt(1)
	v_mfma_f32_16x16x32_bf16 v[120:123], v[8:11], v[196:199], v[100:103]
	v_mfma_f32_16x16x32_bf16 v[96:99], v[176:179], v[196:199], v[96:99]
	v_mfma_f32_16x16x32_bf16 v[124:127], v[12:15], v[72:75], v[68:71]
	v_mfma_f32_16x16x32_bf16 v[116:119], v[138:141], v[72:75], v[76:79]
	v_mfma_f32_16x16x32_bf16 v[108:111], v[12:15], v[184:187], v[84:87]
	v_mfma_f32_16x16x32_bf16 v[100:103], v[138:141], v[184:187], v[92:95]
	v_mfma_f32_16x16x32_bf16 v[92:95], v[12:15], v[192:195], v[112:115]
	v_mfma_f32_16x16x32_bf16 v[84:87], v[138:141], v[192:195], v[104:107]
	s_waitcnt lgkmcnt(0)
	v_mfma_f32_16x16x32_bf16 v[76:79], v[12:15], v[200:203], v[120:123]
	v_mfma_f32_16x16x32_bf16 v[68:71], v[138:141], v[200:203], v[96:99]
	s_barrier
; #define LDA(dst, b, h) _Pragma("unroll") for (int m = 0; m < 4; ++m) _Pragma("unroll") for (int k = 0; k < 2; ++k) \
;     dst[m][k] = *reinterpret_cast<const bf16x8*>(SA(b, h) + lds_byte(wr * 64 + m * 16 + fr, k * 32 + fq * 8))
; #define LDB(dst, b, h) _Pragma("unroll") for (int n = 0; n < 2; ++n) _Pragma("unroll") for (int k = 0; k < 2; ++k) \
;     dst[n][k] = *reinterpret_cast<const bf16x8*>(SB(b, h) + lds_byte(wc * 32 + n * 16 + fr, k * 32 + fq * 8))
; #define WAIT_V(n) asm volatile("s_waitcnt vmcnt(" #n ")" ::: "memory")
; #define WAIT_L(n) asm volatile("s_waitcnt lgkmcnt(" #n ")" ::: "memory")
; #define BAR __builtin_amdgcn_s_barrier()
;     ...
;       LDB(B1, 1, 1); WAIT_V(0); BAR; WAIT_L(0); MMA(0, 1, At, B1); BAR;
;       LDA(At, 1, 1); BAR; WAIT_L(0); MMA(1, 0, At, B0); MMA(1, 1, At, B1); BAR; }
;     if (wr == 0) BAR;
	ds_read_b128 v[204:207], v133
	ds_read_b128 v[208:211], v134
	ds_read_b128 v[212:215], v135
	ds_read_b128 v[134:137], v136
	s_waitcnt vmcnt(0)
	s_barrier
	s_waitcnt lgkmcnt(0)
	s_waitcnt lgkmcnt(3)
	v_mfma_f32_16x16x32_bf16 v[96:99], v[204:207], v[64:67], v[164:167]
	s_waitcnt lgkmcnt(1)
	v_mfma_f32_16x16x32_bf16 v[64:67], v[212:215], v[64:67], v[88:91]
	v_mfma_f32_16x16x32_bf16 v[80:83], v[204:207], v[180:183], v[80:83]
	v_mfma_f32_16x16x32_bf16 v[88:91], v[212:215], v[180:183], v[168:171]
	v_mfma_f32_16x16x32_bf16 v[60:63], v[204:207], v[188:191], v[60:63]
	v_mfma_f32_16x16x32_bf16 v[56:59], v[212:215], v[188:191], v[56:59]
	v_mfma_f32_16x16x32_bf16 v[52:55], v[204:207], v[196:199], v[52:55]
	v_mfma_f32_16x16x32_bf16 v[48:51], v[212:215], v[196:199], v[48:51]
	v_mfma_f32_16x16x32_bf16 v[120:123], v[208:211], v[72:75], v[96:99]
	s_waitcnt lgkmcnt(0)
	v_mfma_f32_16x16x32_bf16 v[112:115], v[134:137], v[72:75], v[64:67]
	v_mfma_f32_16x16x32_bf16 v[104:107], v[208:211], v[184:187], v[80:83]
	v_mfma_f32_16x16x32_bf16 v[96:99], v[134:137], v[184:187], v[88:91]
	v_mfma_f32_16x16x32_bf16 v[88:91], v[208:211], v[192:195], v[60:63]
	v_mfma_f32_16x16x32_bf16 v[80:83], v[134:137], v[192:195], v[56:59]
	v_mfma_f32_16x16x32_bf16 v[72:75], v[208:211], v[200:203], v[52:55]
	v_mfma_f32_16x16x32_bf16 v[64:67], v[134:137], v[200:203], v[48:51]
	s_barrier
	s_nop 0
	ds_read_b128 v[48:51], v129 offset:49152
	ds_read_b128 v[162:165], v129 offset:50176
	ds_read_b128 v[52:55], v132 offset:49152
	ds_read_b128 v[166:169], v132 offset:50176
	ds_read_b128 v[180:183], v131 offset:49152
	ds_read_b128 v[184:187], v131 offset:50176
	ds_read_b128 v[188:191], v130 offset:49152
	ds_read_b128 v[130:133], v130 offset:50176
	s_barrier
	s_waitcnt lgkmcnt(0)
	s_waitcnt lgkmcnt(7)
	v_mfma_f32_16x16x32_bf16 v[44:47], v[8:11], v[48:51], v[44:47]
	v_mfma_f32_16x16x32_bf16 v[40:43], v[176:179], v[48:51], v[40:43]
	s_waitcnt lgkmcnt(5)
	v_mfma_f32_16x16x32_bf16 v[36:39], v[8:11], v[52:55], v[36:39]
	v_mfma_f32_16x16x32_bf16 v[32:35], v[176:179], v[52:55], v[32:35]
	s_waitcnt lgkmcnt(3)
	v_mfma_f32_16x16x32_bf16 v[28:31], v[8:11], v[180:183], v[28:31]
	v_mfma_f32_16x16x32_bf16 v[24:27], v[176:179], v[180:183], v[24:27]
	s_waitcnt lgkmcnt(1)
	v_mfma_f32_16x16x32_bf16 v[8:11], v[8:11], v[188:191], v[20:23]
	v_mfma_f32_16x16x32_bf16 v[16:19], v[176:179], v[188:191], v[16:19]
	v_mfma_f32_16x16x32_bf16 v[60:63], v[12:15], v[162:165], v[44:47]
	v_mfma_f32_16x16x32_bf16 v[56:59], v[138:141], v[162:165], v[40:43]
	v_mfma_f32_16x16x32_bf16 v[44:47], v[12:15], v[166:169], v[36:39]
	v_mfma_f32_16x16x32_bf16 v[40:43], v[138:141], v[166:169], v[32:35]
	v_mfma_f32_16x16x32_bf16 v[28:31], v[12:15], v[184:187], v[28:31]
	v_mfma_f32_16x16x32_bf16 v[24:27], v[138:141], v[184:187], v[24:27]
	s_waitcnt lgkmcnt(0)
	v_mfma_f32_16x16x32_bf16 v[12:15], v[12:15], v[130:133], v[8:11]
	v_mfma_f32_16x16x32_bf16 v[8:11], v[138:141], v[130:133], v[16:19]
	v_mfma_f32_16x16x32_bf16 v[16:19], v[204:207], v[48:51], v[142:145]
	v_mfma_f32_16x16x32_bf16 v[20:23], v[212:215], v[48:51], v[146:149]
	v_mfma_f32_16x16x32_bf16 v[4:7], v[204:207], v[52:55], v[4:7]
	v_mfma_f32_16x16x32_bf16 v[0:3], v[212:215], v[52:55], v[0:3]
	v_mfma_f32_16x16x32_bf16 v[138:141], v[204:207], v[180:183], v[150:153]
	v_mfma_f32_16x16x32_bf16 v[142:145], v[212:215], v[180:183], v[154:157]
	v_mfma_f32_16x16x32_bf16 v[146:149], v[204:207], v[188:191], v[158:161]
	v_mfma_f32_16x16x32_bf16 v[150:153], v[212:215], v[188:191], v[172:175]
	v_mfma_f32_16x16x32_bf16 v[52:55], v[208:211], v[162:165], v[16:19]
	v_mfma_f32_16x16x32_bf16 v[48:51], v[134:137], v[162:165], v[20:23]
	v_mfma_f32_16x16x32_bf16 v[36:39], v[208:211], v[166:169], v[4:7]
	v_mfma_f32_16x16x32_bf16 v[32:35], v[134:137], v[166:169], v[0:3]
	v_mfma_f32_16x16x32_bf16 v[20:23], v[208:211], v[184:187], v[138:141]
	v_mfma_f32_16x16x32_bf16 v[16:19], v[134:137], v[184:187], v[142:145]
	v_mfma_f32_16x16x32_bf16 v[4:7], v[208:211], v[130:133], v[146:149]
	v_mfma_f32_16x16x32_bf16 v[0:3], v[134:137], v[130:133], v[150:153]
	v_cmp_gt_u32_e32 vcc, s74, v128
	s_barrier
	s_and_saveexec_b64 s[4:5], vcc
	s_cbranch_execz .LBB0_760
	s_barrier
